# speedup vs baseline: 1.0326x; 1.0144x over previous
; #define GW_LOAD(KOFF) GW_LOAD2(KOFF, 0)
;   int tid = threadIdx.x;
;   asm volatile("" : "+v"(tid));
;   const int lane = tid & 63, wave = tid >> 6;
;   const int wm = wave >> 1, wn = wave & 1;
;   const int lr = tid >> 3, kc = tid & 7;
;   const u16* ap0 = arow(lr) + kc * 8;
;   const u16* ap1 = arow(lr + 32) + kc * 8;
;   const u16* ap2 = arow(lr + 64) + kc * 8;
;   const u16* ap3 = arow(lr + 96) + kc * 8;
;   const u16* bp0 = Bt + (size_t)lr * ldb + kc * 8;
;   const size_t bstep = 32 * ldb;
;   const int so = lr * LSTR + kc * 16;
;   uint4 ra0, ra1, ra2, ra3, rb0, rb1, rb2, rb3, rb4, rb5, rb6, rb7;
;     ...
;   GW_LOAD(0)
;   GW_STORE()
;   __syncthreads();
; __device__ __forceinline__ void inproj_tile(const Params& P, int l, int mt, int ntw, char* smem) {
;   f32x16 acc[2][4];
; #pragma unroll
;   for (int i = 0; i < 2; ++i)
; #pragma unroll
;     for (int j = 0; j < 4; ++j)
; #pragma unroll
;       for (int r = 0; r < 16; ++r) acc[i][j][r] = 0.f;
;   {
;     const u16* H = WSP(u16, OFF_H) + (size_t)mt * 128 * DM;
;     const u16* Bt = WSP(u16, OFF_WIN) + ((size_t)l * PW + ntw * 256) * DM;
;     gemm_wide([&](int r) { return H + (size_t)r * DM; }, Bt, DM, DM, smem, acc);
.LBB0_236:
	s_lshl_b32 s8, s49, 6
	s_and_b32 s8, s8, 0x1c0
	s_and_b32 s10, s49, 0xfffffe00
	s_or_b32 s8, s8, s10
	s_bfe_u32 s10, s49, 0x60003
	s_or_b32 s8, s8, s10
	s_and_b64 s[10:11], s[0:1], exec
	s_cselect_b32 s8, s8, s49
	s_cmpk_gt_i32 s8, 0x186f
	s_cbranch_scc1 .LBB0_235
	s_mul_hi_i32 s10, s8, 0xb21642c9
	s_add_i32 s10, s10, s8
	s_lshr_b32 s11, s10, 31
	s_ashr_i32 s18, s10, 7
	s_add_i32 s18, s18, s11
	s_lshl_b32 s10, s18, 3
	s_and_b32 s19, s8, 7
	s_mul_i32 s11, s18, 0xffffff48
	s_or_b32 s12, s10, s19
	s_add_i32 s11, s11, s8
	s_ashr_i32 s13, s12, 31
	s_ashr_i32 s14, s11, 3
	s_lshl_b64 s[10:11], s[12:13], 18
	s_add_u32 s20, s28, s10
	s_addc_u32 s21, s29, s11
	s_lshl_b32 s16, s14, 8
	v_mov_b32_e32 v54, v134
	s_ashr_i32 s17, s16, 31
	s_lshl_b64 s[22:23], s[16:17], 11
	v_ashrrev_i32_e32 v50, 3, v54
	v_ashrrev_i32_e32 v51, 31, v50
	s_add_u32 s22, s90, s22
	v_lshlrev_b64 v[52:53], 11, v[50:51]
	v_lshlrev_b32_e32 v4, 4, v54
	s_addc_u32 s23, s91, s23
	v_lshl_add_u64 v[2:3], s[20:21], 0, v[52:53]
	v_and_b32_e32 v136, 0x70, v4
	v_lshl_add_u64 v[140:141], v[2:3], 0, v[136:137]
	v_lshl_add_u64 v[2:3], s[22:23], 0, v[52:53]
	v_lshl_add_u64 v[132:133], v[2:3], 0, v[136:137]
	v_add_co_u32_e32 v2, vcc, s37, v140
	v_mad_u64_u32 v[130:131], s[20:21], v50, s36, v[136:137]
	s_nop 0
	v_addc_co_u32_e32 v3, vcc, 0, v141, vcc
	v_add_co_u32_e32 v6, vcc, s38, v140
	s_mov_b32 s8, 0xfffffc0
	s_nop 0
	v_addc_co_u32_e32 v7, vcc, 0, v141, vcc
	v_add_co_u32_e32 v18, vcc, s39, v140
	global_load_dwordx4 v[2:5], v[2:3], off
	s_nop 0
	global_load_dwordx4 v[6:9], v[6:7], off
	v_addc_co_u32_e32 v19, vcc, 0, v141, vcc
	v_add_co_u32_e32 v22, vcc, s37, v132
	global_load_dwordx4 v[10:13], v[140:141], off
	global_load_dwordx4 v[14:17], v[132:133], off
	v_addc_co_u32_e32 v23, vcc, 0, v133, vcc
	v_add_co_u32_e32 v26, vcc, s38, v132
	global_load_dwordx4 v[18:21], v[18:19], off
	s_nop 0
	global_load_dwordx4 v[22:25], v[22:23], off
	v_addc_co_u32_e32 v27, vcc, 0, v133, vcc
	v_add_co_u32_e32 v30, vcc, s39, v132
	s_mov_b64 s[20:21], 0x10000
	s_nop 0
	v_addc_co_u32_e32 v31, vcc, 0, v133, vcc
	v_add_co_u32_e32 v34, vcc, s40, v132
	global_load_dwordx4 v[26:29], v[26:27], off
	s_nop 0
	global_load_dwordx4 v[30:33], v[30:31], off
	v_addc_co_u32_e32 v35, vcc, 0, v133, vcc
	v_add_co_u32_e32 v38, vcc, s41, v132
	v_lshl_add_u64 v[142:143], v[140:141], 0, s[20:21]
	s_nop 0
	v_addc_co_u32_e32 v39, vcc, 0, v133, vcc
	v_add_co_u32_e32 v42, vcc, s42, v132
	global_load_dwordx4 v[34:37], v[34:35], off
	s_nop 0
	global_load_dwordx4 v[38:41], v[38:39], off
	v_addc_co_u32_e32 v43, vcc, 0, v133, vcc
	v_add_co_u32_e32 v46, vcc, s43, v132
	s_mov_b64 s[20:21], 0x20000
	s_nop 0
	v_addc_co_u32_e32 v47, vcc, 0, v133, vcc
	global_load_dwordx4 v[42:45], v[42:43], off
	s_nop 0
	global_load_dwordx4 v[46:49], v[46:47], off
	v_lshl_add_u64 v[144:145], v[140:141], 0, s[20:21]
	s_mov_b64 s[20:21], 0x30000
	v_lshl_add_u64 v[146:147], v[140:141], 0, s[20:21]
	s_waitcnt vmcnt(9)
	ds_write_b128 v130, v[10:13]
	ds_write_b128 v130, v[2:5] offset:4608
	ds_write_b128 v130, v[6:9] offset:9216
	s_waitcnt vmcnt(7)
	ds_write_b128 v130, v[18:21] offset:13824
	ds_write_b128 v130, v[14:17] offset:18432
	s_waitcnt vmcnt(6)
	ds_write_b128 v130, v[22:25] offset:23040
	s_waitcnt vmcnt(5)
	ds_write_b128 v130, v[26:29] offset:27648
	s_waitcnt vmcnt(4)
	ds_write_b128 v130, v[30:33] offset:32256
	s_waitcnt vmcnt(3)
	ds_write_b128 v130, v[34:37] offset:36864
	s_waitcnt vmcnt(2)
	ds_write_b128 v130, v[38:41] offset:41472
	s_waitcnt vmcnt(1)
	ds_write_b128 v130, v[42:45] offset:46080
	s_waitcnt vmcnt(0)
	ds_write_b128 v130, v[46:49] offset:50688
	v_and_b32_e32 v2, 31, v54
	v_lshrrev_b32_e32 v3, 1, v54
	v_and_or_b32 v4, v3, s8, v2
	v_and_b32_e32 v5, 16, v3
	v_lshlrev_b32_e32 v3, 1, v54
	s_movk_i32 s8, 0x80
	v_and_or_b32 v2, v3, s8, v2
	v_mul_u32_u24_e32 v6, 0x90, v2
	v_lshl_add_u64 v[2:3], s[10:11], 0, v[52:53]
	v_or_b32_e32 v2, v2, v136
	v_mul_lo_u32 v4, v4, s36
	v_lshl_add_u64 v[148:149], s[90:91], 0, v[2:3]
	v_mov_b32_e32 v2, 0
	s_mov_b64 s[10:11], 0
	v_add_u32_e32 v131, v4, v5
	v_add_u32_e32 v136, v6, v5
	v_mov_b32_e32 v3, v2
	v_mov_b32_e32 v4, v2
	v_mov_b32_e32 v5, v2
	v_mov_b32_e32 v6, v2
	v_mov_b32_e32 v7, v2
	v_mov_b32_e32 v8, v2
	v_mov_b32_e32 v9, v2
	v_mov_b32_e32 v10, v2
	v_mov_b32_e32 v11, v2
	v_mov_b32_e32 v12, v2
	v_mov_b32_e32 v13, v2
	v_mov_b32_e32 v14, v2
	v_mov_b32_e32 v15, v2
	v_mov_b32_e32 v16, v2
	v_mov_b32_e32 v17, v2
	v_mov_b32_e32 v18, v2
	v_mov_b32_e32 v19, v2
	v_mov_b32_e32 v20, v2
	v_mov_b32_e32 v21, v2
	v_mov_b32_e32 v22, v2
	v_mov_b32_e32 v23, v2
	v_mov_b32_e32 v24, v2
	v_mov_b32_e32 v25, v2
	v_mov_b32_e32 v26, v2
	v_mov_b32_e32 v27, v2
	v_mov_b32_e32 v28, v2
	v_mov_b32_e32 v29, v2
	v_mov_b32_e32 v30, v2
	v_mov_b32_e32 v31, v2
	v_mov_b32_e32 v32, v2
	v_mov_b32_e32 v33, v2
	v_mov_b32_e32 v34, v2
	v_mov_b32_e32 v35, v2
	v_mov_b32_e32 v36, v2
	v_mov_b32_e32 v37, v2
	v_mov_b32_e32 v38, v2
	v_mov_b32_e32 v39, v2
	v_mov_b32_e32 v40, v2
	v_mov_b32_e32 v41, v2
	v_mov_b32_e32 v42, v2
	v_mov_b32_e32 v43, v2
	v_mov_b32_e32 v44, v2
	v_mov_b32_e32 v45, v2
	v_mov_b32_e32 v46, v2
	v_mov_b32_e32 v47, v2
	v_mov_b32_e32 v48, v2
	v_mov_b32_e32 v49, v2
	v_mov_b32_e32 v50, v2
	v_mov_b32_e32 v51, v2
	v_mov_b32_e32 v52, v2
	v_mov_b32_e32 v53, v2
	v_mov_b32_e32 v54, v2
	v_mov_b32_e32 v55, v2
	v_mov_b32_e32 v56, v2
	v_mov_b32_e32 v57, v2
	v_mov_b32_e32 v58, v2
	v_mov_b32_e32 v59, v2
	v_mov_b32_e32 v60, v2
	v_mov_b32_e32 v61, v2
	v_mov_b32_e32 v62, v2
	v_mov_b32_e32 v63, v2
	v_mov_b32_e32 v64, v2
	v_mov_b32_e32 v65, v2
	v_mov_b32_e32 v66, v2
	v_mov_b32_e32 v67, v2
	v_mov_b32_e32 v68, v2
	v_mov_b32_e32 v69, v2
	v_mov_b32_e32 v70, v2
	v_mov_b32_e32 v71, v2
	v_mov_b32_e32 v72, v2
	v_mov_b32_e32 v73, v2
	v_mov_b32_e32 v74, v2
	v_mov_b32_e32 v75, v2
	v_mov_b32_e32 v76, v2
	v_mov_b32_e32 v77, v2
	v_mov_b32_e32 v78, v2
	v_mov_b32_e32 v79, v2
	v_mov_b32_e32 v80, v2
	v_mov_b32_e32 v81, v2
	v_mov_b32_e32 v82, v2
	v_mov_b32_e32 v83, v2
	v_mov_b32_e32 v84, v2
	v_mov_b32_e32 v85, v2
	v_mov_b32_e32 v86, v2
	v_mov_b32_e32 v87, v2
	v_mov_b32_e32 v88, v2
	v_mov_b32_e32 v89, v2
	v_mov_b32_e32 v90, v2
	v_mov_b32_e32 v91, v2
	v_mov_b32_e32 v92, v2
	v_mov_b32_e32 v93, v2
	v_mov_b32_e32 v94, v2
	v_mov_b32_e32 v95, v2
	v_mov_b32_e32 v96, v2
	v_mov_b32_e32 v97, v2
	v_mov_b32_e32 v98, v2
	v_mov_b32_e32 v99, v2
	v_mov_b32_e32 v100, v2
	v_mov_b32_e32 v101, v2
	v_mov_b32_e32 v102, v2
	v_mov_b32_e32 v103, v2
	v_mov_b32_e32 v104, v2
	v_mov_b32_e32 v105, v2
	v_mov_b32_e32 v106, v2
	v_mov_b32_e32 v107, v2
	v_mov_b32_e32 v108, v2
	v_mov_b32_e32 v109, v2
	v_mov_b32_e32 v110, v2
	v_mov_b32_e32 v111, v2
	v_mov_b32_e32 v112, v2
	v_mov_b32_e32 v113, v2
	v_mov_b32_e32 v114, v2
	v_mov_b32_e32 v115, v2
	v_mov_b32_e32 v116, v2
	v_mov_b32_e32 v117, v2
	v_mov_b32_e32 v118, v2
	v_mov_b32_e32 v119, v2
	v_mov_b32_e32 v120, v2
	v_mov_b32_e32 v121, v2
	v_mov_b32_e32 v122, v2
	v_mov_b32_e32 v123, v2
	v_mov_b32_e32 v124, v2
	v_mov_b32_e32 v125, v2
	v_mov_b32_e32 v126, v2
	v_mov_b32_e32 v127, v2
	v_mov_b32_e32 v128, v2
	v_mov_b32_e32 v129, v2
	s_waitcnt lgkmcnt(0)
;     ...
;   for (int kt = 0; kt < nk; ++kt) {
;     const int kn = (kt + 1 < nk) ? kt + 1 : kt;
;     GW_LOAD2(kn * 64, kn * bkstep)
;     __builtin_amdgcn_sched_barrier(0);
;     __builtin_amdgcn_s_setprio(1);
; #pragma unroll
;     for (int st = 0; st < 4; ++st) {
;       bf16x8 a0 = *(const bf16x8*)(Ab + st * 32);
;       bf16x8 a1 = *(const bf16x8*)(Ab + 32 * LSTR + st * 32);
;       bf16x8 b0 = *(const bf16x8*)(Bb + st * 32);
;       bf16x8 b1 = *(const bf16x8*)(Bb + 32 * LSTR + st * 32);
;       bf16x8 b2 = *(const bf16x8*)(Bb + 64 * LSTR + st * 32);
;       bf16x8 b3 = *(const bf16x8*)(Bb + 96 * LSTR + st * 32);
;       acc[0][0] = mfma32(a0, b0, acc[0][0]);
;       acc[0][1] = mfma32(a0, b1, acc[0][1]);
;       acc[0][2] = mfma32(a0, b2, acc[0][2]);
;       acc[0][3] = mfma32(a0, b3, acc[0][3]);
;       acc[1][0] = mfma32(a1, b0, acc[1][0]);
;       acc[1][1] = mfma32(a1, b1, acc[1][1]);
;       acc[1][2] = mfma32(a1, b2, acc[1][2]);
;       acc[1][3] = mfma32(a1, b3, acc[1][3]);
;     }
;     __builtin_amdgcn_s_setprio(0);
	s_barrier
	v_lshl_add_u64 v[150:151], v[148:149], 0, s[10:11]
	v_add_co_u32_e32 v150, vcc, 0x12c31000, v150
	s_nop 1
	v_addc_co_u32_e32 v151, vcc, 0, v151, vcc
	global_load_dwordx4 v[150:153], v[150:151], off offset:384
	v_lshl_add_u64 v[154:155], v[148:149], 0, s[10:11]
	v_add_co_u32_e32 v154, vcc, 0x12c41000, v154
	s_nop 1
	v_addc_co_u32_e32 v155, vcc, 0, v155, vcc
	global_load_dwordx4 v[154:157], v[154:155], off offset:384
	v_lshl_add_u64 v[158:159], v[148:149], 0, s[10:11]
	v_add_co_u32_e32 v158, vcc, 0x12c51000, v158
	s_nop 1
	v_addc_co_u32_e32 v159, vcc, 0, v159, vcc
	global_load_dwordx4 v[158:161], v[158:159], off offset:384
.LBB0_238:
	s_setprio 1
	ds_read_b128 v[202:205], v131 offset:0
	ds_read_b128 v[214:217], v136 offset:18432
	ds_read_b128 v[218:221], v136 offset:23040
	ds_read_b128 v[224:227], v136 offset:27648
	ds_read_b128 v[228:231], v136 offset:32256
	ds_read_b128 v[210:213], v131 offset:4608
	s_waitcnt lgkmcnt(4)
	v_mfma_f32_32x32x16_bf16 v[114:129], v[202:205], v[214:217], v[114:129]
	ds_read_b128 v[206:209], v131 offset:32
	ds_read_b128 v[232:235], v136 offset:18464
	s_waitcnt lgkmcnt(5)
	v_mfma_f32_32x32x16_bf16 v[98:113], v[202:205], v[218:221], v[98:113]
	v_lshl_add_u64 v[162:163], v[148:149], 0, s[10:11]
	v_add_co_u32_e32 v162, vcc, 0x12c61000, v162
	s_nop 1
	v_addc_co_u32_e32 v163, vcc, 0, v163, vcc
	global_load_dwordx4 v[162:165], v[162:163], off offset:384
	ds_read_b128 v[236:239], v136 offset:23072
	s_waitcnt lgkmcnt(5)
	v_mfma_f32_32x32x16_bf16 v[82:97], v[202:205], v[224:227], v[82:97]
	ds_read_b128 v[240:243], v136 offset:27680
	s_waitcnt lgkmcnt(5)
	v_mfma_f32_32x32x16_bf16 v[66:81], v[202:205], v[228:231], v[66:81]
	v_lshl_add_u64 v[166:167], v[132:133], 0, s[10:11]
	global_load_dwordx4 v[166:169], v[166:167], off offset:128
	ds_read_b128 v[244:247], v136 offset:32288
	s_waitcnt lgkmcnt(5)
	v_mfma_f32_32x32x16_bf16 v[50:65], v[210:213], v[214:217], v[50:65]
	v_mfma_f32_32x32x16_bf16 v[34:49], v[210:213], v[218:221], v[34:49]
	v_lshl_add_u64 v[170:171], v[132:133], 0, s[10:11]
	v_add_co_u32_e32 v170, vcc, s37, v170
	s_nop 1
	v_addc_co_u32_e32 v171, vcc, 0, v171, vcc
	global_load_dwordx4 v[170:173], v[170:171], off offset:128
	v_mfma_f32_32x32x16_bf16 v[18:33], v[210:213], v[224:227], v[18:33]
	v_mfma_f32_32x32x16_bf16 v[2:17], v[210:213], v[228:231], v[2:17]
	v_lshl_add_u64 v[174:175], v[132:133], 0, s[10:11]
	v_add_co_u32_e32 v174, vcc, s38, v174
	s_nop 1
	v_addc_co_u32_e32 v175, vcc, 0, v175, vcc
	global_load_dwordx4 v[174:177], v[174:175], off offset:128
	ds_read_b128 v[210:213], v131 offset:4640
	s_waitcnt lgkmcnt(4)
	v_mfma_f32_32x32x16_bf16 v[114:129], v[206:209], v[232:235], v[114:129]
	ds_read_b128 v[202:205], v131 offset:64
	ds_read_b128 v[214:217], v136 offset:18496
	s_waitcnt lgkmcnt(5)
	v_mfma_f32_32x32x16_bf16 v[98:113], v[206:209], v[236:239], v[98:113]
	v_lshl_add_u64 v[178:179], v[132:133], 0, s[10:11]
	v_add_co_u32_e32 v178, vcc, s39, v178
	s_nop 1
	v_addc_co_u32_e32 v179, vcc, 0, v179, vcc
	global_load_dwordx4 v[178:181], v[178:179], off offset:128
	ds_read_b128 v[218:221], v136 offset:23104
	s_waitcnt lgkmcnt(5)
	v_mfma_f32_32x32x16_bf16 v[82:97], v[206:209], v[240:243], v[82:97]
	ds_read_b128 v[224:227], v136 offset:27712
	s_waitcnt lgkmcnt(5)
	v_mfma_f32_32x32x16_bf16 v[66:81], v[206:209], v[244:247], v[66:81]
	v_lshl_add_u64 v[186:187], v[132:133], 0, s[10:11]
	v_add_co_u32_e32 v186, vcc, s40, v186
	s_nop 1
	v_addc_co_u32_e32 v187, vcc, 0, v187, vcc
	global_load_dwordx4 v[186:189], v[186:187], off offset:128
	ds_read_b128 v[228:231], v136 offset:32320
	s_waitcnt lgkmcnt(5)
	v_mfma_f32_32x32x16_bf16 v[50:65], v[210:213], v[232:235], v[50:65]
	v_mfma_f32_32x32x16_bf16 v[34:49], v[210:213], v[236:239], v[34:49]
	v_lshl_add_u64 v[190:191], v[132:133], 0, s[10:11]
	v_add_co_u32_e32 v190, vcc, s41, v190
	s_nop 1
	v_addc_co_u32_e32 v191, vcc, 0, v191, vcc
	global_load_dwordx4 v[190:193], v[190:191], off offset:128
	v_mfma_f32_32x32x16_bf16 v[18:33], v[210:213], v[240:243], v[18:33]
	v_mfma_f32_32x32x16_bf16 v[2:17], v[210:213], v[244:247], v[2:17]
	v_lshl_add_u64 v[194:195], v[132:133], 0, s[10:11]
	v_add_co_u32_e32 v194, vcc, s42, v194
	s_nop 1
	v_addc_co_u32_e32 v195, vcc, 0, v195, vcc
	global_load_dwordx4 v[194:197], v[194:195], off offset:128
	ds_read_b128 v[210:213], v131 offset:4672
	s_waitcnt lgkmcnt(4)
	v_mfma_f32_32x32x16_bf16 v[114:129], v[202:205], v[214:217], v[114:129]
	ds_read_b128 v[206:209], v131 offset:96
	ds_read_b128 v[232:235], v136 offset:18528
	s_waitcnt lgkmcnt(5)
	v_mfma_f32_32x32x16_bf16 v[98:113], v[202:205], v[218:221], v[98:113]
	v_lshl_add_u64 v[198:199], v[132:133], 0, s[10:11]
	v_add_co_u32_e32 v198, vcc, s43, v198
	s_nop 1
	v_addc_co_u32_e32 v199, vcc, 0, v199, vcc
	global_load_dwordx4 v[198:201], v[198:199], off offset:128
	ds_read_b128 v[236:239], v136 offset:23136
	s_waitcnt lgkmcnt(5)
	v_mfma_f32_32x32x16_bf16 v[82:97], v[202:205], v[224:227], v[82:97]
	ds_read_b128 v[240:243], v136 offset:27744
	s_waitcnt lgkmcnt(5)
	v_mfma_f32_32x32x16_bf16 v[66:81], v[202:205], v[228:231], v[66:81]
	ds_read_b128 v[244:247], v136 offset:32352
	s_waitcnt lgkmcnt(5)
	v_mfma_f32_32x32x16_bf16 v[50:65], v[210:213], v[214:217], v[50:65]
	v_mfma_f32_32x32x16_bf16 v[34:49], v[210:213], v[218:221], v[34:49]
	v_mfma_f32_32x32x16_bf16 v[18:33], v[210:213], v[224:227], v[18:33]
	v_mfma_f32_32x32x16_bf16 v[2:17], v[210:213], v[228:231], v[2:17]
	ds_read_b128 v[210:213], v131 offset:4704
	s_waitcnt lgkmcnt(4)
	v_mfma_f32_32x32x16_bf16 v[114:129], v[206:209], v[232:235], v[114:129]
	s_waitcnt lgkmcnt(3)
	v_mfma_f32_32x32x16_bf16 v[98:113], v[206:209], v[236:239], v[98:113]
	s_waitcnt lgkmcnt(2)
	v_mfma_f32_32x32x16_bf16 v[82:97], v[206:209], v[240:243], v[82:97]
	s_waitcnt lgkmcnt(1)
	v_mfma_f32_32x32x16_bf16 v[66:81], v[206:209], v[244:247], v[66:81]
	s_waitcnt lgkmcnt(0)
	v_mfma_f32_32x32x16_bf16 v[50:65], v[210:213], v[232:235], v[50:65]
	v_mfma_f32_32x32x16_bf16 v[34:49], v[210:213], v[236:239], v[34:49]
	v_mfma_f32_32x32x16_bf16 v[18:33], v[210:213], v[240:243], v[18:33]
	v_mfma_f32_32x32x16_bf16 v[2:17], v[210:213], v[244:247], v[2:17]
	s_setprio 0
	s_add_u32 s10, s10, 0x80
	s_addc_u32 s11, s11, 0
	s_cmpk_lg_i32 s10, 0x700
	s_barrier
;     ...
;   for (int kt = 0; kt < nk; ++kt) {
;     const int kn = (kt + 1 < nk) ? kt + 1 : kt;
;     GW_LOAD2(kn * 64, kn * bkstep)
;     __builtin_amdgcn_sched_barrier(0);
;     __builtin_amdgcn_s_setprio(1);
; #pragma unroll
;     for (int st = 0; st < 4; ++st) {
;       bf16x8 a0 = *(const bf16x8*)(Ab + st * 32);
;       bf16x8 a1 = *(const bf16x8*)(Ab + 32 * LSTR + st * 32);
;       bf16x8 b0 = *(const bf16x8*)(Bb + st * 32);
;       bf16x8 b1 = *(const bf16x8*)(Bb + 32 * LSTR + st * 32);
;       bf16x8 b2 = *(const bf16x8*)(Bb + 64 * LSTR + st * 32);
;       bf16x8 b3 = *(const bf16x8*)(Bb + 96 * LSTR + st * 32);
;       acc[0][0] = mfma32(a0, b0, acc[0][0]);
;       acc[0][1] = mfma32(a0, b1, acc[0][1]);
;       acc[0][2] = mfma32(a0, b2, acc[0][2]);
;       acc[0][3] = mfma32(a0, b3, acc[0][3]);
;       acc[1][0] = mfma32(a1, b0, acc[1][0]);
;       acc[1][1] = mfma32(a1, b1, acc[1][1]);
;       acc[1][2] = mfma32(a1, b2, acc[1][2]);
;       acc[1][3] = mfma32(a1, b3, acc[1][3]);
;     }
;     __builtin_amdgcn_s_setprio(0);
;     __builtin_amdgcn_sched_barrier(0);
;     __syncthreads();
;     GW_STORE()
;     __syncthreads();
	s_waitcnt vmcnt(11)
	ds_write_b128 v130, v[150:153]
	v_lshl_add_u64 v[150:151], v[148:149], 0, s[10:11]
	v_add_co_u32_e32 v150, vcc, 0x12c31000, v150
	s_nop 1
	v_addc_co_u32_e32 v151, vcc, 0, v151, vcc
	global_load_dwordx4 v[150:153], v[150:151], off offset:384
	s_waitcnt vmcnt(11)
	ds_write_b128 v130, v[154:157] offset:4608
	v_lshl_add_u64 v[154:155], v[148:149], 0, s[10:11]
	v_add_co_u32_e32 v154, vcc, 0x12c41000, v154
	s_nop 1
	v_addc_co_u32_e32 v155, vcc, 0, v155, vcc
	global_load_dwordx4 v[154:157], v[154:155], off offset:384
	s_waitcnt vmcnt(11)
	ds_write_b128 v130, v[158:161] offset:9216
	v_lshl_add_u64 v[158:159], v[148:149], 0, s[10:11]
	v_add_co_u32_e32 v158, vcc, 0x12c51000, v158
	s_nop 1
	v_addc_co_u32_e32 v159, vcc, 0, v159, vcc
	global_load_dwordx4 v[158:161], v[158:159], off offset:384
	s_waitcnt vmcnt(11)
	ds_write_b128 v130, v[162:165] offset:13824
	s_waitcnt vmcnt(10)
	ds_write_b128 v130, v[166:169] offset:18432
	s_waitcnt vmcnt(9)
	ds_write_b128 v130, v[170:173] offset:23040
	s_waitcnt vmcnt(8)
	ds_write_b128 v130, v[174:177] offset:27648
	s_waitcnt vmcnt(7)
	ds_write_b128 v130, v[178:181] offset:32256
	s_waitcnt vmcnt(6)
	ds_write_b128 v130, v[186:189] offset:36864
	s_waitcnt vmcnt(5)
	ds_write_b128 v130, v[190:193] offset:41472
	s_waitcnt vmcnt(4)
	ds_write_b128 v130, v[194:197] offset:46080
	s_waitcnt vmcnt(3)
	ds_write_b128 v130, v[198:201] offset:50688
	s_waitcnt lgkmcnt(0)
	s_barrier
	s_cbranch_scc1 .LBB0_238
	s_setprio 1
	ds_read_b128 v[202:205], v131 offset:0
	ds_read_b128 v[214:217], v136 offset:18432
	ds_read_b128 v[218:221], v136 offset:23040
	ds_read_b128 v[224:227], v136 offset:27648
	ds_read_b128 v[228:231], v136 offset:32256
	ds_read_b128 v[210:213], v131 offset:4608
	s_waitcnt lgkmcnt(4)
	v_mfma_f32_32x32x16_bf16 v[114:129], v[202:205], v[214:217], v[114:129]
	ds_read_b128 v[206:209], v131 offset:32
	ds_read_b128 v[232:235], v136 offset:18464
	s_waitcnt lgkmcnt(5)
	v_mfma_f32_32x32x16_bf16 v[98:113], v[202:205], v[218:221], v[98:113]
	v_lshl_add_u64 v[162:163], v[148:149], 0, s[10:11]
	v_add_co_u32_e32 v162, vcc, 0x12c61000, v162
	s_nop 1
	v_addc_co_u32_e32 v163, vcc, 0, v163, vcc
	global_load_dwordx4 v[162:165], v[162:163], off offset:384
	ds_read_b128 v[236:239], v136 offset:23072
	s_waitcnt lgkmcnt(5)
	v_mfma_f32_32x32x16_bf16 v[82:97], v[202:205], v[224:227], v[82:97]
	ds_read_b128 v[240:243], v136 offset:27680
	s_waitcnt lgkmcnt(5)
	v_mfma_f32_32x32x16_bf16 v[66:81], v[202:205], v[228:231], v[66:81]
	v_lshl_add_u64 v[166:167], v[132:133], 0, s[10:11]
	global_load_dwordx4 v[166:169], v[166:167], off offset:128
	ds_read_b128 v[244:247], v136 offset:32288
	s_waitcnt lgkmcnt(5)
	v_mfma_f32_32x32x16_bf16 v[50:65], v[210:213], v[214:217], v[50:65]
	v_mfma_f32_32x32x16_bf16 v[34:49], v[210:213], v[218:221], v[34:49]
	v_lshl_add_u64 v[170:171], v[132:133], 0, s[10:11]
	v_add_co_u32_e32 v170, vcc, s37, v170
	s_nop 1
	v_addc_co_u32_e32 v171, vcc, 0, v171, vcc
	global_load_dwordx4 v[170:173], v[170:171], off offset:128
	v_mfma_f32_32x32x16_bf16 v[18:33], v[210:213], v[224:227], v[18:33]
	v_mfma_f32_32x32x16_bf16 v[2:17], v[210:213], v[228:231], v[2:17]
	v_lshl_add_u64 v[174:175], v[132:133], 0, s[10:11]
	v_add_co_u32_e32 v174, vcc, s38, v174
	s_nop 1
	v_addc_co_u32_e32 v175, vcc, 0, v175, vcc
	global_load_dwordx4 v[174:177], v[174:175], off offset:128
	ds_read_b128 v[210:213], v131 offset:4640
	s_waitcnt lgkmcnt(4)
	v_mfma_f32_32x32x16_bf16 v[114:129], v[206:209], v[232:235], v[114:129]
	ds_read_b128 v[202:205], v131 offset:64
	ds_read_b128 v[214:217], v136 offset:18496
	s_waitcnt lgkmcnt(5)
	v_mfma_f32_32x32x16_bf16 v[98:113], v[206:209], v[236:239], v[98:113]
	v_lshl_add_u64 v[178:179], v[132:133], 0, s[10:11]
	v_add_co_u32_e32 v178, vcc, s39, v178
	s_nop 1
	v_addc_co_u32_e32 v179, vcc, 0, v179, vcc
	global_load_dwordx4 v[178:181], v[178:179], off offset:128
	ds_read_b128 v[218:221], v136 offset:23104
	s_waitcnt lgkmcnt(5)
	v_mfma_f32_32x32x16_bf16 v[82:97], v[206:209], v[240:243], v[82:97]
	ds_read_b128 v[224:227], v136 offset:27712
	s_waitcnt lgkmcnt(5)
	v_mfma_f32_32x32x16_bf16 v[66:81], v[206:209], v[244:247], v[66:81]
	v_lshl_add_u64 v[186:187], v[132:133], 0, s[10:11]
	v_add_co_u32_e32 v186, vcc, s40, v186
	s_nop 1
	v_addc_co_u32_e32 v187, vcc, 0, v187, vcc
	global_load_dwordx4 v[186:189], v[186:187], off offset:128
	ds_read_b128 v[228:231], v136 offset:32320
	s_waitcnt lgkmcnt(5)
	v_mfma_f32_32x32x16_bf16 v[50:65], v[210:213], v[232:235], v[50:65]
	v_mfma_f32_32x32x16_bf16 v[34:49], v[210:213], v[236:239], v[34:49]
	v_lshl_add_u64 v[190:191], v[132:133], 0, s[10:11]
	v_add_co_u32_e32 v190, vcc, s41, v190
	s_nop 1
	v_addc_co_u32_e32 v191, vcc, 0, v191, vcc
	global_load_dwordx4 v[190:193], v[190:191], off offset:128
	v_mfma_f32_32x32x16_bf16 v[18:33], v[210:213], v[240:243], v[18:33]
	v_mfma_f32_32x32x16_bf16 v[2:17], v[210:213], v[244:247], v[2:17]
	v_lshl_add_u64 v[194:195], v[132:133], 0, s[10:11]
	v_add_co_u32_e32 v194, vcc, s42, v194
	s_nop 1
	v_addc_co_u32_e32 v195, vcc, 0, v195, vcc
	global_load_dwordx4 v[194:197], v[194:195], off offset:128
	ds_read_b128 v[210:213], v131 offset:4672
	s_waitcnt lgkmcnt(4)
	v_mfma_f32_32x32x16_bf16 v[114:129], v[202:205], v[214:217], v[114:129]
	ds_read_b128 v[206:209], v131 offset:96
	ds_read_b128 v[232:235], v136 offset:18528
	s_waitcnt lgkmcnt(5)
	v_mfma_f32_32x32x16_bf16 v[98:113], v[202:205], v[218:221], v[98:113]
	v_lshl_add_u64 v[198:199], v[132:133], 0, s[10:11]
	v_add_co_u32_e32 v198, vcc, s43, v198
	s_nop 1
	v_addc_co_u32_e32 v199, vcc, 0, v199, vcc
	global_load_dwordx4 v[198:201], v[198:199], off offset:128
	ds_read_b128 v[236:239], v136 offset:23136
	s_waitcnt lgkmcnt(5)
	v_mfma_f32_32x32x16_bf16 v[82:97], v[202:205], v[224:227], v[82:97]
	ds_read_b128 v[240:243], v136 offset:27744
	s_waitcnt lgkmcnt(5)
	v_mfma_f32_32x32x16_bf16 v[66:81], v[202:205], v[228:231], v[66:81]
	ds_read_b128 v[244:247], v136 offset:32352
	s_waitcnt lgkmcnt(5)
	v_mfma_f32_32x32x16_bf16 v[50:65], v[210:213], v[214:217], v[50:65]
	v_mfma_f32_32x32x16_bf16 v[34:49], v[210:213], v[218:221], v[34:49]
	v_mfma_f32_32x32x16_bf16 v[18:33], v[210:213], v[224:227], v[18:33]
	v_mfma_f32_32x32x16_bf16 v[2:17], v[210:213], v[228:231], v[2:17]
	ds_read_b128 v[210:213], v131 offset:4704
	s_waitcnt lgkmcnt(4)
	v_mfma_f32_32x32x16_bf16 v[114:129], v[206:209], v[232:235], v[114:129]
	s_waitcnt lgkmcnt(3)
	v_mfma_f32_32x32x16_bf16 v[98:113], v[206:209], v[236:239], v[98:113]
	s_waitcnt lgkmcnt(2)
	v_mfma_f32_32x32x16_bf16 v[82:97], v[206:209], v[240:243], v[82:97]
	s_waitcnt lgkmcnt(1)
	v_mfma_f32_32x32x16_bf16 v[66:81], v[206:209], v[244:247], v[66:81]
	s_waitcnt lgkmcnt(0)
	v_mfma_f32_32x32x16_bf16 v[50:65], v[210:213], v[232:235], v[50:65]
	v_mfma_f32_32x32x16_bf16 v[34:49], v[210:213], v[236:239], v[34:49]
	v_mfma_f32_32x32x16_bf16 v[18:33], v[210:213], v[240:243], v[18:33]
	v_mfma_f32_32x32x16_bf16 v[2:17], v[210:213], v[244:247], v[2:17]
	s_setprio 0
	s_add_u32 s10, s10, 0x80
	s_addc_u32 s11, s11, 0
	s_barrier
; #define GW_LOAD(KOFF) GW_LOAD2(KOFF, 0)
;     ...
;   GW_LOAD(0)
;   GW_STORE()
;   __syncthreads();
;   const int nk = K >> 6;
;   const char* Ab = smem + (wm * 64 + (lane & 31)) * LSTR + (lane >> 5) * 16;
;   const char* Bb = smem + WTILE_A + (wn * 128 + (lane & 31)) * LSTR + (lane >> 5) * 16;
;   for (int kt = 0; kt < nk; ++kt) {
;     const int kn = (kt + 1 < nk) ? kt + 1 : kt;
;     GW_LOAD2(kn * 64, kn * bkstep)
;     __builtin_amdgcn_sched_barrier(0);
;     __builtin_amdgcn_s_setprio(1);
; #pragma unroll
;     for (int st = 0; st < 4; ++st) {
;       bf16x8 a0 = *(const bf16x8*)(Ab + st * 32);
;       bf16x8 a1 = *(const bf16x8*)(Ab + 32 * LSTR + st * 32);
;       bf16x8 b0 = *(const bf16x8*)(Bb + st * 32);
;       bf16x8 b1 = *(const bf16x8*)(Bb + 32 * LSTR + st * 32);
;       bf16x8 b2 = *(const bf16x8*)(Bb + 64 * LSTR + st * 32);
;       bf16x8 b3 = *(const bf16x8*)(Bb + 96 * LSTR + st * 32);
;       acc[0][0] = mfma32(a0, b0, acc[0][0]);
;       acc[0][1] = mfma32(a0, b1, acc[0][1]);
;       acc[0][2] = mfma32(a0, b2, acc[0][2]);
;       acc[0][3] = mfma32(a0, b3, acc[0][3]);
;       acc[1][0] = mfma32(a1, b0, acc[1][0]);
;       acc[1][1] = mfma32(a1, b1, acc[1][1]);
;       acc[1][2] = mfma32(a1, b2, acc[1][2]);
;       acc[1][3] = mfma32(a1, b3, acc[1][3]);
;     }
;     __builtin_amdgcn_s_setprio(0);
; __device__ __forceinline__ void inproj_tile(const Params& P, int l, int mt, int ntw, char* smem) {
;     ...
;   float* cs = (float*)smem;
;   const int row0 = mt * 128;
;   const bool isctx = row0 >= NLAT;
;   const int b = isctx ? ((row0 - NLAT) >> 8) : (row0 >> 12);
;   const int pos0 = isctx ? ((row0 - NLAT) & 255) : (row0 & 4095);
;   const int tk0 = isctx ? (SEQ + pos0) : pos0;
	s_waitcnt vmcnt(11)
	ds_write_b128 v130, v[150:153]
	s_waitcnt vmcnt(10)
	ds_write_b128 v130, v[154:157] offset:4608
	s_waitcnt vmcnt(9)
	ds_write_b128 v130, v[158:161] offset:9216
	s_waitcnt vmcnt(8)
	ds_write_b128 v130, v[162:165] offset:13824
	s_waitcnt vmcnt(7)
	ds_write_b128 v130, v[166:169] offset:18432
	s_waitcnt vmcnt(6)
	ds_write_b128 v130, v[170:173] offset:23040
	s_waitcnt vmcnt(5)
	ds_write_b128 v130, v[174:177] offset:27648
	s_waitcnt vmcnt(4)
	ds_write_b128 v130, v[178:181] offset:32256
	s_waitcnt vmcnt(3)
	ds_write_b128 v130, v[186:189] offset:36864
	s_waitcnt vmcnt(2)
	ds_write_b128 v130, v[190:193] offset:41472
	s_waitcnt vmcnt(1)
	ds_write_b128 v130, v[194:197] offset:46080
	s_waitcnt vmcnt(0)
	ds_write_b128 v130, v[198:201] offset:50688
	s_waitcnt lgkmcnt(0)
	s_barrier
	v_add_co_u32_e32 v160, vcc, 0x10000, v132
	s_nop 0
	s_nop 0
	s_nop 0
	v_addc_co_u32_e32 v161, vcc, 0, v133, vcc
	v_add_co_u32_e32 v164, vcc, 0x20000, v132
	s_nop 0
	v_addc_co_u32_e32 v165, vcc, 0, v133, vcc
	v_add_co_u32_e32 v168, vcc, 0x30000, v132
	s_mov_b32 s52, 0
	s_nop 0
	v_addc_co_u32_e32 v169, vcc, 0, v133, vcc
	v_add_co_u32_e32 v172, vcc, 0x40000, v132
	s_nop 0
	v_addc_co_u32_e32 v173, vcc, 0, v133, vcc
	v_add_co_u32_e32 v176, vcc, 0x50000, v132
	s_nop 1
	v_addc_co_u32_e32 v177, vcc, 0, v133, vcc
	v_add_co_u32_e32 v180, vcc, 0x60000, v132
	s_nop 0
	v_addc_co_u32_e32 v181, vcc, 0, v133, vcc
	v_add_co_u32_e32 v132, vcc, 0x70000, v132
	s_nop 1
	v_addc_co_u32_e32 v133, vcc, 0, v133, vcc
	s_setprio 1
	ds_read_b128 v[194:197], v131 offset:0
	ds_read_b128 v[206:209], v136 offset:18432
	ds_read_b128 v[210:213], v136 offset:23040
	ds_read_b128 v[214:217], v136 offset:27648
	ds_read_b128 v[218:221], v136 offset:32256
	ds_read_b128 v[202:205], v131 offset:4608
	s_waitcnt lgkmcnt(4)
	v_mfma_f32_32x32x16_bf16 v[114:129], v[194:197], v[206:209], v[114:129]
	ds_read_b128 v[198:201], v131 offset:32
	ds_read_b128 v[224:227], v136 offset:18464
	s_waitcnt lgkmcnt(5)
	v_mfma_f32_32x32x16_bf16 v[98:113], v[194:197], v[210:213], v[98:113]
	ds_read_b128 v[228:231], v136 offset:23072
	s_waitcnt lgkmcnt(5)
	v_mfma_f32_32x32x16_bf16 v[82:97], v[194:197], v[214:217], v[82:97]
	ds_read_b128 v[232:235], v136 offset:27680
	s_waitcnt lgkmcnt(5)
	v_mfma_f32_32x32x16_bf16 v[66:81], v[194:197], v[218:221], v[66:81]
	ds_read_b128 v[236:239], v136 offset:32288
	s_waitcnt lgkmcnt(5)
	v_mfma_f32_32x32x16_bf16 v[50:65], v[202:205], v[206:209], v[50:65]
	v_mfma_f32_32x32x16_bf16 v[34:49], v[202:205], v[210:213], v[34:49]
	v_mfma_f32_32x32x16_bf16 v[18:33], v[202:205], v[214:217], v[18:33]
	v_mfma_f32_32x32x16_bf16 v[2:17], v[202:205], v[218:221], v[2:17]
	ds_read_b128 v[202:205], v131 offset:4640
	s_waitcnt lgkmcnt(4)
	v_mfma_f32_32x32x16_bf16 v[114:129], v[198:201], v[224:227], v[114:129]
	ds_read_b128 v[194:197], v131 offset:64
	ds_read_b128 v[206:209], v136 offset:18496
	s_waitcnt lgkmcnt(5)
	v_mfma_f32_32x32x16_bf16 v[98:113], v[198:201], v[228:231], v[98:113]
	ds_read_b128 v[210:213], v136 offset:23104
	s_waitcnt lgkmcnt(5)
	v_mfma_f32_32x32x16_bf16 v[82:97], v[198:201], v[232:235], v[82:97]
	ds_read_b128 v[214:217], v136 offset:27712
	s_waitcnt lgkmcnt(5)
	v_mfma_f32_32x32x16_bf16 v[66:81], v[198:201], v[236:239], v[66:81]
	ds_read_b128 v[218:221], v136 offset:32320
	s_waitcnt lgkmcnt(5)
	v_mfma_f32_32x32x16_bf16 v[50:65], v[202:205], v[224:227], v[50:65]
	v_mfma_f32_32x32x16_bf16 v[34:49], v[202:205], v[228:231], v[34:49]
	v_mfma_f32_32x32x16_bf16 v[18:33], v[202:205], v[232:235], v[18:33]
	v_mfma_f32_32x32x16_bf16 v[2:17], v[202:205], v[236:239], v[2:17]
	ds_read_b128 v[202:205], v131 offset:4672
	s_waitcnt lgkmcnt(4)
	v_mfma_f32_32x32x16_bf16 v[114:129], v[194:197], v[206:209], v[114:129]
	ds_read_b128 v[198:201], v131 offset:96
	ds_read_b128 v[224:227], v136 offset:18528
	s_waitcnt lgkmcnt(5)
	v_mfma_f32_32x32x16_bf16 v[98:113], v[194:197], v[210:213], v[98:113]
	ds_read_b128 v[228:231], v136 offset:23136
	s_waitcnt lgkmcnt(5)
	v_mfma_f32_32x32x16_bf16 v[82:97], v[194:197], v[214:217], v[82:97]
	ds_read_b128 v[232:235], v136 offset:27744
	s_waitcnt lgkmcnt(5)
	v_mfma_f32_32x32x16_bf16 v[66:81], v[194:197], v[218:221], v[66:81]
	ds_read_b128 v[236:239], v136 offset:32352
	s_waitcnt lgkmcnt(5)
	v_mfma_f32_32x32x16_bf16 v[50:65], v[202:205], v[206:209], v[50:65]
	v_mfma_f32_32x32x16_bf16 v[34:49], v[202:205], v[210:213], v[34:49]
	v_mfma_f32_32x32x16_bf16 v[18:33], v[202:205], v[214:217], v[18:33]
	v_mfma_f32_32x32x16_bf16 v[2:17], v[202:205], v[218:221], v[2:17]
	ds_read_b128 v[202:205], v131 offset:4704
	s_waitcnt lgkmcnt(4)
	v_mfma_f32_32x32x16_bf16 v[114:129], v[198:201], v[224:227], v[114:129]
	s_waitcnt lgkmcnt(3)
	v_mfma_f32_32x32x16_bf16 v[98:113], v[198:201], v[228:231], v[98:113]
	s_waitcnt lgkmcnt(2)
	v_mfma_f32_32x32x16_bf16 v[82:97], v[198:201], v[232:235], v[82:97]
	s_waitcnt lgkmcnt(1)
	v_mfma_f32_32x32x16_bf16 v[66:81], v[198:201], v[236:239], v[66:81]
	s_waitcnt lgkmcnt(0)
	v_mfma_f32_32x32x16_bf16 v[50:65], v[202:205], v[224:227], v[50:65]
	v_mfma_f32_32x32x16_bf16 v[34:49], v[202:205], v[228:231], v[34:49]
	v_mfma_f32_32x32x16_bf16 v[18:33], v[202:205], v[232:235], v[18:33]
	v_mfma_f32_32x32x16_bf16 v[2:17], v[202:205], v[236:239], v[2:17]
	s_setprio 0
	s_lshl_b32 s20, s12, 7
	s_cmpk_lt_i32 s12, 0x100
	s_cselect_b64 s[10:11], -1, 0
	s_add_i32 s8, s20, 0xffff8000
	s_and_b32 s51, s20, 0x80
	s_lshr_b32 s8, s8, 8
	s_ashr_i32 s22, s18, 2
	s_and_b32 s53, s20, 0xf80
	s_or_b32 s13, s51, 0x1000
	s_barrier
; __device__ __forceinline__ void inproj_tile(const Params& P, int l, int mt, int ntw, char* smem) {
;     ...
;   float* cs = (float*)smem;
;   const int row0 = mt * 128;
;   const bool isctx = row0 >= NLAT;
;   const int b = isctx ? ((row0 - NLAT) >> 8) : (row0 >> 12);
;   const int pos0 = isctx ? ((row0 - NLAT) & 255) : (row0 & 4095);
;   const int tk0 = isctx ? (SEQ + pos0) : pos0;
;   int tid_ = threadIdx.x;
;   asm volatile("" : "+v"(tid_));
;   const int lane = tid_ & 63, wave = tid_ >> 6;
;   const int r = 32 * wave + (lane & 31), half = lane >> 5;
;   const size_t grow = (size_t)row0 + r;
;   const float* crow = cs + r * CSTR + half * 64;
; #pragma unroll 1
;   for (int hsel = 0; hsel < 2; ++hsel) {
;     const int nt = ntw * 2 + hsel;
;     wide_acc_to_lds(acc, cs, hsel);
;     if (nt < 4) {
;       const int part = nt >> 1, cb = (nt & 1) * 128;
;       if (!isctx) {
;         u16* base = WSP(u16, OFF_FTT) + (size_t)b * 256 * 8192 + part * 4096 + pos0;
;         epi_transposed(cs, [&](int ch) { return base + (size_t)(cb + ch) * 8192; });
;       } else {
;         u16* base = WSP(u16, OFF_FTTC) + (size_t)b * 256 * 512 + part * 256 + pos0;
;         epi_transposed(cs, [&](int ch) { return base + (size_t)(cb + ch) * 512; });
;       }
;     } else if (nt < 7 || (nt >= 10 && nt < 13)) {
;       const bool isq = nt < 7;
;       const int head = (isq ? (nt - 4) : (nt - 10)) * 2 + half;
;       const float* g = (isq ? P.na_qn_g : P.na_kn_g) + l * 64;
;       float ss = 0.f;
; #pragma unroll
;       for (int q = 0; q < 16; ++q) {
;         float4 a = *(const float4*)(crow + q * 4);
;         ss += a.x * a.x + a.y * a.y + a.z * a.z + a.w * a.w;
;       }
;       const float rinv = rsqrtf(ss * (1.f / 64.f) + EPS) * (isq ? (0.125f * LOG2E) : 1.f);
;       u16* dst = WSP(u16, isq ? OFF_QN : OFF_KN) + grow * 384 + head * 64;
	s_cmpk_gt_i32 s12, 0xff
	v_mov_b32_e32 v152, v134
	s_waitcnt lgkmcnt(0)
	s_cselect_b32 s54, s13, s53
	s_movk_i32 s13, 0xffe0
	v_ashrrev_i32_e32 v153, 1, v152
	v_bfi_b32 v130, s13, v153, v152
	s_cselect_b32 s12, s8, s22
	s_cselect_b32 s15, s51, s53
	s_ashr_i32 s21, s20, 31
	v_ashrrev_i32_e32 v131, 31, v130
	s_ashr_i32 s23, s22, 31
	v_lshl_add_u64 v[132:133], v[130:131], 0, s[20:21]
	s_lshl_b64 s[20:21], s[22:23], 22
	s_lshl_b32 s22, s14, 12
	s_movk_i32 s13, 0x210
	s_lshl_b32 s33, s14, 1
	s_ashr_i32 s23, s22, 31
	s_lshl_b64 s[24:25], s[8:9], 18
	v_mul_lo_u32 v136, v130, s13
	v_lshlrev_b32_e32 v139, 1, v152
	s_mul_i32 s13, s12, 6
	s_cmp_gt_u32 s33, 9
	v_and_b32_e32 v185, 64, v139
	s_mul_i32 s55, s12, 0x330000
	s_mul_hi_i32 s56, s13, 0x88000
	s_cselect_b64 s[12:13], -1, 0
	s_cmp_gt_u32 s33, 21
	v_lshl_add_u32 v186, v185, 2, v136
	v_add_u32_e32 v136, s15, v153
	s_cselect_b64 s[14:15], -1, 0
	s_cmp_lt_u32 s33, 16
	s_cselect_b64 s[26:27], -1, 0
	s_and_b64 s[26:27], s[26:27], exec
	s_mov_b32 s8, 0x1fffff3
	s_cselect_b32 s50, s8, 0x1ffffed
	s_mov_b32 s8, 0x32a31100
	s_cselect_b32 s8, s8, 0x343b1100
	v_mov_b64_e32 v[144:145], s[90:91]
	v_mad_u64_u32 v[144:145], s[26:27], v132, s44, v[144:145]
	s_add_u32 s8, s90, s8
	s_addc_u32 s26, s91, 0
	s_add_u32 s8, s8, s55
	s_addc_u32 s27, s26, s56
	s_lshl_b32 s26, s54, 1
	s_add_u32 s26, s8, s26
	s_addc_u32 s27, s27, 0
	v_mov_b32_e32 v139, v137
	s_add_u32 s8, s30, s20
	v_lshl_add_u64 v[146:147], s[26:27], 0, v[138:139]
	s_addc_u32 s26, s31, s21
	s_lshl_b64 s[20:21], s[22:23], 1
	s_add_u32 s8, s8, s20
	s_addc_u32 s21, s26, s21
	s_lshl_b32 s20, s53, 1
	s_add_u32 s20, s8, s20
	s_addc_u32 s21, s21, 0
	s_add_u32 s8, s34, s24
	v_lshl_add_u64 v[148:149], s[20:21], 0, v[138:139]
	s_addc_u32 s22, s35, s25
	s_lshl_b64 s[20:21], s[16:17], 1
	s_add_u32 s8, s8, s20
	s_addc_u32 s17, s22, s21
	s_lshl_b32 s20, s51, 1
	v_ashrrev_i32_e32 v136, 2, v136
	s_add_u32 s20, s8, s20
	v_and_b32_e32 v140, -16, v136
	v_lshlrev_b32_e32 v136, 4, v130
	s_addc_u32 s21, s17, 0
	s_lshl_b32 s8, s18, 10
	s_lshl_b32 s17, s19, 7
	v_and_b32_e32 v136, 0x3f0, v136
	s_or_b32 s18, s8, s17
	v_and_b32_e32 v154, 31, v152
	v_mov_b64_e32 v[142:143], v[136:137]
	v_lshrrev_b32_e32 v132, 5, v153
	v_bfe_u32 v136, v152, 5, 1
	s_ashr_i32 s19, s18, 31
	v_mad_i32_i24 v145, v133, s44, v145
	v_lshl_add_u64 v[150:151], s[20:21], 0, v[138:139]
	v_mul_lo_u32 v132, v132, s45
	v_mul_u32_u24_e32 v133, 0x210, v154
	v_lshlrev_b32_e32 v139, 8, v136
	v_lshl_add_u64 v[130:131], s[18:19], 0, v[130:131]
	v_add3_u32 v139, v132, v133, v139
	v_mad_u64_u32 v[132:133], s[18:19], v130, s46, 0
	v_mad_i32_i24 v133, v131, s46, v133
	v_lshl_or_b32 v132, v136, 7, v132
	v_lshl_add_u64 v[152:153], s[4:5], 0, v[132:133]
	v_mov_b64_e32 v[132:133], s[6:7]
	s_add_i32 s51, s16, 0xfffff500
	v_mad_u64_u32 v[154:155], s[16:17], v130, s44, v[132:133]
	v_ashrrev_i32_e32 v141, 31, v140
	v_mad_i32_i24 v155, v131, s44, v155
	s_mov_b64 s[16:17], -1
	s_branch .LBB0_241

; #define GW_LOAD(KOFF) GW_LOAD2(KOFF, 0)
;   int tid = threadIdx.x;
;   asm volatile("" : "+v"(tid));
;   const int lane = tid & 63, wave = tid >> 6;
;   const int wm = wave >> 1, wn = wave & 1;
;   const int lr = tid >> 3, kc = tid & 7;
;   const u16* ap0 = arow(lr) + kc * 8;
;   const u16* ap1 = arow(lr + 32) + kc * 8;
;   const u16* ap2 = arow(lr + 64) + kc * 8;
;   const u16* ap3 = arow(lr + 96) + kc * 8;
;   const u16* bp0 = Bt + (size_t)lr * ldb + kc * 8;
;   const size_t bstep = 32 * ldb;
;   const int so = lr * LSTR + kc * 16;
;   uint4 ra0, ra1, ra2, ra3, rb0, rb1, rb2, rb3, rb4, rb5, rb6, rb7;
;     ...
;   GW_LOAD(0)
;   GW_STORE()
;   __syncthreads();
; template <bool WIDE>
; __device__ __forceinline__ void outproj_tile(const Params& P, int l, int mt, int nt, char* smem) {
;   float* cs = (float*)smem;
;   const u16* A = WSP(u16, OFF_M) + (size_t)mt * 128 * DM;
;   const u16* Bt = WSP(u16, OFF_WOUT) + ((size_t)l * DM + nt * 128) * DM;
;   f32x16 accw[2][4];
;   f32x16 accn[2][2];
;   if constexpr (WIDE) {
; #pragma unroll
;     for (int i = 0; i < 2; ++i)
; #pragma unroll
;       for (int j = 0; j < 4; ++j)
; #pragma unroll
;         for (int r = 0; r < 16; ++r) accw[i][j][r] = 0.f;
;     gemm_wide([&](int rr) { return A + (size_t)rr * DM; }, Bt, DM, DM, smem, accw);
.LBB0_706:
	s_lshl_b32 s14, s51, 6
	s_and_b32 s14, s14, 0x1c0
	s_and_b32 s15, s51, 0xfffffe00
	s_or_b32 s14, s14, s15
	s_bfe_u32 s15, s51, 0x60003
	s_or_b32 s16, s14, s15
	s_and_b64 s[14:15], s[0:1], exec
	s_cselect_b32 s14, s16, s51
	s_ashr_i32 s15, s14, 31
	s_lshr_b32 s15, s15, 27
	s_add_i32 s15, s14, s15
	s_ashr_i32 s16, s15, 5
	s_andn2_b32 s15, s15, 31
	s_lshl_b32 s16, s16, 3
	s_sub_i32 s15, s14, s15
	s_and_b32 s14, s14, 7
	s_or_b32 s16, s16, s14
	s_ashr_i32 s14, s15, 2
	s_ashr_i32 s17, s16, 31
	s_and_b32 s52, s14, -2
	s_lshl_b64 s[18:19], s[16:17], 18
	s_add_u32 s54, s23, s18
	s_addc_u32 s55, s24, s19
	s_lshl_b32 s14, s52, 7
	v_mov_b32_e32 v54, v134
	s_ashr_i32 s15, s14, 31
	s_lshl_b64 s[20:21], s[14:15], 11
	v_ashrrev_i32_e32 v50, 3, v54
	v_ashrrev_i32_e32 v51, 31, v50
	s_add_u32 s56, s25, s20
	v_lshlrev_b64 v[52:53], 11, v[50:51]
	v_lshlrev_b32_e32 v4, 4, v54
	s_addc_u32 s57, s26, s21
	v_lshl_add_u64 v[2:3], s[54:55], 0, v[52:53]
	v_and_b32_e32 v130, 0x70, v4
	v_lshl_add_u64 v[138:139], v[2:3], 0, v[130:131]
	v_lshl_add_u64 v[2:3], s[56:57], 0, v[52:53]
	v_lshl_add_u64 v[136:137], v[2:3], 0, v[130:131]
	v_add_co_u32_e32 v2, vcc, s29, v138
	v_mad_u64_u32 v[132:133], s[54:55], v50, s28, v[130:131]
	s_nop 0
	v_addc_co_u32_e32 v3, vcc, 0, v139, vcc
	v_add_co_u32_e32 v6, vcc, s30, v138
	v_lshl_add_u64 v[140:141], v[138:139], 0, s[4:5]
	s_nop 0
	v_addc_co_u32_e32 v7, vcc, 0, v139, vcc
	v_add_co_u32_e32 v18, vcc, s31, v138
	global_load_dwordx4 v[2:5], v[2:3], off
	s_nop 0
	global_load_dwordx4 v[6:9], v[6:7], off
	v_addc_co_u32_e32 v19, vcc, 0, v139, vcc
	v_add_co_u32_e32 v22, vcc, s29, v136
	global_load_dwordx4 v[10:13], v[138:139], off
	global_load_dwordx4 v[14:17], v[136:137], off
	v_addc_co_u32_e32 v23, vcc, 0, v137, vcc
	v_add_co_u32_e32 v26, vcc, s30, v136
	global_load_dwordx4 v[18:21], v[18:19], off
	s_nop 0
	global_load_dwordx4 v[22:25], v[22:23], off
	v_addc_co_u32_e32 v27, vcc, 0, v137, vcc
	v_add_co_u32_e32 v30, vcc, s31, v136
	v_lshl_add_u64 v[142:143], v[138:139], 0, s[6:7]
	s_nop 0
	v_addc_co_u32_e32 v31, vcc, 0, v137, vcc
	v_add_co_u32_e32 v34, vcc, s33, v136
	global_load_dwordx4 v[26:29], v[26:27], off
	s_nop 0
	global_load_dwordx4 v[30:33], v[30:31], off
	v_addc_co_u32_e32 v35, vcc, 0, v137, vcc
	v_add_co_u32_e32 v38, vcc, s34, v136
	v_lshl_add_u64 v[144:145], v[138:139], 0, s[8:9]
	s_nop 0
	v_addc_co_u32_e32 v39, vcc, 0, v137, vcc
	v_add_co_u32_e32 v42, vcc, s35, v136
	global_load_dwordx4 v[34:37], v[34:35], off
	s_nop 0
	global_load_dwordx4 v[38:41], v[38:39], off
	v_addc_co_u32_e32 v43, vcc, 0, v137, vcc
	v_add_co_u32_e32 v46, vcc, s36, v136
	v_mov_b32_e32 v50, 0
	s_nop 0
	v_addc_co_u32_e32 v47, vcc, 0, v137, vcc
	global_load_dwordx4 v[42:45], v[42:43], off
	s_nop 0
	global_load_dwordx4 v[46:49], v[46:47], off
	v_mov_b32_e32 v51, v131
	v_mov_b32_e32 v55, v131
	v_mov_b32_e32 v56, v131
	v_mov_b32_e32 v57, v131
	v_mov_b32_e32 v58, v131
	v_mov_b32_e32 v59, v131
	v_mov_b32_e32 v60, v131
	v_mov_b32_e32 v61, v131
	v_mov_b32_e32 v62, v131
	v_mov_b32_e32 v63, v131
	v_mov_b32_e32 v64, v131
	v_mov_b32_e32 v65, v131
	v_mov_b32_e32 v66, 0
	v_mov_b32_e32 v67, v131
	v_mov_b32_e32 v68, v131
	v_mov_b32_e32 v69, v131
	v_mov_b32_e32 v70, v131
	v_mov_b32_e32 v71, v131
	v_mov_b32_e32 v72, v131
	v_mov_b32_e32 v73, v131
	v_mov_b32_e32 v74, v131
	v_mov_b32_e32 v75, v131
	v_mov_b32_e32 v76, v131
	v_mov_b32_e32 v77, v131
	v_mov_b32_e32 v78, v131
	v_mov_b32_e32 v79, v131
	v_mov_b32_e32 v80, v131
	v_mov_b32_e32 v81, v131
	v_mov_b32_e32 v82, 0
	v_mov_b32_e32 v83, v131
	s_waitcnt vmcnt(9)
	ds_write_b128 v132, v[10:13]
	ds_write_b128 v132, v[2:5] offset:4608
	ds_write_b128 v132, v[6:9] offset:9216
	s_waitcnt vmcnt(7)
	ds_write_b128 v132, v[18:21] offset:13824
	ds_write_b128 v132, v[14:17] offset:18432
	s_waitcnt vmcnt(6)
	ds_write_b128 v132, v[22:25] offset:23040
	s_waitcnt vmcnt(5)
	ds_write_b128 v132, v[26:29] offset:27648
	s_waitcnt vmcnt(4)
	ds_write_b128 v132, v[30:33] offset:32256
	s_waitcnt vmcnt(3)
	ds_write_b128 v132, v[34:37] offset:36864
	s_waitcnt vmcnt(2)
	ds_write_b128 v132, v[38:41] offset:41472
	s_waitcnt vmcnt(1)
	ds_write_b128 v132, v[42:45] offset:46080
	s_waitcnt vmcnt(0)
	ds_write_b128 v132, v[46:49] offset:50688
	v_and_b32_e32 v2, 31, v54
	v_lshrrev_b32_e32 v3, 1, v54
	v_and_or_b32 v4, v3, s37, v2
	v_and_b32_e32 v5, 16, v3
	v_lshlrev_b32_e32 v3, 1, v54
	v_and_or_b32 v2, v3, s38, v2
	v_mul_u32_u24_e32 v6, 0x90, v2
	v_lshl_add_u64 v[2:3], s[18:19], 0, v[52:53]
	v_or_b32_e32 v2, v2, v130
	v_lshl_add_u64 v[146:147], s[90:91], 0, v[2:3]
	v_lshl_add_u64 v[2:3], v[52:53], 0, s[20:21]
	v_mul_lo_u32 v4, v4, s28
	v_or_b32_e32 v2, v2, v130
	v_lshl_add_u64 v[148:149], s[90:91], 0, v[2:3]
	s_mov_b64 s[18:19], 0
	v_add_u32_e32 v130, v4, v5
	v_add_u32_e32 v133, v6, v5
	v_mov_b32_e32 v2, 0
	v_mov_b32_e32 v3, v131
	v_mov_b32_e32 v4, v131
	v_mov_b32_e32 v5, v131
	v_mov_b32_e32 v6, v131
	v_mov_b32_e32 v7, v131
	v_mov_b32_e32 v8, v131
	v_mov_b32_e32 v9, v131
	v_mov_b32_e32 v10, v131
	v_mov_b32_e32 v11, v131
	v_mov_b32_e32 v12, v131
	v_mov_b32_e32 v13, v131
	v_mov_b32_e32 v14, v131
	v_mov_b32_e32 v15, v131
	v_mov_b32_e32 v16, v131
	v_mov_b32_e32 v17, v131
	v_mov_b32_e32 v18, 0
	v_mov_b32_e32 v19, v131
	v_mov_b32_e32 v20, v131
	v_mov_b32_e32 v21, v131
	v_mov_b32_e32 v22, v131
	v_mov_b32_e32 v23, v131
	v_mov_b32_e32 v24, v131
	v_mov_b32_e32 v25, v131
	v_mov_b32_e32 v26, v131
	v_mov_b32_e32 v27, v131
	v_mov_b32_e32 v28, v131
	v_mov_b32_e32 v29, v131
	v_mov_b32_e32 v30, v131
	v_mov_b32_e32 v31, v131
	v_mov_b32_e32 v32, v131
	v_mov_b32_e32 v33, v131
	v_mov_b32_e32 v34, 0
	v_mov_b32_e32 v35, v131
	v_mov_b32_e32 v36, v131
	v_mov_b32_e32 v37, v131
;     ...
;   for (int kt = 0; kt < nk; ++kt) {
;     const int kn = (kt + 1 < nk) ? kt + 1 : kt;
;     GW_LOAD2(kn * 64, kn * bkstep)
;     __builtin_amdgcn_sched_barrier(0);
;     __builtin_amdgcn_s_setprio(1);
; #pragma unroll
;     for (int st = 0; st < 4; ++st) {
;       bf16x8 a0 = *(const bf16x8*)(Ab + st * 32);
;       bf16x8 a1 = *(const bf16x8*)(Ab + 32 * LSTR + st * 32);
;       bf16x8 b0 = *(const bf16x8*)(Bb + st * 32);
;       bf16x8 b1 = *(const bf16x8*)(Bb + 32 * LSTR + st * 32);
;       bf16x8 b2 = *(const bf16x8*)(Bb + 64 * LSTR + st * 32);
;       bf16x8 b3 = *(const bf16x8*)(Bb + 96 * LSTR + st * 32);
;       acc[0][0] = mfma32(a0, b0, acc[0][0]);
;       acc[0][1] = mfma32(a0, b1, acc[0][1]);
;       acc[0][2] = mfma32(a0, b2, acc[0][2]);
;       acc[0][3] = mfma32(a0, b3, acc[0][3]);
;       acc[1][0] = mfma32(a1, b0, acc[1][0]);
;       acc[1][1] = mfma32(a1, b1, acc[1][1]);
;       acc[1][2] = mfma32(a1, b2, acc[1][2]);
;       acc[1][3] = mfma32(a1, b3, acc[1][3]);
;     }
;     __builtin_amdgcn_s_setprio(0);
; template <bool WIDE>
; __device__ __forceinline__ void outproj_tile(const Params& P, int l, int mt, int nt, char* smem) {
;     ...
; #pragma unroll
;     for (int i = 0; i < 2; ++i)
; #pragma unroll
;       for (int j = 0; j < 4; ++j)
; #pragma unroll
;         for (int r = 0; r < 16; ++r) accw[i][j][r] = 0.f;
	v_mov_b32_e32 v38, v131
	v_mov_b32_e32 v39, v131
	v_mov_b32_e32 v40, v131
	v_mov_b32_e32 v41, v131
	v_mov_b32_e32 v42, v131
	v_mov_b32_e32 v43, v131
	v_mov_b32_e32 v44, v131
	v_mov_b32_e32 v45, v131
	v_mov_b32_e32 v46, v131
	v_mov_b32_e32 v47, v131
	v_mov_b32_e32 v48, v131
	v_mov_b32_e32 v49, v131
	v_mov_b32_e32 v52, v131
	v_mov_b32_e32 v53, v131
	v_mov_b32_e32 v54, v131
	v_mov_b32_e32 v84, v131
	v_mov_b32_e32 v85, v131
	v_mov_b32_e32 v86, v131
	v_mov_b32_e32 v87, v131
	v_mov_b32_e32 v88, v131
	v_mov_b32_e32 v89, v131
	v_mov_b32_e32 v90, v131
	v_mov_b32_e32 v91, v131
	v_mov_b32_e32 v92, v131
	v_mov_b32_e32 v93, v131
	v_mov_b32_e32 v94, v131
	v_mov_b32_e32 v95, v131
	v_mov_b32_e32 v96, v131
	v_mov_b32_e32 v97, v131
	v_mov_b32_e32 v98, 0
	v_mov_b32_e32 v99, v131
	v_mov_b32_e32 v100, v131
	v_mov_b32_e32 v101, v131
	v_mov_b32_e32 v102, v131
	v_mov_b32_e32 v103, v131
	v_mov_b32_e32 v104, v131
	v_mov_b32_e32 v105, v131
	v_mov_b32_e32 v106, v131
	v_mov_b32_e32 v107, v131
	v_mov_b32_e32 v108, v131
	v_mov_b32_e32 v109, v131
	v_mov_b32_e32 v110, v131
	v_mov_b32_e32 v111, v131
	v_mov_b32_e32 v112, v131
	v_mov_b32_e32 v113, v131
	v_mov_b32_e32 v114, 0
	v_mov_b32_e32 v115, v131
	v_mov_b32_e32 v116, v131
	v_mov_b32_e32 v117, v131
	v_mov_b32_e32 v118, v131
	v_mov_b32_e32 v119, v131
	v_mov_b32_e32 v120, v131
	v_mov_b32_e32 v121, v131
	v_mov_b32_e32 v122, v131
	v_mov_b32_e32 v123, v131
	v_mov_b32_e32 v124, v131
	v_mov_b32_e32 v125, v131
	v_mov_b32_e32 v126, v131
	v_mov_b32_e32 v127, v131
	v_mov_b32_e32 v128, v131
	v_mov_b32_e32 v129, v131
	s_waitcnt lgkmcnt(0)
	s_barrier
	v_lshl_add_u64 v[152:153], v[146:147], 0, s[18:19]
	v_add_co_u32_e32 v152, vcc, s39, v152
	s_nop 1
	v_addc_co_u32_e32 v153, vcc, 0, v153, vcc
	global_load_dwordx4 v[152:155], v[152:153], off offset:384
	v_lshl_add_u64 v[156:157], v[146:147], 0, s[18:19]
	v_add_co_u32_e32 v156, vcc, s40, v156
	s_nop 1
	v_addc_co_u32_e32 v157, vcc, 0, v157, vcc
	global_load_dwordx4 v[156:159], v[156:157], off offset:384
	v_lshl_add_u64 v[160:161], v[146:147], 0, s[18:19]
	v_add_co_u32_e32 v160, vcc, s41, v160
	s_nop 1
	v_addc_co_u32_e32 v161, vcc, 0, v161, vcc
	global_load_dwordx4 v[160:163], v[160:161], off offset:384
.LBB0_707:
	s_setprio 1
	ds_read_b128 v[200:203], v130 offset:0
	ds_read_b128 v[212:215], v133 offset:18432
	ds_read_b128 v[216:219], v133 offset:23040
	ds_read_b128 v[224:227], v133 offset:27648
	ds_read_b128 v[228:231], v133 offset:32256
	ds_read_b128 v[208:211], v130 offset:4608
	s_waitcnt lgkmcnt(4)
	v_mfma_f32_32x32x16_bf16 v[114:129], v[200:203], v[212:215], v[114:129]
	ds_read_b128 v[204:207], v130 offset:32
	ds_read_b128 v[232:235], v133 offset:18464
	s_waitcnt lgkmcnt(5)
	v_mfma_f32_32x32x16_bf16 v[98:113], v[200:203], v[216:219], v[98:113]
	v_lshl_add_u64 v[164:165], v[146:147], 0, s[18:19]
	v_add_co_u32_e32 v164, vcc, s42, v164
	s_nop 1
	v_addc_co_u32_e32 v165, vcc, 0, v165, vcc
	global_load_dwordx4 v[164:167], v[164:165], off offset:384
	ds_read_b128 v[236:239], v133 offset:23072
	s_waitcnt lgkmcnt(5)
	v_mfma_f32_32x32x16_bf16 v[82:97], v[200:203], v[224:227], v[82:97]
	ds_read_b128 v[240:243], v133 offset:27680
	s_waitcnt lgkmcnt(5)
	v_mfma_f32_32x32x16_bf16 v[66:81], v[200:203], v[228:231], v[66:81]
	v_lshl_add_u64 v[168:169], v[148:149], 0, s[18:19]
	v_add_co_u32_e32 v168, vcc, s43, v168
	s_nop 1
	v_addc_co_u32_e32 v169, vcc, 0, v169, vcc
	global_load_dwordx4 v[168:171], v[168:169], off offset:128
	ds_read_b128 v[244:247], v133 offset:32288
	s_waitcnt lgkmcnt(5)
	v_mfma_f32_32x32x16_bf16 v[50:65], v[208:211], v[212:215], v[50:65]
	v_mfma_f32_32x32x16_bf16 v[34:49], v[208:211], v[216:219], v[34:49]
	v_lshl_add_u64 v[172:173], v[148:149], 0, s[18:19]
	v_add_co_u32_e32 v172, vcc, s44, v172
	s_nop 1
	v_addc_co_u32_e32 v173, vcc, 0, v173, vcc
	global_load_dwordx4 v[172:175], v[172:173], off offset:128
	v_mfma_f32_32x32x16_bf16 v[18:33], v[208:211], v[224:227], v[18:33]
	v_mfma_f32_32x32x16_bf16 v[2:17], v[208:211], v[228:231], v[2:17]
	v_lshl_add_u64 v[176:177], v[148:149], 0, s[18:19]
	v_add_co_u32_e32 v176, vcc, s45, v176
	s_nop 1
	v_addc_co_u32_e32 v177, vcc, 0, v177, vcc
	global_load_dwordx4 v[176:179], v[176:177], off offset:128
	ds_read_b128 v[208:211], v130 offset:4640
	s_waitcnt lgkmcnt(4)
	v_mfma_f32_32x32x16_bf16 v[114:129], v[204:207], v[232:235], v[114:129]
	ds_read_b128 v[200:203], v130 offset:64
	ds_read_b128 v[212:215], v133 offset:18496
	s_waitcnt lgkmcnt(5)
	v_mfma_f32_32x32x16_bf16 v[98:113], v[204:207], v[236:239], v[98:113]
	v_lshl_add_u64 v[180:181], v[148:149], 0, s[18:19]
	v_add_co_u32_e32 v180, vcc, s46, v180
	s_nop 1
	v_addc_co_u32_e32 v181, vcc, 0, v181, vcc
	global_load_dwordx4 v[180:183], v[180:181], off offset:128
	ds_read_b128 v[216:219], v133 offset:23104
	s_waitcnt lgkmcnt(5)
	v_mfma_f32_32x32x16_bf16 v[82:97], v[204:207], v[240:243], v[82:97]
	ds_read_b128 v[224:227], v133 offset:27712
	s_waitcnt lgkmcnt(5)
	v_mfma_f32_32x32x16_bf16 v[66:81], v[204:207], v[244:247], v[66:81]
	v_lshl_add_u64 v[184:185], v[148:149], 0, s[18:19]
	v_add_co_u32_e32 v184, vcc, s47, v184
	s_nop 1
	v_addc_co_u32_e32 v185, vcc, 0, v185, vcc
	global_load_dwordx4 v[184:187], v[184:185], off offset:128
	ds_read_b128 v[228:231], v133 offset:32320
	s_waitcnt lgkmcnt(5)
	v_mfma_f32_32x32x16_bf16 v[50:65], v[208:211], v[232:235], v[50:65]
	v_mfma_f32_32x32x16_bf16 v[34:49], v[208:211], v[236:239], v[34:49]
	v_lshl_add_u64 v[188:189], v[148:149], 0, s[18:19]
	v_add_co_u32_e32 v188, vcc, s48, v188
	s_nop 1
	v_addc_co_u32_e32 v189, vcc, 0, v189, vcc
	global_load_dwordx4 v[188:191], v[188:189], off offset:128
	v_mfma_f32_32x32x16_bf16 v[18:33], v[208:211], v[240:243], v[18:33]
	v_mfma_f32_32x32x16_bf16 v[2:17], v[208:211], v[244:247], v[2:17]
	v_lshl_add_u64 v[192:193], v[148:149], 0, s[18:19]
	v_add_co_u32_e32 v192, vcc, s49, v192
	s_nop 1
	v_addc_co_u32_e32 v193, vcc, 0, v193, vcc
	global_load_dwordx4 v[192:195], v[192:193], off offset:128
	ds_read_b128 v[208:211], v130 offset:4672
	s_waitcnt lgkmcnt(4)
;     ...
;   for (int kt = 0; kt < nk; ++kt) {
;     const int kn = (kt + 1 < nk) ? kt + 1 : kt;
;     GW_LOAD2(kn * 64, kn * bkstep)
;     __builtin_amdgcn_sched_barrier(0);
;     __builtin_amdgcn_s_setprio(1);
; #pragma unroll
;     for (int st = 0; st < 4; ++st) {
;       bf16x8 a0 = *(const bf16x8*)(Ab + st * 32);
;       bf16x8 a1 = *(const bf16x8*)(Ab + 32 * LSTR + st * 32);
;       bf16x8 b0 = *(const bf16x8*)(Bb + st * 32);
;       bf16x8 b1 = *(const bf16x8*)(Bb + 32 * LSTR + st * 32);
;       bf16x8 b2 = *(const bf16x8*)(Bb + 64 * LSTR + st * 32);
;       bf16x8 b3 = *(const bf16x8*)(Bb + 96 * LSTR + st * 32);
;       acc[0][0] = mfma32(a0, b0, acc[0][0]);
;       acc[0][1] = mfma32(a0, b1, acc[0][1]);
;       acc[0][2] = mfma32(a0, b2, acc[0][2]);
;       acc[0][3] = mfma32(a0, b3, acc[0][3]);
;       acc[1][0] = mfma32(a1, b0, acc[1][0]);
;       acc[1][1] = mfma32(a1, b1, acc[1][1]);
;       acc[1][2] = mfma32(a1, b2, acc[1][2]);
;       acc[1][3] = mfma32(a1, b3, acc[1][3]);
;     }
;     __builtin_amdgcn_s_setprio(0);
;     __builtin_amdgcn_sched_barrier(0);
;     __syncthreads();
;     GW_STORE()
;     __syncthreads();
	v_mfma_f32_32x32x16_bf16 v[114:129], v[200:203], v[212:215], v[114:129]
	ds_read_b128 v[204:207], v130 offset:96
	ds_read_b128 v[232:235], v133 offset:18528
	s_waitcnt lgkmcnt(5)
	v_mfma_f32_32x32x16_bf16 v[98:113], v[200:203], v[216:219], v[98:113]
	v_lshl_add_u64 v[196:197], v[148:149], 0, s[18:19]
	v_add_co_u32_e32 v196, vcc, s50, v196
	s_nop 1
	v_addc_co_u32_e32 v197, vcc, 0, v197, vcc
	global_load_dwordx4 v[196:199], v[196:197], off offset:128
	ds_read_b128 v[236:239], v133 offset:23136
	s_waitcnt lgkmcnt(5)
	v_mfma_f32_32x32x16_bf16 v[82:97], v[200:203], v[224:227], v[82:97]
	ds_read_b128 v[240:243], v133 offset:27744
	s_waitcnt lgkmcnt(5)
	v_mfma_f32_32x32x16_bf16 v[66:81], v[200:203], v[228:231], v[66:81]
	ds_read_b128 v[244:247], v133 offset:32352
	s_waitcnt lgkmcnt(5)
	v_mfma_f32_32x32x16_bf16 v[50:65], v[208:211], v[212:215], v[50:65]
	v_mfma_f32_32x32x16_bf16 v[34:49], v[208:211], v[216:219], v[34:49]
	v_mfma_f32_32x32x16_bf16 v[18:33], v[208:211], v[224:227], v[18:33]
	v_mfma_f32_32x32x16_bf16 v[2:17], v[208:211], v[228:231], v[2:17]
	ds_read_b128 v[208:211], v130 offset:4704
	s_waitcnt lgkmcnt(4)
	v_mfma_f32_32x32x16_bf16 v[114:129], v[204:207], v[232:235], v[114:129]
	s_waitcnt lgkmcnt(3)
	v_mfma_f32_32x32x16_bf16 v[98:113], v[204:207], v[236:239], v[98:113]
	s_waitcnt lgkmcnt(2)
	v_mfma_f32_32x32x16_bf16 v[82:97], v[204:207], v[240:243], v[82:97]
	s_waitcnt lgkmcnt(1)
	v_mfma_f32_32x32x16_bf16 v[66:81], v[204:207], v[244:247], v[66:81]
	s_waitcnt lgkmcnt(0)
	v_mfma_f32_32x32x16_bf16 v[50:65], v[208:211], v[232:235], v[50:65]
	v_mfma_f32_32x32x16_bf16 v[34:49], v[208:211], v[236:239], v[34:49]
	v_mfma_f32_32x32x16_bf16 v[18:33], v[208:211], v[240:243], v[18:33]
	v_mfma_f32_32x32x16_bf16 v[2:17], v[208:211], v[244:247], v[2:17]
	s_setprio 0
	s_add_u32 s18, s18, 0x80
	s_addc_u32 s19, s19, 0
	s_cmpk_lg_i32 s18, 0x700
	s_barrier
	s_waitcnt vmcnt(11)
	ds_write_b128 v132, v[152:155]
	v_lshl_add_u64 v[152:153], v[146:147], 0, s[18:19]
	v_add_co_u32_e32 v152, vcc, s39, v152
	s_nop 1
	v_addc_co_u32_e32 v153, vcc, 0, v153, vcc
	global_load_dwordx4 v[152:155], v[152:153], off offset:384
	s_waitcnt vmcnt(11)
	ds_write_b128 v132, v[156:159] offset:4608
	v_lshl_add_u64 v[156:157], v[146:147], 0, s[18:19]
	v_add_co_u32_e32 v156, vcc, s40, v156
	s_nop 1
	v_addc_co_u32_e32 v157, vcc, 0, v157, vcc
	global_load_dwordx4 v[156:159], v[156:157], off offset:384
	s_waitcnt vmcnt(11)
	ds_write_b128 v132, v[160:163] offset:9216
	v_lshl_add_u64 v[160:161], v[146:147], 0, s[18:19]
	v_add_co_u32_e32 v160, vcc, s41, v160
	s_nop 1
	v_addc_co_u32_e32 v161, vcc, 0, v161, vcc
	global_load_dwordx4 v[160:163], v[160:161], off offset:384
	s_waitcnt vmcnt(11)
	ds_write_b128 v132, v[164:167] offset:13824
	s_waitcnt vmcnt(10)
	ds_write_b128 v132, v[168:171] offset:18432
	s_waitcnt vmcnt(9)
	ds_write_b128 v132, v[172:175] offset:23040
	s_waitcnt vmcnt(8)
	ds_write_b128 v132, v[176:179] offset:27648
	s_waitcnt vmcnt(7)
	ds_write_b128 v132, v[180:183] offset:32256
	s_waitcnt vmcnt(6)
	ds_write_b128 v132, v[184:187] offset:36864
	s_waitcnt vmcnt(5)
	ds_write_b128 v132, v[188:191] offset:41472
	s_waitcnt vmcnt(4)
	ds_write_b128 v132, v[192:195] offset:46080
	s_waitcnt vmcnt(3)
	ds_write_b128 v132, v[196:199] offset:50688
	s_waitcnt lgkmcnt(0)
	s_barrier
	s_cbranch_scc1 .LBB0_707
	s_setprio 1
	ds_read_b128 v[200:203], v130 offset:0
	ds_read_b128 v[212:215], v133 offset:18432
	ds_read_b128 v[216:219], v133 offset:23040
	ds_read_b128 v[224:227], v133 offset:27648
	ds_read_b128 v[228:231], v133 offset:32256
	ds_read_b128 v[208:211], v130 offset:4608
	s_waitcnt lgkmcnt(4)
	v_mfma_f32_32x32x16_bf16 v[114:129], v[200:203], v[212:215], v[114:129]
	ds_read_b128 v[204:207], v130 offset:32
	ds_read_b128 v[232:235], v133 offset:18464
	s_waitcnt lgkmcnt(5)
	v_mfma_f32_32x32x16_bf16 v[98:113], v[200:203], v[216:219], v[98:113]
	v_lshl_add_u64 v[164:165], v[146:147], 0, s[18:19]
	v_add_co_u32_e32 v164, vcc, s42, v164
	s_nop 1
	v_addc_co_u32_e32 v165, vcc, 0, v165, vcc
	global_load_dwordx4 v[164:167], v[164:165], off offset:384
	ds_read_b128 v[236:239], v133 offset:23072
	s_waitcnt lgkmcnt(5)
	v_mfma_f32_32x32x16_bf16 v[82:97], v[200:203], v[224:227], v[82:97]
	ds_read_b128 v[240:243], v133 offset:27680
	s_waitcnt lgkmcnt(5)
	v_mfma_f32_32x32x16_bf16 v[66:81], v[200:203], v[228:231], v[66:81]
	v_lshl_add_u64 v[168:169], v[148:149], 0, s[18:19]
	v_add_co_u32_e32 v168, vcc, s43, v168
	s_nop 1
	v_addc_co_u32_e32 v169, vcc, 0, v169, vcc
	global_load_dwordx4 v[168:171], v[168:169], off offset:128
	ds_read_b128 v[244:247], v133 offset:32288
	s_waitcnt lgkmcnt(5)
	v_mfma_f32_32x32x16_bf16 v[50:65], v[208:211], v[212:215], v[50:65]
	v_mfma_f32_32x32x16_bf16 v[34:49], v[208:211], v[216:219], v[34:49]
	v_lshl_add_u64 v[172:173], v[148:149], 0, s[18:19]
	v_add_co_u32_e32 v172, vcc, s44, v172
	s_nop 1
	v_addc_co_u32_e32 v173, vcc, 0, v173, vcc
	global_load_dwordx4 v[172:175], v[172:173], off offset:128
	v_mfma_f32_32x32x16_bf16 v[18:33], v[208:211], v[224:227], v[18:33]
	v_mfma_f32_32x32x16_bf16 v[2:17], v[208:211], v[228:231], v[2:17]
	v_lshl_add_u64 v[176:177], v[148:149], 0, s[18:19]
	v_add_co_u32_e32 v176, vcc, s45, v176
	s_nop 1
	v_addc_co_u32_e32 v177, vcc, 0, v177, vcc
	global_load_dwordx4 v[176:179], v[176:177], off offset:128
	ds_read_b128 v[208:211], v130 offset:4640
	s_waitcnt lgkmcnt(4)
	v_mfma_f32_32x32x16_bf16 v[114:129], v[204:207], v[232:235], v[114:129]
	ds_read_b128 v[200:203], v130 offset:64
	ds_read_b128 v[212:215], v133 offset:18496
	s_waitcnt lgkmcnt(5)
;     ...
;   for (int kt = 0; kt < nk; ++kt) {
;     const int kn = (kt + 1 < nk) ? kt + 1 : kt;
;     GW_LOAD2(kn * 64, kn * bkstep)
;     __builtin_amdgcn_sched_barrier(0);
;     __builtin_amdgcn_s_setprio(1);
; #pragma unroll
;     for (int st = 0; st < 4; ++st) {
;       bf16x8 a0 = *(const bf16x8*)(Ab + st * 32);
;       bf16x8 a1 = *(const bf16x8*)(Ab + 32 * LSTR + st * 32);
;       bf16x8 b0 = *(const bf16x8*)(Bb + st * 32);
;       bf16x8 b1 = *(const bf16x8*)(Bb + 32 * LSTR + st * 32);
;       bf16x8 b2 = *(const bf16x8*)(Bb + 64 * LSTR + st * 32);
;       bf16x8 b3 = *(const bf16x8*)(Bb + 96 * LSTR + st * 32);
;       acc[0][0] = mfma32(a0, b0, acc[0][0]);
;       acc[0][1] = mfma32(a0, b1, acc[0][1]);
;       acc[0][2] = mfma32(a0, b2, acc[0][2]);
;       acc[0][3] = mfma32(a0, b3, acc[0][3]);
;       acc[1][0] = mfma32(a1, b0, acc[1][0]);
;       acc[1][1] = mfma32(a1, b1, acc[1][1]);
;       acc[1][2] = mfma32(a1, b2, acc[1][2]);
;       acc[1][3] = mfma32(a1, b3, acc[1][3]);
;     }
;     __builtin_amdgcn_s_setprio(0);
;     __builtin_amdgcn_sched_barrier(0);
;     __syncthreads();
;     GW_STORE()
;     __syncthreads();
	v_mfma_f32_32x32x16_bf16 v[98:113], v[204:207], v[236:239], v[98:113]
	v_lshl_add_u64 v[180:181], v[148:149], 0, s[18:19]
	v_add_co_u32_e32 v180, vcc, s46, v180
	s_nop 1
	v_addc_co_u32_e32 v181, vcc, 0, v181, vcc
	global_load_dwordx4 v[180:183], v[180:181], off offset:128
	ds_read_b128 v[216:219], v133 offset:23104
	s_waitcnt lgkmcnt(5)
	v_mfma_f32_32x32x16_bf16 v[82:97], v[204:207], v[240:243], v[82:97]
	ds_read_b128 v[224:227], v133 offset:27712
	s_waitcnt lgkmcnt(5)
	v_mfma_f32_32x32x16_bf16 v[66:81], v[204:207], v[244:247], v[66:81]
	v_lshl_add_u64 v[184:185], v[148:149], 0, s[18:19]
	v_add_co_u32_e32 v184, vcc, s47, v184
	s_nop 1
	v_addc_co_u32_e32 v185, vcc, 0, v185, vcc
	global_load_dwordx4 v[184:187], v[184:185], off offset:128
	ds_read_b128 v[228:231], v133 offset:32320
	s_waitcnt lgkmcnt(5)
	v_mfma_f32_32x32x16_bf16 v[50:65], v[208:211], v[232:235], v[50:65]
	v_mfma_f32_32x32x16_bf16 v[34:49], v[208:211], v[236:239], v[34:49]
	v_lshl_add_u64 v[188:189], v[148:149], 0, s[18:19]
	v_add_co_u32_e32 v188, vcc, s48, v188
	s_nop 1
	v_addc_co_u32_e32 v189, vcc, 0, v189, vcc
	global_load_dwordx4 v[188:191], v[188:189], off offset:128
	v_mfma_f32_32x32x16_bf16 v[18:33], v[208:211], v[240:243], v[18:33]
	v_mfma_f32_32x32x16_bf16 v[2:17], v[208:211], v[244:247], v[2:17]
	v_lshl_add_u64 v[192:193], v[148:149], 0, s[18:19]
	v_add_co_u32_e32 v192, vcc, s49, v192
	s_nop 1
	v_addc_co_u32_e32 v193, vcc, 0, v193, vcc
	global_load_dwordx4 v[192:195], v[192:193], off offset:128
	ds_read_b128 v[208:211], v130 offset:4672
	s_waitcnt lgkmcnt(4)
	v_mfma_f32_32x32x16_bf16 v[114:129], v[200:203], v[212:215], v[114:129]
	ds_read_b128 v[204:207], v130 offset:96
	ds_read_b128 v[232:235], v133 offset:18528
	s_waitcnt lgkmcnt(5)
	v_mfma_f32_32x32x16_bf16 v[98:113], v[200:203], v[216:219], v[98:113]
	v_lshl_add_u64 v[196:197], v[148:149], 0, s[18:19]
	v_add_co_u32_e32 v196, vcc, s50, v196
	s_nop 1
	v_addc_co_u32_e32 v197, vcc, 0, v197, vcc
	global_load_dwordx4 v[196:199], v[196:197], off offset:128
	ds_read_b128 v[236:239], v133 offset:23136
	s_waitcnt lgkmcnt(5)
	v_mfma_f32_32x32x16_bf16 v[82:97], v[200:203], v[224:227], v[82:97]
	ds_read_b128 v[240:243], v133 offset:27744
	s_waitcnt lgkmcnt(5)
	v_mfma_f32_32x32x16_bf16 v[66:81], v[200:203], v[228:231], v[66:81]
	ds_read_b128 v[244:247], v133 offset:32352
	s_waitcnt lgkmcnt(5)
	v_mfma_f32_32x32x16_bf16 v[50:65], v[208:211], v[212:215], v[50:65]
	v_mfma_f32_32x32x16_bf16 v[34:49], v[208:211], v[216:219], v[34:49]
	v_mfma_f32_32x32x16_bf16 v[18:33], v[208:211], v[224:227], v[18:33]
	v_mfma_f32_32x32x16_bf16 v[2:17], v[208:211], v[228:231], v[2:17]
	ds_read_b128 v[208:211], v130 offset:4704
	s_waitcnt lgkmcnt(4)
	v_mfma_f32_32x32x16_bf16 v[114:129], v[204:207], v[232:235], v[114:129]
	s_waitcnt lgkmcnt(3)
	v_mfma_f32_32x32x16_bf16 v[98:113], v[204:207], v[236:239], v[98:113]
	s_waitcnt lgkmcnt(2)
	v_mfma_f32_32x32x16_bf16 v[82:97], v[204:207], v[240:243], v[82:97]
	s_waitcnt lgkmcnt(1)
	v_mfma_f32_32x32x16_bf16 v[66:81], v[204:207], v[244:247], v[66:81]
	s_waitcnt lgkmcnt(0)
	v_mfma_f32_32x32x16_bf16 v[50:65], v[208:211], v[232:235], v[50:65]
	v_mfma_f32_32x32x16_bf16 v[34:49], v[208:211], v[236:239], v[34:49]
	v_mfma_f32_32x32x16_bf16 v[18:33], v[208:211], v[240:243], v[18:33]
	v_mfma_f32_32x32x16_bf16 v[2:17], v[208:211], v[244:247], v[2:17]
	s_setprio 0
	s_add_u32 s18, s18, 0x80
	s_addc_u32 s19, s19, 0
	s_barrier
	s_waitcnt vmcnt(11)
	ds_write_b128 v132, v[152:155]
	s_waitcnt vmcnt(10)
	ds_write_b128 v132, v[156:159] offset:4608
	s_waitcnt vmcnt(9)
	ds_write_b128 v132, v[160:163] offset:9216
	s_waitcnt vmcnt(8)
	ds_write_b128 v132, v[164:167] offset:13824
	s_waitcnt vmcnt(7)
	ds_write_b128 v132, v[168:171] offset:18432
	s_waitcnt vmcnt(6)
	ds_write_b128 v132, v[172:175] offset:23040
	s_waitcnt vmcnt(5)
	ds_write_b128 v132, v[176:179] offset:27648
	s_waitcnt vmcnt(4)
	ds_write_b128 v132, v[180:183] offset:32256
	s_waitcnt vmcnt(3)
	ds_write_b128 v132, v[184:187] offset:36864
	s_waitcnt vmcnt(2)
	ds_write_b128 v132, v[188:191] offset:41472
	s_waitcnt vmcnt(1)
	ds_write_b128 v132, v[192:195] offset:46080
	s_waitcnt vmcnt(0)
	ds_write_b128 v132, v[196:199] offset:50688
	s_waitcnt lgkmcnt(0)
	s_barrier
;     ...
;     for (int st = 0; st < 4; ++st) {
;       bf16x8 a0 = *(const bf16x8*)(Ab + st * 32);
;       bf16x8 a1 = *(const bf16x8*)(Ab + 32 * LSTR + st * 32);
;       bf16x8 b0 = *(const bf16x8*)(Bb + st * 32);
;       bf16x8 b1 = *(const bf16x8*)(Bb + 32 * LSTR + st * 32);
;       bf16x8 b2 = *(const bf16x8*)(Bb + 64 * LSTR + st * 32);
;       bf16x8 b3 = *(const bf16x8*)(Bb + 96 * LSTR + st * 32);
;       acc[0][0] = mfma32(a0, b0, acc[0][0]);
;       acc[0][1] = mfma32(a0, b1, acc[0][1]);
;       acc[0][2] = mfma32(a0, b2, acc[0][2]);
;       acc[0][3] = mfma32(a0, b3, acc[0][3]);
;       acc[1][0] = mfma32(a1, b0, acc[1][0]);
;       acc[1][1] = mfma32(a1, b1, acc[1][1]);
;       acc[1][2] = mfma32(a1, b2, acc[1][2]);
;       acc[1][3] = mfma32(a1, b3, acc[1][3]);
;     }
;     __builtin_amdgcn_s_setprio(0);
	v_add_co_u32_e32 v160, vcc, 0x10000, v136
	s_nop 0
	s_nop 0
	s_nop 0
	v_addc_co_u32_e32 v161, vcc, 0, v137, vcc
	v_add_co_u32_e32 v164, vcc, 0x20000, v136
	s_nop 0
	v_addc_co_u32_e32 v165, vcc, 0, v137, vcc
	v_add_co_u32_e32 v168, vcc, 0x30000, v136
	s_lshl_b64 s[16:17], s[16:17], 7
	s_nop 0
	v_addc_co_u32_e32 v169, vcc, 0, v137, vcc
	v_add_co_u32_e32 v172, vcc, 0x40000, v136
	s_nop 0
	v_addc_co_u32_e32 v173, vcc, 0, v137, vcc
	v_add_co_u32_e32 v176, vcc, 0x50000, v136
	s_mov_b32 s15, 0
	s_nop 0
	v_addc_co_u32_e32 v177, vcc, 0, v137, vcc
	v_add_co_u32_e32 v180, vcc, 0x60000, v136
	s_nop 0
	v_addc_co_u32_e32 v181, vcc, 0, v137, vcc
	v_add_co_u32_e32 v136, vcc, 0x70000, v136
	s_nop 1
	v_addc_co_u32_e32 v137, vcc, 0, v137, vcc
	s_nop 0
	s_setprio 1
	ds_read_b128 v[188:191], v130 offset:0
	ds_read_b128 v[200:203], v133 offset:18432
	ds_read_b128 v[204:207], v133 offset:23040
	ds_read_b128 v[208:211], v133 offset:27648
	ds_read_b128 v[212:215], v133 offset:32256
	ds_read_b128 v[196:199], v130 offset:4608
	s_waitcnt lgkmcnt(4)
	v_mfma_f32_32x32x16_bf16 v[114:129], v[188:191], v[200:203], v[114:129]
	ds_read_b128 v[192:195], v130 offset:32
	ds_read_b128 v[216:219], v133 offset:18464
	s_waitcnt lgkmcnt(5)
	v_mfma_f32_32x32x16_bf16 v[98:113], v[188:191], v[204:207], v[98:113]
	ds_read_b128 v[224:227], v133 offset:23072
	s_waitcnt lgkmcnt(5)
	v_mfma_f32_32x32x16_bf16 v[82:97], v[188:191], v[208:211], v[82:97]
	ds_read_b128 v[228:231], v133 offset:27680
	s_waitcnt lgkmcnt(5)
	v_mfma_f32_32x32x16_bf16 v[66:81], v[188:191], v[212:215], v[66:81]
	ds_read_b128 v[232:235], v133 offset:32288
	s_waitcnt lgkmcnt(5)
	v_mfma_f32_32x32x16_bf16 v[50:65], v[196:199], v[200:203], v[50:65]
	v_mfma_f32_32x32x16_bf16 v[34:49], v[196:199], v[204:207], v[34:49]
	v_mfma_f32_32x32x16_bf16 v[18:33], v[196:199], v[208:211], v[18:33]
	v_mfma_f32_32x32x16_bf16 v[2:17], v[196:199], v[212:215], v[2:17]
	ds_read_b128 v[196:199], v130 offset:4640
	s_waitcnt lgkmcnt(4)
	v_mfma_f32_32x32x16_bf16 v[114:129], v[192:195], v[216:219], v[114:129]
	ds_read_b128 v[188:191], v130 offset:64
	ds_read_b128 v[200:203], v133 offset:18496
	s_waitcnt lgkmcnt(5)
	v_mfma_f32_32x32x16_bf16 v[98:113], v[192:195], v[224:227], v[98:113]
	ds_read_b128 v[204:207], v133 offset:23104
	s_waitcnt lgkmcnt(5)
	v_mfma_f32_32x32x16_bf16 v[82:97], v[192:195], v[228:231], v[82:97]
	ds_read_b128 v[208:211], v133 offset:27712
	s_waitcnt lgkmcnt(5)
	v_mfma_f32_32x32x16_bf16 v[66:81], v[192:195], v[232:235], v[66:81]
	ds_read_b128 v[212:215], v133 offset:32320
	s_waitcnt lgkmcnt(5)
	v_mfma_f32_32x32x16_bf16 v[50:65], v[196:199], v[216:219], v[50:65]
	v_mfma_f32_32x32x16_bf16 v[34:49], v[196:199], v[224:227], v[34:49]
	v_mfma_f32_32x32x16_bf16 v[18:33], v[196:199], v[228:231], v[18:33]
	v_mfma_f32_32x32x16_bf16 v[2:17], v[196:199], v[232:235], v[2:17]
	ds_read_b128 v[196:199], v130 offset:4672
	s_waitcnt lgkmcnt(4)
	v_mfma_f32_32x32x16_bf16 v[114:129], v[188:191], v[200:203], v[114:129]
	ds_read_b128 v[192:195], v130 offset:96
	ds_read_b128 v[216:219], v133 offset:18528
	s_waitcnt lgkmcnt(5)
	v_mfma_f32_32x32x16_bf16 v[98:113], v[188:191], v[204:207], v[98:113]
	ds_read_b128 v[224:227], v133 offset:23136
	s_waitcnt lgkmcnt(5)
	v_mfma_f32_32x32x16_bf16 v[82:97], v[188:191], v[208:211], v[82:97]
	ds_read_b128 v[228:231], v133 offset:27744
	s_waitcnt lgkmcnt(5)
	v_mfma_f32_32x32x16_bf16 v[66:81], v[188:191], v[212:215], v[66:81]
	ds_read_b128 v[232:235], v133 offset:32352
	s_waitcnt lgkmcnt(5)
	v_mfma_f32_32x32x16_bf16 v[50:65], v[196:199], v[200:203], v[50:65]
	v_mfma_f32_32x32x16_bf16 v[34:49], v[196:199], v[204:207], v[34:49]
	v_mfma_f32_32x32x16_bf16 v[18:33], v[196:199], v[208:211], v[18:33]
	v_mfma_f32_32x32x16_bf16 v[2:17], v[196:199], v[212:215], v[2:17]
	ds_read_b128 v[196:199], v130 offset:4704
	s_waitcnt lgkmcnt(4)
	v_mfma_f32_32x32x16_bf16 v[114:129], v[192:195], v[216:219], v[114:129]
	s_waitcnt lgkmcnt(3)
	v_mfma_f32_32x32x16_bf16 v[98:113], v[192:195], v[224:227], v[98:113]
	s_waitcnt lgkmcnt(2)
	v_mfma_f32_32x32x16_bf16 v[82:97], v[192:195], v[228:231], v[82:97]
	s_waitcnt lgkmcnt(1)
	v_mfma_f32_32x32x16_bf16 v[66:81], v[192:195], v[232:235], v[66:81]
	s_waitcnt lgkmcnt(0)
	v_mfma_f32_32x32x16_bf16 v[50:65], v[196:199], v[216:219], v[50:65]
	v_mfma_f32_32x32x16_bf16 v[34:49], v[196:199], v[224:227], v[34:49]
	v_mfma_f32_32x32x16_bf16 v[18:33], v[196:199], v[228:231], v[18:33]
	v_mfma_f32_32x32x16_bf16 v[2:17], v[196:199], v[232:235], v[2:17]
	s_setprio 0
	s_mov_b64 s[18:19], -1
	s_barrier
	s_waitcnt lgkmcnt(0)

; #define GW_LOAD(KOFF) GW_LOAD2(KOFF, 0)
;   int tid = threadIdx.x;
;   asm volatile("" : "+v"(tid));
;   const int lane = tid & 63, wave = tid >> 6;
;   const int wm = wave >> 1, wn = wave & 1;
;   const int lr = tid >> 3, kc = tid & 7;
;   const u16* ap0 = arow(lr) + kc * 8;
;   const u16* ap1 = arow(lr + 32) + kc * 8;
;   const u16* ap2 = arow(lr + 64) + kc * 8;
;   const u16* ap3 = arow(lr + 96) + kc * 8;
;   const u16* bp0 = Bt + (size_t)lr * ldb + kc * 8;
;   const size_t bstep = 32 * ldb;
;   const int so = lr * LSTR + kc * 16;
;   uint4 ra0, ra1, ra2, ra3, rb0, rb1, rb2, rb3, rb4, rb5, rb6, rb7;
;     ...
;   GW_LOAD(0)
;   GW_STORE()
;   __syncthreads();
; __device__ __forceinline__ void expert1_tile(const Params& P, int e, int mt, int ntw, char* smem) {
;   f32x16 acc[2][4];
; #pragma unroll
;   for (int i = 0; i < 2; ++i)
; #pragma unroll
;     for (int j = 0; j < 4; ++j)
; #pragma unroll
;       for (int r = 0; r < 16; ++r) acc[i][j][r] = 0.f;
;   const int* ridx = WSP(int, OFF_ROWIDX) + e * EROWS + mt * 128;
;   const u16* H = WSP(u16, OFF_H);
;   const u16* Bt = WSP(u16, OFF_WGU) + (size_t)e * 4096 * DM + (size_t)ntw * 256 * 64;
;   gemm_wide([&](int rr) { return H + (size_t)ridx[rr] * DM; }, Bt, 64, DM, smem, acc, 4096 * 64);
.LBB0_1033:
	s_lshl_b32 s12, s40, 6
	s_and_b32 s12, s12, 0x1c0
	s_and_b32 s13, s40, 0xfffffe00
	s_or_b32 s12, s12, s13
	s_bfe_u32 s13, s40, 0x60003
	s_or_b32 s14, s12, s13
	s_and_b64 s[12:13], s[0:1], exec
	s_cselect_b32 s13, s14, s40
	s_cmpk_gt_i32 s13, 0x21ff
	s_cbranch_scc1 .LBB0_1032
	s_ashr_i32 s12, s13, 31
	s_lshr_b32 s12, s12, 25
	s_add_i32 s12, s13, s12
	s_ashr_i32 s14, s12, 7
	s_and_b32 s12, s12, 0xffffff80
	s_lshl_b32 s14, s14, 3
	s_sub_i32 s12, s13, s12
	s_and_b32 s13, s13, 7
	s_or_b32 s13, s14, s13
	s_mul_hi_i32 s14, s13, 0x78787879
	s_lshr_b32 s15, s14, 31
	s_ashr_i32 s14, s14, 4
	s_add_i32 s14, s14, s15
	s_mul_i32 s16, s14, 0x1100
	s_mul_i32 s15, s14, 34
	s_ashr_i32 s17, s16, 31
	s_ashr_i32 s12, s12, 3
	s_sub_i32 s13, s13, s15
	s_lshl_b64 s[16:17], s[16:17], 2
	s_add_u32 s15, s23, s16
	s_addc_u32 s20, s24, s17
	s_lshl_b32 s16, s13, 7
	s_ashr_i32 s17, s16, 31
	s_lshl_b64 s[18:19], s[16:17], 2
	v_mov_b32_e32 v57, v134
	s_add_u32 s18, s15, s18
	s_addc_u32 s19, s20, s19
	v_ashrrev_i32_e32 v106, 3, v57
	v_ashrrev_i32_e32 v107, 31, v106
	v_lshl_add_u64 v[2:3], v[106:107], 2, s[18:19]
	global_load_dword v10, v[2:3], off
	global_load_dword v12, v[2:3], off offset:128
	global_load_dword v14, v[2:3], off offset:256
	global_load_dword v16, v[2:3], off offset:384
	s_ashr_i32 s15, s14, 31
	s_lshl_b64 s[18:19], s[14:15], 23
	s_add_u32 s15, s25, s18
	s_addc_u32 s43, s26, s19
	s_ashr_i32 s13, s12, 31
	s_lshl_b64 s[20:21], s[12:13], 15
	s_add_u32 s42, s15, s20
	v_lshlrev_b32_e32 v11, 4, v57
	v_lshlrev_b64 v[108:109], 7, v[106:107]
	s_addc_u32 s43, s43, s21
	v_and_b32_e32 v130, 0x70, v11
	v_lshl_add_u64 v[18:19], s[42:43], 0, v[108:109]
	v_lshl_add_u64 v[136:137], v[18:19], 0, v[130:131]
	v_add_co_u32_e32 v18, vcc, s28, v136
	global_load_dwordx4 v[58:61], v[136:137], off
	s_nop 0
	v_addc_co_u32_e32 v19, vcc, 0, v137, vcc
	v_add_co_u32_e32 v20, vcc, s29, v136
	s_add_u32 s13, s18, s20
	s_nop 0
	v_addc_co_u32_e32 v21, vcc, 0, v137, vcc
	v_add_co_u32_e32 v22, vcc, s30, v136
	v_and_b32_e32 v107, 31, v57
	s_nop 0
	v_addc_co_u32_e32 v23, vcc, 0, v137, vcc
	v_add_co_u32_e32 v24, vcc, s31, v136
	v_lshrrev_b32_e32 v118, 1, v57
	s_nop 0
	v_addc_co_u32_e32 v25, vcc, 0, v137, vcc
	global_load_dwordx4 v[62:65], v[18:19], off offset:-4096
	global_load_dwordx4 v[66:69], v[18:19], off
	global_load_dwordx4 v[70:73], v[20:21], off offset:-4096
	global_load_dwordx4 v[74:77], v[20:21], off
	global_load_dwordx4 v[78:81], v[22:23], off offset:-4096
	global_load_dwordx4 v[82:85], v[22:23], off
	global_load_dwordx4 v[86:89], v[24:25], off
	v_lshlrev_b32_e32 v57, 1, v57
	s_addc_u32 s15, s19, s21
	v_and_or_b32 v119, v118, s33, v107
	v_and_or_b32 v57, v57, s34, v107
	s_add_u32 s18, s90, s13
	v_mov_b32_e32 v2, 0
	v_and_b32_e32 v118, 16, v118
	v_mad_u64_u32 v[132:133], s[42:43], v106, s27, v[130:131]
	v_mul_lo_u32 v106, v119, s27
	v_mul_u32_u24_e32 v57, 0x90, v57
	s_addc_u32 s19, s91, s15
	s_mov_b32 s41, 14
	v_mov_b32_e32 v3, v2
	v_mov_b32_e32 v4, v2
	v_mov_b32_e32 v5, v2
	v_mov_b32_e32 v6, v2
	v_mov_b32_e32 v7, v2
	v_mov_b32_e32 v8, v2
	v_mov_b32_e32 v9, v2
	v_mov_b32_e32 v18, v2
	v_mov_b32_e32 v19, v2
	v_mov_b32_e32 v20, v2
	v_mov_b32_e32 v21, v2
	v_mov_b32_e32 v22, v2
	v_mov_b32_e32 v23, v2
	v_mov_b32_e32 v24, v2
	v_mov_b32_e32 v25, v2
	v_mov_b32_e32 v26, v2
	v_mov_b32_e32 v27, v2
	v_mov_b32_e32 v28, v2
	v_mov_b32_e32 v29, v2
	v_mov_b32_e32 v30, v2
	v_mov_b32_e32 v31, v2
	v_mov_b32_e32 v32, v2
	v_mov_b32_e32 v33, v2
	v_mov_b32_e32 v34, v2
	v_mov_b32_e32 v35, v2
	v_mov_b32_e32 v36, v2
	v_mov_b32_e32 v37, v2
	v_mov_b32_e32 v38, v2
	v_mov_b32_e32 v39, v2
	s_waitcnt vmcnt(11)
	v_ashrrev_i32_e32 v11, 31, v10
	s_waitcnt vmcnt(10)
	v_ashrrev_i32_e32 v13, 31, v12
	s_waitcnt vmcnt(9)
	v_ashrrev_i32_e32 v15, 31, v14
	s_waitcnt vmcnt(8)
	v_ashrrev_i32_e32 v17, 31, v16
	v_lshlrev_b64 v[110:111], 11, v[10:11]
	v_lshlrev_b64 v[112:113], 11, v[12:13]
	v_lshlrev_b64 v[114:115], 11, v[14:15]
	v_lshlrev_b64 v[116:117], 11, v[16:17]
	v_lshl_add_u64 v[10:11], s[2:3], 0, v[110:111]
	v_lshl_add_u64 v[12:13], s[2:3], 0, v[112:113]
	v_lshl_add_u64 v[14:15], s[2:3], 0, v[114:115]
	v_lshl_add_u64 v[16:17], s[2:3], 0, v[116:117]
	v_lshl_add_u64 v[138:139], v[10:11], 0, v[130:131]
	v_lshl_add_u64 v[140:141], v[12:13], 0, v[130:131]
	v_lshl_add_u64 v[142:143], v[14:15], 0, v[130:131]
	v_lshl_add_u64 v[144:145], v[16:17], 0, v[130:131]
	global_load_dwordx4 v[90:93], v[138:139], off
	global_load_dwordx4 v[94:97], v[140:141], off
	global_load_dwordx4 v[98:101], v[142:143], off
	global_load_dwordx4 v[102:105], v[144:145], off
	v_mov_b32_e32 v10, v2
	v_mov_b32_e32 v11, v2
	v_mov_b32_e32 v12, v2
	v_mov_b32_e32 v13, v2
	v_mov_b32_e32 v14, v2
	v_mov_b32_e32 v15, v2
	v_mov_b32_e32 v16, v2
	v_mov_b32_e32 v17, v2
	v_mov_b32_e32 v40, v2
	v_mov_b32_e32 v41, v2
	v_mov_b32_e32 v42, v2
	v_mov_b32_e32 v43, v2
	v_mov_b32_e32 v44, v2
	v_mov_b32_e32 v45, v2
	v_mov_b32_e32 v46, v2
	v_mov_b32_e32 v47, v2
	v_mov_b32_e32 v48, v2
	v_mov_b32_e32 v49, v2
	v_mov_b32_e32 v50, v2
	v_mov_b32_e32 v51, v2
	v_mov_b32_e32 v52, v2
	v_mov_b32_e32 v53, v2
	v_mov_b32_e32 v54, v2
	v_mov_b32_e32 v55, v2
	v_mov_b32_e32 v56, v2
	v_add_u32_e32 v133, v106, v118
	v_add_u32_e32 v156, v57, v118
	v_lshl_add_u64 v[146:147], s[18:19], 0, v[108:109]
	v_lshl_add_u64 v[148:149], s[6:7], 0, v[110:111]
	v_lshl_add_u64 v[150:151], s[6:7], 0, v[112:113]
	v_lshl_add_u64 v[152:153], s[6:7], 0, v[114:115]
	v_lshl_add_u64 v[154:155], s[6:7], 0, v[116:117]
	v_mov_b32_e32 v57, v2
	v_mov_b32_e32 v106, v2
	v_mov_b32_e32 v107, v2
	v_mov_b32_e32 v108, v2
	v_mov_b32_e32 v109, v2
	v_mov_b32_e32 v110, v2
	v_mov_b32_e32 v111, v2
	v_mov_b32_e32 v112, v2
	v_mov_b32_e32 v113, v2
	v_mov_b32_e32 v114, v2
	v_mov_b32_e32 v115, v2
	v_mov_b32_e32 v116, v2
	v_mov_b32_e32 v117, v2
	v_mov_b32_e32 v118, v2
	v_mov_b32_e32 v119, v2
	v_mov_b32_e32 v120, v2
	v_mov_b32_e32 v121, v2
	v_mov_b32_e32 v122, v2
	v_mov_b32_e32 v123, v2
	v_mov_b32_e32 v124, v2
	v_mov_b32_e32 v125, v2
	v_mov_b32_e32 v126, v2
	v_mov_b32_e32 v127, v2
	v_mov_b32_e32 v128, v2
	v_mov_b32_e32 v129, v2
	s_waitcnt vmcnt(11)
; #define GW_LOAD(KOFF) GW_LOAD2(KOFF, 0)
;     ...
;   GW_LOAD(0)
;   GW_STORE()
;   __syncthreads();
;   const int nk = K >> 6;
;   const char* Ab = smem + (wm * 64 + (lane & 31)) * LSTR + (lane >> 5) * 16;
;   const char* Bb = smem + WTILE_A + (wn * 128 + (lane & 31)) * LSTR + (lane >> 5) * 16;
;   for (int kt = 0; kt < nk; ++kt) {
;     const int kn = (kt + 1 < nk) ? kt + 1 : kt;
;     GW_LOAD2(kn * 64, kn * bkstep)
;     __builtin_amdgcn_sched_barrier(0);
;     __builtin_amdgcn_s_setprio(1);
; #pragma unroll
;     for (int st = 0; st < 4; ++st) {
;       bf16x8 a0 = *(const bf16x8*)(Ab + st * 32);
;       bf16x8 a1 = *(const bf16x8*)(Ab + 32 * LSTR + st * 32);
;       bf16x8 b0 = *(const bf16x8*)(Bb + st * 32);
;       bf16x8 b1 = *(const bf16x8*)(Bb + 32 * LSTR + st * 32);
;       bf16x8 b2 = *(const bf16x8*)(Bb + 64 * LSTR + st * 32);
;       bf16x8 b3 = *(const bf16x8*)(Bb + 96 * LSTR + st * 32);
;       acc[0][0] = mfma32(a0, b0, acc[0][0]);
;       acc[0][1] = mfma32(a0, b1, acc[0][1]);
;       acc[0][2] = mfma32(a0, b2, acc[0][2]);
;       acc[0][3] = mfma32(a0, b3, acc[0][3]);
;       acc[1][0] = mfma32(a1, b0, acc[1][0]);
;       acc[1][1] = mfma32(a1, b1, acc[1][1]);
;       acc[1][2] = mfma32(a1, b2, acc[1][2]);
;       acc[1][3] = mfma32(a1, b3, acc[1][3]);
;     }
;     __builtin_amdgcn_s_setprio(0);
	ds_write_b128 v132, v[58:61] offset:18432
	s_waitcnt vmcnt(10)
	ds_write_b128 v132, v[62:65] offset:23040
	s_waitcnt vmcnt(9)
	ds_write_b128 v132, v[66:69] offset:27648
	s_waitcnt vmcnt(8)
	ds_write_b128 v132, v[70:73] offset:32256
	s_waitcnt vmcnt(7)
	ds_write_b128 v132, v[74:77] offset:36864
	s_waitcnt vmcnt(6)
	ds_write_b128 v132, v[78:81] offset:41472
	s_waitcnt vmcnt(5)
	ds_write_b128 v132, v[82:85] offset:46080
	s_waitcnt vmcnt(4)
	ds_write_b128 v132, v[86:89] offset:50688
	s_waitcnt vmcnt(3)
	ds_write_b128 v132, v[90:93]
	s_waitcnt vmcnt(2)
	ds_write_b128 v132, v[94:97] offset:4608
	s_waitcnt vmcnt(1)
	ds_write_b128 v132, v[98:101] offset:9216
	s_waitcnt vmcnt(0)
	ds_write_b128 v132, v[102:105] offset:13824
	v_mov_b32_e32 v58, v2
	v_mov_b32_e32 v59, v2
	v_mov_b32_e32 v60, v2
	v_mov_b32_e32 v61, v2
	v_mov_b32_e32 v62, v2
	v_mov_b32_e32 v63, v2
	v_mov_b32_e32 v64, v2
	v_mov_b32_e32 v65, v2
	v_mov_b32_e32 v66, v2
	v_mov_b32_e32 v67, v2
	v_mov_b32_e32 v68, v2
	v_mov_b32_e32 v69, v2
	v_mov_b32_e32 v70, v2
	v_mov_b32_e32 v71, v2
	v_mov_b32_e32 v72, v2
	v_mov_b32_e32 v73, v2
	v_mov_b32_e32 v74, v2
	v_mov_b32_e32 v75, v2
	v_mov_b32_e32 v76, v2
	v_mov_b32_e32 v77, v2
	v_mov_b32_e32 v78, v2
	v_mov_b32_e32 v79, v2
	v_mov_b32_e32 v80, v2
	v_mov_b32_e32 v81, v2
	v_mov_b32_e32 v82, v2
	v_mov_b32_e32 v83, v2
	v_mov_b32_e32 v84, v2
	v_mov_b32_e32 v85, v2
	v_mov_b32_e32 v86, v2
	v_mov_b32_e32 v87, v2
	v_mov_b32_e32 v88, v2
	v_mov_b32_e32 v89, v2
	v_mov_b32_e32 v90, v2
	v_mov_b32_e32 v91, v2
	v_mov_b32_e32 v92, v2
	v_mov_b32_e32 v93, v2
	v_mov_b32_e32 v94, v2
	v_mov_b32_e32 v95, v2
	v_mov_b32_e32 v96, v2
	v_mov_b32_e32 v97, v2
	v_mov_b32_e32 v98, v2
	v_mov_b32_e32 v99, v2
	v_mov_b32_e32 v100, v2
	v_mov_b32_e32 v101, v2
	v_mov_b32_e32 v102, v2
	v_mov_b32_e32 v103, v2
	v_mov_b32_e32 v104, v2
	v_mov_b32_e32 v105, v2
	s_waitcnt lgkmcnt(0)
	s_barrier
	v_lshl_add_u64 v[158:159], v[148:149], 0, v[130:131]
	global_load_dwordx4 v[158:161], v[158:159], off
	v_lshl_add_u64 v[162:163], v[150:151], 0, v[130:131]
	global_load_dwordx4 v[162:165], v[162:163], off
	v_lshl_add_u64 v[166:167], v[152:153], 0, v[130:131]
	global_load_dwordx4 v[166:169], v[166:167], off
.LBB0_1035:
	s_setprio 1
	ds_read_b128 v[206:209], v133 offset:0
	ds_read_b128 v[218:221], v156 offset:18432
	ds_read_b128 v[224:227], v156 offset:23040
	ds_read_b128 v[228:231], v156 offset:27648
	ds_read_b128 v[232:235], v156 offset:32256
	ds_read_b128 v[214:217], v133 offset:4608
	s_waitcnt lgkmcnt(4)
	v_mfma_f32_32x32x16_bf16 v[114:129], v[206:209], v[218:221], v[114:129]
	ds_read_b128 v[210:213], v133 offset:32
	ds_read_b128 v[236:239], v156 offset:18464
	s_waitcnt lgkmcnt(5)
	v_mfma_f32_32x32x16_bf16 v[98:113], v[206:209], v[224:227], v[98:113]
	v_lshl_add_u64 v[170:171], v[154:155], 0, v[130:131]
	global_load_dwordx4 v[170:173], v[170:171], off
	ds_read_b128 v[240:243], v156 offset:23072
	s_waitcnt lgkmcnt(5)
	v_mfma_f32_32x32x16_bf16 v[82:97], v[206:209], v[228:231], v[82:97]
	ds_read_b128 v[244:247], v156 offset:27680
	s_waitcnt lgkmcnt(5)
	v_mfma_f32_32x32x16_bf16 v[66:81], v[206:209], v[232:235], v[66:81]
	v_lshl_add_u64 v[174:175], v[146:147], 0, v[130:131]
	v_add_co_u32_e32 v174, vcc, s35, v174
	s_nop 1
	v_addc_co_u32_e32 v175, vcc, 0, v175, vcc
	global_load_dwordx4 v[174:177], v[174:175], off offset:-4096
	ds_read_b128 v[248:251], v156 offset:32288
	s_waitcnt lgkmcnt(5)
	v_mfma_f32_32x32x16_bf16 v[50:65], v[214:217], v[218:221], v[50:65]
	v_mfma_f32_32x32x16_bf16 v[34:49], v[214:217], v[224:227], v[34:49]
	v_lshl_add_u64 v[178:179], v[146:147], 0, v[130:131]
	v_add_co_u32_e32 v178, vcc, s35, v178
	s_nop 1
	v_addc_co_u32_e32 v179, vcc, 0, v179, vcc
	global_load_dwordx4 v[178:181], v[178:179], off
	v_mfma_f32_32x32x16_bf16 v[18:33], v[214:217], v[228:231], v[18:33]
	v_mfma_f32_32x32x16_bf16 v[2:17], v[214:217], v[232:235], v[2:17]
	v_lshl_add_u64 v[182:183], v[146:147], 0, v[130:131]
	v_add_co_u32_e32 v182, vcc, s36, v182
	s_nop 1
	v_addc_co_u32_e32 v183, vcc, 0, v183, vcc
	global_load_dwordx4 v[182:185], v[182:183], off offset:-4096
	ds_read_b128 v[214:217], v133 offset:4640
	s_waitcnt lgkmcnt(4)
	v_mfma_f32_32x32x16_bf16 v[114:129], v[210:213], v[236:239], v[114:129]
	ds_read_b128 v[206:209], v133 offset:64
	ds_read_b128 v[218:221], v156 offset:18496
	s_waitcnt lgkmcnt(5)
	v_mfma_f32_32x32x16_bf16 v[98:113], v[210:213], v[240:243], v[98:113]
	v_lshl_add_u64 v[186:187], v[146:147], 0, v[130:131]
	v_add_co_u32_e32 v186, vcc, s36, v186
	s_nop 1
	v_addc_co_u32_e32 v187, vcc, 0, v187, vcc
	global_load_dwordx4 v[186:189], v[186:187], off
	ds_read_b128 v[224:227], v156 offset:23104
	s_waitcnt lgkmcnt(5)
	v_mfma_f32_32x32x16_bf16 v[82:97], v[210:213], v[244:247], v[82:97]
	ds_read_b128 v[228:231], v156 offset:27712
	s_waitcnt lgkmcnt(5)
	v_mfma_f32_32x32x16_bf16 v[66:81], v[210:213], v[248:251], v[66:81]
	v_lshl_add_u64 v[190:191], v[146:147], 0, v[130:131]
	v_add_co_u32_e32 v190, vcc, s37, v190
	s_nop 1
	v_addc_co_u32_e32 v191, vcc, 0, v191, vcc
	global_load_dwordx4 v[190:193], v[190:191], off offset:-4096
	ds_read_b128 v[232:235], v156 offset:32320
	s_waitcnt lgkmcnt(5)
	v_mfma_f32_32x32x16_bf16 v[50:65], v[214:217], v[236:239], v[50:65]
	v_mfma_f32_32x32x16_bf16 v[34:49], v[214:217], v[240:243], v[34:49]
	v_lshl_add_u64 v[194:195], v[146:147], 0, v[130:131]
	v_add_co_u32_e32 v194, vcc, s37, v194
	s_nop 1
	v_addc_co_u32_e32 v195, vcc, 0, v195, vcc
	global_load_dwordx4 v[194:197], v[194:195], off
	v_mfma_f32_32x32x16_bf16 v[18:33], v[214:217], v[244:247], v[18:33]
	v_mfma_f32_32x32x16_bf16 v[2:17], v[214:217], v[248:251], v[2:17]
	v_lshl_add_u64 v[198:199], v[146:147], 0, v[130:131]
	v_add_co_u32_e32 v198, vcc, s38, v198
	s_nop 1
	v_addc_co_u32_e32 v199, vcc, 0, v199, vcc
	global_load_dwordx4 v[198:201], v[198:199], off offset:-4096
	ds_read_b128 v[214:217], v133 offset:4672
	s_waitcnt lgkmcnt(4)
;     ...
;   for (int kt = 0; kt < nk; ++kt) {
;     const int kn = (kt + 1 < nk) ? kt + 1 : kt;
;     GW_LOAD2(kn * 64, kn * bkstep)
;     __builtin_amdgcn_sched_barrier(0);
;     __builtin_amdgcn_s_setprio(1);
; #pragma unroll
;     for (int st = 0; st < 4; ++st) {
;       bf16x8 a0 = *(const bf16x8*)(Ab + st * 32);
;       bf16x8 a1 = *(const bf16x8*)(Ab + 32 * LSTR + st * 32);
;       bf16x8 b0 = *(const bf16x8*)(Bb + st * 32);
;       bf16x8 b1 = *(const bf16x8*)(Bb + 32 * LSTR + st * 32);
;       bf16x8 b2 = *(const bf16x8*)(Bb + 64 * LSTR + st * 32);
;       bf16x8 b3 = *(const bf16x8*)(Bb + 96 * LSTR + st * 32);
;       acc[0][0] = mfma32(a0, b0, acc[0][0]);
;       acc[0][1] = mfma32(a0, b1, acc[0][1]);
;       acc[0][2] = mfma32(a0, b2, acc[0][2]);
;       acc[0][3] = mfma32(a0, b3, acc[0][3]);
;       acc[1][0] = mfma32(a1, b0, acc[1][0]);
;       acc[1][1] = mfma32(a1, b1, acc[1][1]);
;       acc[1][2] = mfma32(a1, b2, acc[1][2]);
;       acc[1][3] = mfma32(a1, b3, acc[1][3]);
;     }
;     __builtin_amdgcn_s_setprio(0);
;     __builtin_amdgcn_sched_barrier(0);
;     __syncthreads();
;     GW_STORE()
;     __syncthreads();
	v_mfma_f32_32x32x16_bf16 v[114:129], v[206:209], v[218:221], v[114:129]
	ds_read_b128 v[210:213], v133 offset:96
	ds_read_b128 v[236:239], v156 offset:18528
	s_waitcnt lgkmcnt(5)
	v_mfma_f32_32x32x16_bf16 v[98:113], v[206:209], v[224:227], v[98:113]
	v_lshl_add_u64 v[202:203], v[146:147], 0, v[130:131]
	v_add_co_u32_e32 v202, vcc, s38, v202
	s_nop 1
	v_addc_co_u32_e32 v203, vcc, 0, v203, vcc
	global_load_dwordx4 v[202:205], v[202:203], off
	ds_read_b128 v[240:243], v156 offset:23136
	s_waitcnt lgkmcnt(5)
	v_mfma_f32_32x32x16_bf16 v[82:97], v[206:209], v[228:231], v[82:97]
	ds_read_b128 v[244:247], v156 offset:27744
	s_waitcnt lgkmcnt(5)
	v_mfma_f32_32x32x16_bf16 v[66:81], v[206:209], v[232:235], v[66:81]
	ds_read_b128 v[248:251], v156 offset:32352
	s_waitcnt lgkmcnt(5)
	v_mfma_f32_32x32x16_bf16 v[50:65], v[214:217], v[218:221], v[50:65]
	v_mfma_f32_32x32x16_bf16 v[34:49], v[214:217], v[224:227], v[34:49]
	v_mfma_f32_32x32x16_bf16 v[18:33], v[214:217], v[228:231], v[18:33]
	v_mfma_f32_32x32x16_bf16 v[2:17], v[214:217], v[232:235], v[2:17]
	ds_read_b128 v[214:217], v133 offset:4704
	s_waitcnt lgkmcnt(4)
	v_mfma_f32_32x32x16_bf16 v[114:129], v[210:213], v[236:239], v[114:129]
	s_waitcnt lgkmcnt(3)
	v_mfma_f32_32x32x16_bf16 v[98:113], v[210:213], v[240:243], v[98:113]
	s_waitcnt lgkmcnt(2)
	v_mfma_f32_32x32x16_bf16 v[82:97], v[210:213], v[244:247], v[82:97]
	s_waitcnt lgkmcnt(1)
	v_mfma_f32_32x32x16_bf16 v[66:81], v[210:213], v[248:251], v[66:81]
	s_waitcnt lgkmcnt(0)
	v_mfma_f32_32x32x16_bf16 v[50:65], v[214:217], v[236:239], v[50:65]
	v_mfma_f32_32x32x16_bf16 v[34:49], v[214:217], v[240:243], v[34:49]
	v_mfma_f32_32x32x16_bf16 v[18:33], v[214:217], v[244:247], v[18:33]
	v_mfma_f32_32x32x16_bf16 v[2:17], v[214:217], v[248:251], v[2:17]
	s_setprio 0
	s_add_i32 s41, s41, -1
	v_lshl_add_u64 v[146:147], v[146:147], 0, s[8:9]
	v_lshl_add_u64 v[148:149], v[148:149], 0, s[10:11]
	v_lshl_add_u64 v[150:151], v[150:151], 0, s[10:11]
	v_lshl_add_u64 v[152:153], v[152:153], 0, s[10:11]
	s_cmp_lg_u32 s41, 0
	v_lshl_add_u64 v[154:155], v[154:155], 0, s[10:11]
	s_barrier
	s_waitcnt vmcnt(11)
	ds_write_b128 v132, v[158:161]
	v_lshl_add_u64 v[158:159], v[148:149], 0, v[130:131]
	global_load_dwordx4 v[158:161], v[158:159], off
	s_waitcnt vmcnt(11)
	ds_write_b128 v132, v[162:165] offset:4608
	v_lshl_add_u64 v[162:163], v[150:151], 0, v[130:131]
	global_load_dwordx4 v[162:165], v[162:163], off
	s_waitcnt vmcnt(11)
	ds_write_b128 v132, v[166:169] offset:9216
	v_lshl_add_u64 v[166:167], v[152:153], 0, v[130:131]
	global_load_dwordx4 v[166:169], v[166:167], off
	s_waitcnt vmcnt(11)
	ds_write_b128 v132, v[170:173] offset:13824
	s_waitcnt vmcnt(10)
	ds_write_b128 v132, v[174:177] offset:18432
	s_waitcnt vmcnt(9)
	ds_write_b128 v132, v[178:181] offset:23040
	s_waitcnt vmcnt(8)
	ds_write_b128 v132, v[182:185] offset:27648
	s_waitcnt vmcnt(7)
	ds_write_b128 v132, v[186:189] offset:32256
	s_waitcnt vmcnt(6)
	ds_write_b128 v132, v[190:193] offset:36864
	s_waitcnt vmcnt(5)
	ds_write_b128 v132, v[194:197] offset:41472
	s_waitcnt vmcnt(4)
	ds_write_b128 v132, v[198:201] offset:46080
	s_waitcnt vmcnt(3)
	ds_write_b128 v132, v[202:205] offset:50688
	s_waitcnt lgkmcnt(0)
	s_barrier
	s_cbranch_scc1 .LBB0_1035
	s_setprio 1
	ds_read_b128 v[206:209], v133 offset:0
	ds_read_b128 v[218:221], v156 offset:18432
	ds_read_b128 v[224:227], v156 offset:23040
	ds_read_b128 v[228:231], v156 offset:27648
	ds_read_b128 v[232:235], v156 offset:32256
	ds_read_b128 v[214:217], v133 offset:4608
	s_waitcnt lgkmcnt(4)
	v_mfma_f32_32x32x16_bf16 v[114:129], v[206:209], v[218:221], v[114:129]
	ds_read_b128 v[210:213], v133 offset:32
	ds_read_b128 v[236:239], v156 offset:18464
	s_waitcnt lgkmcnt(5)
	v_mfma_f32_32x32x16_bf16 v[98:113], v[206:209], v[224:227], v[98:113]
	v_lshl_add_u64 v[170:171], v[154:155], 0, v[130:131]
	global_load_dwordx4 v[170:173], v[170:171], off
	ds_read_b128 v[240:243], v156 offset:23072
	s_waitcnt lgkmcnt(5)
	v_mfma_f32_32x32x16_bf16 v[82:97], v[206:209], v[228:231], v[82:97]
	ds_read_b128 v[244:247], v156 offset:27680
	s_waitcnt lgkmcnt(5)
	v_mfma_f32_32x32x16_bf16 v[66:81], v[206:209], v[232:235], v[66:81]
	v_lshl_add_u64 v[174:175], v[146:147], 0, v[130:131]
	v_add_co_u32_e32 v174, vcc, s35, v174
	s_nop 1
	v_addc_co_u32_e32 v175, vcc, 0, v175, vcc
	global_load_dwordx4 v[174:177], v[174:175], off offset:-4096
	ds_read_b128 v[248:251], v156 offset:32288
	s_waitcnt lgkmcnt(5)
	v_mfma_f32_32x32x16_bf16 v[50:65], v[214:217], v[218:221], v[50:65]
	v_mfma_f32_32x32x16_bf16 v[34:49], v[214:217], v[224:227], v[34:49]
	v_lshl_add_u64 v[178:179], v[146:147], 0, v[130:131]
	v_add_co_u32_e32 v178, vcc, s35, v178
	s_nop 1
	v_addc_co_u32_e32 v179, vcc, 0, v179, vcc
	global_load_dwordx4 v[178:181], v[178:179], off
	v_mfma_f32_32x32x16_bf16 v[18:33], v[214:217], v[228:231], v[18:33]
	v_mfma_f32_32x32x16_bf16 v[2:17], v[214:217], v[232:235], v[2:17]
	v_lshl_add_u64 v[182:183], v[146:147], 0, v[130:131]
	v_add_co_u32_e32 v182, vcc, s36, v182
	s_nop 1
	v_addc_co_u32_e32 v183, vcc, 0, v183, vcc
	global_load_dwordx4 v[182:185], v[182:183], off offset:-4096
	ds_read_b128 v[214:217], v133 offset:4640
	s_waitcnt lgkmcnt(4)
	v_mfma_f32_32x32x16_bf16 v[114:129], v[210:213], v[236:239], v[114:129]
	ds_read_b128 v[206:209], v133 offset:64
	ds_read_b128 v[218:221], v156 offset:18496
	s_waitcnt lgkmcnt(5)
	v_mfma_f32_32x32x16_bf16 v[98:113], v[210:213], v[240:243], v[98:113]
	v_lshl_add_u64 v[186:187], v[146:147], 0, v[130:131]
	v_add_co_u32_e32 v186, vcc, s36, v186
	s_nop 1
	v_addc_co_u32_e32 v187, vcc, 0, v187, vcc
	global_load_dwordx4 v[186:189], v[186:187], off
	ds_read_b128 v[224:227], v156 offset:23104
	s_waitcnt lgkmcnt(5)
;     ...
;   for (int kt = 0; kt < nk; ++kt) {
;     const int kn = (kt + 1 < nk) ? kt + 1 : kt;
;     GW_LOAD2(kn * 64, kn * bkstep)
;     __builtin_amdgcn_sched_barrier(0);
;     __builtin_amdgcn_s_setprio(1);
; #pragma unroll
;     for (int st = 0; st < 4; ++st) {
;       bf16x8 a0 = *(const bf16x8*)(Ab + st * 32);
;       bf16x8 a1 = *(const bf16x8*)(Ab + 32 * LSTR + st * 32);
;       bf16x8 b0 = *(const bf16x8*)(Bb + st * 32);
;       bf16x8 b1 = *(const bf16x8*)(Bb + 32 * LSTR + st * 32);
;       bf16x8 b2 = *(const bf16x8*)(Bb + 64 * LSTR + st * 32);
;       bf16x8 b3 = *(const bf16x8*)(Bb + 96 * LSTR + st * 32);
;       acc[0][0] = mfma32(a0, b0, acc[0][0]);
;       acc[0][1] = mfma32(a0, b1, acc[0][1]);
;       acc[0][2] = mfma32(a0, b2, acc[0][2]);
;       acc[0][3] = mfma32(a0, b3, acc[0][3]);
;       acc[1][0] = mfma32(a1, b0, acc[1][0]);
;       acc[1][1] = mfma32(a1, b1, acc[1][1]);
;       acc[1][2] = mfma32(a1, b2, acc[1][2]);
;       acc[1][3] = mfma32(a1, b3, acc[1][3]);
;     }
;     __builtin_amdgcn_s_setprio(0);
;     __builtin_amdgcn_sched_barrier(0);
;     __syncthreads();
;     GW_STORE()
;     __syncthreads();
	v_mfma_f32_32x32x16_bf16 v[82:97], v[210:213], v[244:247], v[82:97]
	ds_read_b128 v[228:231], v156 offset:27712
	s_waitcnt lgkmcnt(5)
	v_mfma_f32_32x32x16_bf16 v[66:81], v[210:213], v[248:251], v[66:81]
	v_lshl_add_u64 v[190:191], v[146:147], 0, v[130:131]
	v_add_co_u32_e32 v190, vcc, s37, v190
	s_nop 1
	v_addc_co_u32_e32 v191, vcc, 0, v191, vcc
	global_load_dwordx4 v[190:193], v[190:191], off offset:-4096
	ds_read_b128 v[232:235], v156 offset:32320
	s_waitcnt lgkmcnt(5)
	v_mfma_f32_32x32x16_bf16 v[50:65], v[214:217], v[236:239], v[50:65]
	v_mfma_f32_32x32x16_bf16 v[34:49], v[214:217], v[240:243], v[34:49]
	v_lshl_add_u64 v[194:195], v[146:147], 0, v[130:131]
	v_add_co_u32_e32 v194, vcc, s37, v194
	s_nop 1
	v_addc_co_u32_e32 v195, vcc, 0, v195, vcc
	global_load_dwordx4 v[194:197], v[194:195], off
	v_mfma_f32_32x32x16_bf16 v[18:33], v[214:217], v[244:247], v[18:33]
	v_mfma_f32_32x32x16_bf16 v[2:17], v[214:217], v[248:251], v[2:17]
	v_lshl_add_u64 v[198:199], v[146:147], 0, v[130:131]
	v_add_co_u32_e32 v198, vcc, s38, v198
	s_nop 1
	v_addc_co_u32_e32 v199, vcc, 0, v199, vcc
	global_load_dwordx4 v[198:201], v[198:199], off offset:-4096
	ds_read_b128 v[214:217], v133 offset:4672
	s_waitcnt lgkmcnt(4)
	v_mfma_f32_32x32x16_bf16 v[114:129], v[206:209], v[218:221], v[114:129]
	ds_read_b128 v[210:213], v133 offset:96
	ds_read_b128 v[236:239], v156 offset:18528
	s_waitcnt lgkmcnt(5)
	v_mfma_f32_32x32x16_bf16 v[98:113], v[206:209], v[224:227], v[98:113]
	v_lshl_add_u64 v[202:203], v[146:147], 0, v[130:131]
	v_add_co_u32_e32 v202, vcc, s38, v202
	s_nop 1
	v_addc_co_u32_e32 v203, vcc, 0, v203, vcc
	global_load_dwordx4 v[202:205], v[202:203], off
	ds_read_b128 v[240:243], v156 offset:23136
	s_waitcnt lgkmcnt(5)
	v_mfma_f32_32x32x16_bf16 v[82:97], v[206:209], v[228:231], v[82:97]
	ds_read_b128 v[244:247], v156 offset:27744
	s_waitcnt lgkmcnt(5)
	v_mfma_f32_32x32x16_bf16 v[66:81], v[206:209], v[232:235], v[66:81]
	ds_read_b128 v[248:251], v156 offset:32352
	s_waitcnt lgkmcnt(5)
	v_mfma_f32_32x32x16_bf16 v[50:65], v[214:217], v[218:221], v[50:65]
	v_mfma_f32_32x32x16_bf16 v[34:49], v[214:217], v[224:227], v[34:49]
	v_mfma_f32_32x32x16_bf16 v[18:33], v[214:217], v[228:231], v[18:33]
	v_mfma_f32_32x32x16_bf16 v[2:17], v[214:217], v[232:235], v[2:17]
	ds_read_b128 v[214:217], v133 offset:4704
	s_waitcnt lgkmcnt(4)
	v_mfma_f32_32x32x16_bf16 v[114:129], v[210:213], v[236:239], v[114:129]
	s_waitcnt lgkmcnt(3)
	v_mfma_f32_32x32x16_bf16 v[98:113], v[210:213], v[240:243], v[98:113]
	s_waitcnt lgkmcnt(2)
	v_mfma_f32_32x32x16_bf16 v[82:97], v[210:213], v[244:247], v[82:97]
	s_waitcnt lgkmcnt(1)
	v_mfma_f32_32x32x16_bf16 v[66:81], v[210:213], v[248:251], v[66:81]
	s_waitcnt lgkmcnt(0)
	v_mfma_f32_32x32x16_bf16 v[50:65], v[214:217], v[236:239], v[50:65]
	v_mfma_f32_32x32x16_bf16 v[34:49], v[214:217], v[240:243], v[34:49]
	v_mfma_f32_32x32x16_bf16 v[18:33], v[214:217], v[244:247], v[18:33]
	v_mfma_f32_32x32x16_bf16 v[2:17], v[214:217], v[248:251], v[2:17]
	s_setprio 0
	v_lshl_add_u64 v[146:147], v[146:147], 0, s[8:9]
	v_lshl_add_u64 v[148:149], v[148:149], 0, s[10:11]
	v_lshl_add_u64 v[150:151], v[150:151], 0, s[10:11]
	v_lshl_add_u64 v[152:153], v[152:153], 0, s[10:11]
	v_lshl_add_u64 v[154:155], v[154:155], 0, s[10:11]
	s_barrier
	s_waitcnt vmcnt(11)
	ds_write_b128 v132, v[158:161]
	s_waitcnt vmcnt(10)
	ds_write_b128 v132, v[162:165] offset:4608
	s_waitcnt vmcnt(9)
	ds_write_b128 v132, v[166:169] offset:9216
	s_waitcnt vmcnt(8)
	ds_write_b128 v132, v[170:173] offset:13824
	s_waitcnt vmcnt(7)
	ds_write_b128 v132, v[174:177] offset:18432
	s_waitcnt vmcnt(6)
	ds_write_b128 v132, v[178:181] offset:23040
	s_waitcnt vmcnt(5)
	ds_write_b128 v132, v[182:185] offset:27648
	s_waitcnt vmcnt(4)
	ds_write_b128 v132, v[186:189] offset:32256
	s_waitcnt vmcnt(3)
	ds_write_b128 v132, v[190:193] offset:36864
	s_waitcnt vmcnt(2)
	ds_write_b128 v132, v[194:197] offset:41472
	s_waitcnt vmcnt(1)
	ds_write_b128 v132, v[198:201] offset:46080
	s_waitcnt vmcnt(0)
	ds_write_b128 v132, v[202:205] offset:50688
	s_waitcnt lgkmcnt(0)
	s_barrier
;     ...
;     for (int st = 0; st < 4; ++st) {
;       bf16x8 a0 = *(const bf16x8*)(Ab + st * 32);
;       bf16x8 a1 = *(const bf16x8*)(Ab + 32 * LSTR + st * 32);
;       bf16x8 b0 = *(const bf16x8*)(Bb + st * 32);
;       bf16x8 b1 = *(const bf16x8*)(Bb + 32 * LSTR + st * 32);
;       bf16x8 b2 = *(const bf16x8*)(Bb + 64 * LSTR + st * 32);
;       bf16x8 b3 = *(const bf16x8*)(Bb + 96 * LSTR + st * 32);
;       acc[0][0] = mfma32(a0, b0, acc[0][0]);
;       acc[0][1] = mfma32(a0, b1, acc[0][1]);
;       acc[0][2] = mfma32(a0, b2, acc[0][2]);
;       acc[0][3] = mfma32(a0, b3, acc[0][3]);
;       acc[1][0] = mfma32(a1, b0, acc[1][0]);
;       acc[1][1] = mfma32(a1, b1, acc[1][1]);
;       acc[1][2] = mfma32(a1, b2, acc[1][2]);
;       acc[1][3] = mfma32(a1, b3, acc[1][3]);
;     }
;     __builtin_amdgcn_s_setprio(0);
; __device__ __forceinline__ void expert1_tile(const Params& P, int e, int mt, int ntw, char* smem) {
;     ...
;   float* cs = (float*)smem;
;   int tid_ = threadIdx.x;
;   asm volatile("" : "+v"(tid_));
;   const int lane = tid_ & 63, wave = tid_ >> 6;
;   const int r = 32 * wave + (lane & 31), part = lane >> 5;
; #pragma unroll 1
;   for (int h = 0; h < 2; ++h) {
;     wide_acc_to_lds(acc, cs, h);
;     u16* dst = WSP(u16, OFF_HID) + ((size_t)e * EROWS + mt * 128 + r) * 2048 + (ntw * 2 + h) * 64 + part * 32;
	v_add_co_u32_e32 v154, vcc, 0x780000, v136
	s_nop 0
	s_nop 0
	s_nop 0
	v_addc_co_u32_e32 v155, vcc, 0, v137, vcc
	v_add_co_u32_e32 v162, vcc, 0x781000, v136
	s_mov_b32 s18, 0
	s_nop 0
	v_addc_co_u32_e32 v163, vcc, 0, v137, vcc
	s_nop 0
	v_add_co_u32_e32 v154, vcc, 0x782000, v136
	s_nop 1
	v_addc_co_u32_e32 v155, vcc, 0, v137, vcc
	v_add_co_u32_e32 v170, vcc, 0x783000, v136
	s_nop 1
	v_addc_co_u32_e32 v171, vcc, 0, v137, vcc
	s_nop 0
	v_add_co_u32_e32 v154, vcc, 0x784000, v136
	s_nop 1
	v_addc_co_u32_e32 v155, vcc, 0, v137, vcc
	v_add_co_u32_e32 v178, vcc, 0x785000, v136
	s_nop 1
	v_addc_co_u32_e32 v179, vcc, 0, v137, vcc
	s_nop 0
	v_add_co_u32_e32 v154, vcc, 0x786000, v136
	s_nop 1
	v_addc_co_u32_e32 v155, vcc, 0, v137, vcc
	v_add_co_u32_e32 v136, vcc, 0x787000, v136
	s_nop 1
	v_addc_co_u32_e32 v137, vcc, 0, v137, vcc
	s_setprio 1
	ds_read_b128 v[190:193], v133 offset:0
	ds_read_b128 v[202:205], v156 offset:18432
	ds_read_b128 v[206:209], v156 offset:23040
	ds_read_b128 v[210:213], v156 offset:27648
	ds_read_b128 v[214:217], v156 offset:32256
	ds_read_b128 v[198:201], v133 offset:4608
	s_waitcnt lgkmcnt(4)
	v_mfma_f32_32x32x16_bf16 v[114:129], v[190:193], v[202:205], v[114:129]
	ds_read_b128 v[194:197], v133 offset:32
	ds_read_b128 v[218:221], v156 offset:18464
	s_waitcnt lgkmcnt(5)
	v_mfma_f32_32x32x16_bf16 v[98:113], v[190:193], v[206:209], v[98:113]
	ds_read_b128 v[224:227], v156 offset:23072
	s_waitcnt lgkmcnt(5)
	v_mfma_f32_32x32x16_bf16 v[82:97], v[190:193], v[210:213], v[82:97]
	ds_read_b128 v[228:231], v156 offset:27680
	s_waitcnt lgkmcnt(5)
	v_mfma_f32_32x32x16_bf16 v[66:81], v[190:193], v[214:217], v[66:81]
	ds_read_b128 v[232:235], v156 offset:32288
	s_waitcnt lgkmcnt(5)
	v_mfma_f32_32x32x16_bf16 v[50:65], v[198:201], v[202:205], v[50:65]
	v_mfma_f32_32x32x16_bf16 v[34:49], v[198:201], v[206:209], v[34:49]
	v_mfma_f32_32x32x16_bf16 v[18:33], v[198:201], v[210:213], v[18:33]
	v_mfma_f32_32x32x16_bf16 v[2:17], v[198:201], v[214:217], v[2:17]
	ds_read_b128 v[198:201], v133 offset:4640
	s_waitcnt lgkmcnt(4)
	v_mfma_f32_32x32x16_bf16 v[114:129], v[194:197], v[218:221], v[114:129]
	ds_read_b128 v[190:193], v133 offset:64
	ds_read_b128 v[202:205], v156 offset:18496
	s_waitcnt lgkmcnt(5)
	v_mfma_f32_32x32x16_bf16 v[98:113], v[194:197], v[224:227], v[98:113]
	ds_read_b128 v[206:209], v156 offset:23104
	s_waitcnt lgkmcnt(5)
	v_mfma_f32_32x32x16_bf16 v[82:97], v[194:197], v[228:231], v[82:97]
	ds_read_b128 v[210:213], v156 offset:27712
	s_waitcnt lgkmcnt(5)
	v_mfma_f32_32x32x16_bf16 v[66:81], v[194:197], v[232:235], v[66:81]
	ds_read_b128 v[214:217], v156 offset:32320
	s_waitcnt lgkmcnt(5)
	v_mfma_f32_32x32x16_bf16 v[50:65], v[198:201], v[218:221], v[50:65]
	v_mfma_f32_32x32x16_bf16 v[34:49], v[198:201], v[224:227], v[34:49]
	v_mfma_f32_32x32x16_bf16 v[18:33], v[198:201], v[228:231], v[18:33]
	v_mfma_f32_32x32x16_bf16 v[2:17], v[198:201], v[232:235], v[2:17]
	ds_read_b128 v[198:201], v133 offset:4672
	s_waitcnt lgkmcnt(4)
	v_mfma_f32_32x32x16_bf16 v[114:129], v[190:193], v[202:205], v[114:129]
	ds_read_b128 v[194:197], v133 offset:96
	ds_read_b128 v[218:221], v156 offset:18528
	s_waitcnt lgkmcnt(5)
	v_mfma_f32_32x32x16_bf16 v[98:113], v[190:193], v[206:209], v[98:113]
	ds_read_b128 v[224:227], v156 offset:23136
	s_waitcnt lgkmcnt(5)
	v_mfma_f32_32x32x16_bf16 v[82:97], v[190:193], v[210:213], v[82:97]
	ds_read_b128 v[228:231], v156 offset:27744
	s_waitcnt lgkmcnt(5)
	v_mfma_f32_32x32x16_bf16 v[66:81], v[190:193], v[214:217], v[66:81]
	ds_read_b128 v[232:235], v156 offset:32352
	s_waitcnt lgkmcnt(5)
	v_mfma_f32_32x32x16_bf16 v[50:65], v[198:201], v[202:205], v[50:65]
	v_mfma_f32_32x32x16_bf16 v[34:49], v[198:201], v[206:209], v[34:49]
	v_mfma_f32_32x32x16_bf16 v[18:33], v[198:201], v[210:213], v[18:33]
	v_mfma_f32_32x32x16_bf16 v[2:17], v[198:201], v[214:217], v[2:17]
	ds_read_b128 v[198:201], v133 offset:4704
	s_waitcnt lgkmcnt(4)
	v_mfma_f32_32x32x16_bf16 v[114:129], v[194:197], v[218:221], v[114:129]
	s_waitcnt lgkmcnt(3)
	v_mfma_f32_32x32x16_bf16 v[98:113], v[194:197], v[224:227], v[98:113]
	s_waitcnt lgkmcnt(2)
	v_mfma_f32_32x32x16_bf16 v[82:97], v[194:197], v[228:231], v[82:97]
	s_waitcnt lgkmcnt(1)
	v_mfma_f32_32x32x16_bf16 v[66:81], v[194:197], v[232:235], v[66:81]
	s_waitcnt lgkmcnt(0)
	v_mfma_f32_32x32x16_bf16 v[50:65], v[198:201], v[218:221], v[50:65]
	v_mfma_f32_32x32x16_bf16 v[34:49], v[198:201], v[224:227], v[34:49]
	v_mfma_f32_32x32x16_bf16 v[18:33], v[198:201], v[228:231], v[18:33]
	v_mfma_f32_32x32x16_bf16 v[2:17], v[198:201], v[232:235], v[2:17]
	s_setprio 0
	v_mov_b32_e32 v130, v134
	s_barrier
	s_waitcnt lgkmcnt(0)
	s_mul_hi_i32 s13, s14, 0x1100
	v_ashrrev_i32_e32 v132, 1, v130
	s_mulk_i32 s14, 0x1100
	v_bfi_b32 v132, s39, v132, v130
	s_add_u32 s14, s14, s16
	s_addc_u32 s15, s13, s17
	v_ashrrev_i32_e32 v133, 31, v132
	v_lshl_add_u64 v[136:137], s[14:15], 0, v[132:133]
	v_and_b32_e32 v130, 32, v130
	v_lshlrev_b64 v[136:137], 12, v[136:137]
	v_mul_lo_u32 v132, v132, s22
	v_lshl_add_u32 v138, v130, 2, v132
	v_lshl_add_u64 v[132:133], s[4:5], 0, v[136:137]
	v_lshlrev_b32_e32 v130, 1, v130
	s_lshl_b32 s16, s12, 7
	v_lshl_add_u64 v[132:133], v[132:133], 0, v[130:131]
	s_mov_b64 s[12:13], -1
	s_branch .LBB0_1038

; #define GW_LOAD(KOFF) GW_LOAD2(KOFF, 0)
;   int tid = threadIdx.x;
;   asm volatile("" : "+v"(tid));
;   const int lane = tid & 63, wave = tid >> 6;
;   const int wm = wave >> 1, wn = wave & 1;
;   const int lr = tid >> 3, kc = tid & 7;
;   const u16* ap0 = arow(lr) + kc * 8;
;   const u16* ap1 = arow(lr + 32) + kc * 8;
;   const u16* ap2 = arow(lr + 64) + kc * 8;
;   const u16* ap3 = arow(lr + 96) + kc * 8;
;   const u16* bp0 = Bt + (size_t)lr * ldb + kc * 8;
;   const size_t bstep = 32 * ldb;
;   const int so = lr * LSTR + kc * 16;
;   uint4 ra0, ra1, ra2, ra3, rb0, rb1, rb2, rb3, rb4, rb5, rb6, rb7;
;     ...
;   GW_LOAD(0)
;   GW_STORE()
;   __syncthreads();
; __device__ __forceinline__ void expert2_tile(const Params& P, int e, int mt, int ntw, char* smem) {
;   f32x16 acc[2][4];
; #pragma unroll
;   for (int i = 0; i < 2; ++i)
; #pragma unroll
;     for (int j = 0; j < 4; ++j)
; #pragma unroll
;       for (int r = 0; r < 16; ++r) acc[i][j][r] = 0.f;
;   const u16* A = WSP(u16, OFF_HID) + ((size_t)e * EROWS + mt * 128) * 2048;
;   const u16* Bt = WSP(u16, OFF_WDN) + (size_t)e * DM * 2048 + (size_t)ntw * 256 * 64;
;   gemm_wide([&](int rr) { return A + (size_t)rr * 2048; }, Bt, 64, 2048, smem, acc, 1024 * 64);
.LBB0_1112:
	s_lshl_b32 s12, s45, 6
	s_and_b32 s12, s12, 0x1c0
	s_and_b32 s13, s45, 0xfffffe00
	s_or_b32 s12, s12, s13
	s_bfe_u32 s13, s45, 0x60003
	s_or_b32 s14, s12, s13
	s_and_b64 s[12:13], s[0:1], exec
	s_cselect_b32 s12, s14, s45
	s_ashr_i32 s13, s12, 31
	s_lshr_b32 s13, s13, 27
	s_add_i32 s13, s12, s13
	s_ashr_i32 s52, s13, 5
	s_lshl_b32 s15, s52, 3
	s_and_b32 s14, s13, 0xffffffe0
	s_sub_i32 s14, s12, s14
	s_and_b32 s53, s12, 7
	s_and_b32 s12, s15, 24
	s_ashr_i32 s16, s13, 7
	s_or_b32 s12, s12, s53
	s_ashr_i32 s14, s14, 3
	s_ashr_i32 s17, s16, 31
	s_mul_i32 s15, s16, 0x1100
	s_lshl_b32 s12, s12, 7
	s_mul_hi_i32 s13, s16, 0x1100
	s_add_u32 s12, s15, s12
	s_addc_u32 s13, s13, 0
	s_lshl_b64 s[18:19], s[12:13], 12
	s_add_u32 s46, s21, s18
	s_addc_u32 s47, s22, s19
	s_lshl_b64 s[18:19], s[16:17], 22
	s_add_u32 s17, s23, s18
	v_mov_b32_e32 v56, v134
	s_addc_u32 s51, s24, s19
	s_ashr_i32 s15, s14, 31
	s_lshl_b64 s[48:49], s[14:15], 15
	v_ashrrev_i32_e32 v50, 3, v56
	v_ashrrev_i32_e32 v51, 31, v50
	s_add_u32 s50, s17, s48
	v_lshlrev_b64 v[52:53], 12, v[50:51]
	v_lshlrev_b32_e32 v4, 4, v56
	s_addc_u32 s51, s51, s49
	v_lshl_add_u64 v[2:3], s[46:47], 0, v[52:53]
	v_and_b32_e32 v130, 0x70, v4
	v_lshlrev_b64 v[54:55], 7, v[50:51]
	v_lshl_add_u64 v[138:139], v[2:3], 0, v[130:131]
	v_lshl_add_u64 v[2:3], s[50:51], 0, v[54:55]
	v_lshl_add_u64 v[136:137], v[2:3], 0, v[130:131]
	v_add_co_u32_e32 v2, vcc, s27, v138
	s_add_u32 s15, s18, s48
	s_nop 0
	v_addc_co_u32_e32 v3, vcc, 0, v139, vcc
	v_add_co_u32_e32 v6, vcc, s28, v138
	s_addc_u32 s17, s19, s49
	s_nop 0
	v_addc_co_u32_e32 v7, vcc, 0, v139, vcc
	v_add_co_u32_e32 v10, vcc, s29, v138
	global_load_dwordx4 v[2:5], v[2:3], off
	s_nop 0
	global_load_dwordx4 v[6:9], v[6:7], off
	v_addc_co_u32_e32 v11, vcc, 0, v139, vcc
	v_add_co_u32_e32 v26, vcc, s30, v136
	global_load_dwordx4 v[10:13], v[10:11], off
	s_nop 0
	global_load_dwordx4 v[14:17], v[138:139], off
	global_load_dwordx4 v[18:21], v[136:137], off
	v_addc_co_u32_e32 v27, vcc, 0, v137, vcc
	v_add_co_u32_e32 v34, vcc, s31, v136
	global_load_dwordx4 v[22:25], v[26:27], off offset:-4096
	s_nop 0
	global_load_dwordx4 v[26:29], v[26:27], off
	v_addc_co_u32_e32 v35, vcc, 0, v137, vcc
	v_add_co_u32_e32 v42, vcc, s33, v136
	global_load_dwordx4 v[30:33], v[34:35], off offset:-4096
	s_nop 0
	global_load_dwordx4 v[34:37], v[34:35], off
	v_addc_co_u32_e32 v43, vcc, 0, v137, vcc
	global_load_dwordx4 v[38:41], v[42:43], off offset:-4096
	s_nop 0
	global_load_dwordx4 v[42:45], v[42:43], off
	v_add_co_u32_e32 v46, vcc, s34, v136
	s_add_u32 s18, s90, s15
	s_nop 0
	v_addc_co_u32_e32 v47, vcc, 0, v137, vcc
	global_load_dwordx4 v[46:49], v[46:47], off
	s_addc_u32 s19, s91, s17
	s_lshl_b32 s17, s52, 22
	v_lshl_add_u64 v[146:147], s[18:19], 0, v[54:55]
	s_and_b32 s17, s17, 0xc00000
	s_lshl_b32 s18, s53, 19
	s_or_b32 s17, s17, s18
	v_mad_u64_u32 v[132:133], s[46:47], v50, s26, v[130:131]
	s_add_u32 s17, s90, s17
	s_mul_hi_i32 s15, s16, 0x1100000
	s_mul_i32 s16, s16, 0x1100000
	s_addc_u32 s18, s91, 0
	s_add_u32 s16, s17, s16
	s_addc_u32 s17, s18, s15
	v_lshl_add_u64 v[140:141], v[138:139], 0, s[4:5]
	v_lshl_add_u64 v[142:143], v[138:139], 0, s[6:7]
	v_lshl_add_u64 v[144:145], v[138:139], 0, s[8:9]
	v_lshl_add_u64 v[148:149], s[16:17], 0, v[52:53]
	s_mov_b32 s15, 30
	v_mov_b32_e32 v50, v131
	v_mov_b32_e32 v51, v131
	v_mov_b32_e32 v52, v131
	v_mov_b32_e32 v53, v131
	v_mov_b32_e32 v54, v131
	v_mov_b32_e32 v55, v131
	v_mov_b32_e32 v57, v131
	v_mov_b32_e32 v58, v131
	v_mov_b32_e32 v59, v131
	v_mov_b32_e32 v60, v131
	v_mov_b32_e32 v61, v131
	v_mov_b32_e32 v62, v131
	v_mov_b32_e32 v63, v131
	s_waitcnt vmcnt(8)
	ds_write_b128 v132, v[14:17]
	ds_write_b128 v132, v[2:5] offset:4608
	ds_write_b128 v132, v[6:9] offset:9216
	ds_write_b128 v132, v[10:13] offset:13824
	s_waitcnt vmcnt(7)
	ds_write_b128 v132, v[18:21] offset:18432
	s_waitcnt vmcnt(6)
	ds_write_b128 v132, v[22:25] offset:23040
	s_waitcnt vmcnt(5)
	ds_write_b128 v132, v[26:29] offset:27648
	s_waitcnt vmcnt(4)
	ds_write_b128 v132, v[30:33] offset:32256
	s_waitcnt vmcnt(3)
	ds_write_b128 v132, v[34:37] offset:36864
	s_waitcnt vmcnt(2)
	ds_write_b128 v132, v[38:41] offset:41472
	s_waitcnt vmcnt(1)
	ds_write_b128 v132, v[42:45] offset:46080
	s_waitcnt vmcnt(0)
;     ...
;   for (int kt = 0; kt < nk; ++kt) {
;     const int kn = (kt + 1 < nk) ? kt + 1 : kt;
;     GW_LOAD2(kn * 64, kn * bkstep)
;     __builtin_amdgcn_sched_barrier(0);
;     __builtin_amdgcn_s_setprio(1);
; #pragma unroll
;     for (int st = 0; st < 4; ++st) {
;       bf16x8 a0 = *(const bf16x8*)(Ab + st * 32);
;       bf16x8 a1 = *(const bf16x8*)(Ab + 32 * LSTR + st * 32);
;       bf16x8 b0 = *(const bf16x8*)(Bb + st * 32);
;       bf16x8 b1 = *(const bf16x8*)(Bb + 32 * LSTR + st * 32);
;       bf16x8 b2 = *(const bf16x8*)(Bb + 64 * LSTR + st * 32);
;       bf16x8 b3 = *(const bf16x8*)(Bb + 96 * LSTR + st * 32);
;       acc[0][0] = mfma32(a0, b0, acc[0][0]);
;       acc[0][1] = mfma32(a0, b1, acc[0][1]);
;       acc[0][2] = mfma32(a0, b2, acc[0][2]);
;       acc[0][3] = mfma32(a0, b3, acc[0][3]);
;       acc[1][0] = mfma32(a1, b0, acc[1][0]);
;       acc[1][1] = mfma32(a1, b1, acc[1][1]);
;       acc[1][2] = mfma32(a1, b2, acc[1][2]);
;       acc[1][3] = mfma32(a1, b3, acc[1][3]);
;     }
;     __builtin_amdgcn_s_setprio(0);
	ds_write_b128 v132, v[46:49] offset:50688
	v_and_b32_e32 v2, 31, v56
	v_lshrrev_b32_e32 v3, 1, v56
	v_lshlrev_b32_e32 v5, 1, v56
	v_and_or_b32 v4, v3, s35, v2
	v_and_or_b32 v2, v5, s36, v2
	v_mul_lo_u32 v4, v4, s26
	v_and_b32_e32 v3, 16, v3
	v_mul_u32_u24_e32 v2, 0x90, v2
	v_add_u32_e32 v133, v4, v3
	v_add_u32_e32 v150, v2, v3
	v_mov_b32_e32 v2, v131
	v_mov_b32_e32 v3, v131
	v_mov_b32_e32 v4, v131
	v_mov_b32_e32 v5, v131
	v_mov_b32_e32 v6, v131
	v_mov_b32_e32 v7, v131
	v_mov_b32_e32 v8, v131
	v_mov_b32_e32 v9, v131
	v_mov_b32_e32 v10, v131
	v_mov_b32_e32 v11, v131
	v_mov_b32_e32 v12, v131
	v_mov_b32_e32 v13, v131
	v_mov_b32_e32 v14, v131
	v_mov_b32_e32 v15, v131
	v_mov_b32_e32 v16, v131
	v_mov_b32_e32 v17, v131
	v_mov_b32_e32 v18, v131
	v_mov_b32_e32 v19, v131
	v_mov_b32_e32 v20, v131
	v_mov_b32_e32 v21, v131
	v_mov_b32_e32 v22, v131
	v_mov_b32_e32 v23, v131
	v_mov_b32_e32 v24, v131
	v_mov_b32_e32 v25, v131
	v_mov_b32_e32 v26, v131
	v_mov_b32_e32 v27, v131
	v_mov_b32_e32 v28, v131
	v_mov_b32_e32 v29, v131
	v_mov_b32_e32 v30, v131
	v_mov_b32_e32 v31, v131
	v_mov_b32_e32 v32, v131
	v_mov_b32_e32 v33, v131
	v_mov_b32_e32 v34, v131
	v_mov_b32_e32 v35, v131
	v_mov_b32_e32 v36, v131
	v_mov_b32_e32 v37, v131
	v_mov_b32_e32 v38, v131
	v_mov_b32_e32 v39, v131
	v_mov_b32_e32 v40, v131
	v_mov_b32_e32 v41, v131
	v_mov_b32_e32 v42, v131
	v_mov_b32_e32 v43, v131
	v_mov_b32_e32 v44, v131
	v_mov_b32_e32 v45, v131
	v_mov_b32_e32 v46, v131
	v_mov_b32_e32 v47, v131
	v_mov_b32_e32 v48, v131
	v_mov_b32_e32 v49, v131
	v_mov_b32_e32 v56, v131
	v_mov_b32_e32 v64, v131
	v_mov_b32_e32 v65, v131
	v_mov_b32_e32 v66, v131
	v_mov_b32_e32 v67, v131
	v_mov_b32_e32 v68, v131
	v_mov_b32_e32 v69, v131
	v_mov_b32_e32 v70, v131
	v_mov_b32_e32 v71, v131
	v_mov_b32_e32 v72, v131
	v_mov_b32_e32 v73, v131
	v_mov_b32_e32 v74, v131
	v_mov_b32_e32 v75, v131
	v_mov_b32_e32 v76, v131
	v_mov_b32_e32 v77, v131
	v_mov_b32_e32 v78, v131
	v_mov_b32_e32 v79, v131
	v_mov_b32_e32 v80, v131
	v_mov_b32_e32 v81, v131
	v_mov_b32_e32 v82, v131
	v_mov_b32_e32 v83, v131
	v_mov_b32_e32 v84, v131
	v_mov_b32_e32 v85, v131
	v_mov_b32_e32 v86, v131
	v_mov_b32_e32 v87, v131
	v_mov_b32_e32 v88, v131
	v_mov_b32_e32 v89, v131
	v_mov_b32_e32 v90, v131
	v_mov_b32_e32 v91, v131
	v_mov_b32_e32 v92, v131
	v_mov_b32_e32 v93, v131
	v_mov_b32_e32 v94, v131
	v_mov_b32_e32 v95, v131
	v_mov_b32_e32 v96, v131
	v_mov_b32_e32 v97, v131
	v_mov_b32_e32 v98, v131
	v_mov_b32_e32 v99, v131
	v_mov_b32_e32 v100, v131
	v_mov_b32_e32 v101, v131
	v_mov_b32_e32 v102, v131
	v_mov_b32_e32 v103, v131
	v_mov_b32_e32 v104, v131
	v_mov_b32_e32 v105, v131
	v_mov_b32_e32 v106, v131
	v_mov_b32_e32 v107, v131
	v_mov_b32_e32 v108, v131
	v_mov_b32_e32 v109, v131
	v_mov_b32_e32 v110, v131
	v_mov_b32_e32 v111, v131
	v_mov_b32_e32 v112, v131
	v_mov_b32_e32 v113, v131
	v_mov_b32_e32 v114, v131
	v_mov_b32_e32 v115, v131
	v_mov_b32_e32 v116, v131
	v_mov_b32_e32 v117, v131
	v_mov_b32_e32 v118, v131
	v_mov_b32_e32 v119, v131
	v_mov_b32_e32 v120, v131
	v_mov_b32_e32 v121, v131
	v_mov_b32_e32 v122, v131
	v_mov_b32_e32 v123, v131
	v_mov_b32_e32 v124, v131
	v_mov_b32_e32 v125, v131
	v_mov_b32_e32 v126, v131
	v_mov_b32_e32 v127, v131
	v_mov_b32_e32 v128, v131
	v_mov_b32_e32 v129, v131
	s_waitcnt lgkmcnt(0)
	s_barrier
	v_lshl_add_u64 v[152:153], v[148:149], 0, v[130:131]
	v_add_co_u32_e32 v152, vcc, s37, v152
	s_nop 1
	v_addc_co_u32_e32 v153, vcc, 0, v153, vcc
	global_load_dwordx4 v[152:155], v[152:153], off offset:384
	v_lshl_add_u64 v[156:157], v[148:149], 0, v[130:131]
	v_add_co_u32_e32 v156, vcc, s38, v156
	s_nop 1
	v_addc_co_u32_e32 v157, vcc, 0, v157, vcc
	global_load_dwordx4 v[156:159], v[156:157], off offset:384
	v_lshl_add_u64 v[160:161], v[148:149], 0, v[130:131]
	v_add_co_u32_e32 v160, vcc, s39, v160
	s_nop 1
	v_addc_co_u32_e32 v161, vcc, 0, v161, vcc
	global_load_dwordx4 v[160:163], v[160:161], off offset:384
.LBB0_1113:
	s_setprio 1
	ds_read_b128 v[200:203], v133 offset:0
	ds_read_b128 v[212:215], v150 offset:18432
	ds_read_b128 v[216:219], v150 offset:23040
	ds_read_b128 v[224:227], v150 offset:27648
	ds_read_b128 v[228:231], v150 offset:32256
	ds_read_b128 v[208:211], v133 offset:4608
	s_waitcnt lgkmcnt(4)
	v_mfma_f32_32x32x16_bf16 v[114:129], v[200:203], v[212:215], v[114:129]
	ds_read_b128 v[204:207], v133 offset:32
	ds_read_b128 v[232:235], v150 offset:18464
	s_waitcnt lgkmcnt(5)
	v_mfma_f32_32x32x16_bf16 v[98:113], v[200:203], v[216:219], v[98:113]
	v_lshl_add_u64 v[164:165], v[148:149], 0, v[130:131]
	v_add_co_u32_e32 v164, vcc, s40, v164
	s_nop 1
	v_addc_co_u32_e32 v165, vcc, 0, v165, vcc
	global_load_dwordx4 v[164:167], v[164:165], off offset:384
	ds_read_b128 v[236:239], v150 offset:23072
	s_waitcnt lgkmcnt(5)
	v_mfma_f32_32x32x16_bf16 v[82:97], v[200:203], v[224:227], v[82:97]
	ds_read_b128 v[240:243], v150 offset:27680
	s_waitcnt lgkmcnt(5)
	v_mfma_f32_32x32x16_bf16 v[66:81], v[200:203], v[228:231], v[66:81]
	v_lshl_add_u64 v[168:169], v[146:147], 0, v[130:131]
	v_add_co_u32_e32 v168, vcc, s41, v168
	s_nop 1
	v_addc_co_u32_e32 v169, vcc, 0, v169, vcc
	global_load_dwordx4 v[168:171], v[168:169], off offset:-4096
	ds_read_b128 v[244:247], v150 offset:32288
	s_waitcnt lgkmcnt(5)
	v_mfma_f32_32x32x16_bf16 v[50:65], v[208:211], v[212:215], v[50:65]
	v_mfma_f32_32x32x16_bf16 v[34:49], v[208:211], v[216:219], v[34:49]
	v_lshl_add_u64 v[172:173], v[146:147], 0, v[130:131]
	v_add_co_u32_e32 v172, vcc, s41, v172
	s_nop 1
	v_addc_co_u32_e32 v173, vcc, 0, v173, vcc
	global_load_dwordx4 v[172:175], v[172:173], off
	v_mfma_f32_32x32x16_bf16 v[18:33], v[208:211], v[224:227], v[18:33]
	v_mfma_f32_32x32x16_bf16 v[2:17], v[208:211], v[228:231], v[2:17]
	v_lshl_add_u64 v[176:177], v[146:147], 0, v[130:131]
	v_add_co_u32_e32 v176, vcc, s42, v176
	s_nop 1
	v_addc_co_u32_e32 v177, vcc, 0, v177, vcc
	global_load_dwordx4 v[176:179], v[176:177], off offset:-4096
	ds_read_b128 v[208:211], v133 offset:4640
	s_waitcnt lgkmcnt(4)
;     ...
;   for (int kt = 0; kt < nk; ++kt) {
;     const int kn = (kt + 1 < nk) ? kt + 1 : kt;
;     GW_LOAD2(kn * 64, kn * bkstep)
;     __builtin_amdgcn_sched_barrier(0);
;     __builtin_amdgcn_s_setprio(1);
; #pragma unroll
;     for (int st = 0; st < 4; ++st) {
;       bf16x8 a0 = *(const bf16x8*)(Ab + st * 32);
;       bf16x8 a1 = *(const bf16x8*)(Ab + 32 * LSTR + st * 32);
;       bf16x8 b0 = *(const bf16x8*)(Bb + st * 32);
;       bf16x8 b1 = *(const bf16x8*)(Bb + 32 * LSTR + st * 32);
;       bf16x8 b2 = *(const bf16x8*)(Bb + 64 * LSTR + st * 32);
;       bf16x8 b3 = *(const bf16x8*)(Bb + 96 * LSTR + st * 32);
;       acc[0][0] = mfma32(a0, b0, acc[0][0]);
;       acc[0][1] = mfma32(a0, b1, acc[0][1]);
;       acc[0][2] = mfma32(a0, b2, acc[0][2]);
;       acc[0][3] = mfma32(a0, b3, acc[0][3]);
;       acc[1][0] = mfma32(a1, b0, acc[1][0]);
;       acc[1][1] = mfma32(a1, b1, acc[1][1]);
;       acc[1][2] = mfma32(a1, b2, acc[1][2]);
;       acc[1][3] = mfma32(a1, b3, acc[1][3]);
;     }
;     __builtin_amdgcn_s_setprio(0);
;     __builtin_amdgcn_sched_barrier(0);
;     __syncthreads();
;     GW_STORE()
;     __syncthreads();
	v_mfma_f32_32x32x16_bf16 v[114:129], v[204:207], v[232:235], v[114:129]
	ds_read_b128 v[200:203], v133 offset:64
	ds_read_b128 v[212:215], v150 offset:18496
	s_waitcnt lgkmcnt(5)
	v_mfma_f32_32x32x16_bf16 v[98:113], v[204:207], v[236:239], v[98:113]
	v_lshl_add_u64 v[180:181], v[146:147], 0, v[130:131]
	v_add_co_u32_e32 v180, vcc, s42, v180
	s_nop 1
	v_addc_co_u32_e32 v181, vcc, 0, v181, vcc
	global_load_dwordx4 v[180:183], v[180:181], off
	ds_read_b128 v[216:219], v150 offset:23104
	s_waitcnt lgkmcnt(5)
	v_mfma_f32_32x32x16_bf16 v[82:97], v[204:207], v[240:243], v[82:97]
	ds_read_b128 v[224:227], v150 offset:27712
	s_waitcnt lgkmcnt(5)
	v_mfma_f32_32x32x16_bf16 v[66:81], v[204:207], v[244:247], v[66:81]
	v_lshl_add_u64 v[184:185], v[146:147], 0, v[130:131]
	v_add_co_u32_e32 v184, vcc, s43, v184
	s_nop 1
	v_addc_co_u32_e32 v185, vcc, 0, v185, vcc
	global_load_dwordx4 v[184:187], v[184:185], off offset:-4096
	ds_read_b128 v[228:231], v150 offset:32320
	s_waitcnt lgkmcnt(5)
	v_mfma_f32_32x32x16_bf16 v[50:65], v[208:211], v[232:235], v[50:65]
	v_mfma_f32_32x32x16_bf16 v[34:49], v[208:211], v[236:239], v[34:49]
	v_lshl_add_u64 v[188:189], v[146:147], 0, v[130:131]
	v_add_co_u32_e32 v188, vcc, s43, v188
	s_nop 1
	v_addc_co_u32_e32 v189, vcc, 0, v189, vcc
	global_load_dwordx4 v[188:191], v[188:189], off
	v_mfma_f32_32x32x16_bf16 v[18:33], v[208:211], v[240:243], v[18:33]
	v_mfma_f32_32x32x16_bf16 v[2:17], v[208:211], v[244:247], v[2:17]
	v_lshl_add_u64 v[192:193], v[146:147], 0, v[130:131]
	v_add_co_u32_e32 v192, vcc, s44, v192
	s_nop 1
	v_addc_co_u32_e32 v193, vcc, 0, v193, vcc
	global_load_dwordx4 v[192:195], v[192:193], off offset:-4096
	ds_read_b128 v[208:211], v133 offset:4672
	s_waitcnt lgkmcnt(4)
	v_mfma_f32_32x32x16_bf16 v[114:129], v[200:203], v[212:215], v[114:129]
	ds_read_b128 v[204:207], v133 offset:96
	ds_read_b128 v[232:235], v150 offset:18528
	s_waitcnt lgkmcnt(5)
	v_mfma_f32_32x32x16_bf16 v[98:113], v[200:203], v[216:219], v[98:113]
	v_lshl_add_u64 v[196:197], v[146:147], 0, v[130:131]
	v_add_co_u32_e32 v196, vcc, s44, v196
	s_nop 1
	v_addc_co_u32_e32 v197, vcc, 0, v197, vcc
	global_load_dwordx4 v[196:199], v[196:197], off
	ds_read_b128 v[236:239], v150 offset:23136
	s_waitcnt lgkmcnt(5)
	v_mfma_f32_32x32x16_bf16 v[82:97], v[200:203], v[224:227], v[82:97]
	ds_read_b128 v[240:243], v150 offset:27744
	s_waitcnt lgkmcnt(5)
	v_mfma_f32_32x32x16_bf16 v[66:81], v[200:203], v[228:231], v[66:81]
	ds_read_b128 v[244:247], v150 offset:32352
	s_waitcnt lgkmcnt(5)
	v_mfma_f32_32x32x16_bf16 v[50:65], v[208:211], v[212:215], v[50:65]
	v_mfma_f32_32x32x16_bf16 v[34:49], v[208:211], v[216:219], v[34:49]
	v_mfma_f32_32x32x16_bf16 v[18:33], v[208:211], v[224:227], v[18:33]
	v_mfma_f32_32x32x16_bf16 v[2:17], v[208:211], v[228:231], v[2:17]
	ds_read_b128 v[208:211], v133 offset:4704
	s_waitcnt lgkmcnt(4)
	v_mfma_f32_32x32x16_bf16 v[114:129], v[204:207], v[232:235], v[114:129]
	s_waitcnt lgkmcnt(3)
	v_mfma_f32_32x32x16_bf16 v[98:113], v[204:207], v[236:239], v[98:113]
	s_waitcnt lgkmcnt(2)
	v_mfma_f32_32x32x16_bf16 v[82:97], v[204:207], v[240:243], v[82:97]
	s_waitcnt lgkmcnt(1)
	v_mfma_f32_32x32x16_bf16 v[66:81], v[204:207], v[244:247], v[66:81]
	s_waitcnt lgkmcnt(0)
	v_mfma_f32_32x32x16_bf16 v[50:65], v[208:211], v[232:235], v[50:65]
	v_mfma_f32_32x32x16_bf16 v[34:49], v[208:211], v[236:239], v[34:49]
	v_mfma_f32_32x32x16_bf16 v[18:33], v[208:211], v[240:243], v[18:33]
	v_mfma_f32_32x32x16_bf16 v[2:17], v[208:211], v[244:247], v[2:17]
	s_setprio 0
	s_add_i32 s15, s15, -1
	v_lshl_add_u64 v[146:147], v[146:147], 0, s[4:5]
	s_cmp_lg_u32 s15, 0
	v_lshl_add_u64 v[148:149], v[148:149], 0, s[10:11]
	s_barrier
	s_waitcnt vmcnt(11)
	ds_write_b128 v132, v[152:155]
	v_lshl_add_u64 v[152:153], v[148:149], 0, v[130:131]
	v_add_co_u32_e32 v152, vcc, s37, v152
	s_nop 1
	v_addc_co_u32_e32 v153, vcc, 0, v153, vcc
	global_load_dwordx4 v[152:155], v[152:153], off offset:384
	s_waitcnt vmcnt(11)
	ds_write_b128 v132, v[156:159] offset:4608
	v_lshl_add_u64 v[156:157], v[148:149], 0, v[130:131]
	v_add_co_u32_e32 v156, vcc, s38, v156
	s_nop 1
	v_addc_co_u32_e32 v157, vcc, 0, v157, vcc
	global_load_dwordx4 v[156:159], v[156:157], off offset:384
	s_waitcnt vmcnt(11)
	ds_write_b128 v132, v[160:163] offset:9216
	v_lshl_add_u64 v[160:161], v[148:149], 0, v[130:131]
	v_add_co_u32_e32 v160, vcc, s39, v160
	s_nop 1
	v_addc_co_u32_e32 v161, vcc, 0, v161, vcc
	global_load_dwordx4 v[160:163], v[160:161], off offset:384
	s_waitcnt vmcnt(11)
	ds_write_b128 v132, v[164:167] offset:13824
	s_waitcnt vmcnt(10)
	ds_write_b128 v132, v[168:171] offset:18432
	s_waitcnt vmcnt(9)
	ds_write_b128 v132, v[172:175] offset:23040
	s_waitcnt vmcnt(8)
	ds_write_b128 v132, v[176:179] offset:27648
	s_waitcnt vmcnt(7)
	ds_write_b128 v132, v[180:183] offset:32256
	s_waitcnt vmcnt(6)
	ds_write_b128 v132, v[184:187] offset:36864
	s_waitcnt vmcnt(5)
	ds_write_b128 v132, v[188:191] offset:41472
	s_waitcnt vmcnt(4)
	ds_write_b128 v132, v[192:195] offset:46080
	s_waitcnt vmcnt(3)
	ds_write_b128 v132, v[196:199] offset:50688
	s_waitcnt lgkmcnt(0)
	s_barrier
	s_cbranch_scc1 .LBB0_1113
;     ...
;   for (int kt = 0; kt < nk; ++kt) {
;     const int kn = (kt + 1 < nk) ? kt + 1 : kt;
;     GW_LOAD2(kn * 64, kn * bkstep)
;     __builtin_amdgcn_sched_barrier(0);
;     __builtin_amdgcn_s_setprio(1);
; #pragma unroll
;     for (int st = 0; st < 4; ++st) {
;       bf16x8 a0 = *(const bf16x8*)(Ab + st * 32);
;       bf16x8 a1 = *(const bf16x8*)(Ab + 32 * LSTR + st * 32);
;       bf16x8 b0 = *(const bf16x8*)(Bb + st * 32);
;       bf16x8 b1 = *(const bf16x8*)(Bb + 32 * LSTR + st * 32);
;       bf16x8 b2 = *(const bf16x8*)(Bb + 64 * LSTR + st * 32);
;       bf16x8 b3 = *(const bf16x8*)(Bb + 96 * LSTR + st * 32);
;       acc[0][0] = mfma32(a0, b0, acc[0][0]);
;       acc[0][1] = mfma32(a0, b1, acc[0][1]);
;       acc[0][2] = mfma32(a0, b2, acc[0][2]);
;       acc[0][3] = mfma32(a0, b3, acc[0][3]);
;       acc[1][0] = mfma32(a1, b0, acc[1][0]);
;       acc[1][1] = mfma32(a1, b1, acc[1][1]);
;       acc[1][2] = mfma32(a1, b2, acc[1][2]);
;       acc[1][3] = mfma32(a1, b3, acc[1][3]);
;     }
;     __builtin_amdgcn_s_setprio(0);
	s_setprio 1
	ds_read_b128 v[200:203], v133 offset:0
	ds_read_b128 v[212:215], v150 offset:18432
	ds_read_b128 v[216:219], v150 offset:23040
	ds_read_b128 v[224:227], v150 offset:27648
	ds_read_b128 v[228:231], v150 offset:32256
	ds_read_b128 v[208:211], v133 offset:4608
	s_waitcnt lgkmcnt(4)
	v_mfma_f32_32x32x16_bf16 v[114:129], v[200:203], v[212:215], v[114:129]
	ds_read_b128 v[204:207], v133 offset:32
	ds_read_b128 v[232:235], v150 offset:18464
	s_waitcnt lgkmcnt(5)
	v_mfma_f32_32x32x16_bf16 v[98:113], v[200:203], v[216:219], v[98:113]
	v_lshl_add_u64 v[164:165], v[148:149], 0, v[130:131]
	v_add_co_u32_e32 v164, vcc, s40, v164
	s_nop 1
	v_addc_co_u32_e32 v165, vcc, 0, v165, vcc
	global_load_dwordx4 v[164:167], v[164:165], off offset:384
	ds_read_b128 v[236:239], v150 offset:23072
	s_waitcnt lgkmcnt(5)
	v_mfma_f32_32x32x16_bf16 v[82:97], v[200:203], v[224:227], v[82:97]
	ds_read_b128 v[240:243], v150 offset:27680
	s_waitcnt lgkmcnt(5)
	v_mfma_f32_32x32x16_bf16 v[66:81], v[200:203], v[228:231], v[66:81]
	v_lshl_add_u64 v[168:169], v[146:147], 0, v[130:131]
	v_add_co_u32_e32 v168, vcc, s41, v168
	s_nop 1
	v_addc_co_u32_e32 v169, vcc, 0, v169, vcc
	global_load_dwordx4 v[168:171], v[168:169], off offset:-4096
	ds_read_b128 v[244:247], v150 offset:32288
	s_waitcnt lgkmcnt(5)
	v_mfma_f32_32x32x16_bf16 v[50:65], v[208:211], v[212:215], v[50:65]
	v_mfma_f32_32x32x16_bf16 v[34:49], v[208:211], v[216:219], v[34:49]
	v_lshl_add_u64 v[172:173], v[146:147], 0, v[130:131]
	v_add_co_u32_e32 v172, vcc, s41, v172
	s_nop 1
	v_addc_co_u32_e32 v173, vcc, 0, v173, vcc
	global_load_dwordx4 v[172:175], v[172:173], off
	v_mfma_f32_32x32x16_bf16 v[18:33], v[208:211], v[224:227], v[18:33]
	v_mfma_f32_32x32x16_bf16 v[2:17], v[208:211], v[228:231], v[2:17]
	v_lshl_add_u64 v[176:177], v[146:147], 0, v[130:131]
	v_add_co_u32_e32 v176, vcc, s42, v176
	s_nop 1
	v_addc_co_u32_e32 v177, vcc, 0, v177, vcc
	global_load_dwordx4 v[176:179], v[176:177], off offset:-4096
	ds_read_b128 v[208:211], v133 offset:4640
	s_waitcnt lgkmcnt(4)
	v_mfma_f32_32x32x16_bf16 v[114:129], v[204:207], v[232:235], v[114:129]
	ds_read_b128 v[200:203], v133 offset:64
	ds_read_b128 v[212:215], v150 offset:18496
	s_waitcnt lgkmcnt(5)
	v_mfma_f32_32x32x16_bf16 v[98:113], v[204:207], v[236:239], v[98:113]
	v_lshl_add_u64 v[180:181], v[146:147], 0, v[130:131]
	v_add_co_u32_e32 v180, vcc, s42, v180
	s_nop 1
	v_addc_co_u32_e32 v181, vcc, 0, v181, vcc
	global_load_dwordx4 v[180:183], v[180:181], off
	ds_read_b128 v[216:219], v150 offset:23104
	s_waitcnt lgkmcnt(5)
	v_mfma_f32_32x32x16_bf16 v[82:97], v[204:207], v[240:243], v[82:97]
	ds_read_b128 v[224:227], v150 offset:27712
	s_waitcnt lgkmcnt(5)
	v_mfma_f32_32x32x16_bf16 v[66:81], v[204:207], v[244:247], v[66:81]
	v_lshl_add_u64 v[184:185], v[146:147], 0, v[130:131]
	v_add_co_u32_e32 v184, vcc, s43, v184
	s_nop 1
	v_addc_co_u32_e32 v185, vcc, 0, v185, vcc
	global_load_dwordx4 v[184:187], v[184:185], off offset:-4096
	ds_read_b128 v[228:231], v150 offset:32320
	s_waitcnt lgkmcnt(5)
	v_mfma_f32_32x32x16_bf16 v[50:65], v[208:211], v[232:235], v[50:65]
	v_mfma_f32_32x32x16_bf16 v[34:49], v[208:211], v[236:239], v[34:49]
	v_lshl_add_u64 v[188:189], v[146:147], 0, v[130:131]
	v_add_co_u32_e32 v188, vcc, s43, v188
	s_nop 1
	v_addc_co_u32_e32 v189, vcc, 0, v189, vcc
	global_load_dwordx4 v[188:191], v[188:189], off
	v_mfma_f32_32x32x16_bf16 v[18:33], v[208:211], v[240:243], v[18:33]
	v_mfma_f32_32x32x16_bf16 v[2:17], v[208:211], v[244:247], v[2:17]
	v_lshl_add_u64 v[192:193], v[146:147], 0, v[130:131]
	v_add_co_u32_e32 v192, vcc, s44, v192
	s_nop 1
	v_addc_co_u32_e32 v193, vcc, 0, v193, vcc
	global_load_dwordx4 v[192:195], v[192:193], off offset:-4096
	ds_read_b128 v[208:211], v133 offset:4672
	s_waitcnt lgkmcnt(4)
	v_mfma_f32_32x32x16_bf16 v[114:129], v[200:203], v[212:215], v[114:129]
	ds_read_b128 v[204:207], v133 offset:96
	ds_read_b128 v[232:235], v150 offset:18528
	s_waitcnt lgkmcnt(5)
	v_mfma_f32_32x32x16_bf16 v[98:113], v[200:203], v[216:219], v[98:113]
	v_lshl_add_u64 v[196:197], v[146:147], 0, v[130:131]
	v_add_co_u32_e32 v196, vcc, s44, v196
	s_nop 1
	v_addc_co_u32_e32 v197, vcc, 0, v197, vcc
	global_load_dwordx4 v[196:199], v[196:197], off
	ds_read_b128 v[236:239], v150 offset:23136
	s_waitcnt lgkmcnt(5)
	v_mfma_f32_32x32x16_bf16 v[82:97], v[200:203], v[224:227], v[82:97]
	ds_read_b128 v[240:243], v150 offset:27744
	s_waitcnt lgkmcnt(5)
	v_mfma_f32_32x32x16_bf16 v[66:81], v[200:203], v[228:231], v[66:81]
	ds_read_b128 v[244:247], v150 offset:32352
	s_waitcnt lgkmcnt(5)
	v_mfma_f32_32x32x16_bf16 v[50:65], v[208:211], v[212:215], v[50:65]
	v_mfma_f32_32x32x16_bf16 v[34:49], v[208:211], v[216:219], v[34:49]
	v_mfma_f32_32x32x16_bf16 v[18:33], v[208:211], v[224:227], v[18:33]
	v_mfma_f32_32x32x16_bf16 v[2:17], v[208:211], v[228:231], v[2:17]
	ds_read_b128 v[208:211], v133 offset:4704
	s_waitcnt lgkmcnt(4)
	v_mfma_f32_32x32x16_bf16 v[114:129], v[204:207], v[232:235], v[114:129]
	s_waitcnt lgkmcnt(3)
	v_mfma_f32_32x32x16_bf16 v[98:113], v[204:207], v[236:239], v[98:113]
	s_waitcnt lgkmcnt(2)
	v_mfma_f32_32x32x16_bf16 v[82:97], v[204:207], v[240:243], v[82:97]
	s_waitcnt lgkmcnt(1)
	v_mfma_f32_32x32x16_bf16 v[66:81], v[204:207], v[244:247], v[66:81]
	s_waitcnt lgkmcnt(0)
	v_mfma_f32_32x32x16_bf16 v[50:65], v[208:211], v[232:235], v[50:65]
	v_mfma_f32_32x32x16_bf16 v[34:49], v[208:211], v[236:239], v[34:49]
	v_mfma_f32_32x32x16_bf16 v[18:33], v[208:211], v[240:243], v[18:33]
	v_mfma_f32_32x32x16_bf16 v[2:17], v[208:211], v[244:247], v[2:17]
	s_setprio 0
	v_lshl_add_u64 v[146:147], v[146:147], 0, s[4:5]
	v_lshl_add_u64 v[148:149], v[148:149], 0, s[10:11]
	s_barrier
; #define GW_LOAD(KOFF) GW_LOAD2(KOFF, 0)
;     ...
;   GW_LOAD(0)
;   GW_STORE()
;   __syncthreads();
;   const int nk = K >> 6;
;   const char* Ab = smem + (wm * 64 + (lane & 31)) * LSTR + (lane >> 5) * 16;
;   const char* Bb = smem + WTILE_A + (wn * 128 + (lane & 31)) * LSTR + (lane >> 5) * 16;
;   for (int kt = 0; kt < nk; ++kt) {
;     const int kn = (kt + 1 < nk) ? kt + 1 : kt;
;     GW_LOAD2(kn * 64, kn * bkstep)
;     __builtin_amdgcn_sched_barrier(0);
;     __builtin_amdgcn_s_setprio(1);
; #pragma unroll
;     for (int st = 0; st < 4; ++st) {
;       bf16x8 a0 = *(const bf16x8*)(Ab + st * 32);
;       bf16x8 a1 = *(const bf16x8*)(Ab + 32 * LSTR + st * 32);
;       bf16x8 b0 = *(const bf16x8*)(Bb + st * 32);
;       bf16x8 b1 = *(const bf16x8*)(Bb + 32 * LSTR + st * 32);
;       bf16x8 b2 = *(const bf16x8*)(Bb + 64 * LSTR + st * 32);
;       bf16x8 b3 = *(const bf16x8*)(Bb + 96 * LSTR + st * 32);
;       acc[0][0] = mfma32(a0, b0, acc[0][0]);
;       acc[0][1] = mfma32(a0, b1, acc[0][1]);
;       acc[0][2] = mfma32(a0, b2, acc[0][2]);
;       acc[0][3] = mfma32(a0, b3, acc[0][3]);
;       acc[1][0] = mfma32(a1, b0, acc[1][0]);
;       acc[1][1] = mfma32(a1, b1, acc[1][1]);
;       acc[1][2] = mfma32(a1, b2, acc[1][2]);
;       acc[1][3] = mfma32(a1, b3, acc[1][3]);
;     }
;     __builtin_amdgcn_s_setprio(0);
;     __builtin_amdgcn_sched_barrier(0);
;     __syncthreads();
;     GW_STORE()
;     __syncthreads();
	s_waitcnt vmcnt(11)
	ds_write_b128 v132, v[152:155]
	s_waitcnt vmcnt(10)
	ds_write_b128 v132, v[156:159] offset:4608
	s_waitcnt vmcnt(9)
	ds_write_b128 v132, v[160:163] offset:9216
	s_waitcnt vmcnt(8)
	ds_write_b128 v132, v[164:167] offset:13824
	s_waitcnt vmcnt(7)
	ds_write_b128 v132, v[168:171] offset:18432
	s_waitcnt vmcnt(6)
	ds_write_b128 v132, v[172:175] offset:23040
	s_waitcnt vmcnt(5)
	ds_write_b128 v132, v[176:179] offset:27648
	s_waitcnt vmcnt(4)
	ds_write_b128 v132, v[180:183] offset:32256
	s_waitcnt vmcnt(3)
	ds_write_b128 v132, v[184:187] offset:36864
	s_waitcnt vmcnt(2)
	ds_write_b128 v132, v[188:191] offset:41472
	s_waitcnt vmcnt(1)
	ds_write_b128 v132, v[192:195] offset:46080
	s_waitcnt vmcnt(0)
	ds_write_b128 v132, v[196:199] offset:50688
	s_waitcnt lgkmcnt(0)
	s_barrier
	v_add_co_u32_e32 v156, vcc, 0x3e0000, v136
	s_nop 0
	s_nop 0
	s_nop 0
	v_addc_co_u32_e32 v157, vcc, 0, v137, vcc
	v_add_co_u32_e32 v160, vcc, 0x3e1000, v136
	s_mov_b32 s18, 0
	s_nop 0
	v_addc_co_u32_e32 v161, vcc, 0, v137, vcc
	v_add_co_u32_e32 v164, vcc, 0x3e2000, v136
	s_nop 0
	v_addc_co_u32_e32 v165, vcc, 0, v137, vcc
	v_add_co_u32_e32 v168, vcc, 0x3e3000, v136
	s_nop 1
	v_addc_co_u32_e32 v169, vcc, 0, v137, vcc
	v_add_co_u32_e32 v172, vcc, 0x3e4000, v136
	s_nop 0
	v_addc_co_u32_e32 v173, vcc, 0, v137, vcc
	v_add_co_u32_e32 v176, vcc, 0x3e5000, v136
	s_nop 1
	v_addc_co_u32_e32 v177, vcc, 0, v137, vcc
	v_add_co_u32_e32 v180, vcc, 0x3e6000, v136
	s_nop 0
	v_addc_co_u32_e32 v181, vcc, 0, v137, vcc
	v_add_co_u32_e32 v136, vcc, 0x3e7000, v136
	s_nop 1
	v_addc_co_u32_e32 v137, vcc, 0, v137, vcc
	s_nop 0
	s_setprio 1
	ds_read_b128 v[188:191], v133 offset:0
	ds_read_b128 v[200:203], v150 offset:18432
	ds_read_b128 v[204:207], v150 offset:23040
	ds_read_b128 v[208:211], v150 offset:27648
	ds_read_b128 v[212:215], v150 offset:32256
	ds_read_b128 v[196:199], v133 offset:4608
	s_waitcnt lgkmcnt(4)
	v_mfma_f32_32x32x16_bf16 v[114:129], v[188:191], v[200:203], v[114:129]
	ds_read_b128 v[192:195], v133 offset:32
	ds_read_b128 v[216:219], v150 offset:18464
	s_waitcnt lgkmcnt(5)
	v_mfma_f32_32x32x16_bf16 v[98:113], v[188:191], v[204:207], v[98:113]
	ds_read_b128 v[224:227], v150 offset:23072
	s_waitcnt lgkmcnt(5)
	v_mfma_f32_32x32x16_bf16 v[82:97], v[188:191], v[208:211], v[82:97]
	ds_read_b128 v[228:231], v150 offset:27680
	s_waitcnt lgkmcnt(5)
	v_mfma_f32_32x32x16_bf16 v[66:81], v[188:191], v[212:215], v[66:81]
	ds_read_b128 v[232:235], v150 offset:32288
	s_waitcnt lgkmcnt(5)
	v_mfma_f32_32x32x16_bf16 v[50:65], v[196:199], v[200:203], v[50:65]
	v_mfma_f32_32x32x16_bf16 v[34:49], v[196:199], v[204:207], v[34:49]
	v_mfma_f32_32x32x16_bf16 v[18:33], v[196:199], v[208:211], v[18:33]
	v_mfma_f32_32x32x16_bf16 v[2:17], v[196:199], v[212:215], v[2:17]
	ds_read_b128 v[196:199], v133 offset:4640
	s_waitcnt lgkmcnt(4)
	v_mfma_f32_32x32x16_bf16 v[114:129], v[192:195], v[216:219], v[114:129]
	ds_read_b128 v[188:191], v133 offset:64
	ds_read_b128 v[200:203], v150 offset:18496
	s_waitcnt lgkmcnt(5)
	v_mfma_f32_32x32x16_bf16 v[98:113], v[192:195], v[224:227], v[98:113]
	ds_read_b128 v[204:207], v150 offset:23104
	s_waitcnt lgkmcnt(5)
	v_mfma_f32_32x32x16_bf16 v[82:97], v[192:195], v[228:231], v[82:97]
	ds_read_b128 v[208:211], v150 offset:27712
	s_waitcnt lgkmcnt(5)
	v_mfma_f32_32x32x16_bf16 v[66:81], v[192:195], v[232:235], v[66:81]
	ds_read_b128 v[212:215], v150 offset:32320
	s_waitcnt lgkmcnt(5)
	v_mfma_f32_32x32x16_bf16 v[50:65], v[196:199], v[216:219], v[50:65]
	v_mfma_f32_32x32x16_bf16 v[34:49], v[196:199], v[224:227], v[34:49]
	v_mfma_f32_32x32x16_bf16 v[18:33], v[196:199], v[228:231], v[18:33]
	v_mfma_f32_32x32x16_bf16 v[2:17], v[196:199], v[232:235], v[2:17]
	ds_read_b128 v[196:199], v133 offset:4672
	s_waitcnt lgkmcnt(4)
	v_mfma_f32_32x32x16_bf16 v[114:129], v[188:191], v[200:203], v[114:129]
	ds_read_b128 v[192:195], v133 offset:96
	ds_read_b128 v[216:219], v150 offset:18528
	s_waitcnt lgkmcnt(5)
	v_mfma_f32_32x32x16_bf16 v[98:113], v[188:191], v[204:207], v[98:113]
	ds_read_b128 v[224:227], v150 offset:23136
	s_waitcnt lgkmcnt(5)
	v_mfma_f32_32x32x16_bf16 v[82:97], v[188:191], v[208:211], v[82:97]
	ds_read_b128 v[228:231], v150 offset:27744
	s_waitcnt lgkmcnt(5)
	v_mfma_f32_32x32x16_bf16 v[66:81], v[188:191], v[212:215], v[66:81]
	ds_read_b128 v[232:235], v150 offset:32352
	s_waitcnt lgkmcnt(5)
	v_mfma_f32_32x32x16_bf16 v[50:65], v[196:199], v[200:203], v[50:65]
	v_mfma_f32_32x32x16_bf16 v[34:49], v[196:199], v[204:207], v[34:49]
	v_mfma_f32_32x32x16_bf16 v[18:33], v[196:199], v[208:211], v[18:33]
	v_mfma_f32_32x32x16_bf16 v[2:17], v[196:199], v[212:215], v[2:17]
	ds_read_b128 v[196:199], v133 offset:4704
	s_waitcnt lgkmcnt(4)
	v_mfma_f32_32x32x16_bf16 v[114:129], v[192:195], v[216:219], v[114:129]
	s_waitcnt lgkmcnt(3)
	v_mfma_f32_32x32x16_bf16 v[98:113], v[192:195], v[224:227], v[98:113]
	s_waitcnt lgkmcnt(2)
	v_mfma_f32_32x32x16_bf16 v[82:97], v[192:195], v[228:231], v[82:97]
	s_waitcnt lgkmcnt(1)
	v_mfma_f32_32x32x16_bf16 v[66:81], v[192:195], v[232:235], v[66:81]
	s_waitcnt lgkmcnt(0)
	v_mfma_f32_32x32x16_bf16 v[50:65], v[196:199], v[216:219], v[50:65]
	v_mfma_f32_32x32x16_bf16 v[34:49], v[196:199], v[224:227], v[34:49]
	v_mfma_f32_32x32x16_bf16 v[18:33], v[196:199], v[228:231], v[18:33]
	v_mfma_f32_32x32x16_bf16 v[2:17], v[196:199], v[232:235], v[2:17]
	s_setprio 0
	v_readlane_b32 s48, v253, 37
	v_readlane_b32 s49, v253, 38
	v_readlane_b32 s50, v253, 39
	v_readlane_b32 s51, v253, 40
	v_readlane_b32 s52, v253, 41
	v_readlane_b32 s53, v253, 42
	v_readlane_b32 s54, v253, 43
	v_readlane_b32 s55, v253, 44
	v_readlane_b32 s56, v253, 45
	v_readlane_b32 s57, v253, 46
	v_readlane_b32 s58, v253, 47
	v_readlane_b32 s59, v253, 48
	v_readlane_b32 s60, v253, 49
	v_readlane_b32 s61, v253, 50
	v_readlane_b32 s62, v253, 51
	v_readlane_b32 s63, v253, 52
	s_mov_b64 s[48:49], s[56:57]
	s_lshl_b32 s19, s14, 8
	s_mov_b64 s[14:15], -1
	s_mov_b64 s[50:51], s[58:59]
	s_mov_b64 s[52:53], s[60:61]
	s_mov_b64 s[54:55], s[62:63]
	s_barrier
	s_waitcnt lgkmcnt(0)
	s_branch .LBB0_1116

; #define GW_LOAD(KOFF) GW_LOAD2(KOFF, 0)
;   int tid = threadIdx.x;
;   asm volatile("" : "+v"(tid));
;   const int lane = tid & 63, wave = tid >> 6;
;   const int wm = wave >> 1, wn = wave & 1;
;   const int lr = tid >> 3, kc = tid & 7;
;   const u16* ap0 = arow(lr) + kc * 8;
;   const u16* ap1 = arow(lr + 32) + kc * 8;
;   const u16* ap2 = arow(lr + 64) + kc * 8;
;   const u16* ap3 = arow(lr + 96) + kc * 8;
;   const u16* bp0 = Bt + (size_t)lr * ldb + kc * 8;
;   const size_t bstep = 32 * ldb;
;   const int so = lr * LSTR + kc * 16;
;   uint4 ra0, ra1, ra2, ra3, rb0, rb1, rb2, rb3, rb4, rb5, rb6, rb7;
;     ...
;   GW_LOAD(0)
;   GW_STORE()
;   __syncthreads();
.LBB0_1283:
	s_ashr_i32 s11, s10, 31
	v_mov_b32_e32 v56, v134
	s_lshl_b64 s[8:9], s[10:11], 18
	s_add_u32 s18, s26, s8
	v_ashrrev_i32_e32 v50, 3, v56
	v_ashrrev_i32_e32 v51, 31, v50
	s_addc_u32 s19, s27, s9
	v_lshlrev_b64 v[52:53], 11, v[50:51]
	v_lshlrev_b32_e32 v4, 4, v56
	v_lshl_add_u64 v[2:3], s[18:19], 0, v[52:53]
	v_and_b32_e32 v138, 0x70, v4
	s_lshl_b32 s14, s16, 8
	v_lshl_add_u64 v[132:133], v[2:3], 0, v[138:139]
	s_mov_b32 s6, 0x10000
	s_ashr_i32 s15, s14, 31
	v_add_co_u32_e32 v6, vcc, s6, v132
	s_lshl_b64 s[12:13], s[14:15], 11
	s_nop 0
	v_addc_co_u32_e32 v7, vcc, 0, v133, vcc
	s_mov_b32 s6, 0x20000
	s_add_u32 s20, s90, s12
	v_add_co_u32_e32 v10, vcc, s6, v132
	s_addc_u32 s21, s91, s13
	s_nop 0
	v_addc_co_u32_e32 v11, vcc, 0, v133, vcc
	s_mov_b32 s6, 0x30000
	v_lshl_add_u64 v[2:3], s[20:21], 0, v[52:53]
	v_add_co_u32_e32 v14, vcc, s6, v132
	v_lshl_add_u64 v[54:55], v[2:3], 0, v[138:139]
	s_nop 0
	v_addc_co_u32_e32 v15, vcc, 0, v133, vcc
	v_add_co_u32_e32 v18, vcc, s35, v54
	global_load_dwordx4 v[2:5], v[132:133], off
	s_nop 0
	global_load_dwordx4 v[6:9], v[6:7], off
	v_addc_co_u32_e32 v19, vcc, 0, v55, vcc
	v_add_co_u32_e32 v22, vcc, s36, v54
	global_load_dwordx4 v[10:13], v[10:11], off
	s_nop 0
	global_load_dwordx4 v[14:17], v[14:15], off
	v_addc_co_u32_e32 v23, vcc, 0, v55, vcc
	v_add_co_u32_e32 v26, vcc, s37, v54
	global_load_dwordx4 v[18:21], v[18:19], off
	s_nop 0
	global_load_dwordx4 v[22:25], v[22:23], off
	v_addc_co_u32_e32 v27, vcc, 0, v55, vcc
	v_add_co_u32_e32 v30, vcc, s38, v54
	v_mad_u64_u32 v[130:131], s[18:19], v50, s34, v[138:139]
	s_nop 0
	v_addc_co_u32_e32 v31, vcc, 0, v55, vcc
	v_add_co_u32_e32 v34, vcc, s39, v54
	global_load_dwordx4 v[26:29], v[26:27], off
	s_nop 0
	global_load_dwordx4 v[30:33], v[30:31], off
	v_addc_co_u32_e32 v35, vcc, 0, v55, vcc
	v_add_co_u32_e32 v38, vcc, s40, v54
	s_mov_b32 s6, 0xfffffc0
	s_nop 0
	v_addc_co_u32_e32 v39, vcc, 0, v55, vcc
	v_add_co_u32_e32 v42, vcc, s41, v54
	global_load_dwordx4 v[34:37], v[34:35], off
	s_nop 0
	global_load_dwordx4 v[38:41], v[38:39], off
	v_addc_co_u32_e32 v43, vcc, 0, v55, vcc
	v_add_co_u32_e32 v46, vcc, s42, v54
	s_mov_b64 s[18:19], 0x10000
	s_nop 0
	v_addc_co_u32_e32 v47, vcc, 0, v55, vcc
	global_load_dwordx4 v[42:45], v[42:43], off
	s_nop 0
	global_load_dwordx4 v[46:49], v[46:47], off
	v_lshl_add_u64 v[144:145], v[132:133], 0, s[18:19]
	s_mov_b64 s[18:19], 0x20000
	v_lshl_add_u64 v[146:147], v[132:133], 0, s[18:19]
	s_mov_b64 s[18:19], 0x30000
	v_lshl_add_u64 v[148:149], v[132:133], 0, s[18:19]
	s_mov_b64 s[18:19], 0xb80000
	v_lshl_add_u64 v[142:143], v[54:55], 0, s[18:19]
	s_waitcnt vmcnt(11)
	ds_write_b128 v130, v[2:5]
	s_waitcnt vmcnt(10)
	ds_write_b128 v130, v[6:9] offset:4608
	s_waitcnt vmcnt(9)
	ds_write_b128 v130, v[10:13] offset:9216
	s_waitcnt vmcnt(8)
	ds_write_b128 v130, v[14:17] offset:13824
	s_waitcnt vmcnt(7)
	ds_write_b128 v130, v[18:21] offset:18432
	s_waitcnt vmcnt(6)
	ds_write_b128 v130, v[22:25] offset:23040
	s_waitcnt vmcnt(5)
	ds_write_b128 v130, v[26:29] offset:27648
	s_waitcnt vmcnt(4)
	ds_write_b128 v130, v[30:33] offset:32256
	s_waitcnt vmcnt(3)
	ds_write_b128 v130, v[34:37] offset:36864
	s_waitcnt vmcnt(2)
	ds_write_b128 v130, v[38:41] offset:41472
	s_waitcnt vmcnt(1)
	ds_write_b128 v130, v[42:45] offset:46080
	s_waitcnt vmcnt(0)
	ds_write_b128 v130, v[46:49] offset:50688
	v_and_b32_e32 v2, 31, v56
	v_lshrrev_b32_e32 v3, 1, v56
	v_and_or_b32 v4, v3, s6, v2
	v_and_b32_e32 v5, 16, v3
	v_lshlrev_b32_e32 v3, 1, v56
	s_movk_i32 s6, 0x80
	v_and_or_b32 v2, v3, s6, v2
	v_mul_u32_u24_e32 v6, 0x90, v2
	v_lshl_add_u64 v[2:3], s[8:9], 0, v[52:53]
	v_or_b32_e32 v2, v2, v138
	v_lshl_add_u64 v[150:151], s[90:91], 0, v[2:3]
	v_lshl_add_u64 v[2:3], v[52:53], 0, s[12:13]
	v_or_b32_e32 v2, v2, v138
	v_mul_lo_u32 v4, v4, s34
	v_lshl_add_u64 v[152:153], s[90:91], 0, v[2:3]
	v_mov_b32_e32 v2, 0
	s_mov_b64 s[8:9], 0
	v_add_u32_e32 v131, v4, v5
	v_add_u32_e32 v138, v6, v5
	v_mov_b32_e32 v3, v2
	v_mov_b32_e32 v4, v2
	v_mov_b32_e32 v5, v2
	v_mov_b32_e32 v6, v2
	v_mov_b32_e32 v7, v2
	v_mov_b32_e32 v8, v2
	v_mov_b32_e32 v9, v2
	v_mov_b32_e32 v10, v2
	v_mov_b32_e32 v11, v2
	v_mov_b32_e32 v12, v2
	v_mov_b32_e32 v13, v2
	v_mov_b32_e32 v14, v2
	v_mov_b32_e32 v15, v2
	v_mov_b32_e32 v16, v2
	v_mov_b32_e32 v17, v2
	v_mov_b32_e32 v18, v2
	v_mov_b32_e32 v19, v2
	v_mov_b32_e32 v20, v2
	v_mov_b32_e32 v21, v2
	v_mov_b32_e32 v22, v2
	v_mov_b32_e32 v23, v2
	v_mov_b32_e32 v24, v2
	v_mov_b32_e32 v25, v2
	v_mov_b32_e32 v26, v2
	v_mov_b32_e32 v27, v2
	v_mov_b32_e32 v28, v2
	v_mov_b32_e32 v29, v2
	v_mov_b32_e32 v30, v2
	v_mov_b32_e32 v31, v2
	v_mov_b32_e32 v32, v2
	v_mov_b32_e32 v33, v2
	v_mov_b32_e32 v34, v2
	v_mov_b32_e32 v35, v2
	v_mov_b32_e32 v36, v2
	v_mov_b32_e32 v37, v2
	v_mov_b32_e32 v38, v2
	v_mov_b32_e32 v39, v2
	v_mov_b32_e32 v40, v2
	v_mov_b32_e32 v41, v2
	v_mov_b32_e32 v42, v2
	v_mov_b32_e32 v43, v2
	v_mov_b32_e32 v44, v2
	v_mov_b32_e32 v45, v2
	v_mov_b32_e32 v46, v2
	v_mov_b32_e32 v47, v2
	v_mov_b32_e32 v48, v2
	v_mov_b32_e32 v49, v2
	v_mov_b32_e32 v50, v2
	v_mov_b32_e32 v51, v2
	v_mov_b32_e32 v52, v2
	v_mov_b32_e32 v53, v2
	v_mov_b32_e32 v54, v2
	v_mov_b32_e32 v55, v2
	v_mov_b32_e32 v56, v2
	v_mov_b32_e32 v57, v2
	v_mov_b32_e32 v58, v2
	v_mov_b32_e32 v59, v2
	v_mov_b32_e32 v60, v2
	v_mov_b32_e32 v61, v2
	v_mov_b32_e32 v62, v2
	v_mov_b32_e32 v63, v2
	v_mov_b32_e32 v64, v2
	v_mov_b32_e32 v65, v2
	v_mov_b32_e32 v66, v2
	v_mov_b32_e32 v67, v2
	v_mov_b32_e32 v68, v2
	v_mov_b32_e32 v69, v2
	v_mov_b32_e32 v70, v2
	v_mov_b32_e32 v71, v2
	v_mov_b32_e32 v72, v2
	v_mov_b32_e32 v73, v2
	v_mov_b32_e32 v74, v2
	v_mov_b32_e32 v75, v2
	v_mov_b32_e32 v76, v2
	v_mov_b32_e32 v77, v2
	v_mov_b32_e32 v78, v2
	v_mov_b32_e32 v79, v2
	v_mov_b32_e32 v80, v2
	v_mov_b32_e32 v81, v2
	v_mov_b32_e32 v82, v2
	v_mov_b32_e32 v83, v2
	v_mov_b32_e32 v84, v2
	v_mov_b32_e32 v85, v2
	v_mov_b32_e32 v86, v2
	v_mov_b32_e32 v87, v2
	v_mov_b32_e32 v88, v2
	v_mov_b32_e32 v89, v2
	v_mov_b32_e32 v90, v2
	v_mov_b32_e32 v91, v2
	v_mov_b32_e32 v92, v2
	v_mov_b32_e32 v93, v2
	v_mov_b32_e32 v94, v2
	v_mov_b32_e32 v95, v2
	v_mov_b32_e32 v96, v2
	v_mov_b32_e32 v97, v2
	v_mov_b32_e32 v98, v2
	v_mov_b32_e32 v99, v2
	v_mov_b32_e32 v100, v2
	v_mov_b32_e32 v101, v2
	v_mov_b32_e32 v102, v2
	v_mov_b32_e32 v103, v2
	v_mov_b32_e32 v104, v2
	v_mov_b32_e32 v105, v2
	v_mov_b32_e32 v106, v2
	v_mov_b32_e32 v107, v2
	v_mov_b32_e32 v108, v2
	v_mov_b32_e32 v109, v2
	v_mov_b32_e32 v110, v2
	v_mov_b32_e32 v111, v2
	v_mov_b32_e32 v112, v2
	v_mov_b32_e32 v113, v2
	v_mov_b32_e32 v114, v2
	v_mov_b32_e32 v115, v2
	v_mov_b32_e32 v116, v2
	v_mov_b32_e32 v117, v2
	v_mov_b32_e32 v118, v2
	v_mov_b32_e32 v119, v2
	v_mov_b32_e32 v120, v2
	v_mov_b32_e32 v121, v2
	v_mov_b32_e32 v122, v2
	v_mov_b32_e32 v123, v2
	v_mov_b32_e32 v124, v2
	v_mov_b32_e32 v125, v2
	v_mov_b32_e32 v126, v2
	v_mov_b32_e32 v127, v2
	v_mov_b32_e32 v128, v2
	v_mov_b32_e32 v129, v2
	s_waitcnt lgkmcnt(0)
	s_barrier
;     ...
;   for (int kt = 0; kt < nk; ++kt) {
;     const int kn = (kt + 1 < nk) ? kt + 1 : kt;
;     GW_LOAD2(kn * 64, kn * bkstep)
;     __builtin_amdgcn_sched_barrier(0);
;     __builtin_amdgcn_s_setprio(1);
; #pragma unroll
;     for (int st = 0; st < 4; ++st) {
;       bf16x8 a0 = *(const bf16x8*)(Ab + st * 32);
;       bf16x8 a1 = *(const bf16x8*)(Ab + 32 * LSTR + st * 32);
;       bf16x8 b0 = *(const bf16x8*)(Bb + st * 32);
;       bf16x8 b1 = *(const bf16x8*)(Bb + 32 * LSTR + st * 32);
;       bf16x8 b2 = *(const bf16x8*)(Bb + 64 * LSTR + st * 32);
;       bf16x8 b3 = *(const bf16x8*)(Bb + 96 * LSTR + st * 32);
;       acc[0][0] = mfma32(a0, b0, acc[0][0]);
;       acc[0][1] = mfma32(a0, b1, acc[0][1]);
;       acc[0][2] = mfma32(a0, b2, acc[0][2]);
;       acc[0][3] = mfma32(a0, b3, acc[0][3]);
;       acc[1][0] = mfma32(a1, b0, acc[1][0]);
;       acc[1][1] = mfma32(a1, b1, acc[1][1]);
;       acc[1][2] = mfma32(a1, b2, acc[1][2]);
;       acc[1][3] = mfma32(a1, b3, acc[1][3]);
;     }
	v_lshl_add_u64 v[154:155], v[150:151], 0, s[8:9]
	v_add_co_u32_e32 v154, vcc, s43, v154
	s_nop 1
	v_addc_co_u32_e32 v155, vcc, 0, v155, vcc
	global_load_dwordx4 v[154:157], v[154:155], off offset:384
	v_lshl_add_u64 v[158:159], v[150:151], 0, s[8:9]
	v_add_co_u32_e32 v158, vcc, s44, v158
	s_nop 1
	v_addc_co_u32_e32 v159, vcc, 0, v159, vcc
	global_load_dwordx4 v[158:161], v[158:159], off offset:384
	v_lshl_add_u64 v[162:163], v[150:151], 0, s[8:9]
	v_add_co_u32_e32 v162, vcc, s45, v162
	s_nop 1
	v_addc_co_u32_e32 v163, vcc, 0, v163, vcc
	global_load_dwordx4 v[162:165], v[162:163], off offset:384
.LBB0_1284:
	s_setprio 1
	ds_read_b128 v[204:207], v131 offset:0
	ds_read_b128 v[216:219], v138 offset:18432
	ds_read_b128 v[224:227], v138 offset:23040
	ds_read_b128 v[228:231], v138 offset:27648
	ds_read_b128 v[232:235], v138 offset:32256
	ds_read_b128 v[212:215], v131 offset:4608
	s_waitcnt lgkmcnt(4)
	v_mfma_f32_32x32x16_bf16 v[114:129], v[204:207], v[216:219], v[114:129]
	ds_read_b128 v[208:211], v131 offset:32
	ds_read_b128 v[236:239], v138 offset:18464
	s_waitcnt lgkmcnt(5)
	v_mfma_f32_32x32x16_bf16 v[98:113], v[204:207], v[224:227], v[98:113]
	v_lshl_add_u64 v[166:167], v[150:151], 0, s[8:9]
	v_add_co_u32_e32 v166, vcc, s46, v166
	s_nop 1
	v_addc_co_u32_e32 v167, vcc, 0, v167, vcc
	global_load_dwordx4 v[166:169], v[166:167], off offset:384
	ds_read_b128 v[240:243], v138 offset:23072
	s_waitcnt lgkmcnt(5)
	v_mfma_f32_32x32x16_bf16 v[82:97], v[204:207], v[228:231], v[82:97]
	ds_read_b128 v[244:247], v138 offset:27680
	s_waitcnt lgkmcnt(5)
	v_mfma_f32_32x32x16_bf16 v[66:81], v[204:207], v[232:235], v[66:81]
	v_lshl_add_u64 v[170:171], v[152:153], 0, s[8:9]
	v_add_co_u32_e32 v170, vcc, s35, v170
	s_nop 1
	v_addc_co_u32_e32 v171, vcc, 0, v171, vcc
	global_load_dwordx4 v[170:173], v[170:171], off offset:128
	ds_read_b128 v[248:251], v138 offset:32288
	s_waitcnt lgkmcnt(5)
	v_mfma_f32_32x32x16_bf16 v[50:65], v[212:215], v[216:219], v[50:65]
	v_mfma_f32_32x32x16_bf16 v[34:49], v[212:215], v[224:227], v[34:49]
	v_lshl_add_u64 v[174:175], v[152:153], 0, s[8:9]
	v_add_co_u32_e32 v174, vcc, s36, v174
	s_nop 1
	v_addc_co_u32_e32 v175, vcc, 0, v175, vcc
	global_load_dwordx4 v[174:177], v[174:175], off offset:128
	v_mfma_f32_32x32x16_bf16 v[18:33], v[212:215], v[228:231], v[18:33]
	v_mfma_f32_32x32x16_bf16 v[2:17], v[212:215], v[232:235], v[2:17]
	v_lshl_add_u64 v[178:179], v[152:153], 0, s[8:9]
	v_add_co_u32_e32 v178, vcc, s37, v178
	s_nop 1
	v_addc_co_u32_e32 v179, vcc, 0, v179, vcc
	global_load_dwordx4 v[178:181], v[178:179], off offset:128
	ds_read_b128 v[212:215], v131 offset:4640
	s_waitcnt lgkmcnt(4)
	v_mfma_f32_32x32x16_bf16 v[114:129], v[208:211], v[236:239], v[114:129]
	ds_read_b128 v[204:207], v131 offset:64
	ds_read_b128 v[216:219], v138 offset:18496
	s_waitcnt lgkmcnt(5)
	v_mfma_f32_32x32x16_bf16 v[98:113], v[208:211], v[240:243], v[98:113]
	v_lshl_add_u64 v[184:185], v[152:153], 0, s[8:9]
	v_add_co_u32_e32 v184, vcc, s38, v184
	s_nop 1
	v_addc_co_u32_e32 v185, vcc, 0, v185, vcc
	global_load_dwordx4 v[184:187], v[184:185], off offset:128
	ds_read_b128 v[224:227], v138 offset:23104
	s_waitcnt lgkmcnt(5)
	v_mfma_f32_32x32x16_bf16 v[82:97], v[208:211], v[244:247], v[82:97]
	ds_read_b128 v[228:231], v138 offset:27712
	s_waitcnt lgkmcnt(5)
	v_mfma_f32_32x32x16_bf16 v[66:81], v[208:211], v[248:251], v[66:81]
	v_lshl_add_u64 v[188:189], v[152:153], 0, s[8:9]
	v_add_co_u32_e32 v188, vcc, s39, v188
	s_nop 1
	v_addc_co_u32_e32 v189, vcc, 0, v189, vcc
	global_load_dwordx4 v[188:191], v[188:189], off offset:128
	ds_read_b128 v[232:235], v138 offset:32320
	s_waitcnt lgkmcnt(5)
	v_mfma_f32_32x32x16_bf16 v[50:65], v[212:215], v[236:239], v[50:65]
	v_mfma_f32_32x32x16_bf16 v[34:49], v[212:215], v[240:243], v[34:49]
	v_lshl_add_u64 v[192:193], v[152:153], 0, s[8:9]
	v_add_co_u32_e32 v192, vcc, s40, v192
	s_nop 1
	v_addc_co_u32_e32 v193, vcc, 0, v193, vcc
	global_load_dwordx4 v[192:195], v[192:193], off offset:128
	v_mfma_f32_32x32x16_bf16 v[18:33], v[212:215], v[244:247], v[18:33]
	v_mfma_f32_32x32x16_bf16 v[2:17], v[212:215], v[248:251], v[2:17]
	v_lshl_add_u64 v[196:197], v[152:153], 0, s[8:9]
	v_add_co_u32_e32 v196, vcc, s41, v196
	s_nop 1
	v_addc_co_u32_e32 v197, vcc, 0, v197, vcc
	global_load_dwordx4 v[196:199], v[196:197], off offset:128
	ds_read_b128 v[212:215], v131 offset:4672
	s_waitcnt lgkmcnt(4)
	v_mfma_f32_32x32x16_bf16 v[114:129], v[204:207], v[216:219], v[114:129]
	ds_read_b128 v[208:211], v131 offset:96
	ds_read_b128 v[236:239], v138 offset:18528
	s_waitcnt lgkmcnt(5)
	v_mfma_f32_32x32x16_bf16 v[98:113], v[204:207], v[224:227], v[98:113]
	v_lshl_add_u64 v[200:201], v[152:153], 0, s[8:9]
	v_add_co_u32_e32 v200, vcc, s42, v200
	s_nop 1
	v_addc_co_u32_e32 v201, vcc, 0, v201, vcc
	global_load_dwordx4 v[200:203], v[200:201], off offset:128
	ds_read_b128 v[240:243], v138 offset:23136
	s_waitcnt lgkmcnt(5)
	v_mfma_f32_32x32x16_bf16 v[82:97], v[204:207], v[228:231], v[82:97]
	ds_read_b128 v[244:247], v138 offset:27744
	s_waitcnt lgkmcnt(5)
	v_mfma_f32_32x32x16_bf16 v[66:81], v[204:207], v[232:235], v[66:81]
	ds_read_b128 v[248:251], v138 offset:32352
	s_waitcnt lgkmcnt(5)
	v_mfma_f32_32x32x16_bf16 v[50:65], v[212:215], v[216:219], v[50:65]
	v_mfma_f32_32x32x16_bf16 v[34:49], v[212:215], v[224:227], v[34:49]
	v_mfma_f32_32x32x16_bf16 v[18:33], v[212:215], v[228:231], v[18:33]
	v_mfma_f32_32x32x16_bf16 v[2:17], v[212:215], v[232:235], v[2:17]
	ds_read_b128 v[212:215], v131 offset:4704
	s_waitcnt lgkmcnt(4)
	v_mfma_f32_32x32x16_bf16 v[114:129], v[208:211], v[236:239], v[114:129]
	s_waitcnt lgkmcnt(3)
	v_mfma_f32_32x32x16_bf16 v[98:113], v[208:211], v[240:243], v[98:113]
	s_waitcnt lgkmcnt(2)
	v_mfma_f32_32x32x16_bf16 v[82:97], v[208:211], v[244:247], v[82:97]
	s_waitcnt lgkmcnt(1)
	v_mfma_f32_32x32x16_bf16 v[66:81], v[208:211], v[248:251], v[66:81]
	s_waitcnt lgkmcnt(0)
	v_mfma_f32_32x32x16_bf16 v[50:65], v[212:215], v[236:239], v[50:65]
	v_mfma_f32_32x32x16_bf16 v[34:49], v[212:215], v[240:243], v[34:49]
	v_mfma_f32_32x32x16_bf16 v[18:33], v[212:215], v[244:247], v[18:33]
	v_mfma_f32_32x32x16_bf16 v[2:17], v[212:215], v[248:251], v[2:17]
	s_setprio 0
	s_add_u32 s8, s8, 0x80
	s_addc_u32 s9, s9, 0
	s_cmpk_lg_i32 s8, 0x700
	s_barrier
;     ...
;   for (int kt = 0; kt < nk; ++kt) {
;     const int kn = (kt + 1 < nk) ? kt + 1 : kt;
;     GW_LOAD2(kn * 64, kn * bkstep)
;     __builtin_amdgcn_sched_barrier(0);
;     __builtin_amdgcn_s_setprio(1);
; #pragma unroll
;     for (int st = 0; st < 4; ++st) {
;       bf16x8 a0 = *(const bf16x8*)(Ab + st * 32);
;       bf16x8 a1 = *(const bf16x8*)(Ab + 32 * LSTR + st * 32);
;       bf16x8 b0 = *(const bf16x8*)(Bb + st * 32);
;       bf16x8 b1 = *(const bf16x8*)(Bb + 32 * LSTR + st * 32);
;       bf16x8 b2 = *(const bf16x8*)(Bb + 64 * LSTR + st * 32);
;       bf16x8 b3 = *(const bf16x8*)(Bb + 96 * LSTR + st * 32);
;       acc[0][0] = mfma32(a0, b0, acc[0][0]);
;       acc[0][1] = mfma32(a0, b1, acc[0][1]);
;       acc[0][2] = mfma32(a0, b2, acc[0][2]);
;       acc[0][3] = mfma32(a0, b3, acc[0][3]);
;       acc[1][0] = mfma32(a1, b0, acc[1][0]);
;       acc[1][1] = mfma32(a1, b1, acc[1][1]);
;       acc[1][2] = mfma32(a1, b2, acc[1][2]);
;       acc[1][3] = mfma32(a1, b3, acc[1][3]);
;     }
;     __builtin_amdgcn_s_setprio(0);
;     __builtin_amdgcn_sched_barrier(0);
;     __syncthreads();
;     GW_STORE()
;     __syncthreads();
	s_waitcnt vmcnt(11)
	ds_write_b128 v130, v[154:157]
	v_lshl_add_u64 v[154:155], v[150:151], 0, s[8:9]
	v_add_co_u32_e32 v154, vcc, s43, v154
	s_nop 1
	v_addc_co_u32_e32 v155, vcc, 0, v155, vcc
	global_load_dwordx4 v[154:157], v[154:155], off offset:384
	s_waitcnt vmcnt(11)
	ds_write_b128 v130, v[158:161] offset:4608
	v_lshl_add_u64 v[158:159], v[150:151], 0, s[8:9]
	v_add_co_u32_e32 v158, vcc, s44, v158
	s_nop 1
	v_addc_co_u32_e32 v159, vcc, 0, v159, vcc
	global_load_dwordx4 v[158:161], v[158:159], off offset:384
	s_waitcnt vmcnt(11)
	ds_write_b128 v130, v[162:165] offset:9216
	v_lshl_add_u64 v[162:163], v[150:151], 0, s[8:9]
	v_add_co_u32_e32 v162, vcc, s45, v162
	s_nop 1
	v_addc_co_u32_e32 v163, vcc, 0, v163, vcc
	global_load_dwordx4 v[162:165], v[162:163], off offset:384
	s_waitcnt vmcnt(11)
	ds_write_b128 v130, v[166:169] offset:13824
	s_waitcnt vmcnt(10)
	ds_write_b128 v130, v[170:173] offset:18432
	s_waitcnt vmcnt(9)
	ds_write_b128 v130, v[174:177] offset:23040
	s_waitcnt vmcnt(8)
	ds_write_b128 v130, v[178:181] offset:27648
	s_waitcnt vmcnt(7)
	ds_write_b128 v130, v[184:187] offset:32256
	s_waitcnt vmcnt(6)
	ds_write_b128 v130, v[188:191] offset:36864
	s_waitcnt vmcnt(5)
	ds_write_b128 v130, v[192:195] offset:41472
	s_waitcnt vmcnt(4)
	ds_write_b128 v130, v[196:199] offset:46080
	s_waitcnt vmcnt(3)
	ds_write_b128 v130, v[200:203] offset:50688
	s_waitcnt lgkmcnt(0)
	s_barrier
	s_cbranch_scc1 .LBB0_1284
	s_setprio 1
	ds_read_b128 v[204:207], v131 offset:0
	ds_read_b128 v[216:219], v138 offset:18432
	ds_read_b128 v[224:227], v138 offset:23040
	ds_read_b128 v[228:231], v138 offset:27648
	ds_read_b128 v[232:235], v138 offset:32256
	ds_read_b128 v[212:215], v131 offset:4608
	s_waitcnt lgkmcnt(4)
	v_mfma_f32_32x32x16_bf16 v[114:129], v[204:207], v[216:219], v[114:129]
	ds_read_b128 v[208:211], v131 offset:32
	ds_read_b128 v[236:239], v138 offset:18464
	s_waitcnt lgkmcnt(5)
	v_mfma_f32_32x32x16_bf16 v[98:113], v[204:207], v[224:227], v[98:113]
	v_lshl_add_u64 v[166:167], v[150:151], 0, s[8:9]
	v_add_co_u32_e32 v166, vcc, s46, v166
	s_nop 1
	v_addc_co_u32_e32 v167, vcc, 0, v167, vcc
	global_load_dwordx4 v[166:169], v[166:167], off offset:384
	ds_read_b128 v[240:243], v138 offset:23072
	s_waitcnt lgkmcnt(5)
	v_mfma_f32_32x32x16_bf16 v[82:97], v[204:207], v[228:231], v[82:97]
	ds_read_b128 v[244:247], v138 offset:27680
	s_waitcnt lgkmcnt(5)
	v_mfma_f32_32x32x16_bf16 v[66:81], v[204:207], v[232:235], v[66:81]
	v_lshl_add_u64 v[170:171], v[152:153], 0, s[8:9]
	v_add_co_u32_e32 v170, vcc, s35, v170
	s_nop 1
	v_addc_co_u32_e32 v171, vcc, 0, v171, vcc
	global_load_dwordx4 v[170:173], v[170:171], off offset:128
	ds_read_b128 v[248:251], v138 offset:32288
	s_waitcnt lgkmcnt(5)
	v_mfma_f32_32x32x16_bf16 v[50:65], v[212:215], v[216:219], v[50:65]
	v_mfma_f32_32x32x16_bf16 v[34:49], v[212:215], v[224:227], v[34:49]
	v_lshl_add_u64 v[174:175], v[152:153], 0, s[8:9]
	v_add_co_u32_e32 v174, vcc, s36, v174
	s_nop 1
	v_addc_co_u32_e32 v175, vcc, 0, v175, vcc
	global_load_dwordx4 v[174:177], v[174:175], off offset:128
	v_mfma_f32_32x32x16_bf16 v[18:33], v[212:215], v[228:231], v[18:33]
	v_mfma_f32_32x32x16_bf16 v[2:17], v[212:215], v[232:235], v[2:17]
	v_lshl_add_u64 v[178:179], v[152:153], 0, s[8:9]
	v_add_co_u32_e32 v178, vcc, s37, v178
	s_nop 1
	v_addc_co_u32_e32 v179, vcc, 0, v179, vcc
	global_load_dwordx4 v[178:181], v[178:179], off offset:128
	ds_read_b128 v[212:215], v131 offset:4640
	s_waitcnt lgkmcnt(4)
	v_mfma_f32_32x32x16_bf16 v[114:129], v[208:211], v[236:239], v[114:129]
	ds_read_b128 v[204:207], v131 offset:64
	ds_read_b128 v[216:219], v138 offset:18496
	s_waitcnt lgkmcnt(5)
	v_mfma_f32_32x32x16_bf16 v[98:113], v[208:211], v[240:243], v[98:113]
	v_lshl_add_u64 v[184:185], v[152:153], 0, s[8:9]
	v_add_co_u32_e32 v184, vcc, s38, v184
	s_nop 1
	v_addc_co_u32_e32 v185, vcc, 0, v185, vcc
	global_load_dwordx4 v[184:187], v[184:185], off offset:128
	ds_read_b128 v[224:227], v138 offset:23104
	s_waitcnt lgkmcnt(5)
	v_mfma_f32_32x32x16_bf16 v[82:97], v[208:211], v[244:247], v[82:97]
	ds_read_b128 v[228:231], v138 offset:27712
	s_waitcnt lgkmcnt(5)
	v_mfma_f32_32x32x16_bf16 v[66:81], v[208:211], v[248:251], v[66:81]
	v_lshl_add_u64 v[188:189], v[152:153], 0, s[8:9]
	v_add_co_u32_e32 v188, vcc, s39, v188
	s_nop 1
	v_addc_co_u32_e32 v189, vcc, 0, v189, vcc
	global_load_dwordx4 v[188:191], v[188:189], off offset:128
	ds_read_b128 v[232:235], v138 offset:32320
	s_waitcnt lgkmcnt(5)
	v_mfma_f32_32x32x16_bf16 v[50:65], v[212:215], v[236:239], v[50:65]
	v_mfma_f32_32x32x16_bf16 v[34:49], v[212:215], v[240:243], v[34:49]
	v_lshl_add_u64 v[192:193], v[152:153], 0, s[8:9]
	v_add_co_u32_e32 v192, vcc, s40, v192
	s_nop 1
	v_addc_co_u32_e32 v193, vcc, 0, v193, vcc
	global_load_dwordx4 v[192:195], v[192:193], off offset:128
	v_mfma_f32_32x32x16_bf16 v[18:33], v[212:215], v[244:247], v[18:33]
	v_mfma_f32_32x32x16_bf16 v[2:17], v[212:215], v[248:251], v[2:17]
	v_lshl_add_u64 v[196:197], v[152:153], 0, s[8:9]
	v_add_co_u32_e32 v196, vcc, s41, v196
	s_nop 1
	v_addc_co_u32_e32 v197, vcc, 0, v197, vcc
	global_load_dwordx4 v[196:199], v[196:197], off offset:128
	ds_read_b128 v[212:215], v131 offset:4672
	s_waitcnt lgkmcnt(4)
	v_mfma_f32_32x32x16_bf16 v[114:129], v[204:207], v[216:219], v[114:129]
	ds_read_b128 v[208:211], v131 offset:96
	ds_read_b128 v[236:239], v138 offset:18528
	s_waitcnt lgkmcnt(5)
	v_mfma_f32_32x32x16_bf16 v[98:113], v[204:207], v[224:227], v[98:113]
	v_lshl_add_u64 v[200:201], v[152:153], 0, s[8:9]
	v_add_co_u32_e32 v200, vcc, s42, v200
	s_nop 1
	v_addc_co_u32_e32 v201, vcc, 0, v201, vcc
	global_load_dwordx4 v[200:203], v[200:201], off offset:128
	ds_read_b128 v[240:243], v138 offset:23136
	s_waitcnt lgkmcnt(5)
	v_mfma_f32_32x32x16_bf16 v[82:97], v[204:207], v[228:231], v[82:97]
	ds_read_b128 v[244:247], v138 offset:27744
	s_waitcnt lgkmcnt(5)
	v_mfma_f32_32x32x16_bf16 v[66:81], v[204:207], v[232:235], v[66:81]
	ds_read_b128 v[248:251], v138 offset:32352
	s_waitcnt lgkmcnt(5)
	v_mfma_f32_32x32x16_bf16 v[50:65], v[212:215], v[216:219], v[50:65]
	v_mfma_f32_32x32x16_bf16 v[34:49], v[212:215], v[224:227], v[34:49]
	v_mfma_f32_32x32x16_bf16 v[18:33], v[212:215], v[228:231], v[18:33]
	v_mfma_f32_32x32x16_bf16 v[2:17], v[212:215], v[232:235], v[2:17]
	ds_read_b128 v[212:215], v131 offset:4704
	s_waitcnt lgkmcnt(4)
	v_mfma_f32_32x32x16_bf16 v[114:129], v[208:211], v[236:239], v[114:129]
	s_waitcnt lgkmcnt(3)
	v_mfma_f32_32x32x16_bf16 v[98:113], v[208:211], v[240:243], v[98:113]
	s_waitcnt lgkmcnt(2)
	v_mfma_f32_32x32x16_bf16 v[82:97], v[208:211], v[244:247], v[82:97]
	s_waitcnt lgkmcnt(1)
	v_mfma_f32_32x32x16_bf16 v[66:81], v[208:211], v[248:251], v[66:81]
	s_waitcnt lgkmcnt(0)
	v_mfma_f32_32x32x16_bf16 v[50:65], v[212:215], v[236:239], v[50:65]
	v_mfma_f32_32x32x16_bf16 v[34:49], v[212:215], v[240:243], v[34:49]
	v_mfma_f32_32x32x16_bf16 v[18:33], v[212:215], v[244:247], v[18:33]
	v_mfma_f32_32x32x16_bf16 v[2:17], v[212:215], v[248:251], v[2:17]
	s_setprio 0
	s_add_u32 s8, s8, 0x80
	s_addc_u32 s9, s9, 0
	s_barrier
;     ...
;   for (int kt = 0; kt < nk; ++kt) {
;     const int kn = (kt + 1 < nk) ? kt + 1 : kt;
;     GW_LOAD2(kn * 64, kn * bkstep)
;     __builtin_amdgcn_sched_barrier(0);
;     __builtin_amdgcn_s_setprio(1);
; #pragma unroll
;     for (int st = 0; st < 4; ++st) {
;       bf16x8 a0 = *(const bf16x8*)(Ab + st * 32);
;       bf16x8 a1 = *(const bf16x8*)(Ab + 32 * LSTR + st * 32);
;       bf16x8 b0 = *(const bf16x8*)(Bb + st * 32);
;       bf16x8 b1 = *(const bf16x8*)(Bb + 32 * LSTR + st * 32);
;       bf16x8 b2 = *(const bf16x8*)(Bb + 64 * LSTR + st * 32);
;       bf16x8 b3 = *(const bf16x8*)(Bb + 96 * LSTR + st * 32);
;       acc[0][0] = mfma32(a0, b0, acc[0][0]);
;       acc[0][1] = mfma32(a0, b1, acc[0][1]);
;       acc[0][2] = mfma32(a0, b2, acc[0][2]);
;       acc[0][3] = mfma32(a0, b3, acc[0][3]);
;       acc[1][0] = mfma32(a1, b0, acc[1][0]);
;       acc[1][1] = mfma32(a1, b1, acc[1][1]);
;       acc[1][2] = mfma32(a1, b2, acc[1][2]);
;       acc[1][3] = mfma32(a1, b3, acc[1][3]);
;     }
;     __builtin_amdgcn_s_setprio(0);
;     __builtin_amdgcn_sched_barrier(0);
;     __syncthreads();
;     GW_STORE()
;     __syncthreads();
; __device__ __forceinline__ void inproj_tile(const Params& P, int l, int mt, int ntw, char* smem) {
;     ...
;   const int row0 = mt * 128;
;   const bool isctx = row0 >= NLAT;
;   const int b = isctx ? ((row0 - NLAT) >> 8) : (row0 >> 12);
;   const int pos0 = isctx ? ((row0 - NLAT) & 255) : (row0 & 4095);
;   const int tk0 = isctx ? (SEQ + pos0) : pos0;
	s_waitcnt vmcnt(11)
	ds_write_b128 v130, v[154:157]
	s_waitcnt vmcnt(10)
	ds_write_b128 v130, v[158:161] offset:4608
	s_waitcnt vmcnt(9)
	ds_write_b128 v130, v[162:165] offset:9216
	s_waitcnt vmcnt(8)
	ds_write_b128 v130, v[166:169] offset:13824
	s_waitcnt vmcnt(7)
	ds_write_b128 v130, v[170:173] offset:18432
	s_waitcnt vmcnt(6)
	ds_write_b128 v130, v[174:177] offset:23040
	s_waitcnt vmcnt(5)
	ds_write_b128 v130, v[178:181] offset:27648
	s_waitcnt vmcnt(4)
	ds_write_b128 v130, v[184:187] offset:32256
	s_waitcnt vmcnt(3)
	ds_write_b128 v130, v[188:191] offset:36864
	s_waitcnt vmcnt(2)
	ds_write_b128 v130, v[192:195] offset:41472
	s_waitcnt vmcnt(1)
	ds_write_b128 v130, v[196:199] offset:46080
	s_waitcnt vmcnt(0)
	ds_write_b128 v130, v[200:203] offset:50688
	s_waitcnt lgkmcnt(0)
	s_barrier
	s_nop 0
	s_nop 0
	v_add_co_u32_e32 v132, vcc, 0x10000, v142
	s_mov_b32 s58, 0
	s_nop 0
	v_addc_co_u32_e32 v133, vcc, 0, v143, vcc
	v_add_co_u32_e32 v132, vcc, 0x20000, v142
	s_nop 1
	v_addc_co_u32_e32 v133, vcc, 0, v143, vcc
	v_add_co_u32_e32 v148, vcc, 0x30000, v142
	s_nop 1
	v_addc_co_u32_e32 v149, vcc, 0, v143, vcc
	v_add_co_u32_e32 v132, vcc, 0x40000, v142
	s_nop 1
	v_addc_co_u32_e32 v133, vcc, 0, v143, vcc
	v_add_co_u32_e32 v148, vcc, 0x50000, v142
	s_nop 1
	v_addc_co_u32_e32 v149, vcc, 0, v143, vcc
	v_add_co_u32_e32 v132, vcc, 0x60000, v142
	s_nop 1
	v_addc_co_u32_e32 v133, vcc, 0, v143, vcc
	v_add_co_u32_e32 v142, vcc, 0x70000, v142
	s_nop 1
	v_addc_co_u32_e32 v143, vcc, 0, v143, vcc
	s_setprio 1
	ds_read_b128 v[196:199], v131 offset:0
	ds_read_b128 v[208:211], v138 offset:18432
	ds_read_b128 v[212:215], v138 offset:23040
	ds_read_b128 v[216:219], v138 offset:27648
	ds_read_b128 v[224:227], v138 offset:32256
	ds_read_b128 v[204:207], v131 offset:4608
	s_waitcnt lgkmcnt(4)
	v_mfma_f32_32x32x16_bf16 v[114:129], v[196:199], v[208:211], v[114:129]
	ds_read_b128 v[200:203], v131 offset:32
	ds_read_b128 v[228:231], v138 offset:18464
	s_waitcnt lgkmcnt(5)
	v_mfma_f32_32x32x16_bf16 v[98:113], v[196:199], v[212:215], v[98:113]
	ds_read_b128 v[232:235], v138 offset:23072
	s_waitcnt lgkmcnt(5)
	v_mfma_f32_32x32x16_bf16 v[82:97], v[196:199], v[216:219], v[82:97]
	ds_read_b128 v[236:239], v138 offset:27680
	s_waitcnt lgkmcnt(5)
	v_mfma_f32_32x32x16_bf16 v[66:81], v[196:199], v[224:227], v[66:81]
	ds_read_b128 v[240:243], v138 offset:32288
	s_waitcnt lgkmcnt(5)
	v_mfma_f32_32x32x16_bf16 v[50:65], v[204:207], v[208:211], v[50:65]
	v_mfma_f32_32x32x16_bf16 v[34:49], v[204:207], v[212:215], v[34:49]
	v_mfma_f32_32x32x16_bf16 v[18:33], v[204:207], v[216:219], v[18:33]
	v_mfma_f32_32x32x16_bf16 v[2:17], v[204:207], v[224:227], v[2:17]
	ds_read_b128 v[204:207], v131 offset:4640
	s_waitcnt lgkmcnt(4)
	v_mfma_f32_32x32x16_bf16 v[114:129], v[200:203], v[228:231], v[114:129]
	ds_read_b128 v[196:199], v131 offset:64
	ds_read_b128 v[208:211], v138 offset:18496
	s_waitcnt lgkmcnt(5)
	v_mfma_f32_32x32x16_bf16 v[98:113], v[200:203], v[232:235], v[98:113]
	ds_read_b128 v[212:215], v138 offset:23104
	s_waitcnt lgkmcnt(5)
	v_mfma_f32_32x32x16_bf16 v[82:97], v[200:203], v[236:239], v[82:97]
	ds_read_b128 v[216:219], v138 offset:27712
	s_waitcnt lgkmcnt(5)
	v_mfma_f32_32x32x16_bf16 v[66:81], v[200:203], v[240:243], v[66:81]
	ds_read_b128 v[224:227], v138 offset:32320
	s_waitcnt lgkmcnt(5)
	v_mfma_f32_32x32x16_bf16 v[50:65], v[204:207], v[228:231], v[50:65]
	v_mfma_f32_32x32x16_bf16 v[34:49], v[204:207], v[232:235], v[34:49]
	v_mfma_f32_32x32x16_bf16 v[18:33], v[204:207], v[236:239], v[18:33]
	v_mfma_f32_32x32x16_bf16 v[2:17], v[204:207], v[240:243], v[2:17]
	ds_read_b128 v[204:207], v131 offset:4672
	s_waitcnt lgkmcnt(4)
	v_mfma_f32_32x32x16_bf16 v[114:129], v[196:199], v[208:211], v[114:129]
	ds_read_b128 v[200:203], v131 offset:96
	ds_read_b128 v[228:231], v138 offset:18528
	s_waitcnt lgkmcnt(5)
	v_mfma_f32_32x32x16_bf16 v[98:113], v[196:199], v[212:215], v[98:113]
	ds_read_b128 v[232:235], v138 offset:23136
	s_waitcnt lgkmcnt(5)
	v_mfma_f32_32x32x16_bf16 v[82:97], v[196:199], v[216:219], v[82:97]
	ds_read_b128 v[236:239], v138 offset:27744
	s_waitcnt lgkmcnt(5)
	v_mfma_f32_32x32x16_bf16 v[66:81], v[196:199], v[224:227], v[66:81]
	ds_read_b128 v[240:243], v138 offset:32352
	s_waitcnt lgkmcnt(5)
	v_mfma_f32_32x32x16_bf16 v[50:65], v[204:207], v[208:211], v[50:65]
	v_mfma_f32_32x32x16_bf16 v[34:49], v[204:207], v[212:215], v[34:49]
	v_mfma_f32_32x32x16_bf16 v[18:33], v[204:207], v[216:219], v[18:33]
	v_mfma_f32_32x32x16_bf16 v[2:17], v[204:207], v[224:227], v[2:17]
	ds_read_b128 v[204:207], v131 offset:4704
	s_waitcnt lgkmcnt(4)
	v_mfma_f32_32x32x16_bf16 v[114:129], v[200:203], v[228:231], v[114:129]
	s_waitcnt lgkmcnt(3)
	v_mfma_f32_32x32x16_bf16 v[98:113], v[200:203], v[232:235], v[98:113]
	s_waitcnt lgkmcnt(2)
	v_mfma_f32_32x32x16_bf16 v[82:97], v[200:203], v[236:239], v[82:97]
	s_waitcnt lgkmcnt(1)
	v_mfma_f32_32x32x16_bf16 v[66:81], v[200:203], v[240:243], v[66:81]
	s_waitcnt lgkmcnt(0)
	v_mfma_f32_32x32x16_bf16 v[50:65], v[204:207], v[228:231], v[50:65]
	v_mfma_f32_32x32x16_bf16 v[34:49], v[204:207], v[232:235], v[34:49]
	v_mfma_f32_32x32x16_bf16 v[18:33], v[204:207], v[236:239], v[18:33]
	v_mfma_f32_32x32x16_bf16 v[2:17], v[204:207], v[240:243], v[2:17]
	s_setprio 0
	s_lshl_b32 s18, s10, 7
	s_cmpk_lt_i32 s10, 0x100
	s_cselect_b64 s[8:9], -1, 0
	s_add_i32 s6, s18, 0xffff8000
	s_and_b32 s57, s18, 0x80
	s_barrier
; __device__ __forceinline__ void inproj_tile(const Params& P, int l, int mt, int ntw, char* smem) {
;     ...
;   float* cs = (float*)smem;
;   const int row0 = mt * 128;
;   const bool isctx = row0 >= NLAT;
;   const int b = isctx ? ((row0 - NLAT) >> 8) : (row0 >> 12);
;   const int pos0 = isctx ? ((row0 - NLAT) & 255) : (row0 & 4095);
;   const int tk0 = isctx ? (SEQ + pos0) : pos0;
;   int tid_ = threadIdx.x;
;   asm volatile("" : "+v"(tid_));
;   const int lane = tid_ & 63, wave = tid_ >> 6;
;   const int r = 32 * wave + (lane & 31), half = lane >> 5;
;   const size_t grow = (size_t)row0 + r;
;   const float* crow = cs + r * CSTR + half * 64;
; #pragma unroll 1
;   for (int hsel = 0; hsel < 2; ++hsel) {
;     const int nt = ntw * 2 + hsel;
;     wide_acc_to_lds(acc, cs, hsel);
;     if (nt < 4) {
;       const int part = nt >> 1, cb = (nt & 1) * 128;
;       if (!isctx) {
;         u16* base = WSP(u16, OFF_FTT) + (size_t)b * 256 * 8192 + part * 4096 + pos0;
;         epi_transposed(cs, [&](int ch) { return base + (size_t)(cb + ch) * 8192; });
;       } else {
;         u16* base = WSP(u16, OFF_FTTC) + (size_t)b * 256 * 512 + part * 256 + pos0;
;         epi_transposed(cs, [&](int ch) { return base + (size_t)(cb + ch) * 512; });
;       }
;     } else if (nt < 7 || (nt >= 10 && nt < 13)) {
;       const bool isq = nt < 7;
;       const int head = (isq ? (nt - 4) : (nt - 10)) * 2 + half;
	s_lshr_b32 s6, s6, 8
	s_ashr_i32 s12, s10, 5
	s_and_b32 s59, s18, 0xf80
	s_or_b32 s11, s57, 0x1000
	v_mov_b32_e32 v154, v134
	s_waitcnt lgkmcnt(0)
	s_cmpk_gt_i32 s10, 0xff
	s_cselect_b32 s60, s11, s59
	v_ashrrev_i32_e32 v155, 1, v154
	v_bfi_b32 v130, s47, v155, v154
	s_movk_i32 s11, 0x210
	v_lshlrev_b32_e32 v133, 1, v154
	s_cselect_b32 s13, s57, s59
	v_mul_lo_u32 v132, v130, s11
	v_and_b32_e32 v184, 64, v133
	s_cselect_b32 s10, s6, s12
	v_lshl_add_u32 v185, v184, 2, v132
	s_lshl_b32 s33, s16, 1
	v_add_u32_e32 v132, s13, v155
	s_ashr_i32 s13, s12, 31
	s_lshl_b32 s16, s16, 12
	s_ashr_i32 s19, s18, 31
	s_lshl_b64 s[20:21], s[12:13], 22
	s_ashr_i32 s17, s16, 31
	s_lshl_b64 s[22:23], s[6:7], 18
	s_mul_i32 s11, s10, 6
	s_cmp_gt_u32 s33, 9
	s_mul_i32 s61, s10, 0x330000
	s_mul_hi_i32 s62, s11, 0x88000
	s_cselect_b64 s[10:11], -1, 0
	s_cmp_gt_u32 s33, 21
	s_cselect_b64 s[12:13], -1, 0
	s_cmp_lt_u32 s33, 16
	v_ashrrev_i32_e32 v132, 2, v132
	s_cselect_b64 s[24:25], -1, 0
	v_ashrrev_i32_e32 v131, 31, v130
	v_and_b32_e32 v142, -16, v132
	v_lshlrev_b32_e32 v132, 4, v130
	s_and_b64 s[24:25], s[24:25], exec
	v_and_b32_e32 v138, 0x3f0, v132
	s_cselect_b32 s6, s49, 0x343b1100
	v_lshl_add_u64 v[130:131], s[18:19], 0, v[130:131]
	v_mov_b64_e32 v[132:133], s[90:91]
	s_cselect_b32 s56, s48, 0x1ffffed
	v_mad_u64_u32 v[146:147], s[18:19], v130, s50, v[132:133]
	s_add_u32 s6, s90, s6
	s_addc_u32 s18, s91, 0
	s_add_u32 s6, s6, s61
	s_addc_u32 s19, s18, s62
	s_lshl_b32 s18, s60, 1
	s_add_u32 s18, s6, s18
	s_addc_u32 s19, s19, 0
	v_mov_b32_e32 v141, v139
	s_add_u32 s6, s28, s20
	v_lshl_add_u64 v[148:149], s[18:19], 0, v[140:141]
	s_addc_u32 s18, s29, s21
	s_lshl_b64 s[16:17], s[16:17], 1
	s_add_u32 s6, s6, s16
	s_addc_u32 s17, s18, s17
	s_lshl_b32 s16, s59, 1
	s_add_u32 s16, s6, s16
	s_addc_u32 s17, s17, 0
	s_add_u32 s6, s30, s22
	v_lshl_add_u64 v[150:151], s[16:17], 0, v[140:141]
	s_addc_u32 s18, s31, s23
	s_lshl_b64 s[16:17], s[14:15], 1
	s_add_u32 s6, s6, s16
	s_addc_u32 s15, s18, s17
	s_lshl_b32 s16, s57, 1
	s_add_u32 s16, s6, s16
	v_and_b32_e32 v156, 31, v154
	v_mov_b64_e32 v[144:145], v[138:139]
	s_addc_u32 s17, s15, 0
	v_lshrrev_b32_e32 v132, 5, v155
	v_bfe_u32 v138, v154, 5, 1
	v_lshl_add_u64 v[152:153], s[16:17], 0, v[140:141]
	v_mul_lo_u32 v132, v132, s51
	v_mul_u32_u24_e32 v133, 0x210, v156
	v_lshlrev_b32_e32 v141, 8, v138
	v_add3_u32 v141, v132, v133, v141
	v_mad_u64_u32 v[132:133], s[16:17], v130, s52, 0
	v_mad_i32_i24 v147, v131, s50, v147
	v_mad_i32_i24 v131, v131, s52, v133
	v_lshl_or_b32 v130, v138, 7, v132
	v_ashrrev_i32_e32 v143, 31, v142
	v_lshl_add_u64 v[154:155], s[4:5], 0, v[130:131]
	s_add_i32 s57, s14, 0xfffff500
	s_mov_b64 s[14:15], -1
	s_branch .LBB0_1287

; #define GW_LOAD(KOFF) GW_LOAD2(KOFF, 0)
;   int tid = threadIdx.x;
;   asm volatile("" : "+v"(tid));
;   const int lane = tid & 63, wave = tid >> 6;
;   const int wm = wave >> 1, wn = wave & 1;
;   const int lr = tid >> 3, kc = tid & 7;
;   const u16* ap0 = arow(lr) + kc * 8;
;   const u16* ap1 = arow(lr + 32) + kc * 8;
;   const u16* ap2 = arow(lr + 64) + kc * 8;
;   const u16* ap3 = arow(lr + 96) + kc * 8;
;   const u16* bp0 = Bt + (size_t)lr * ldb + kc * 8;
;   const size_t bstep = 32 * ldb;
;   const int so = lr * LSTR + kc * 16;
;   uint4 ra0, ra1, ra2, ra3, rb0, rb1, rb2, rb3, rb4, rb5, rb6, rb7;
;     ...
;   GW_LOAD(0)
;   GW_STORE()
; __device__ __forceinline__ void run_phase(const Params& P, int ph, char* smem) {
;     ...
;       for (int it = blockIdx.x; it < 1024; it += gridDim.x) {
;         int q = xcd_remap(it);
;         int mt, ntw; tile_of(q, 4, mt, ntw);
;         outproj_tile<true>(P, l, mt, ntw * 2, smem);
.LBB0_1714:
	s_lshl_b32 s12, s51, 6
	s_and_b32 s12, s12, 0x1c0
	s_and_b32 s13, s51, 0xfffffe00
	s_or_b32 s12, s12, s13
	s_bfe_u32 s13, s51, 0x60003
	s_or_b32 s14, s12, s13
	s_and_b64 s[12:13], s[0:1], exec
	s_cselect_b32 s12, s14, s51
	s_ashr_i32 s13, s12, 31
	s_lshr_b32 s13, s13, 27
	s_add_i32 s13, s12, s13
	s_ashr_i32 s14, s13, 5
	s_andn2_b32 s13, s13, 31
	s_lshl_b32 s14, s14, 3
	s_sub_i32 s13, s12, s13
	s_and_b32 s12, s12, 7
	s_or_b32 s12, s14, s12
	s_ashr_i32 s13, s13, 2
	s_and_b32 s52, s13, -2
	s_ashr_i32 s13, s12, 31
	s_lshl_b64 s[14:15], s[12:13], 18
	s_add_u32 s54, s19, s14
	s_addc_u32 s55, s20, s15
	s_lshl_b32 s16, s52, 7
	v_mov_b32_e32 v54, v134
	s_ashr_i32 s17, s16, 31
	s_lshl_b64 s[16:17], s[16:17], 11
	v_ashrrev_i32_e32 v50, 3, v54
	v_ashrrev_i32_e32 v51, 31, v50
	s_add_u32 s56, s21, s16
	v_lshlrev_b64 v[52:53], 11, v[50:51]
	v_lshlrev_b32_e32 v4, 4, v54
	s_addc_u32 s57, s22, s17
	v_lshl_add_u64 v[2:3], s[54:55], 0, v[52:53]
	v_and_b32_e32 v130, 0x70, v4
	v_lshl_add_u64 v[140:141], v[2:3], 0, v[130:131]
	v_lshl_add_u64 v[2:3], s[56:57], 0, v[52:53]
	v_lshl_add_u64 v[138:139], v[2:3], 0, v[130:131]
	v_add_co_u32_e32 v2, vcc, s27, v140
	v_mad_u64_u32 v[132:133], s[54:55], v50, s26, v[130:131]
	s_nop 0
	v_addc_co_u32_e32 v3, vcc, 0, v141, vcc
	v_add_co_u32_e32 v6, vcc, s28, v140
	v_lshl_add_u64 v[142:143], v[140:141], 0, s[2:3]
	s_nop 0
	v_addc_co_u32_e32 v7, vcc, 0, v141, vcc
	v_add_co_u32_e32 v18, vcc, s29, v140
	global_load_dwordx4 v[2:5], v[2:3], off
	s_nop 0
	global_load_dwordx4 v[6:9], v[6:7], off
	v_addc_co_u32_e32 v19, vcc, 0, v141, vcc
	v_add_co_u32_e32 v22, vcc, s27, v138
	global_load_dwordx4 v[10:13], v[140:141], off
	global_load_dwordx4 v[14:17], v[138:139], off
	v_addc_co_u32_e32 v23, vcc, 0, v139, vcc
	v_add_co_u32_e32 v26, vcc, s28, v138
	global_load_dwordx4 v[18:21], v[18:19], off
	s_nop 0
	global_load_dwordx4 v[22:25], v[22:23], off
	v_addc_co_u32_e32 v27, vcc, 0, v139, vcc
	v_add_co_u32_e32 v30, vcc, s29, v138
	v_lshl_add_u64 v[144:145], v[140:141], 0, s[4:5]
	s_nop 0
	v_addc_co_u32_e32 v31, vcc, 0, v139, vcc
	v_add_co_u32_e32 v34, vcc, s30, v138
	global_load_dwordx4 v[26:29], v[26:27], off
	s_nop 0
	global_load_dwordx4 v[30:33], v[30:31], off
	v_addc_co_u32_e32 v35, vcc, 0, v139, vcc
	v_add_co_u32_e32 v38, vcc, s31, v138
	v_lshl_add_u64 v[146:147], v[140:141], 0, s[6:7]
	s_nop 0
	v_addc_co_u32_e32 v39, vcc, 0, v139, vcc
	v_add_co_u32_e32 v42, vcc, s33, v138
	global_load_dwordx4 v[34:37], v[34:35], off
	s_nop 0
	global_load_dwordx4 v[38:41], v[38:39], off
	v_addc_co_u32_e32 v43, vcc, 0, v139, vcc
	v_add_co_u32_e32 v46, vcc, s34, v138
	v_mov_b32_e32 v50, 0
	s_nop 0
	v_addc_co_u32_e32 v47, vcc, 0, v139, vcc
	global_load_dwordx4 v[42:45], v[42:43], off
	s_nop 0
	global_load_dwordx4 v[46:49], v[46:47], off
	v_mov_b32_e32 v51, v131
	v_mov_b32_e32 v55, v131
	v_mov_b32_e32 v56, v131
	v_mov_b32_e32 v57, v131
	v_mov_b32_e32 v58, v131
	v_mov_b32_e32 v59, v131
	v_mov_b32_e32 v60, v131
	v_mov_b32_e32 v61, v131
	v_mov_b32_e32 v62, v131
	v_mov_b32_e32 v63, v131
	v_mov_b32_e32 v64, v131
	v_mov_b32_e32 v65, v131
	v_mov_b32_e32 v66, 0
	v_mov_b32_e32 v67, v131
	v_mov_b32_e32 v68, v131
	v_mov_b32_e32 v69, v131
	v_mov_b32_e32 v70, v131
	v_mov_b32_e32 v71, v131
	v_mov_b32_e32 v72, v131
	v_mov_b32_e32 v73, v131
	v_mov_b32_e32 v74, v131
	s_waitcnt vmcnt(13)
	v_mov_b32_e32 v75, v131
	s_waitcnt vmcnt(12)
	v_mov_b32_e32 v76, v131
	v_mov_b32_e32 v77, v131
	v_mov_b32_e32 v78, v131
	v_mov_b32_e32 v79, v131
	v_mov_b32_e32 v80, v131
	v_mov_b32_e32 v81, v131
	v_mov_b32_e32 v82, 0
	v_mov_b32_e32 v83, v131
	s_waitcnt vmcnt(9)
	ds_write_b128 v132, v[10:13]
	ds_write_b128 v132, v[2:5] offset:4608
	ds_write_b128 v132, v[6:9] offset:9216
	s_waitcnt vmcnt(7)
	ds_write_b128 v132, v[18:21] offset:13824
	ds_write_b128 v132, v[14:17] offset:18432
	s_waitcnt vmcnt(6)
	ds_write_b128 v132, v[22:25] offset:23040
	s_waitcnt vmcnt(5)
	ds_write_b128 v132, v[26:29] offset:27648
	s_waitcnt vmcnt(4)
	ds_write_b128 v132, v[30:33] offset:32256
	s_waitcnt vmcnt(3)
	ds_write_b128 v132, v[34:37] offset:36864
	s_waitcnt vmcnt(2)
	ds_write_b128 v132, v[38:41] offset:41472
	s_waitcnt vmcnt(1)
	ds_write_b128 v132, v[42:45] offset:46080
	s_waitcnt vmcnt(0)
	ds_write_b128 v132, v[46:49] offset:50688
	v_and_b32_e32 v2, 31, v54
	v_lshrrev_b32_e32 v3, 1, v54
	v_and_or_b32 v4, v3, s35, v2
	v_and_b32_e32 v5, 16, v3
	v_lshlrev_b32_e32 v3, 1, v54
	v_and_or_b32 v2, v3, s36, v2
	v_mul_u32_u24_e32 v6, 0x90, v2
	v_lshl_add_u64 v[2:3], s[14:15], 0, v[52:53]
	v_or_b32_e32 v2, v2, v130
	v_lshl_add_u64 v[148:149], s[90:91], 0, v[2:3]
	v_lshl_add_u64 v[2:3], v[52:53], 0, s[16:17]
	v_mul_lo_u32 v4, v4, s26
	v_or_b32_e32 v2, v2, v130
	v_lshl_add_u64 v[150:151], s[90:91], 0, v[2:3]
	s_mov_b64 s[14:15], 0
	v_add_u32_e32 v130, v4, v5
	v_add_u32_e32 v133, v6, v5
	v_mov_b32_e32 v2, 0
	v_mov_b32_e32 v3, v131
	v_mov_b32_e32 v4, v131
	v_mov_b32_e32 v5, v131
	v_mov_b32_e32 v6, v131
	v_mov_b32_e32 v7, v131
	v_mov_b32_e32 v8, v131
	v_mov_b32_e32 v9, v131
	v_mov_b32_e32 v10, v131
	v_mov_b32_e32 v11, v131
	v_mov_b32_e32 v12, v131
	v_mov_b32_e32 v13, v131
	v_mov_b32_e32 v14, v131
	v_mov_b32_e32 v15, v131
	v_mov_b32_e32 v16, v131
	v_mov_b32_e32 v17, v131
	v_mov_b32_e32 v18, 0
	v_mov_b32_e32 v19, v131
	v_mov_b32_e32 v20, v131
	v_mov_b32_e32 v21, v131
	v_mov_b32_e32 v22, v131
	v_mov_b32_e32 v23, v131
	v_mov_b32_e32 v24, v131
	v_mov_b32_e32 v25, v131
	v_mov_b32_e32 v26, v131
	v_mov_b32_e32 v27, v131
	v_mov_b32_e32 v28, v131
	v_mov_b32_e32 v29, v131
	v_mov_b32_e32 v30, v131
	v_mov_b32_e32 v31, v131
	v_mov_b32_e32 v32, v131
	v_mov_b32_e32 v33, v131
	v_mov_b32_e32 v34, 0
	v_mov_b32_e32 v35, v131
; #define GW_LOAD(KOFF) GW_LOAD2(KOFF, 0)
;     ...
;   GW_LOAD(0)
;   GW_STORE()
;   __syncthreads();
;   const int nk = K >> 6;
;   const char* Ab = smem + (wm * 64 + (lane & 31)) * LSTR + (lane >> 5) * 16;
;   const char* Bb = smem + WTILE_A + (wn * 128 + (lane & 31)) * LSTR + (lane >> 5) * 16;
;   for (int kt = 0; kt < nk; ++kt) {
;     const int kn = (kt + 1 < nk) ? kt + 1 : kt;
;     GW_LOAD2(kn * 64, kn * bkstep)
;     __builtin_amdgcn_sched_barrier(0);
;     __builtin_amdgcn_s_setprio(1);
; #pragma unroll
;     for (int st = 0; st < 4; ++st) {
;       bf16x8 a0 = *(const bf16x8*)(Ab + st * 32);
;       bf16x8 a1 = *(const bf16x8*)(Ab + 32 * LSTR + st * 32);
;       bf16x8 b0 = *(const bf16x8*)(Bb + st * 32);
;       bf16x8 b1 = *(const bf16x8*)(Bb + 32 * LSTR + st * 32);
;       bf16x8 b2 = *(const bf16x8*)(Bb + 64 * LSTR + st * 32);
;       bf16x8 b3 = *(const bf16x8*)(Bb + 96 * LSTR + st * 32);
;       acc[0][0] = mfma32(a0, b0, acc[0][0]);
;       acc[0][1] = mfma32(a0, b1, acc[0][1]);
;       acc[0][2] = mfma32(a0, b2, acc[0][2]);
;       acc[0][3] = mfma32(a0, b3, acc[0][3]);
;       acc[1][0] = mfma32(a1, b0, acc[1][0]);
;       acc[1][1] = mfma32(a1, b1, acc[1][1]);
;       acc[1][2] = mfma32(a1, b2, acc[1][2]);
;       acc[1][3] = mfma32(a1, b3, acc[1][3]);
;     }
	v_mov_b32_e32 v36, v131
	v_mov_b32_e32 v37, v131
	v_mov_b32_e32 v38, v131
	v_mov_b32_e32 v39, v131
	v_mov_b32_e32 v40, v131
	v_mov_b32_e32 v41, v131
	v_mov_b32_e32 v42, v131
	v_mov_b32_e32 v43, v131
	v_mov_b32_e32 v44, v131
	v_mov_b32_e32 v45, v131
	v_mov_b32_e32 v46, v131
	v_mov_b32_e32 v47, v131
	v_mov_b32_e32 v48, v131
	v_mov_b32_e32 v49, v131
	v_mov_b32_e32 v52, v131
	v_mov_b32_e32 v53, v131
	v_mov_b32_e32 v54, v131
	v_mov_b32_e32 v84, v131
	v_mov_b32_e32 v85, v131
	v_mov_b32_e32 v86, v131
	v_mov_b32_e32 v87, v131
	v_mov_b32_e32 v88, v131
	v_mov_b32_e32 v89, v131
	v_mov_b32_e32 v90, v131
	v_mov_b32_e32 v91, v131
	v_mov_b32_e32 v92, v131
	v_mov_b32_e32 v93, v131
	v_mov_b32_e32 v94, v131
	v_mov_b32_e32 v95, v131
	v_mov_b32_e32 v96, v131
	v_mov_b32_e32 v97, v131
	v_mov_b32_e32 v98, 0
	v_mov_b32_e32 v99, v131
	v_mov_b32_e32 v100, v131
	v_mov_b32_e32 v101, v131
	v_mov_b32_e32 v102, v131
	v_mov_b32_e32 v103, v131
	v_mov_b32_e32 v104, v131
	v_mov_b32_e32 v105, v131
	v_mov_b32_e32 v106, v131
	v_mov_b32_e32 v107, v131
	v_mov_b32_e32 v108, v131
	v_mov_b32_e32 v109, v131
	v_mov_b32_e32 v110, v131
	v_mov_b32_e32 v111, v131
	v_mov_b32_e32 v112, v131
	v_mov_b32_e32 v113, v131
	v_mov_b32_e32 v114, 0
	v_mov_b32_e32 v115, v131
	v_mov_b32_e32 v116, v131
	v_mov_b32_e32 v117, v131
	v_mov_b32_e32 v118, v131
	v_mov_b32_e32 v119, v131
	v_mov_b32_e32 v120, v131
	v_mov_b32_e32 v121, v131
	v_mov_b32_e32 v122, v131
	v_mov_b32_e32 v123, v131
	v_mov_b32_e32 v124, v131
	v_mov_b32_e32 v125, v131
	v_mov_b32_e32 v126, v131
	v_mov_b32_e32 v127, v131
	v_mov_b32_e32 v128, v131
	v_mov_b32_e32 v129, v131
	s_waitcnt lgkmcnt(0)
	s_barrier
	v_lshl_add_u64 v[152:153], v[148:149], 0, s[14:15]
	v_add_co_u32_e32 v152, vcc, s37, v152
	s_nop 1
	v_addc_co_u32_e32 v153, vcc, 0, v153, vcc
	global_load_dwordx4 v[152:155], v[152:153], off offset:384
	v_lshl_add_u64 v[156:157], v[148:149], 0, s[14:15]
	v_add_co_u32_e32 v156, vcc, s38, v156
	s_nop 1
	v_addc_co_u32_e32 v157, vcc, 0, v157, vcc
	global_load_dwordx4 v[156:159], v[156:157], off offset:384
	v_lshl_add_u64 v[160:161], v[148:149], 0, s[14:15]
	v_add_co_u32_e32 v160, vcc, s39, v160
	s_nop 1
	v_addc_co_u32_e32 v161, vcc, 0, v161, vcc
	global_load_dwordx4 v[160:163], v[160:161], off offset:384
.LBB0_1715:
	s_setprio 1
	ds_read_b128 v[200:203], v130 offset:0
	ds_read_b128 v[212:215], v133 offset:18432
	ds_read_b128 v[216:219], v133 offset:23040
	ds_read_b128 v[224:227], v133 offset:27648
	ds_read_b128 v[228:231], v133 offset:32256
	ds_read_b128 v[208:211], v130 offset:4608
	s_waitcnt lgkmcnt(4)
	v_mfma_f32_32x32x16_bf16 v[114:129], v[200:203], v[212:215], v[114:129]
	ds_read_b128 v[204:207], v130 offset:32
	ds_read_b128 v[232:235], v133 offset:18464
	s_waitcnt lgkmcnt(5)
	v_mfma_f32_32x32x16_bf16 v[98:113], v[200:203], v[216:219], v[98:113]
	v_lshl_add_u64 v[164:165], v[148:149], 0, s[14:15]
	v_add_co_u32_e32 v164, vcc, s40, v164
	s_nop 1
	v_addc_co_u32_e32 v165, vcc, 0, v165, vcc
	global_load_dwordx4 v[164:167], v[164:165], off offset:384
	ds_read_b128 v[236:239], v133 offset:23072
	s_waitcnt lgkmcnt(5)
	v_mfma_f32_32x32x16_bf16 v[82:97], v[200:203], v[224:227], v[82:97]
	ds_read_b128 v[240:243], v133 offset:27680
	s_waitcnt lgkmcnt(5)
	v_mfma_f32_32x32x16_bf16 v[66:81], v[200:203], v[228:231], v[66:81]
	v_lshl_add_u64 v[168:169], v[150:151], 0, s[14:15]
	v_add_co_u32_e32 v168, vcc, s41, v168
	s_nop 1
	v_addc_co_u32_e32 v169, vcc, 0, v169, vcc
	global_load_dwordx4 v[168:171], v[168:169], off offset:128
	ds_read_b128 v[244:247], v133 offset:32288
	s_waitcnt lgkmcnt(5)
	v_mfma_f32_32x32x16_bf16 v[50:65], v[208:211], v[212:215], v[50:65]
	v_mfma_f32_32x32x16_bf16 v[34:49], v[208:211], v[216:219], v[34:49]
	v_lshl_add_u64 v[172:173], v[150:151], 0, s[14:15]
	v_add_co_u32_e32 v172, vcc, s42, v172
	s_nop 1
	v_addc_co_u32_e32 v173, vcc, 0, v173, vcc
	global_load_dwordx4 v[172:175], v[172:173], off offset:128
	v_mfma_f32_32x32x16_bf16 v[18:33], v[208:211], v[224:227], v[18:33]
	v_mfma_f32_32x32x16_bf16 v[2:17], v[208:211], v[228:231], v[2:17]
	v_lshl_add_u64 v[176:177], v[150:151], 0, s[14:15]
	v_add_co_u32_e32 v176, vcc, s43, v176
	s_nop 1
	v_addc_co_u32_e32 v177, vcc, 0, v177, vcc
	global_load_dwordx4 v[176:179], v[176:177], off offset:128
	ds_read_b128 v[208:211], v130 offset:4640
	s_waitcnt lgkmcnt(4)
	v_mfma_f32_32x32x16_bf16 v[114:129], v[204:207], v[232:235], v[114:129]
	ds_read_b128 v[200:203], v130 offset:64
	ds_read_b128 v[212:215], v133 offset:18496
	s_waitcnt lgkmcnt(5)
	v_mfma_f32_32x32x16_bf16 v[98:113], v[204:207], v[236:239], v[98:113]
	v_lshl_add_u64 v[180:181], v[150:151], 0, s[14:15]
	v_add_co_u32_e32 v180, vcc, s44, v180
	s_nop 1
	v_addc_co_u32_e32 v181, vcc, 0, v181, vcc
	global_load_dwordx4 v[180:183], v[180:181], off offset:128
	ds_read_b128 v[216:219], v133 offset:23104
	s_waitcnt lgkmcnt(5)
	v_mfma_f32_32x32x16_bf16 v[82:97], v[204:207], v[240:243], v[82:97]
	ds_read_b128 v[224:227], v133 offset:27712
	s_waitcnt lgkmcnt(5)
	v_mfma_f32_32x32x16_bf16 v[66:81], v[204:207], v[244:247], v[66:81]
	v_lshl_add_u64 v[184:185], v[150:151], 0, s[14:15]
	v_add_co_u32_e32 v184, vcc, s45, v184
	s_nop 1
	v_addc_co_u32_e32 v185, vcc, 0, v185, vcc
	global_load_dwordx4 v[184:187], v[184:185], off offset:128
	ds_read_b128 v[228:231], v133 offset:32320
	s_waitcnt lgkmcnt(5)
;     ...
;   for (int kt = 0; kt < nk; ++kt) {
;     const int kn = (kt + 1 < nk) ? kt + 1 : kt;
;     GW_LOAD2(kn * 64, kn * bkstep)
;     __builtin_amdgcn_sched_barrier(0);
;     __builtin_amdgcn_s_setprio(1);
; #pragma unroll
;     for (int st = 0; st < 4; ++st) {
;       bf16x8 a0 = *(const bf16x8*)(Ab + st * 32);
;       bf16x8 a1 = *(const bf16x8*)(Ab + 32 * LSTR + st * 32);
;       bf16x8 b0 = *(const bf16x8*)(Bb + st * 32);
;       bf16x8 b1 = *(const bf16x8*)(Bb + 32 * LSTR + st * 32);
;       bf16x8 b2 = *(const bf16x8*)(Bb + 64 * LSTR + st * 32);
;       bf16x8 b3 = *(const bf16x8*)(Bb + 96 * LSTR + st * 32);
;       acc[0][0] = mfma32(a0, b0, acc[0][0]);
;       acc[0][1] = mfma32(a0, b1, acc[0][1]);
;       acc[0][2] = mfma32(a0, b2, acc[0][2]);
;       acc[0][3] = mfma32(a0, b3, acc[0][3]);
;       acc[1][0] = mfma32(a1, b0, acc[1][0]);
;       acc[1][1] = mfma32(a1, b1, acc[1][1]);
;       acc[1][2] = mfma32(a1, b2, acc[1][2]);
;       acc[1][3] = mfma32(a1, b3, acc[1][3]);
;     }
;     __builtin_amdgcn_s_setprio(0);
;     __builtin_amdgcn_sched_barrier(0);
;     __syncthreads();
;     GW_STORE()
;     __syncthreads();
	v_mfma_f32_32x32x16_bf16 v[50:65], v[208:211], v[232:235], v[50:65]
	v_mfma_f32_32x32x16_bf16 v[34:49], v[208:211], v[236:239], v[34:49]
	v_lshl_add_u64 v[188:189], v[150:151], 0, s[14:15]
	v_add_co_u32_e32 v188, vcc, s46, v188
	s_nop 1
	v_addc_co_u32_e32 v189, vcc, 0, v189, vcc
	global_load_dwordx4 v[188:191], v[188:189], off offset:128
	v_mfma_f32_32x32x16_bf16 v[18:33], v[208:211], v[240:243], v[18:33]
	v_mfma_f32_32x32x16_bf16 v[2:17], v[208:211], v[244:247], v[2:17]
	v_lshl_add_u64 v[192:193], v[150:151], 0, s[14:15]
	v_add_co_u32_e32 v192, vcc, s47, v192
	s_nop 1
	v_addc_co_u32_e32 v193, vcc, 0, v193, vcc
	global_load_dwordx4 v[192:195], v[192:193], off offset:128
	ds_read_b128 v[208:211], v130 offset:4672
	s_waitcnt lgkmcnt(4)
	v_mfma_f32_32x32x16_bf16 v[114:129], v[200:203], v[212:215], v[114:129]
	ds_read_b128 v[204:207], v130 offset:96
	ds_read_b128 v[232:235], v133 offset:18528
	s_waitcnt lgkmcnt(5)
	v_mfma_f32_32x32x16_bf16 v[98:113], v[200:203], v[216:219], v[98:113]
	v_lshl_add_u64 v[196:197], v[150:151], 0, s[14:15]
	v_add_co_u32_e32 v196, vcc, s48, v196
	s_nop 1
	v_addc_co_u32_e32 v197, vcc, 0, v197, vcc
	global_load_dwordx4 v[196:199], v[196:197], off offset:128
	ds_read_b128 v[236:239], v133 offset:23136
	s_waitcnt lgkmcnt(5)
	v_mfma_f32_32x32x16_bf16 v[82:97], v[200:203], v[224:227], v[82:97]
	ds_read_b128 v[240:243], v133 offset:27744
	s_waitcnt lgkmcnt(5)
	v_mfma_f32_32x32x16_bf16 v[66:81], v[200:203], v[228:231], v[66:81]
	ds_read_b128 v[244:247], v133 offset:32352
	s_waitcnt lgkmcnt(5)
	v_mfma_f32_32x32x16_bf16 v[50:65], v[208:211], v[212:215], v[50:65]
	v_mfma_f32_32x32x16_bf16 v[34:49], v[208:211], v[216:219], v[34:49]
	v_mfma_f32_32x32x16_bf16 v[18:33], v[208:211], v[224:227], v[18:33]
	v_mfma_f32_32x32x16_bf16 v[2:17], v[208:211], v[228:231], v[2:17]
	ds_read_b128 v[208:211], v130 offset:4704
	s_waitcnt lgkmcnt(4)
	v_mfma_f32_32x32x16_bf16 v[114:129], v[204:207], v[232:235], v[114:129]
	s_waitcnt lgkmcnt(3)
	v_mfma_f32_32x32x16_bf16 v[98:113], v[204:207], v[236:239], v[98:113]
	s_waitcnt lgkmcnt(2)
	v_mfma_f32_32x32x16_bf16 v[82:97], v[204:207], v[240:243], v[82:97]
	s_waitcnt lgkmcnt(1)
	v_mfma_f32_32x32x16_bf16 v[66:81], v[204:207], v[244:247], v[66:81]
	s_waitcnt lgkmcnt(0)
	v_mfma_f32_32x32x16_bf16 v[50:65], v[208:211], v[232:235], v[50:65]
	v_mfma_f32_32x32x16_bf16 v[34:49], v[208:211], v[236:239], v[34:49]
	v_mfma_f32_32x32x16_bf16 v[18:33], v[208:211], v[240:243], v[18:33]
	v_mfma_f32_32x32x16_bf16 v[2:17], v[208:211], v[244:247], v[2:17]
	s_setprio 0
	s_add_u32 s14, s14, 0x80
	s_addc_u32 s15, s15, 0
	s_cmpk_lg_i32 s14, 0x700
	s_barrier
	s_waitcnt vmcnt(11)
	ds_write_b128 v132, v[152:155]
	v_lshl_add_u64 v[152:153], v[148:149], 0, s[14:15]
	v_add_co_u32_e32 v152, vcc, s37, v152
	s_nop 1
	v_addc_co_u32_e32 v153, vcc, 0, v153, vcc
	global_load_dwordx4 v[152:155], v[152:153], off offset:384
	s_waitcnt vmcnt(11)
	ds_write_b128 v132, v[156:159] offset:4608
	v_lshl_add_u64 v[156:157], v[148:149], 0, s[14:15]
	v_add_co_u32_e32 v156, vcc, s38, v156
	s_nop 1
	v_addc_co_u32_e32 v157, vcc, 0, v157, vcc
	global_load_dwordx4 v[156:159], v[156:157], off offset:384
	s_waitcnt vmcnt(11)
	ds_write_b128 v132, v[160:163] offset:9216
	v_lshl_add_u64 v[160:161], v[148:149], 0, s[14:15]
	v_add_co_u32_e32 v160, vcc, s39, v160
	s_nop 1
	v_addc_co_u32_e32 v161, vcc, 0, v161, vcc
	global_load_dwordx4 v[160:163], v[160:161], off offset:384
	s_waitcnt vmcnt(11)
	ds_write_b128 v132, v[164:167] offset:13824
	s_waitcnt vmcnt(10)
	ds_write_b128 v132, v[168:171] offset:18432
	s_waitcnt vmcnt(9)
	ds_write_b128 v132, v[172:175] offset:23040
	s_waitcnt vmcnt(8)
	ds_write_b128 v132, v[176:179] offset:27648
	s_waitcnt vmcnt(7)
	ds_write_b128 v132, v[180:183] offset:32256
	s_waitcnt vmcnt(6)
	ds_write_b128 v132, v[184:187] offset:36864
	s_waitcnt vmcnt(5)
	ds_write_b128 v132, v[188:191] offset:41472
	s_waitcnt vmcnt(4)
	ds_write_b128 v132, v[192:195] offset:46080
	s_waitcnt vmcnt(3)
	ds_write_b128 v132, v[196:199] offset:50688
	s_waitcnt lgkmcnt(0)
	s_barrier
	s_cbranch_scc1 .LBB0_1715
	s_setprio 1
	ds_read_b128 v[200:203], v130 offset:0
	ds_read_b128 v[212:215], v133 offset:18432
	ds_read_b128 v[216:219], v133 offset:23040
	ds_read_b128 v[224:227], v133 offset:27648
	ds_read_b128 v[228:231], v133 offset:32256
	ds_read_b128 v[208:211], v130 offset:4608
	s_waitcnt lgkmcnt(4)
	v_mfma_f32_32x32x16_bf16 v[114:129], v[200:203], v[212:215], v[114:129]
	ds_read_b128 v[204:207], v130 offset:32
	ds_read_b128 v[232:235], v133 offset:18464
	s_waitcnt lgkmcnt(5)
	v_mfma_f32_32x32x16_bf16 v[98:113], v[200:203], v[216:219], v[98:113]
	v_lshl_add_u64 v[164:165], v[148:149], 0, s[14:15]
	v_add_co_u32_e32 v164, vcc, s40, v164
	s_nop 1
	v_addc_co_u32_e32 v165, vcc, 0, v165, vcc
	global_load_dwordx4 v[164:167], v[164:165], off offset:384
	ds_read_b128 v[236:239], v133 offset:23072
	s_waitcnt lgkmcnt(5)
	v_mfma_f32_32x32x16_bf16 v[82:97], v[200:203], v[224:227], v[82:97]
	ds_read_b128 v[240:243], v133 offset:27680
	s_waitcnt lgkmcnt(5)
	v_mfma_f32_32x32x16_bf16 v[66:81], v[200:203], v[228:231], v[66:81]
	v_lshl_add_u64 v[168:169], v[150:151], 0, s[14:15]
	v_add_co_u32_e32 v168, vcc, s41, v168
	s_nop 1
	v_addc_co_u32_e32 v169, vcc, 0, v169, vcc
	global_load_dwordx4 v[168:171], v[168:169], off offset:128
	ds_read_b128 v[244:247], v133 offset:32288
	s_waitcnt lgkmcnt(5)
;     ...
;   for (int kt = 0; kt < nk; ++kt) {
;     const int kn = (kt + 1 < nk) ? kt + 1 : kt;
;     GW_LOAD2(kn * 64, kn * bkstep)
;     __builtin_amdgcn_sched_barrier(0);
;     __builtin_amdgcn_s_setprio(1);
; #pragma unroll
;     for (int st = 0; st < 4; ++st) {
;       bf16x8 a0 = *(const bf16x8*)(Ab + st * 32);
;       bf16x8 a1 = *(const bf16x8*)(Ab + 32 * LSTR + st * 32);
;       bf16x8 b0 = *(const bf16x8*)(Bb + st * 32);
;       bf16x8 b1 = *(const bf16x8*)(Bb + 32 * LSTR + st * 32);
;       bf16x8 b2 = *(const bf16x8*)(Bb + 64 * LSTR + st * 32);
;       bf16x8 b3 = *(const bf16x8*)(Bb + 96 * LSTR + st * 32);
;       acc[0][0] = mfma32(a0, b0, acc[0][0]);
;       acc[0][1] = mfma32(a0, b1, acc[0][1]);
;       acc[0][2] = mfma32(a0, b2, acc[0][2]);
;       acc[0][3] = mfma32(a0, b3, acc[0][3]);
;       acc[1][0] = mfma32(a1, b0, acc[1][0]);
;       acc[1][1] = mfma32(a1, b1, acc[1][1]);
;       acc[1][2] = mfma32(a1, b2, acc[1][2]);
;       acc[1][3] = mfma32(a1, b3, acc[1][3]);
;     }
;     __builtin_amdgcn_s_setprio(0);
;     __builtin_amdgcn_sched_barrier(0);
;     __syncthreads();
;     GW_STORE()
;     __syncthreads();
	v_mfma_f32_32x32x16_bf16 v[50:65], v[208:211], v[212:215], v[50:65]
	v_mfma_f32_32x32x16_bf16 v[34:49], v[208:211], v[216:219], v[34:49]
	v_lshl_add_u64 v[172:173], v[150:151], 0, s[14:15]
	v_add_co_u32_e32 v172, vcc, s42, v172
	s_nop 1
	v_addc_co_u32_e32 v173, vcc, 0, v173, vcc
	global_load_dwordx4 v[172:175], v[172:173], off offset:128
	v_mfma_f32_32x32x16_bf16 v[18:33], v[208:211], v[224:227], v[18:33]
	v_mfma_f32_32x32x16_bf16 v[2:17], v[208:211], v[228:231], v[2:17]
	v_lshl_add_u64 v[176:177], v[150:151], 0, s[14:15]
	v_add_co_u32_e32 v176, vcc, s43, v176
	s_nop 1
	v_addc_co_u32_e32 v177, vcc, 0, v177, vcc
	global_load_dwordx4 v[176:179], v[176:177], off offset:128
	ds_read_b128 v[208:211], v130 offset:4640
	s_waitcnt lgkmcnt(4)
	v_mfma_f32_32x32x16_bf16 v[114:129], v[204:207], v[232:235], v[114:129]
	ds_read_b128 v[200:203], v130 offset:64
	ds_read_b128 v[212:215], v133 offset:18496
	s_waitcnt lgkmcnt(5)
	v_mfma_f32_32x32x16_bf16 v[98:113], v[204:207], v[236:239], v[98:113]
	v_lshl_add_u64 v[180:181], v[150:151], 0, s[14:15]
	v_add_co_u32_e32 v180, vcc, s44, v180
	s_nop 1
	v_addc_co_u32_e32 v181, vcc, 0, v181, vcc
	global_load_dwordx4 v[180:183], v[180:181], off offset:128
	ds_read_b128 v[216:219], v133 offset:23104
	s_waitcnt lgkmcnt(5)
	v_mfma_f32_32x32x16_bf16 v[82:97], v[204:207], v[240:243], v[82:97]
	ds_read_b128 v[224:227], v133 offset:27712
	s_waitcnt lgkmcnt(5)
	v_mfma_f32_32x32x16_bf16 v[66:81], v[204:207], v[244:247], v[66:81]
	v_lshl_add_u64 v[184:185], v[150:151], 0, s[14:15]
	v_add_co_u32_e32 v184, vcc, s45, v184
	s_nop 1
	v_addc_co_u32_e32 v185, vcc, 0, v185, vcc
	global_load_dwordx4 v[184:187], v[184:185], off offset:128
	ds_read_b128 v[228:231], v133 offset:32320
	s_waitcnt lgkmcnt(5)
	v_mfma_f32_32x32x16_bf16 v[50:65], v[208:211], v[232:235], v[50:65]
	v_mfma_f32_32x32x16_bf16 v[34:49], v[208:211], v[236:239], v[34:49]
	v_lshl_add_u64 v[188:189], v[150:151], 0, s[14:15]
	v_add_co_u32_e32 v188, vcc, s46, v188
	s_nop 1
	v_addc_co_u32_e32 v189, vcc, 0, v189, vcc
	global_load_dwordx4 v[188:191], v[188:189], off offset:128
	v_mfma_f32_32x32x16_bf16 v[18:33], v[208:211], v[240:243], v[18:33]
	v_mfma_f32_32x32x16_bf16 v[2:17], v[208:211], v[244:247], v[2:17]
	v_lshl_add_u64 v[192:193], v[150:151], 0, s[14:15]
	v_add_co_u32_e32 v192, vcc, s47, v192
	s_nop 1
	v_addc_co_u32_e32 v193, vcc, 0, v193, vcc
	global_load_dwordx4 v[192:195], v[192:193], off offset:128
	ds_read_b128 v[208:211], v130 offset:4672
	s_waitcnt lgkmcnt(4)
	v_mfma_f32_32x32x16_bf16 v[114:129], v[200:203], v[212:215], v[114:129]
	ds_read_b128 v[204:207], v130 offset:96
	ds_read_b128 v[232:235], v133 offset:18528
	s_waitcnt lgkmcnt(5)
	v_mfma_f32_32x32x16_bf16 v[98:113], v[200:203], v[216:219], v[98:113]
	v_lshl_add_u64 v[196:197], v[150:151], 0, s[14:15]
	v_add_co_u32_e32 v196, vcc, s48, v196
	s_nop 1
	v_addc_co_u32_e32 v197, vcc, 0, v197, vcc
	global_load_dwordx4 v[196:199], v[196:197], off offset:128
	ds_read_b128 v[236:239], v133 offset:23136
	s_waitcnt lgkmcnt(5)
	v_mfma_f32_32x32x16_bf16 v[82:97], v[200:203], v[224:227], v[82:97]
	ds_read_b128 v[240:243], v133 offset:27744
	s_waitcnt lgkmcnt(5)
	v_mfma_f32_32x32x16_bf16 v[66:81], v[200:203], v[228:231], v[66:81]
	ds_read_b128 v[244:247], v133 offset:32352
	s_waitcnt lgkmcnt(5)
	v_mfma_f32_32x32x16_bf16 v[50:65], v[208:211], v[212:215], v[50:65]
	v_mfma_f32_32x32x16_bf16 v[34:49], v[208:211], v[216:219], v[34:49]
	v_mfma_f32_32x32x16_bf16 v[18:33], v[208:211], v[224:227], v[18:33]
	v_mfma_f32_32x32x16_bf16 v[2:17], v[208:211], v[228:231], v[2:17]
	ds_read_b128 v[208:211], v130 offset:4704
	s_waitcnt lgkmcnt(4)
	v_mfma_f32_32x32x16_bf16 v[114:129], v[204:207], v[232:235], v[114:129]
	s_waitcnt lgkmcnt(3)
	v_mfma_f32_32x32x16_bf16 v[98:113], v[204:207], v[236:239], v[98:113]
	s_waitcnt lgkmcnt(2)
	v_mfma_f32_32x32x16_bf16 v[82:97], v[204:207], v[240:243], v[82:97]
	s_waitcnt lgkmcnt(1)
	v_mfma_f32_32x32x16_bf16 v[66:81], v[204:207], v[244:247], v[66:81]
	s_waitcnt lgkmcnt(0)
	v_mfma_f32_32x32x16_bf16 v[50:65], v[208:211], v[232:235], v[50:65]
	v_mfma_f32_32x32x16_bf16 v[34:49], v[208:211], v[236:239], v[34:49]
	v_mfma_f32_32x32x16_bf16 v[18:33], v[208:211], v[240:243], v[18:33]
	v_mfma_f32_32x32x16_bf16 v[2:17], v[208:211], v[244:247], v[2:17]
	s_setprio 0
	s_add_u32 s14, s14, 0x80
	s_addc_u32 s15, s15, 0
	s_barrier
	s_waitcnt vmcnt(11)
	ds_write_b128 v132, v[152:155]
	s_waitcnt vmcnt(10)
	ds_write_b128 v132, v[156:159] offset:4608
	s_waitcnt vmcnt(9)
	ds_write_b128 v132, v[160:163] offset:9216
	s_waitcnt vmcnt(8)
	ds_write_b128 v132, v[164:167] offset:13824
	s_waitcnt vmcnt(7)
	ds_write_b128 v132, v[168:171] offset:18432
	s_waitcnt vmcnt(6)
	ds_write_b128 v132, v[172:175] offset:23040
	s_waitcnt vmcnt(5)
	ds_write_b128 v132, v[176:179] offset:27648
	s_waitcnt vmcnt(4)
	ds_write_b128 v132, v[180:183] offset:32256
	s_waitcnt vmcnt(3)
	ds_write_b128 v132, v[184:187] offset:36864
	s_waitcnt vmcnt(2)
	ds_write_b128 v132, v[188:191] offset:41472
	s_waitcnt vmcnt(1)
	ds_write_b128 v132, v[192:195] offset:46080
	s_waitcnt vmcnt(0)
	ds_write_b128 v132, v[196:199] offset:50688
	s_waitcnt lgkmcnt(0)
	s_barrier
;     ...
;   for (int kt = 0; kt < nk; ++kt) {
;     const int kn = (kt + 1 < nk) ? kt + 1 : kt;
;     GW_LOAD2(kn * 64, kn * bkstep)
;     __builtin_amdgcn_sched_barrier(0);
;     __builtin_amdgcn_s_setprio(1);
; #pragma unroll
;     for (int st = 0; st < 4; ++st) {
;       bf16x8 a0 = *(const bf16x8*)(Ab + st * 32);
;       bf16x8 a1 = *(const bf16x8*)(Ab + 32 * LSTR + st * 32);
;       bf16x8 b0 = *(const bf16x8*)(Bb + st * 32);
;       bf16x8 b1 = *(const bf16x8*)(Bb + 32 * LSTR + st * 32);
;       bf16x8 b2 = *(const bf16x8*)(Bb + 64 * LSTR + st * 32);
;       bf16x8 b3 = *(const bf16x8*)(Bb + 96 * LSTR + st * 32);
;       acc[0][0] = mfma32(a0, b0, acc[0][0]);
;       acc[0][1] = mfma32(a0, b1, acc[0][1]);
;       acc[0][2] = mfma32(a0, b2, acc[0][2]);
;       acc[0][3] = mfma32(a0, b3, acc[0][3]);
;       acc[1][0] = mfma32(a1, b0, acc[1][0]);
;       acc[1][1] = mfma32(a1, b1, acc[1][1]);
;       acc[1][2] = mfma32(a1, b2, acc[1][2]);
;       acc[1][3] = mfma32(a1, b3, acc[1][3]);
;     }
;     __builtin_amdgcn_s_setprio(0);
;     __builtin_amdgcn_sched_barrier(0);
;     __syncthreads();
;     GW_STORE()
;     __syncthreads();
	v_add_co_u32_e32 v160, vcc, 0x10000, v138
	s_nop 0
	s_nop 0
	s_nop 0
	v_addc_co_u32_e32 v161, vcc, 0, v139, vcc
	v_add_co_u32_e32 v164, vcc, 0x20000, v138
	s_nop 0
	v_addc_co_u32_e32 v165, vcc, 0, v139, vcc
	v_add_co_u32_e32 v168, vcc, 0x30000, v138
	s_lshl_b64 s[12:13], s[12:13], 7
	s_nop 0
	v_addc_co_u32_e32 v169, vcc, 0, v139, vcc
	v_add_co_u32_e32 v172, vcc, 0x40000, v138
	s_nop 0
	v_addc_co_u32_e32 v173, vcc, 0, v139, vcc
	v_add_co_u32_e32 v176, vcc, 0x50000, v138
	s_mov_b32 s53, 0
	s_nop 0
	v_addc_co_u32_e32 v177, vcc, 0, v139, vcc
	v_add_co_u32_e32 v180, vcc, 0x60000, v138
	s_nop 0
	v_addc_co_u32_e32 v181, vcc, 0, v139, vcc
	v_add_co_u32_e32 v138, vcc, 0x70000, v138
	s_nop 1
	v_addc_co_u32_e32 v139, vcc, 0, v139, vcc
	s_nop 0
	s_setprio 1
	ds_read_b128 v[188:191], v130 offset:0
	ds_read_b128 v[200:203], v133 offset:18432
	ds_read_b128 v[204:207], v133 offset:23040
	ds_read_b128 v[208:211], v133 offset:27648
	ds_read_b128 v[212:215], v133 offset:32256
	ds_read_b128 v[196:199], v130 offset:4608
	s_waitcnt lgkmcnt(4)
	v_mfma_f32_32x32x16_bf16 v[114:129], v[188:191], v[200:203], v[114:129]
	ds_read_b128 v[192:195], v130 offset:32
	ds_read_b128 v[216:219], v133 offset:18464
	s_waitcnt lgkmcnt(5)
	v_mfma_f32_32x32x16_bf16 v[98:113], v[188:191], v[204:207], v[98:113]
	ds_read_b128 v[224:227], v133 offset:23072
	s_waitcnt lgkmcnt(5)
	v_mfma_f32_32x32x16_bf16 v[82:97], v[188:191], v[208:211], v[82:97]
	ds_read_b128 v[228:231], v133 offset:27680
	s_waitcnt lgkmcnt(5)
	v_mfma_f32_32x32x16_bf16 v[66:81], v[188:191], v[212:215], v[66:81]
	ds_read_b128 v[232:235], v133 offset:32288
	s_waitcnt lgkmcnt(5)
	v_mfma_f32_32x32x16_bf16 v[50:65], v[196:199], v[200:203], v[50:65]
	v_mfma_f32_32x32x16_bf16 v[34:49], v[196:199], v[204:207], v[34:49]
	v_mfma_f32_32x32x16_bf16 v[18:33], v[196:199], v[208:211], v[18:33]
	v_mfma_f32_32x32x16_bf16 v[2:17], v[196:199], v[212:215], v[2:17]
	ds_read_b128 v[196:199], v130 offset:4640
	s_waitcnt lgkmcnt(4)
	v_mfma_f32_32x32x16_bf16 v[114:129], v[192:195], v[216:219], v[114:129]
	ds_read_b128 v[188:191], v130 offset:64
	ds_read_b128 v[200:203], v133 offset:18496
	s_waitcnt lgkmcnt(5)
	v_mfma_f32_32x32x16_bf16 v[98:113], v[192:195], v[224:227], v[98:113]
	ds_read_b128 v[204:207], v133 offset:23104
	s_waitcnt lgkmcnt(5)
	v_mfma_f32_32x32x16_bf16 v[82:97], v[192:195], v[228:231], v[82:97]
	ds_read_b128 v[208:211], v133 offset:27712
	s_waitcnt lgkmcnt(5)
	v_mfma_f32_32x32x16_bf16 v[66:81], v[192:195], v[232:235], v[66:81]
	ds_read_b128 v[212:215], v133 offset:32320
	s_waitcnt lgkmcnt(5)
	v_mfma_f32_32x32x16_bf16 v[50:65], v[196:199], v[216:219], v[50:65]
	v_mfma_f32_32x32x16_bf16 v[34:49], v[196:199], v[224:227], v[34:49]
	v_mfma_f32_32x32x16_bf16 v[18:33], v[196:199], v[228:231], v[18:33]
	v_mfma_f32_32x32x16_bf16 v[2:17], v[196:199], v[232:235], v[2:17]
	ds_read_b128 v[196:199], v130 offset:4672
	s_waitcnt lgkmcnt(4)
	v_mfma_f32_32x32x16_bf16 v[114:129], v[188:191], v[200:203], v[114:129]
	ds_read_b128 v[192:195], v130 offset:96
	ds_read_b128 v[216:219], v133 offset:18528
	s_waitcnt lgkmcnt(5)
	v_mfma_f32_32x32x16_bf16 v[98:113], v[188:191], v[204:207], v[98:113]
	ds_read_b128 v[224:227], v133 offset:23136
	s_waitcnt lgkmcnt(5)
	v_mfma_f32_32x32x16_bf16 v[82:97], v[188:191], v[208:211], v[82:97]
	ds_read_b128 v[228:231], v133 offset:27744
	s_waitcnt lgkmcnt(5)
	v_mfma_f32_32x32x16_bf16 v[66:81], v[188:191], v[212:215], v[66:81]
	ds_read_b128 v[232:235], v133 offset:32352
	s_waitcnt lgkmcnt(5)
	v_mfma_f32_32x32x16_bf16 v[50:65], v[196:199], v[200:203], v[50:65]
	v_mfma_f32_32x32x16_bf16 v[34:49], v[196:199], v[204:207], v[34:49]
	v_mfma_f32_32x32x16_bf16 v[18:33], v[196:199], v[208:211], v[18:33]
	v_mfma_f32_32x32x16_bf16 v[2:17], v[196:199], v[212:215], v[2:17]
	ds_read_b128 v[196:199], v130 offset:4704
	s_waitcnt lgkmcnt(4)
	v_mfma_f32_32x32x16_bf16 v[114:129], v[192:195], v[216:219], v[114:129]
	s_waitcnt lgkmcnt(3)
	v_mfma_f32_32x32x16_bf16 v[98:113], v[192:195], v[224:227], v[98:113]
	s_waitcnt lgkmcnt(2)
	v_mfma_f32_32x32x16_bf16 v[82:97], v[192:195], v[228:231], v[82:97]
	s_waitcnt lgkmcnt(1)
	v_mfma_f32_32x32x16_bf16 v[66:81], v[192:195], v[232:235], v[66:81]
	s_waitcnt lgkmcnt(0)
	v_mfma_f32_32x32x16_bf16 v[50:65], v[196:199], v[216:219], v[50:65]
	v_mfma_f32_32x32x16_bf16 v[34:49], v[196:199], v[224:227], v[34:49]
	v_mfma_f32_32x32x16_bf16 v[18:33], v[196:199], v[228:231], v[18:33]
	v_mfma_f32_32x32x16_bf16 v[2:17], v[196:199], v[232:235], v[2:17]
	s_setprio 0
	s_mov_b64 s[16:17], -1
	s_barrier
	s_waitcnt lgkmcnt(0)

; #define GW_LOAD(KOFF) GW_LOAD2(KOFF, 0)
;   int tid = threadIdx.x;
;   asm volatile("" : "+v"(tid));
;   const int lane = tid & 63, wave = tid >> 6;
;   const int wm = wave >> 1, wn = wave & 1;
;   const int lr = tid >> 3, kc = tid & 7;
;   const u16* ap0 = arow(lr) + kc * 8;
;   const u16* ap1 = arow(lr + 32) + kc * 8;
;   const u16* ap2 = arow(lr + 64) + kc * 8;
;   const u16* ap3 = arow(lr + 96) + kc * 8;
;   const u16* bp0 = Bt + (size_t)lr * ldb + kc * 8;
;   const size_t bstep = 32 * ldb;
;   const int so = lr * LSTR + kc * 16;
;   uint4 ra0, ra1, ra2, ra3, rb0, rb1, rb2, rb3, rb4, rb5, rb6, rb7;
;     ...
;   GW_LOAD(0)
;   GW_STORE()
; __device__ __forceinline__ void expert1_tile(const Params& P, int e, int mt, int ntw, char* smem) {
;   f32x16 acc[2][4];
; #pragma unroll
;   for (int i = 0; i < 2; ++i)
; #pragma unroll
;     for (int j = 0; j < 4; ++j)
; #pragma unroll
;       for (int r = 0; r < 16; ++r) acc[i][j][r] = 0.f;
;   const int* ridx = WSP(int, OFF_ROWIDX) + e * EROWS + mt * 128;
;   const u16* H = WSP(u16, OFF_H);
;   const u16* Bt = WSP(u16, OFF_WGU) + (size_t)e * 4096 * DM + (size_t)ntw * 256 * 64;
;   gemm_wide([&](int rr) { return H + (size_t)ridx[rr] * DM; }, Bt, 64, DM, smem, acc, 4096 * 64);
.LBB0_2063:
	s_lshl_b32 s12, s40, 6
	s_and_b32 s12, s12, 0x1c0
	s_and_b32 s13, s40, 0xfffffe00
	s_or_b32 s12, s12, s13
	s_bfe_u32 s13, s40, 0x60003
	s_or_b32 s14, s12, s13
	s_and_b64 s[12:13], s[0:1], exec
	s_cselect_b32 s13, s14, s40
	s_cmpk_gt_i32 s13, 0x1fff
	s_cbranch_scc1 .LBB0_2062
	s_ashr_i32 s12, s13, 31
	s_lshr_b32 s12, s12, 25
	s_add_i32 s12, s13, s12
	s_ashr_i32 s14, s12, 7
	s_and_b32 s12, s12, 0xffffff80
	s_lshl_b32 s15, s14, 3
	s_sub_i32 s12, s13, s12
	s_and_b32 s13, s13, 7
	s_or_b32 s13, s15, s13
	s_lshr_b32 s14, s14, 27
	s_add_i32 s15, s13, s14
	s_ashr_i32 s14, s15, 5
	s_mul_i32 s16, s14, 0x1100
	s_and_b32 s15, s15, 0x1ffffe0
	s_ashr_i32 s17, s16, 31
	s_ashr_i32 s12, s12, 3
	s_sub_i32 s13, s13, s15
	s_lshl_b64 s[16:17], s[16:17], 2
	s_add_u32 s15, s23, s16
	s_addc_u32 s20, s24, s17
	s_lshl_b32 s16, s13, 7
	s_ashr_i32 s17, s16, 31
	s_lshl_b64 s[18:19], s[16:17], 2
	v_mov_b32_e32 v57, v134
	s_add_u32 s18, s15, s18
	s_addc_u32 s19, s20, s19
	v_ashrrev_i32_e32 v106, 3, v57
	v_ashrrev_i32_e32 v107, 31, v106
	v_lshl_add_u64 v[2:3], v[106:107], 2, s[18:19]
	global_load_dword v10, v[2:3], off
	global_load_dword v12, v[2:3], off offset:128
	global_load_dword v14, v[2:3], off offset:256
	global_load_dword v16, v[2:3], off offset:384
	s_ashr_i32 s15, s14, 31
	s_lshl_b64 s[18:19], s[14:15], 23
	s_add_u32 s15, s25, s18
	s_addc_u32 s43, s26, s19
	s_ashr_i32 s13, s12, 31
	s_lshl_b64 s[20:21], s[12:13], 15
	s_add_u32 s42, s15, s20
	v_lshlrev_b32_e32 v11, 4, v57
	v_lshlrev_b64 v[108:109], 7, v[106:107]
	s_addc_u32 s43, s43, s21
	v_and_b32_e32 v130, 0x70, v11
	v_lshl_add_u64 v[18:19], s[42:43], 0, v[108:109]
	v_lshl_add_u64 v[138:139], v[18:19], 0, v[130:131]
	v_add_co_u32_e32 v18, vcc, s28, v138
	global_load_dwordx4 v[58:61], v[138:139], off
	s_nop 0
	v_addc_co_u32_e32 v19, vcc, 0, v139, vcc
	v_add_co_u32_e32 v20, vcc, s29, v138
	s_add_u32 s13, s18, s20
	s_nop 0
	v_addc_co_u32_e32 v21, vcc, 0, v139, vcc
	v_add_co_u32_e32 v22, vcc, s30, v138
	v_and_b32_e32 v107, 31, v57
	s_nop 0
	v_addc_co_u32_e32 v23, vcc, 0, v139, vcc
	v_add_co_u32_e32 v24, vcc, s31, v138
	v_lshrrev_b32_e32 v118, 1, v57
	s_nop 0
	v_addc_co_u32_e32 v25, vcc, 0, v139, vcc
	global_load_dwordx4 v[62:65], v[18:19], off offset:-4096
	global_load_dwordx4 v[66:69], v[18:19], off
	global_load_dwordx4 v[70:73], v[20:21], off offset:-4096
	global_load_dwordx4 v[74:77], v[20:21], off
	global_load_dwordx4 v[78:81], v[22:23], off offset:-4096
	global_load_dwordx4 v[82:85], v[22:23], off
	global_load_dwordx4 v[86:89], v[24:25], off
	v_lshlrev_b32_e32 v57, 1, v57
	s_addc_u32 s15, s19, s21
	v_and_or_b32 v119, v118, s33, v107
	v_and_or_b32 v57, v57, s34, v107
	s_add_u32 s18, s90, s13
	v_mov_b32_e32 v2, 0
	v_and_b32_e32 v118, 16, v118
	v_mad_u64_u32 v[132:133], s[42:43], v106, s27, v[130:131]
	v_mul_lo_u32 v106, v119, s27
	v_mul_u32_u24_e32 v57, 0x90, v57
	s_addc_u32 s19, s91, s15
	s_mov_b32 s41, 14
	v_mov_b32_e32 v3, v2
	v_mov_b32_e32 v4, v2
	v_mov_b32_e32 v5, v2
	v_mov_b32_e32 v6, v2
	v_mov_b32_e32 v7, v2
	v_mov_b32_e32 v8, v2
	v_mov_b32_e32 v9, v2
	v_mov_b32_e32 v18, v2
	v_mov_b32_e32 v19, v2
	v_mov_b32_e32 v20, v2
	v_mov_b32_e32 v21, v2
	v_mov_b32_e32 v22, v2
	v_mov_b32_e32 v23, v2
	v_mov_b32_e32 v24, v2
	v_mov_b32_e32 v25, v2
	v_mov_b32_e32 v26, v2
	v_mov_b32_e32 v27, v2
	v_mov_b32_e32 v28, v2
	v_mov_b32_e32 v29, v2
	v_mov_b32_e32 v30, v2
	v_mov_b32_e32 v31, v2
	v_mov_b32_e32 v32, v2
	v_mov_b32_e32 v33, v2
	v_mov_b32_e32 v34, v2
	v_mov_b32_e32 v35, v2
	v_mov_b32_e32 v36, v2
	v_mov_b32_e32 v37, v2
	v_mov_b32_e32 v38, v2
	v_mov_b32_e32 v39, v2
	s_waitcnt vmcnt(11)
	v_ashrrev_i32_e32 v11, 31, v10
	s_waitcnt vmcnt(10)
	v_ashrrev_i32_e32 v13, 31, v12
	s_waitcnt vmcnt(9)
	v_ashrrev_i32_e32 v15, 31, v14
	s_waitcnt vmcnt(8)
	v_ashrrev_i32_e32 v17, 31, v16
	v_lshlrev_b64 v[110:111], 11, v[10:11]
	v_lshlrev_b64 v[112:113], 11, v[12:13]
	v_lshlrev_b64 v[114:115], 11, v[14:15]
	v_lshlrev_b64 v[116:117], 11, v[16:17]
	v_lshl_add_u64 v[10:11], s[2:3], 0, v[110:111]
	v_lshl_add_u64 v[12:13], s[2:3], 0, v[112:113]
	v_lshl_add_u64 v[14:15], s[2:3], 0, v[114:115]
	v_lshl_add_u64 v[16:17], s[2:3], 0, v[116:117]
	v_lshl_add_u64 v[140:141], v[10:11], 0, v[130:131]
	v_lshl_add_u64 v[142:143], v[12:13], 0, v[130:131]
	v_lshl_add_u64 v[144:145], v[14:15], 0, v[130:131]
	v_lshl_add_u64 v[146:147], v[16:17], 0, v[130:131]
	global_load_dwordx4 v[90:93], v[140:141], off
	global_load_dwordx4 v[94:97], v[142:143], off
	global_load_dwordx4 v[98:101], v[144:145], off
	global_load_dwordx4 v[102:105], v[146:147], off
	v_mov_b32_e32 v10, v2
	v_mov_b32_e32 v11, v2
	v_mov_b32_e32 v12, v2
	v_mov_b32_e32 v13, v2
	v_mov_b32_e32 v14, v2
	v_mov_b32_e32 v15, v2
	v_mov_b32_e32 v16, v2
	v_mov_b32_e32 v17, v2
	v_mov_b32_e32 v40, v2
	v_mov_b32_e32 v41, v2
	v_mov_b32_e32 v42, v2
	v_mov_b32_e32 v43, v2
	v_mov_b32_e32 v44, v2
	v_mov_b32_e32 v45, v2
	v_mov_b32_e32 v46, v2
	v_mov_b32_e32 v47, v2
	v_mov_b32_e32 v48, v2
	v_mov_b32_e32 v49, v2
	v_mov_b32_e32 v50, v2
	v_mov_b32_e32 v51, v2
	v_mov_b32_e32 v52, v2
	v_mov_b32_e32 v53, v2
	v_mov_b32_e32 v54, v2
	v_mov_b32_e32 v55, v2
	v_mov_b32_e32 v56, v2
	v_add_u32_e32 v133, v106, v118
	v_add_u32_e32 v137, v57, v118
	v_lshl_add_u64 v[148:149], s[18:19], 0, v[108:109]
	v_lshl_add_u64 v[150:151], s[6:7], 0, v[110:111]
	v_lshl_add_u64 v[152:153], s[6:7], 0, v[112:113]
	v_lshl_add_u64 v[154:155], s[6:7], 0, v[114:115]
	v_lshl_add_u64 v[156:157], s[6:7], 0, v[116:117]
	v_mov_b32_e32 v57, v2
	v_mov_b32_e32 v106, v2
	v_mov_b32_e32 v107, v2
	v_mov_b32_e32 v108, v2
	v_mov_b32_e32 v109, v2
	v_mov_b32_e32 v110, v2
	v_mov_b32_e32 v111, v2
	v_mov_b32_e32 v112, v2
	v_mov_b32_e32 v113, v2
	v_mov_b32_e32 v114, v2
	v_mov_b32_e32 v115, v2
	v_mov_b32_e32 v116, v2
	v_mov_b32_e32 v117, v2
	v_mov_b32_e32 v118, v2
	v_mov_b32_e32 v119, v2
	v_mov_b32_e32 v120, v2
	v_mov_b32_e32 v121, v2
	v_mov_b32_e32 v122, v2
	v_mov_b32_e32 v123, v2
	v_mov_b32_e32 v124, v2
	v_mov_b32_e32 v125, v2
	v_mov_b32_e32 v126, v2
	v_mov_b32_e32 v127, v2
	v_mov_b32_e32 v128, v2
	v_mov_b32_e32 v129, v2
	s_waitcnt vmcnt(11)
; #define GW_LOAD(KOFF) GW_LOAD2(KOFF, 0)
;     ...
;   GW_LOAD(0)
;   GW_STORE()
;   __syncthreads();
;   const int nk = K >> 6;
;   const char* Ab = smem + (wm * 64 + (lane & 31)) * LSTR + (lane >> 5) * 16;
;   const char* Bb = smem + WTILE_A + (wn * 128 + (lane & 31)) * LSTR + (lane >> 5) * 16;
;   for (int kt = 0; kt < nk; ++kt) {
;     const int kn = (kt + 1 < nk) ? kt + 1 : kt;
;     GW_LOAD2(kn * 64, kn * bkstep)
;     __builtin_amdgcn_sched_barrier(0);
;     __builtin_amdgcn_s_setprio(1);
; #pragma unroll
;     for (int st = 0; st < 4; ++st) {
;       bf16x8 a0 = *(const bf16x8*)(Ab + st * 32);
;       bf16x8 a1 = *(const bf16x8*)(Ab + 32 * LSTR + st * 32);
;       bf16x8 b0 = *(const bf16x8*)(Bb + st * 32);
;       bf16x8 b1 = *(const bf16x8*)(Bb + 32 * LSTR + st * 32);
;       bf16x8 b2 = *(const bf16x8*)(Bb + 64 * LSTR + st * 32);
;       bf16x8 b3 = *(const bf16x8*)(Bb + 96 * LSTR + st * 32);
;       acc[0][0] = mfma32(a0, b0, acc[0][0]);
;       acc[0][1] = mfma32(a0, b1, acc[0][1]);
;       acc[0][2] = mfma32(a0, b2, acc[0][2]);
;       acc[0][3] = mfma32(a0, b3, acc[0][3]);
;       acc[1][0] = mfma32(a1, b0, acc[1][0]);
;       acc[1][1] = mfma32(a1, b1, acc[1][1]);
;       acc[1][2] = mfma32(a1, b2, acc[1][2]);
;       acc[1][3] = mfma32(a1, b3, acc[1][3]);
;     }
	ds_write_b128 v132, v[58:61] offset:18432
	s_waitcnt vmcnt(10)
	ds_write_b128 v132, v[62:65] offset:23040
	s_waitcnt vmcnt(9)
	ds_write_b128 v132, v[66:69] offset:27648
	s_waitcnt vmcnt(8)
	ds_write_b128 v132, v[70:73] offset:32256
	s_waitcnt vmcnt(7)
	ds_write_b128 v132, v[74:77] offset:36864
	s_waitcnt vmcnt(6)
	ds_write_b128 v132, v[78:81] offset:41472
	s_waitcnt vmcnt(5)
	ds_write_b128 v132, v[82:85] offset:46080
	s_waitcnt vmcnt(4)
	ds_write_b128 v132, v[86:89] offset:50688
	s_waitcnt vmcnt(3)
	ds_write_b128 v132, v[90:93]
	s_waitcnt vmcnt(2)
	ds_write_b128 v132, v[94:97] offset:4608
	s_waitcnt vmcnt(1)
	ds_write_b128 v132, v[98:101] offset:9216
	s_waitcnt vmcnt(0)
	ds_write_b128 v132, v[102:105] offset:13824
	v_mov_b32_e32 v58, v2
	v_mov_b32_e32 v59, v2
	v_mov_b32_e32 v60, v2
	v_mov_b32_e32 v61, v2
	v_mov_b32_e32 v62, v2
	v_mov_b32_e32 v63, v2
	v_mov_b32_e32 v64, v2
	v_mov_b32_e32 v65, v2
	v_mov_b32_e32 v66, v2
	v_mov_b32_e32 v67, v2
	v_mov_b32_e32 v68, v2
	v_mov_b32_e32 v69, v2
	v_mov_b32_e32 v70, v2
	v_mov_b32_e32 v71, v2
	v_mov_b32_e32 v72, v2
	v_mov_b32_e32 v73, v2
	v_mov_b32_e32 v74, v2
	v_mov_b32_e32 v75, v2
	v_mov_b32_e32 v76, v2
	v_mov_b32_e32 v77, v2
	v_mov_b32_e32 v78, v2
	v_mov_b32_e32 v79, v2
	v_mov_b32_e32 v80, v2
	v_mov_b32_e32 v81, v2
	v_mov_b32_e32 v82, v2
	v_mov_b32_e32 v83, v2
	v_mov_b32_e32 v84, v2
	v_mov_b32_e32 v85, v2
	v_mov_b32_e32 v86, v2
	v_mov_b32_e32 v87, v2
	v_mov_b32_e32 v88, v2
	v_mov_b32_e32 v89, v2
	v_mov_b32_e32 v90, v2
	v_mov_b32_e32 v91, v2
	v_mov_b32_e32 v92, v2
	v_mov_b32_e32 v93, v2
	v_mov_b32_e32 v94, v2
	v_mov_b32_e32 v95, v2
	v_mov_b32_e32 v96, v2
	v_mov_b32_e32 v97, v2
	v_mov_b32_e32 v98, v2
	v_mov_b32_e32 v99, v2
	v_mov_b32_e32 v100, v2
	v_mov_b32_e32 v101, v2
	v_mov_b32_e32 v102, v2
	v_mov_b32_e32 v103, v2
	v_mov_b32_e32 v104, v2
	v_mov_b32_e32 v105, v2
	s_waitcnt lgkmcnt(0)
	s_barrier
	v_lshl_add_u64 v[158:159], v[150:151], 0, v[130:131]
	global_load_dwordx4 v[158:161], v[158:159], off
	v_lshl_add_u64 v[162:163], v[152:153], 0, v[130:131]
	global_load_dwordx4 v[162:165], v[162:163], off
	v_lshl_add_u64 v[166:167], v[154:155], 0, v[130:131]
	global_load_dwordx4 v[166:169], v[166:167], off
.LBB0_2065:
	s_setprio 1
	ds_read_b128 v[206:209], v133 offset:0
	ds_read_b128 v[218:221], v137 offset:18432
	ds_read_b128 v[224:227], v137 offset:23040
	ds_read_b128 v[228:231], v137 offset:27648
	ds_read_b128 v[232:235], v137 offset:32256
	ds_read_b128 v[214:217], v133 offset:4608
	s_waitcnt lgkmcnt(4)
	v_mfma_f32_32x32x16_bf16 v[114:129], v[206:209], v[218:221], v[114:129]
	ds_read_b128 v[210:213], v133 offset:32
	ds_read_b128 v[236:239], v137 offset:18464
	s_waitcnt lgkmcnt(5)
	v_mfma_f32_32x32x16_bf16 v[98:113], v[206:209], v[224:227], v[98:113]
	v_lshl_add_u64 v[170:171], v[156:157], 0, v[130:131]
	global_load_dwordx4 v[170:173], v[170:171], off
	ds_read_b128 v[240:243], v137 offset:23072
	s_waitcnt lgkmcnt(5)
	v_mfma_f32_32x32x16_bf16 v[82:97], v[206:209], v[228:231], v[82:97]
	ds_read_b128 v[244:247], v137 offset:27680
	s_waitcnt lgkmcnt(5)
	v_mfma_f32_32x32x16_bf16 v[66:81], v[206:209], v[232:235], v[66:81]
	v_lshl_add_u64 v[174:175], v[148:149], 0, v[130:131]
	v_add_co_u32_e32 v174, vcc, s35, v174
	s_nop 1
	v_addc_co_u32_e32 v175, vcc, 0, v175, vcc
	global_load_dwordx4 v[174:177], v[174:175], off offset:-4096
	ds_read_b128 v[248:251], v137 offset:32288
	s_waitcnt lgkmcnt(5)
	v_mfma_f32_32x32x16_bf16 v[50:65], v[214:217], v[218:221], v[50:65]
	v_mfma_f32_32x32x16_bf16 v[34:49], v[214:217], v[224:227], v[34:49]
	v_lshl_add_u64 v[178:179], v[148:149], 0, v[130:131]
	v_add_co_u32_e32 v178, vcc, s35, v178
	s_nop 1
	v_addc_co_u32_e32 v179, vcc, 0, v179, vcc
	global_load_dwordx4 v[178:181], v[178:179], off
	v_mfma_f32_32x32x16_bf16 v[18:33], v[214:217], v[228:231], v[18:33]
	v_mfma_f32_32x32x16_bf16 v[2:17], v[214:217], v[232:235], v[2:17]
	v_lshl_add_u64 v[182:183], v[148:149], 0, v[130:131]
	v_add_co_u32_e32 v182, vcc, s36, v182
	s_nop 1
	v_addc_co_u32_e32 v183, vcc, 0, v183, vcc
	global_load_dwordx4 v[182:185], v[182:183], off offset:-4096
	ds_read_b128 v[214:217], v133 offset:4640
	s_waitcnt lgkmcnt(4)
	v_mfma_f32_32x32x16_bf16 v[114:129], v[210:213], v[236:239], v[114:129]
	ds_read_b128 v[206:209], v133 offset:64
	ds_read_b128 v[218:221], v137 offset:18496
	s_waitcnt lgkmcnt(5)
	v_mfma_f32_32x32x16_bf16 v[98:113], v[210:213], v[240:243], v[98:113]
	v_lshl_add_u64 v[186:187], v[148:149], 0, v[130:131]
	v_add_co_u32_e32 v186, vcc, s36, v186
	s_nop 1
	v_addc_co_u32_e32 v187, vcc, 0, v187, vcc
	global_load_dwordx4 v[186:189], v[186:187], off
	ds_read_b128 v[224:227], v137 offset:23104
	s_waitcnt lgkmcnt(5)
	v_mfma_f32_32x32x16_bf16 v[82:97], v[210:213], v[244:247], v[82:97]
	ds_read_b128 v[228:231], v137 offset:27712
	s_waitcnt lgkmcnt(5)
	v_mfma_f32_32x32x16_bf16 v[66:81], v[210:213], v[248:251], v[66:81]
	v_lshl_add_u64 v[190:191], v[148:149], 0, v[130:131]
	v_add_co_u32_e32 v190, vcc, s37, v190
	s_nop 1
	v_addc_co_u32_e32 v191, vcc, 0, v191, vcc
	global_load_dwordx4 v[190:193], v[190:191], off offset:-4096
	ds_read_b128 v[232:235], v137 offset:32320
	s_waitcnt lgkmcnt(5)
	v_mfma_f32_32x32x16_bf16 v[50:65], v[214:217], v[236:239], v[50:65]
	v_mfma_f32_32x32x16_bf16 v[34:49], v[214:217], v[240:243], v[34:49]
	v_lshl_add_u64 v[194:195], v[148:149], 0, v[130:131]
	v_add_co_u32_e32 v194, vcc, s37, v194
	s_nop 1
	v_addc_co_u32_e32 v195, vcc, 0, v195, vcc
	global_load_dwordx4 v[194:197], v[194:195], off
	v_mfma_f32_32x32x16_bf16 v[18:33], v[214:217], v[244:247], v[18:33]
	v_mfma_f32_32x32x16_bf16 v[2:17], v[214:217], v[248:251], v[2:17]
	v_lshl_add_u64 v[198:199], v[148:149], 0, v[130:131]
	v_add_co_u32_e32 v198, vcc, s38, v198
	s_nop 1
	v_addc_co_u32_e32 v199, vcc, 0, v199, vcc
	global_load_dwordx4 v[198:201], v[198:199], off offset:-4096
	ds_read_b128 v[214:217], v133 offset:4672
	s_waitcnt lgkmcnt(4)
;     ...
;   for (int kt = 0; kt < nk; ++kt) {
;     const int kn = (kt + 1 < nk) ? kt + 1 : kt;
;     GW_LOAD2(kn * 64, kn * bkstep)
;     __builtin_amdgcn_sched_barrier(0);
;     __builtin_amdgcn_s_setprio(1);
; #pragma unroll
;     for (int st = 0; st < 4; ++st) {
;       bf16x8 a0 = *(const bf16x8*)(Ab + st * 32);
;       bf16x8 a1 = *(const bf16x8*)(Ab + 32 * LSTR + st * 32);
;       bf16x8 b0 = *(const bf16x8*)(Bb + st * 32);
;       bf16x8 b1 = *(const bf16x8*)(Bb + 32 * LSTR + st * 32);
;       bf16x8 b2 = *(const bf16x8*)(Bb + 64 * LSTR + st * 32);
;       bf16x8 b3 = *(const bf16x8*)(Bb + 96 * LSTR + st * 32);
;       acc[0][0] = mfma32(a0, b0, acc[0][0]);
;       acc[0][1] = mfma32(a0, b1, acc[0][1]);
;       acc[0][2] = mfma32(a0, b2, acc[0][2]);
;       acc[0][3] = mfma32(a0, b3, acc[0][3]);
;       acc[1][0] = mfma32(a1, b0, acc[1][0]);
;       acc[1][1] = mfma32(a1, b1, acc[1][1]);
;       acc[1][2] = mfma32(a1, b2, acc[1][2]);
;       acc[1][3] = mfma32(a1, b3, acc[1][3]);
;     }
;     __builtin_amdgcn_s_setprio(0);
;     __builtin_amdgcn_sched_barrier(0);
;     __syncthreads();
;     GW_STORE()
;     __syncthreads();
	v_mfma_f32_32x32x16_bf16 v[114:129], v[206:209], v[218:221], v[114:129]
	ds_read_b128 v[210:213], v133 offset:96
	ds_read_b128 v[236:239], v137 offset:18528
	s_waitcnt lgkmcnt(5)
	v_mfma_f32_32x32x16_bf16 v[98:113], v[206:209], v[224:227], v[98:113]
	v_lshl_add_u64 v[202:203], v[148:149], 0, v[130:131]
	v_add_co_u32_e32 v202, vcc, s38, v202
	s_nop 1
	v_addc_co_u32_e32 v203, vcc, 0, v203, vcc
	global_load_dwordx4 v[202:205], v[202:203], off
	ds_read_b128 v[240:243], v137 offset:23136
	s_waitcnt lgkmcnt(5)
	v_mfma_f32_32x32x16_bf16 v[82:97], v[206:209], v[228:231], v[82:97]
	ds_read_b128 v[244:247], v137 offset:27744
	s_waitcnt lgkmcnt(5)
	v_mfma_f32_32x32x16_bf16 v[66:81], v[206:209], v[232:235], v[66:81]
	ds_read_b128 v[248:251], v137 offset:32352
	s_waitcnt lgkmcnt(5)
	v_mfma_f32_32x32x16_bf16 v[50:65], v[214:217], v[218:221], v[50:65]
	v_mfma_f32_32x32x16_bf16 v[34:49], v[214:217], v[224:227], v[34:49]
	v_mfma_f32_32x32x16_bf16 v[18:33], v[214:217], v[228:231], v[18:33]
	v_mfma_f32_32x32x16_bf16 v[2:17], v[214:217], v[232:235], v[2:17]
	ds_read_b128 v[214:217], v133 offset:4704
	s_waitcnt lgkmcnt(4)
	v_mfma_f32_32x32x16_bf16 v[114:129], v[210:213], v[236:239], v[114:129]
	s_waitcnt lgkmcnt(3)
	v_mfma_f32_32x32x16_bf16 v[98:113], v[210:213], v[240:243], v[98:113]
	s_waitcnt lgkmcnt(2)
	v_mfma_f32_32x32x16_bf16 v[82:97], v[210:213], v[244:247], v[82:97]
	s_waitcnt lgkmcnt(1)
	v_mfma_f32_32x32x16_bf16 v[66:81], v[210:213], v[248:251], v[66:81]
	s_waitcnt lgkmcnt(0)
	v_mfma_f32_32x32x16_bf16 v[50:65], v[214:217], v[236:239], v[50:65]
	v_mfma_f32_32x32x16_bf16 v[34:49], v[214:217], v[240:243], v[34:49]
	v_mfma_f32_32x32x16_bf16 v[18:33], v[214:217], v[244:247], v[18:33]
	v_mfma_f32_32x32x16_bf16 v[2:17], v[214:217], v[248:251], v[2:17]
	s_setprio 0
	s_add_i32 s41, s41, -1
	v_lshl_add_u64 v[148:149], v[148:149], 0, s[8:9]
	v_lshl_add_u64 v[150:151], v[150:151], 0, s[10:11]
	v_lshl_add_u64 v[152:153], v[152:153], 0, s[10:11]
	v_lshl_add_u64 v[154:155], v[154:155], 0, s[10:11]
	s_cmp_lg_u32 s41, 0
	v_lshl_add_u64 v[156:157], v[156:157], 0, s[10:11]
	s_barrier
	s_waitcnt vmcnt(11)
	ds_write_b128 v132, v[158:161]
	v_lshl_add_u64 v[158:159], v[150:151], 0, v[130:131]
	global_load_dwordx4 v[158:161], v[158:159], off
	s_waitcnt vmcnt(11)
	ds_write_b128 v132, v[162:165] offset:4608
	v_lshl_add_u64 v[162:163], v[152:153], 0, v[130:131]
	global_load_dwordx4 v[162:165], v[162:163], off
	s_waitcnt vmcnt(11)
	ds_write_b128 v132, v[166:169] offset:9216
	v_lshl_add_u64 v[166:167], v[154:155], 0, v[130:131]
	global_load_dwordx4 v[166:169], v[166:167], off
	s_waitcnt vmcnt(11)
	ds_write_b128 v132, v[170:173] offset:13824
	s_waitcnt vmcnt(10)
	ds_write_b128 v132, v[174:177] offset:18432
	s_waitcnt vmcnt(9)
	ds_write_b128 v132, v[178:181] offset:23040
	s_waitcnt vmcnt(8)
	ds_write_b128 v132, v[182:185] offset:27648
	s_waitcnt vmcnt(7)
	ds_write_b128 v132, v[186:189] offset:32256
	s_waitcnt vmcnt(6)
	ds_write_b128 v132, v[190:193] offset:36864
	s_waitcnt vmcnt(5)
	ds_write_b128 v132, v[194:197] offset:41472
	s_waitcnt vmcnt(4)
	ds_write_b128 v132, v[198:201] offset:46080
	s_waitcnt vmcnt(3)
	ds_write_b128 v132, v[202:205] offset:50688
	s_waitcnt lgkmcnt(0)
	s_barrier
	s_cbranch_scc1 .LBB0_2065
	s_setprio 1
	ds_read_b128 v[206:209], v133 offset:0
	ds_read_b128 v[218:221], v137 offset:18432
	ds_read_b128 v[224:227], v137 offset:23040
	ds_read_b128 v[228:231], v137 offset:27648
	ds_read_b128 v[232:235], v137 offset:32256
	ds_read_b128 v[214:217], v133 offset:4608
	s_waitcnt lgkmcnt(4)
	v_mfma_f32_32x32x16_bf16 v[114:129], v[206:209], v[218:221], v[114:129]
	ds_read_b128 v[210:213], v133 offset:32
	ds_read_b128 v[236:239], v137 offset:18464
	s_waitcnt lgkmcnt(5)
	v_mfma_f32_32x32x16_bf16 v[98:113], v[206:209], v[224:227], v[98:113]
	v_lshl_add_u64 v[170:171], v[156:157], 0, v[130:131]
	global_load_dwordx4 v[170:173], v[170:171], off
	ds_read_b128 v[240:243], v137 offset:23072
	s_waitcnt lgkmcnt(5)
	v_mfma_f32_32x32x16_bf16 v[82:97], v[206:209], v[228:231], v[82:97]
	ds_read_b128 v[244:247], v137 offset:27680
	s_waitcnt lgkmcnt(5)
	v_mfma_f32_32x32x16_bf16 v[66:81], v[206:209], v[232:235], v[66:81]
	v_lshl_add_u64 v[174:175], v[148:149], 0, v[130:131]
	v_add_co_u32_e32 v174, vcc, s35, v174
	s_nop 1
	v_addc_co_u32_e32 v175, vcc, 0, v175, vcc
	global_load_dwordx4 v[174:177], v[174:175], off offset:-4096
	ds_read_b128 v[248:251], v137 offset:32288
	s_waitcnt lgkmcnt(5)
	v_mfma_f32_32x32x16_bf16 v[50:65], v[214:217], v[218:221], v[50:65]
	v_mfma_f32_32x32x16_bf16 v[34:49], v[214:217], v[224:227], v[34:49]
	v_lshl_add_u64 v[178:179], v[148:149], 0, v[130:131]
	v_add_co_u32_e32 v178, vcc, s35, v178
	s_nop 1
	v_addc_co_u32_e32 v179, vcc, 0, v179, vcc
	global_load_dwordx4 v[178:181], v[178:179], off
	v_mfma_f32_32x32x16_bf16 v[18:33], v[214:217], v[228:231], v[18:33]
	v_mfma_f32_32x32x16_bf16 v[2:17], v[214:217], v[232:235], v[2:17]
	v_lshl_add_u64 v[182:183], v[148:149], 0, v[130:131]
	v_add_co_u32_e32 v182, vcc, s36, v182
	s_nop 1
	v_addc_co_u32_e32 v183, vcc, 0, v183, vcc
	global_load_dwordx4 v[182:185], v[182:183], off offset:-4096
	ds_read_b128 v[214:217], v133 offset:4640
	s_waitcnt lgkmcnt(4)
	v_mfma_f32_32x32x16_bf16 v[114:129], v[210:213], v[236:239], v[114:129]
	ds_read_b128 v[206:209], v133 offset:64
	ds_read_b128 v[218:221], v137 offset:18496
	s_waitcnt lgkmcnt(5)
	v_mfma_f32_32x32x16_bf16 v[98:113], v[210:213], v[240:243], v[98:113]
	v_lshl_add_u64 v[186:187], v[148:149], 0, v[130:131]
	v_add_co_u32_e32 v186, vcc, s36, v186
	s_nop 1
	v_addc_co_u32_e32 v187, vcc, 0, v187, vcc
	global_load_dwordx4 v[186:189], v[186:187], off
	ds_read_b128 v[224:227], v137 offset:23104
	s_waitcnt lgkmcnt(5)
;     ...
;   for (int kt = 0; kt < nk; ++kt) {
;     const int kn = (kt + 1 < nk) ? kt + 1 : kt;
;     GW_LOAD2(kn * 64, kn * bkstep)
;     __builtin_amdgcn_sched_barrier(0);
;     __builtin_amdgcn_s_setprio(1);
; #pragma unroll
;     for (int st = 0; st < 4; ++st) {
;       bf16x8 a0 = *(const bf16x8*)(Ab + st * 32);
;       bf16x8 a1 = *(const bf16x8*)(Ab + 32 * LSTR + st * 32);
;       bf16x8 b0 = *(const bf16x8*)(Bb + st * 32);
;       bf16x8 b1 = *(const bf16x8*)(Bb + 32 * LSTR + st * 32);
;       bf16x8 b2 = *(const bf16x8*)(Bb + 64 * LSTR + st * 32);
;       bf16x8 b3 = *(const bf16x8*)(Bb + 96 * LSTR + st * 32);
;       acc[0][0] = mfma32(a0, b0, acc[0][0]);
;       acc[0][1] = mfma32(a0, b1, acc[0][1]);
;       acc[0][2] = mfma32(a0, b2, acc[0][2]);
;       acc[0][3] = mfma32(a0, b3, acc[0][3]);
;       acc[1][0] = mfma32(a1, b0, acc[1][0]);
;       acc[1][1] = mfma32(a1, b1, acc[1][1]);
;       acc[1][2] = mfma32(a1, b2, acc[1][2]);
;       acc[1][3] = mfma32(a1, b3, acc[1][3]);
;     }
;     __builtin_amdgcn_s_setprio(0);
;     __builtin_amdgcn_sched_barrier(0);
;     __syncthreads();
;     GW_STORE()
;     __syncthreads();
	v_mfma_f32_32x32x16_bf16 v[82:97], v[210:213], v[244:247], v[82:97]
	ds_read_b128 v[228:231], v137 offset:27712
	s_waitcnt lgkmcnt(5)
	v_mfma_f32_32x32x16_bf16 v[66:81], v[210:213], v[248:251], v[66:81]
	v_lshl_add_u64 v[190:191], v[148:149], 0, v[130:131]
	v_add_co_u32_e32 v190, vcc, s37, v190
	s_nop 1
	v_addc_co_u32_e32 v191, vcc, 0, v191, vcc
	global_load_dwordx4 v[190:193], v[190:191], off offset:-4096
	ds_read_b128 v[232:235], v137 offset:32320
	s_waitcnt lgkmcnt(5)
	v_mfma_f32_32x32x16_bf16 v[50:65], v[214:217], v[236:239], v[50:65]
	v_mfma_f32_32x32x16_bf16 v[34:49], v[214:217], v[240:243], v[34:49]
	v_lshl_add_u64 v[194:195], v[148:149], 0, v[130:131]
	v_add_co_u32_e32 v194, vcc, s37, v194
	s_nop 1
	v_addc_co_u32_e32 v195, vcc, 0, v195, vcc
	global_load_dwordx4 v[194:197], v[194:195], off
	v_mfma_f32_32x32x16_bf16 v[18:33], v[214:217], v[244:247], v[18:33]
	v_mfma_f32_32x32x16_bf16 v[2:17], v[214:217], v[248:251], v[2:17]
	v_lshl_add_u64 v[198:199], v[148:149], 0, v[130:131]
	v_add_co_u32_e32 v198, vcc, s38, v198
	s_nop 1
	v_addc_co_u32_e32 v199, vcc, 0, v199, vcc
	global_load_dwordx4 v[198:201], v[198:199], off offset:-4096
	ds_read_b128 v[214:217], v133 offset:4672
	s_waitcnt lgkmcnt(4)
	v_mfma_f32_32x32x16_bf16 v[114:129], v[206:209], v[218:221], v[114:129]
	ds_read_b128 v[210:213], v133 offset:96
	ds_read_b128 v[236:239], v137 offset:18528
	s_waitcnt lgkmcnt(5)
	v_mfma_f32_32x32x16_bf16 v[98:113], v[206:209], v[224:227], v[98:113]
	v_lshl_add_u64 v[202:203], v[148:149], 0, v[130:131]
	v_add_co_u32_e32 v202, vcc, s38, v202
	s_nop 1
	v_addc_co_u32_e32 v203, vcc, 0, v203, vcc
	global_load_dwordx4 v[202:205], v[202:203], off
	ds_read_b128 v[240:243], v137 offset:23136
	s_waitcnt lgkmcnt(5)
	v_mfma_f32_32x32x16_bf16 v[82:97], v[206:209], v[228:231], v[82:97]
	ds_read_b128 v[244:247], v137 offset:27744
	s_waitcnt lgkmcnt(5)
	v_mfma_f32_32x32x16_bf16 v[66:81], v[206:209], v[232:235], v[66:81]
	ds_read_b128 v[248:251], v137 offset:32352
	s_waitcnt lgkmcnt(5)
	v_mfma_f32_32x32x16_bf16 v[50:65], v[214:217], v[218:221], v[50:65]
	v_mfma_f32_32x32x16_bf16 v[34:49], v[214:217], v[224:227], v[34:49]
	v_mfma_f32_32x32x16_bf16 v[18:33], v[214:217], v[228:231], v[18:33]
	v_mfma_f32_32x32x16_bf16 v[2:17], v[214:217], v[232:235], v[2:17]
	ds_read_b128 v[214:217], v133 offset:4704
	s_waitcnt lgkmcnt(4)
	v_mfma_f32_32x32x16_bf16 v[114:129], v[210:213], v[236:239], v[114:129]
	s_waitcnt lgkmcnt(3)
	v_mfma_f32_32x32x16_bf16 v[98:113], v[210:213], v[240:243], v[98:113]
	s_waitcnt lgkmcnt(2)
	v_mfma_f32_32x32x16_bf16 v[82:97], v[210:213], v[244:247], v[82:97]
	s_waitcnt lgkmcnt(1)
	v_mfma_f32_32x32x16_bf16 v[66:81], v[210:213], v[248:251], v[66:81]
	s_waitcnt lgkmcnt(0)
	v_mfma_f32_32x32x16_bf16 v[50:65], v[214:217], v[236:239], v[50:65]
	v_mfma_f32_32x32x16_bf16 v[34:49], v[214:217], v[240:243], v[34:49]
	v_mfma_f32_32x32x16_bf16 v[18:33], v[214:217], v[244:247], v[18:33]
	v_mfma_f32_32x32x16_bf16 v[2:17], v[214:217], v[248:251], v[2:17]
	s_setprio 0
	v_lshl_add_u64 v[148:149], v[148:149], 0, s[8:9]
	v_lshl_add_u64 v[150:151], v[150:151], 0, s[10:11]
	v_lshl_add_u64 v[152:153], v[152:153], 0, s[10:11]
	v_lshl_add_u64 v[154:155], v[154:155], 0, s[10:11]
	v_lshl_add_u64 v[156:157], v[156:157], 0, s[10:11]
	s_barrier
	s_waitcnt vmcnt(11)
	ds_write_b128 v132, v[158:161]
	s_waitcnt vmcnt(10)
	ds_write_b128 v132, v[162:165] offset:4608
	s_waitcnt vmcnt(9)
	ds_write_b128 v132, v[166:169] offset:9216
	s_waitcnt vmcnt(8)
	ds_write_b128 v132, v[170:173] offset:13824
	s_waitcnt vmcnt(7)
	ds_write_b128 v132, v[174:177] offset:18432
	s_waitcnt vmcnt(6)
	ds_write_b128 v132, v[178:181] offset:23040
	s_waitcnt vmcnt(5)
	ds_write_b128 v132, v[182:185] offset:27648
	s_waitcnt vmcnt(4)
	ds_write_b128 v132, v[186:189] offset:32256
	s_waitcnt vmcnt(3)
	ds_write_b128 v132, v[190:193] offset:36864
	s_waitcnt vmcnt(2)
	ds_write_b128 v132, v[194:197] offset:41472
	s_waitcnt vmcnt(1)
	ds_write_b128 v132, v[198:201] offset:46080
	s_waitcnt vmcnt(0)
	ds_write_b128 v132, v[202:205] offset:50688
	s_waitcnt lgkmcnt(0)
	s_barrier
;     ...
;   for (int kt = 0; kt < nk; ++kt) {
;     const int kn = (kt + 1 < nk) ? kt + 1 : kt;
;     GW_LOAD2(kn * 64, kn * bkstep)
;     __builtin_amdgcn_sched_barrier(0);
;     __builtin_amdgcn_s_setprio(1);
; #pragma unroll
;     for (int st = 0; st < 4; ++st) {
;       bf16x8 a0 = *(const bf16x8*)(Ab + st * 32);
;       bf16x8 a1 = *(const bf16x8*)(Ab + 32 * LSTR + st * 32);
;       bf16x8 b0 = *(const bf16x8*)(Bb + st * 32);
;       bf16x8 b1 = *(const bf16x8*)(Bb + 32 * LSTR + st * 32);
;       bf16x8 b2 = *(const bf16x8*)(Bb + 64 * LSTR + st * 32);
;       bf16x8 b3 = *(const bf16x8*)(Bb + 96 * LSTR + st * 32);
;       acc[0][0] = mfma32(a0, b0, acc[0][0]);
;       acc[0][1] = mfma32(a0, b1, acc[0][1]);
;       acc[0][2] = mfma32(a0, b2, acc[0][2]);
;       acc[0][3] = mfma32(a0, b3, acc[0][3]);
;       acc[1][0] = mfma32(a1, b0, acc[1][0]);
;       acc[1][1] = mfma32(a1, b1, acc[1][1]);
;       acc[1][2] = mfma32(a1, b2, acc[1][2]);
;       acc[1][3] = mfma32(a1, b3, acc[1][3]);
;     }
;     __builtin_amdgcn_s_setprio(0);
;     __builtin_amdgcn_sched_barrier(0);
;     __syncthreads();
;     GW_STORE()
;     __syncthreads();
; __device__ __forceinline__ void expert1_tile(const Params& P, int e, int mt, int ntw, char* smem) {
;     ...
;   float* cs = (float*)smem;
;   int tid_ = threadIdx.x;
;   asm volatile("" : "+v"(tid_));
;   const int lane = tid_ & 63, wave = tid_ >> 6;
;   const int r = 32 * wave + (lane & 31), part = lane >> 5;
; #pragma unroll 1
;   for (int h = 0; h < 2; ++h) {
;     wide_acc_to_lds(acc, cs, h);
;     u16* dst = WSP(u16, OFF_HID) + ((size_t)e * EROWS + mt * 128 + r) * 2048 + (ntw * 2 + h) * 64 + part * 32;
	v_add_co_u32_e32 v156, vcc, 0x780000, v138
	s_nop 0
	s_nop 0
	s_nop 0
	v_addc_co_u32_e32 v157, vcc, 0, v139, vcc
	v_add_co_u32_e32 v160, vcc, 0x781000, v138
	s_mov_b32 s18, 0
	s_nop 0
	v_addc_co_u32_e32 v161, vcc, 0, v139, vcc
	v_add_co_u32_e32 v164, vcc, 0x782000, v138
	s_nop 0
	v_addc_co_u32_e32 v165, vcc, 0, v139, vcc
	v_add_co_u32_e32 v168, vcc, 0x783000, v138
	s_nop 1
	v_addc_co_u32_e32 v169, vcc, 0, v139, vcc
	v_add_co_u32_e32 v172, vcc, 0x784000, v138
	s_nop 0
	v_addc_co_u32_e32 v173, vcc, 0, v139, vcc
	v_add_co_u32_e32 v176, vcc, 0x785000, v138
	s_nop 1
	v_addc_co_u32_e32 v177, vcc, 0, v139, vcc
	v_add_co_u32_e32 v180, vcc, 0x786000, v138
	s_nop 0
	v_addc_co_u32_e32 v181, vcc, 0, v139, vcc
	v_add_co_u32_e32 v138, vcc, 0x787000, v138
	s_nop 1
	v_addc_co_u32_e32 v139, vcc, 0, v139, vcc
	s_nop 0
	s_setprio 1
	ds_read_b128 v[188:191], v133 offset:0
	ds_read_b128 v[200:203], v137 offset:18432
	ds_read_b128 v[204:207], v137 offset:23040
	ds_read_b128 v[208:211], v137 offset:27648
	ds_read_b128 v[212:215], v137 offset:32256
	ds_read_b128 v[196:199], v133 offset:4608
	s_waitcnt lgkmcnt(4)
	v_mfma_f32_32x32x16_bf16 v[114:129], v[188:191], v[200:203], v[114:129]
	ds_read_b128 v[192:195], v133 offset:32
	ds_read_b128 v[216:219], v137 offset:18464
	s_waitcnt lgkmcnt(5)
	v_mfma_f32_32x32x16_bf16 v[98:113], v[188:191], v[204:207], v[98:113]
	ds_read_b128 v[224:227], v137 offset:23072
	s_waitcnt lgkmcnt(5)
	v_mfma_f32_32x32x16_bf16 v[82:97], v[188:191], v[208:211], v[82:97]
	ds_read_b128 v[228:231], v137 offset:27680
	s_waitcnt lgkmcnt(5)
	v_mfma_f32_32x32x16_bf16 v[66:81], v[188:191], v[212:215], v[66:81]
	ds_read_b128 v[232:235], v137 offset:32288
	s_waitcnt lgkmcnt(5)
	v_mfma_f32_32x32x16_bf16 v[50:65], v[196:199], v[200:203], v[50:65]
	v_mfma_f32_32x32x16_bf16 v[34:49], v[196:199], v[204:207], v[34:49]
	v_mfma_f32_32x32x16_bf16 v[18:33], v[196:199], v[208:211], v[18:33]
	v_mfma_f32_32x32x16_bf16 v[2:17], v[196:199], v[212:215], v[2:17]
	ds_read_b128 v[196:199], v133 offset:4640
	s_waitcnt lgkmcnt(4)
	v_mfma_f32_32x32x16_bf16 v[114:129], v[192:195], v[216:219], v[114:129]
	ds_read_b128 v[188:191], v133 offset:64
	ds_read_b128 v[200:203], v137 offset:18496
	s_waitcnt lgkmcnt(5)
	v_mfma_f32_32x32x16_bf16 v[98:113], v[192:195], v[224:227], v[98:113]
	ds_read_b128 v[204:207], v137 offset:23104
	s_waitcnt lgkmcnt(5)
	v_mfma_f32_32x32x16_bf16 v[82:97], v[192:195], v[228:231], v[82:97]
	ds_read_b128 v[208:211], v137 offset:27712
	s_waitcnt lgkmcnt(5)
	v_mfma_f32_32x32x16_bf16 v[66:81], v[192:195], v[232:235], v[66:81]
	ds_read_b128 v[212:215], v137 offset:32320
	s_waitcnt lgkmcnt(5)
	v_mfma_f32_32x32x16_bf16 v[50:65], v[196:199], v[216:219], v[50:65]
	v_mfma_f32_32x32x16_bf16 v[34:49], v[196:199], v[224:227], v[34:49]
	v_mfma_f32_32x32x16_bf16 v[18:33], v[196:199], v[228:231], v[18:33]
	v_mfma_f32_32x32x16_bf16 v[2:17], v[196:199], v[232:235], v[2:17]
	ds_read_b128 v[196:199], v133 offset:4672
	s_waitcnt lgkmcnt(4)
	v_mfma_f32_32x32x16_bf16 v[114:129], v[188:191], v[200:203], v[114:129]
	ds_read_b128 v[192:195], v133 offset:96
	ds_read_b128 v[216:219], v137 offset:18528
	s_waitcnt lgkmcnt(5)
	v_mfma_f32_32x32x16_bf16 v[98:113], v[188:191], v[204:207], v[98:113]
	ds_read_b128 v[224:227], v137 offset:23136
	s_waitcnt lgkmcnt(5)
	v_mfma_f32_32x32x16_bf16 v[82:97], v[188:191], v[208:211], v[82:97]
	ds_read_b128 v[228:231], v137 offset:27744
	s_waitcnt lgkmcnt(5)
	v_mfma_f32_32x32x16_bf16 v[66:81], v[188:191], v[212:215], v[66:81]
	ds_read_b128 v[232:235], v137 offset:32352
	s_waitcnt lgkmcnt(5)
	v_mfma_f32_32x32x16_bf16 v[50:65], v[196:199], v[200:203], v[50:65]
	v_mfma_f32_32x32x16_bf16 v[34:49], v[196:199], v[204:207], v[34:49]
	v_mfma_f32_32x32x16_bf16 v[18:33], v[196:199], v[208:211], v[18:33]
	v_mfma_f32_32x32x16_bf16 v[2:17], v[196:199], v[212:215], v[2:17]
	ds_read_b128 v[196:199], v133 offset:4704
	s_waitcnt lgkmcnt(4)
	v_mfma_f32_32x32x16_bf16 v[114:129], v[192:195], v[216:219], v[114:129]
	s_waitcnt lgkmcnt(3)
	v_mfma_f32_32x32x16_bf16 v[98:113], v[192:195], v[224:227], v[98:113]
	s_waitcnt lgkmcnt(2)
	v_mfma_f32_32x32x16_bf16 v[82:97], v[192:195], v[228:231], v[82:97]
	s_waitcnt lgkmcnt(1)
	v_mfma_f32_32x32x16_bf16 v[66:81], v[192:195], v[232:235], v[66:81]
	s_waitcnt lgkmcnt(0)
	v_mfma_f32_32x32x16_bf16 v[50:65], v[196:199], v[216:219], v[50:65]
	v_mfma_f32_32x32x16_bf16 v[34:49], v[196:199], v[224:227], v[34:49]
	v_mfma_f32_32x32x16_bf16 v[18:33], v[196:199], v[228:231], v[18:33]
	v_mfma_f32_32x32x16_bf16 v[2:17], v[196:199], v[232:235], v[2:17]
	s_setprio 0
	v_mov_b32_e32 v130, v134
	s_barrier
	s_waitcnt lgkmcnt(0)
	s_mul_hi_i32 s13, s14, 0x1100
	v_ashrrev_i32_e32 v132, 1, v130
	s_mulk_i32 s14, 0x1100
	v_bfi_b32 v132, s39, v132, v130
	s_add_u32 s14, s14, s16
	s_addc_u32 s15, s13, s17
	v_ashrrev_i32_e32 v133, 31, v132
	v_lshl_add_u64 v[138:139], s[14:15], 0, v[132:133]
	v_and_b32_e32 v130, 32, v130
	v_lshlrev_b64 v[138:139], 12, v[138:139]
	v_mul_lo_u32 v132, v132, s22
	v_lshl_add_u32 v137, v130, 2, v132
	v_lshl_add_u64 v[132:133], s[4:5], 0, v[138:139]
	v_lshlrev_b32_e32 v130, 1, v130
	s_lshl_b32 s16, s12, 7
	v_lshl_add_u64 v[132:133], v[132:133], 0, v[130:131]
	s_mov_b64 s[12:13], -1
	s_branch .LBB0_2068

; #define GW_LOAD(KOFF) GW_LOAD2(KOFF, 0)
;   int tid = threadIdx.x;
;   asm volatile("" : "+v"(tid));
;   const int lane = tid & 63, wave = tid >> 6;
;   const int wm = wave >> 1, wn = wave & 1;
;   const int lr = tid >> 3, kc = tid & 7;
;   const u16* ap0 = arow(lr) + kc * 8;
;   const u16* ap1 = arow(lr + 32) + kc * 8;
;   const u16* ap2 = arow(lr + 64) + kc * 8;
;   const u16* ap3 = arow(lr + 96) + kc * 8;
;   const u16* bp0 = Bt + (size_t)lr * ldb + kc * 8;
;   const size_t bstep = 32 * ldb;
;   const int so = lr * LSTR + kc * 16;
;   uint4 ra0, ra1, ra2, ra3, rb0, rb1, rb2, rb3, rb4, rb5, rb6, rb7;
;     ...
;   GW_LOAD(0)
;   GW_STORE()
; __device__ __forceinline__ void expert2_tile(const Params& P, int e, int mt, int ntw, char* smem) {
;   f32x16 acc[2][4];
; #pragma unroll
;   for (int i = 0; i < 2; ++i)
; #pragma unroll
;     for (int j = 0; j < 4; ++j)
; #pragma unroll
;       for (int r = 0; r < 16; ++r) acc[i][j][r] = 0.f;
;   const u16* A = WSP(u16, OFF_HID) + ((size_t)e * EROWS + mt * 128) * 2048;
;   const u16* Bt = WSP(u16, OFF_WDN) + (size_t)e * DM * 2048 + (size_t)ntw * 256 * 64;
;   gemm_wide([&](int rr) { return A + (size_t)rr * 2048; }, Bt, 64, 2048, smem, acc, 1024 * 64);
.LBB0_2142:
	s_lshl_b32 s12, s45, 6
	s_and_b32 s12, s12, 0x1c0
	s_and_b32 s13, s45, 0xfffffe00
	s_or_b32 s12, s12, s13
	s_bfe_u32 s13, s45, 0x60003
	s_or_b32 s14, s12, s13
	s_and_b64 s[12:13], s[0:1], exec
	s_cselect_b32 s12, s14, s45
	s_ashr_i32 s13, s12, 31
	s_lshr_b32 s13, s13, 27
	s_add_i32 s13, s12, s13
	s_ashr_i32 s52, s13, 5
	s_lshl_b32 s15, s52, 3
	s_and_b32 s14, s13, 0xffffffe0
	s_sub_i32 s14, s12, s14
	s_and_b32 s53, s12, 7
	s_and_b32 s12, s15, 24
	s_ashr_i32 s16, s13, 7
	s_or_b32 s12, s12, s53
	s_ashr_i32 s14, s14, 3
	s_ashr_i32 s17, s16, 31
	s_mul_i32 s15, s16, 0x1100
	s_lshl_b32 s12, s12, 7
	s_mul_hi_i32 s13, s16, 0x1100
	s_add_u32 s12, s15, s12
	s_addc_u32 s13, s13, 0
	s_lshl_b64 s[18:19], s[12:13], 12
	s_add_u32 s46, s21, s18
	s_addc_u32 s47, s22, s19
	s_lshl_b64 s[18:19], s[16:17], 22
	s_add_u32 s17, s23, s18
	v_mov_b32_e32 v56, v134
	s_addc_u32 s51, s24, s19
	s_ashr_i32 s15, s14, 31
	s_lshl_b64 s[48:49], s[14:15], 15
	v_ashrrev_i32_e32 v50, 3, v56
	v_ashrrev_i32_e32 v51, 31, v50
	s_add_u32 s50, s17, s48
	v_lshlrev_b64 v[52:53], 12, v[50:51]
	v_lshlrev_b32_e32 v4, 4, v56
	s_addc_u32 s51, s51, s49
	v_lshl_add_u64 v[2:3], s[46:47], 0, v[52:53]
	v_and_b32_e32 v130, 0x70, v4
	v_lshlrev_b64 v[54:55], 7, v[50:51]
	v_lshl_add_u64 v[140:141], v[2:3], 0, v[130:131]
	v_lshl_add_u64 v[2:3], s[50:51], 0, v[54:55]
	v_lshl_add_u64 v[138:139], v[2:3], 0, v[130:131]
	v_add_co_u32_e32 v2, vcc, s27, v140
	s_add_u32 s15, s18, s48
	s_nop 0
	v_addc_co_u32_e32 v3, vcc, 0, v141, vcc
	v_add_co_u32_e32 v6, vcc, s28, v140
	s_addc_u32 s17, s19, s49
	s_nop 0
	v_addc_co_u32_e32 v7, vcc, 0, v141, vcc
	v_add_co_u32_e32 v10, vcc, s29, v140
	global_load_dwordx4 v[2:5], v[2:3], off
	s_nop 0
	global_load_dwordx4 v[6:9], v[6:7], off
	v_addc_co_u32_e32 v11, vcc, 0, v141, vcc
	v_add_co_u32_e32 v26, vcc, s30, v138
	global_load_dwordx4 v[10:13], v[10:11], off
	s_nop 0
	global_load_dwordx4 v[14:17], v[140:141], off
	global_load_dwordx4 v[18:21], v[138:139], off
	v_addc_co_u32_e32 v27, vcc, 0, v139, vcc
	v_add_co_u32_e32 v34, vcc, s31, v138
	global_load_dwordx4 v[22:25], v[26:27], off offset:-4096
	s_nop 0
	global_load_dwordx4 v[26:29], v[26:27], off
	v_addc_co_u32_e32 v35, vcc, 0, v139, vcc
	v_add_co_u32_e32 v42, vcc, s33, v138
	global_load_dwordx4 v[30:33], v[34:35], off offset:-4096
	s_nop 0
	global_load_dwordx4 v[34:37], v[34:35], off
	v_addc_co_u32_e32 v43, vcc, 0, v139, vcc
	global_load_dwordx4 v[38:41], v[42:43], off offset:-4096
	s_nop 0
	global_load_dwordx4 v[42:45], v[42:43], off
	v_add_co_u32_e32 v46, vcc, s34, v138
	s_add_u32 s18, s90, s15
	s_nop 0
	v_addc_co_u32_e32 v47, vcc, 0, v139, vcc
	global_load_dwordx4 v[46:49], v[46:47], off
	s_addc_u32 s19, s91, s17
	s_lshl_b32 s17, s52, 22
	v_lshl_add_u64 v[148:149], s[18:19], 0, v[54:55]
	s_and_b32 s17, s17, 0xc00000
	s_lshl_b32 s18, s53, 19
	s_or_b32 s17, s17, s18
	v_mad_u64_u32 v[132:133], s[46:47], v50, s26, v[130:131]
	s_add_u32 s17, s90, s17
	s_mul_hi_i32 s15, s16, 0x1100000
	s_mul_i32 s16, s16, 0x1100000
	s_addc_u32 s18, s91, 0
	s_add_u32 s16, s17, s16
	s_addc_u32 s17, s18, s15
	v_lshl_add_u64 v[142:143], v[140:141], 0, s[4:5]
	v_lshl_add_u64 v[144:145], v[140:141], 0, s[6:7]
	v_lshl_add_u64 v[146:147], v[140:141], 0, s[8:9]
	v_lshl_add_u64 v[150:151], s[16:17], 0, v[52:53]
	s_mov_b32 s15, 30
	v_mov_b32_e32 v50, v131
	v_mov_b32_e32 v51, v131
	v_mov_b32_e32 v52, v131
	v_mov_b32_e32 v53, v131
	v_mov_b32_e32 v54, v131
	v_mov_b32_e32 v55, v131
	v_mov_b32_e32 v57, v131
	v_mov_b32_e32 v58, v131
	v_mov_b32_e32 v59, v131
	v_mov_b32_e32 v60, v131
	v_mov_b32_e32 v61, v131
	v_mov_b32_e32 v62, v131
	v_mov_b32_e32 v63, v131
	s_waitcnt vmcnt(8)
	ds_write_b128 v132, v[14:17]
	ds_write_b128 v132, v[2:5] offset:4608
	ds_write_b128 v132, v[6:9] offset:9216
	ds_write_b128 v132, v[10:13] offset:13824
	s_waitcnt vmcnt(7)
	ds_write_b128 v132, v[18:21] offset:18432
	s_waitcnt vmcnt(6)
	ds_write_b128 v132, v[22:25] offset:23040
	s_waitcnt vmcnt(5)
	ds_write_b128 v132, v[26:29] offset:27648
	s_waitcnt vmcnt(4)
	ds_write_b128 v132, v[30:33] offset:32256
	s_waitcnt vmcnt(3)
	ds_write_b128 v132, v[34:37] offset:36864
	s_waitcnt vmcnt(2)
	ds_write_b128 v132, v[38:41] offset:41472
	s_waitcnt vmcnt(1)
	ds_write_b128 v132, v[42:45] offset:46080
	s_waitcnt vmcnt(0)
; #define GW_LOAD(KOFF) GW_LOAD2(KOFF, 0)
;     ...
;   GW_LOAD(0)
;   GW_STORE()
;   __syncthreads();
;   const int nk = K >> 6;
;   const char* Ab = smem + (wm * 64 + (lane & 31)) * LSTR + (lane >> 5) * 16;
;   const char* Bb = smem + WTILE_A + (wn * 128 + (lane & 31)) * LSTR + (lane >> 5) * 16;
;   for (int kt = 0; kt < nk; ++kt) {
;     const int kn = (kt + 1 < nk) ? kt + 1 : kt;
;     GW_LOAD2(kn * 64, kn * bkstep)
;     __builtin_amdgcn_sched_barrier(0);
;     __builtin_amdgcn_s_setprio(1);
; #pragma unroll
;     for (int st = 0; st < 4; ++st) {
;       bf16x8 a0 = *(const bf16x8*)(Ab + st * 32);
;       bf16x8 a1 = *(const bf16x8*)(Ab + 32 * LSTR + st * 32);
;       bf16x8 b0 = *(const bf16x8*)(Bb + st * 32);
;       bf16x8 b1 = *(const bf16x8*)(Bb + 32 * LSTR + st * 32);
;       bf16x8 b2 = *(const bf16x8*)(Bb + 64 * LSTR + st * 32);
;       bf16x8 b3 = *(const bf16x8*)(Bb + 96 * LSTR + st * 32);
;       acc[0][0] = mfma32(a0, b0, acc[0][0]);
;       acc[0][1] = mfma32(a0, b1, acc[0][1]);
;       acc[0][2] = mfma32(a0, b2, acc[0][2]);
;       acc[0][3] = mfma32(a0, b3, acc[0][3]);
;       acc[1][0] = mfma32(a1, b0, acc[1][0]);
;       acc[1][1] = mfma32(a1, b1, acc[1][1]);
;       acc[1][2] = mfma32(a1, b2, acc[1][2]);
;       acc[1][3] = mfma32(a1, b3, acc[1][3]);
;     }
	ds_write_b128 v132, v[46:49] offset:50688
	v_and_b32_e32 v2, 31, v56
	v_lshrrev_b32_e32 v3, 1, v56
	v_lshlrev_b32_e32 v5, 1, v56
	v_and_or_b32 v4, v3, s35, v2
	v_and_or_b32 v2, v5, s36, v2
	v_mul_lo_u32 v4, v4, s26
	v_and_b32_e32 v3, 16, v3
	v_mul_u32_u24_e32 v2, 0x90, v2
	v_add_u32_e32 v133, v4, v3
	v_add_u32_e32 v137, v2, v3
	v_mov_b32_e32 v2, v131
	v_mov_b32_e32 v3, v131
	v_mov_b32_e32 v4, v131
	v_mov_b32_e32 v5, v131
	v_mov_b32_e32 v6, v131
	v_mov_b32_e32 v7, v131
	v_mov_b32_e32 v8, v131
	v_mov_b32_e32 v9, v131
	v_mov_b32_e32 v10, v131
	v_mov_b32_e32 v11, v131
	v_mov_b32_e32 v12, v131
	v_mov_b32_e32 v13, v131
	v_mov_b32_e32 v14, v131
	v_mov_b32_e32 v15, v131
	v_mov_b32_e32 v16, v131
	v_mov_b32_e32 v17, v131
	v_mov_b32_e32 v18, v131
	v_mov_b32_e32 v19, v131
	v_mov_b32_e32 v20, v131
	v_mov_b32_e32 v21, v131
	v_mov_b32_e32 v22, v131
	v_mov_b32_e32 v23, v131
	v_mov_b32_e32 v24, v131
	v_mov_b32_e32 v25, v131
	v_mov_b32_e32 v26, v131
	v_mov_b32_e32 v27, v131
	v_mov_b32_e32 v28, v131
	v_mov_b32_e32 v29, v131
	v_mov_b32_e32 v30, v131
	v_mov_b32_e32 v31, v131
	v_mov_b32_e32 v32, v131
	v_mov_b32_e32 v33, v131
	v_mov_b32_e32 v34, v131
	v_mov_b32_e32 v35, v131
	v_mov_b32_e32 v36, v131
	v_mov_b32_e32 v37, v131
	v_mov_b32_e32 v38, v131
	v_mov_b32_e32 v39, v131
	v_mov_b32_e32 v40, v131
	v_mov_b32_e32 v41, v131
	v_mov_b32_e32 v42, v131
	v_mov_b32_e32 v43, v131
	v_mov_b32_e32 v44, v131
	v_mov_b32_e32 v45, v131
	v_mov_b32_e32 v46, v131
	v_mov_b32_e32 v47, v131
	v_mov_b32_e32 v48, v131
	v_mov_b32_e32 v49, v131
	v_mov_b32_e32 v56, v131
	v_mov_b32_e32 v64, v131
	v_mov_b32_e32 v65, v131
	v_mov_b32_e32 v66, v131
	v_mov_b32_e32 v67, v131
	v_mov_b32_e32 v68, v131
	v_mov_b32_e32 v69, v131
	v_mov_b32_e32 v70, v131
	v_mov_b32_e32 v71, v131
	v_mov_b32_e32 v72, v131
	v_mov_b32_e32 v73, v131
	v_mov_b32_e32 v74, v131
	v_mov_b32_e32 v75, v131
	v_mov_b32_e32 v76, v131
	v_mov_b32_e32 v77, v131
	v_mov_b32_e32 v78, v131
	v_mov_b32_e32 v79, v131
	v_mov_b32_e32 v80, v131
	v_mov_b32_e32 v81, v131
	v_mov_b32_e32 v82, v131
	v_mov_b32_e32 v83, v131
	v_mov_b32_e32 v84, v131
	v_mov_b32_e32 v85, v131
	v_mov_b32_e32 v86, v131
	v_mov_b32_e32 v87, v131
	v_mov_b32_e32 v88, v131
	v_mov_b32_e32 v89, v131
	v_mov_b32_e32 v90, v131
	v_mov_b32_e32 v91, v131
	v_mov_b32_e32 v92, v131
	v_mov_b32_e32 v93, v131
	v_mov_b32_e32 v94, v131
	v_mov_b32_e32 v95, v131
	v_mov_b32_e32 v96, v131
	v_mov_b32_e32 v97, v131
	v_mov_b32_e32 v98, v131
	v_mov_b32_e32 v99, v131
	v_mov_b32_e32 v100, v131
	v_mov_b32_e32 v101, v131
	v_mov_b32_e32 v102, v131
	v_mov_b32_e32 v103, v131
	v_mov_b32_e32 v104, v131
	v_mov_b32_e32 v105, v131
	v_mov_b32_e32 v106, v131
	v_mov_b32_e32 v107, v131
	v_mov_b32_e32 v108, v131
	v_mov_b32_e32 v109, v131
	v_mov_b32_e32 v110, v131
	v_mov_b32_e32 v111, v131
	v_mov_b32_e32 v112, v131
	v_mov_b32_e32 v113, v131
	v_mov_b32_e32 v114, v131
	v_mov_b32_e32 v115, v131
	v_mov_b32_e32 v116, v131
	v_mov_b32_e32 v117, v131
	v_mov_b32_e32 v118, v131
	v_mov_b32_e32 v119, v131
	v_mov_b32_e32 v120, v131
	v_mov_b32_e32 v121, v131
	v_mov_b32_e32 v122, v131
	v_mov_b32_e32 v123, v131
	v_mov_b32_e32 v124, v131
	v_mov_b32_e32 v125, v131
	v_mov_b32_e32 v126, v131
	v_mov_b32_e32 v127, v131
	v_mov_b32_e32 v128, v131
	v_mov_b32_e32 v129, v131
	s_waitcnt lgkmcnt(0)
	s_barrier
	v_lshl_add_u64 v[152:153], v[150:151], 0, v[130:131]
	v_add_co_u32_e32 v152, vcc, s37, v152
	s_nop 1
	v_addc_co_u32_e32 v153, vcc, 0, v153, vcc
	global_load_dwordx4 v[152:155], v[152:153], off offset:384
	v_lshl_add_u64 v[156:157], v[150:151], 0, v[130:131]
	v_add_co_u32_e32 v156, vcc, s38, v156
	s_nop 1
	v_addc_co_u32_e32 v157, vcc, 0, v157, vcc
	global_load_dwordx4 v[156:159], v[156:157], off offset:384
	v_lshl_add_u64 v[160:161], v[150:151], 0, v[130:131]
	v_add_co_u32_e32 v160, vcc, s39, v160
	s_nop 1
	v_addc_co_u32_e32 v161, vcc, 0, v161, vcc
	global_load_dwordx4 v[160:163], v[160:161], off offset:384
.LBB0_2143:
	s_setprio 1
	ds_read_b128 v[200:203], v133 offset:0
	ds_read_b128 v[212:215], v137 offset:18432
	ds_read_b128 v[216:219], v137 offset:23040
	ds_read_b128 v[224:227], v137 offset:27648
	ds_read_b128 v[228:231], v137 offset:32256
	ds_read_b128 v[208:211], v133 offset:4608
	s_waitcnt lgkmcnt(4)
	v_mfma_f32_32x32x16_bf16 v[114:129], v[200:203], v[212:215], v[114:129]
	ds_read_b128 v[204:207], v133 offset:32
	ds_read_b128 v[232:235], v137 offset:18464
	s_waitcnt lgkmcnt(5)
	v_mfma_f32_32x32x16_bf16 v[98:113], v[200:203], v[216:219], v[98:113]
	v_lshl_add_u64 v[164:165], v[150:151], 0, v[130:131]
	v_add_co_u32_e32 v164, vcc, s40, v164
	s_nop 1
	v_addc_co_u32_e32 v165, vcc, 0, v165, vcc
	global_load_dwordx4 v[164:167], v[164:165], off offset:384
	ds_read_b128 v[236:239], v137 offset:23072
	s_waitcnt lgkmcnt(5)
	v_mfma_f32_32x32x16_bf16 v[82:97], v[200:203], v[224:227], v[82:97]
	ds_read_b128 v[240:243], v137 offset:27680
	s_waitcnt lgkmcnt(5)
	v_mfma_f32_32x32x16_bf16 v[66:81], v[200:203], v[228:231], v[66:81]
	v_lshl_add_u64 v[168:169], v[148:149], 0, v[130:131]
	v_add_co_u32_e32 v168, vcc, s41, v168
	s_nop 1
	v_addc_co_u32_e32 v169, vcc, 0, v169, vcc
	global_load_dwordx4 v[168:171], v[168:169], off offset:-4096
	ds_read_b128 v[244:247], v137 offset:32288
	s_waitcnt lgkmcnt(5)
	v_mfma_f32_32x32x16_bf16 v[50:65], v[208:211], v[212:215], v[50:65]
	v_mfma_f32_32x32x16_bf16 v[34:49], v[208:211], v[216:219], v[34:49]
	v_lshl_add_u64 v[172:173], v[148:149], 0, v[130:131]
	v_add_co_u32_e32 v172, vcc, s41, v172
	s_nop 1
	v_addc_co_u32_e32 v173, vcc, 0, v173, vcc
	global_load_dwordx4 v[172:175], v[172:173], off
	v_mfma_f32_32x32x16_bf16 v[18:33], v[208:211], v[224:227], v[18:33]
	v_mfma_f32_32x32x16_bf16 v[2:17], v[208:211], v[228:231], v[2:17]
	v_lshl_add_u64 v[176:177], v[148:149], 0, v[130:131]
	v_add_co_u32_e32 v176, vcc, s42, v176
	s_nop 1
	v_addc_co_u32_e32 v177, vcc, 0, v177, vcc
	global_load_dwordx4 v[176:179], v[176:177], off offset:-4096
	ds_read_b128 v[208:211], v133 offset:4640
	s_waitcnt lgkmcnt(4)
;     ...
;   for (int kt = 0; kt < nk; ++kt) {
;     const int kn = (kt + 1 < nk) ? kt + 1 : kt;
;     GW_LOAD2(kn * 64, kn * bkstep)
;     __builtin_amdgcn_sched_barrier(0);
;     __builtin_amdgcn_s_setprio(1);
; #pragma unroll
;     for (int st = 0; st < 4; ++st) {
;       bf16x8 a0 = *(const bf16x8*)(Ab + st * 32);
;       bf16x8 a1 = *(const bf16x8*)(Ab + 32 * LSTR + st * 32);
;       bf16x8 b0 = *(const bf16x8*)(Bb + st * 32);
;       bf16x8 b1 = *(const bf16x8*)(Bb + 32 * LSTR + st * 32);
;       bf16x8 b2 = *(const bf16x8*)(Bb + 64 * LSTR + st * 32);
;       bf16x8 b3 = *(const bf16x8*)(Bb + 96 * LSTR + st * 32);
;       acc[0][0] = mfma32(a0, b0, acc[0][0]);
;       acc[0][1] = mfma32(a0, b1, acc[0][1]);
;       acc[0][2] = mfma32(a0, b2, acc[0][2]);
;       acc[0][3] = mfma32(a0, b3, acc[0][3]);
;       acc[1][0] = mfma32(a1, b0, acc[1][0]);
;       acc[1][1] = mfma32(a1, b1, acc[1][1]);
;       acc[1][2] = mfma32(a1, b2, acc[1][2]);
;       acc[1][3] = mfma32(a1, b3, acc[1][3]);
;     }
;     __builtin_amdgcn_s_setprio(0);
;     __builtin_amdgcn_sched_barrier(0);
;     __syncthreads();
;     GW_STORE()
;     __syncthreads();
	v_mfma_f32_32x32x16_bf16 v[114:129], v[204:207], v[232:235], v[114:129]
	ds_read_b128 v[200:203], v133 offset:64
	ds_read_b128 v[212:215], v137 offset:18496
	s_waitcnt lgkmcnt(5)
	v_mfma_f32_32x32x16_bf16 v[98:113], v[204:207], v[236:239], v[98:113]
	v_lshl_add_u64 v[180:181], v[148:149], 0, v[130:131]
	v_add_co_u32_e32 v180, vcc, s42, v180
	s_nop 1
	v_addc_co_u32_e32 v181, vcc, 0, v181, vcc
	global_load_dwordx4 v[180:183], v[180:181], off
	ds_read_b128 v[216:219], v137 offset:23104
	s_waitcnt lgkmcnt(5)
	v_mfma_f32_32x32x16_bf16 v[82:97], v[204:207], v[240:243], v[82:97]
	ds_read_b128 v[224:227], v137 offset:27712
	s_waitcnt lgkmcnt(5)
	v_mfma_f32_32x32x16_bf16 v[66:81], v[204:207], v[244:247], v[66:81]
	v_lshl_add_u64 v[184:185], v[148:149], 0, v[130:131]
	v_add_co_u32_e32 v184, vcc, s43, v184
	s_nop 1
	v_addc_co_u32_e32 v185, vcc, 0, v185, vcc
	global_load_dwordx4 v[184:187], v[184:185], off offset:-4096
	ds_read_b128 v[228:231], v137 offset:32320
	s_waitcnt lgkmcnt(5)
	v_mfma_f32_32x32x16_bf16 v[50:65], v[208:211], v[232:235], v[50:65]
	v_mfma_f32_32x32x16_bf16 v[34:49], v[208:211], v[236:239], v[34:49]
	v_lshl_add_u64 v[188:189], v[148:149], 0, v[130:131]
	v_add_co_u32_e32 v188, vcc, s43, v188
	s_nop 1
	v_addc_co_u32_e32 v189, vcc, 0, v189, vcc
	global_load_dwordx4 v[188:191], v[188:189], off
	v_mfma_f32_32x32x16_bf16 v[18:33], v[208:211], v[240:243], v[18:33]
	v_mfma_f32_32x32x16_bf16 v[2:17], v[208:211], v[244:247], v[2:17]
	v_lshl_add_u64 v[192:193], v[148:149], 0, v[130:131]
	v_add_co_u32_e32 v192, vcc, s44, v192
	s_nop 1
	v_addc_co_u32_e32 v193, vcc, 0, v193, vcc
	global_load_dwordx4 v[192:195], v[192:193], off offset:-4096
	ds_read_b128 v[208:211], v133 offset:4672
	s_waitcnt lgkmcnt(4)
	v_mfma_f32_32x32x16_bf16 v[114:129], v[200:203], v[212:215], v[114:129]
	ds_read_b128 v[204:207], v133 offset:96
	ds_read_b128 v[232:235], v137 offset:18528
	s_waitcnt lgkmcnt(5)
	v_mfma_f32_32x32x16_bf16 v[98:113], v[200:203], v[216:219], v[98:113]
	v_lshl_add_u64 v[196:197], v[148:149], 0, v[130:131]
	v_add_co_u32_e32 v196, vcc, s44, v196
	s_nop 1
	v_addc_co_u32_e32 v197, vcc, 0, v197, vcc
	global_load_dwordx4 v[196:199], v[196:197], off
	ds_read_b128 v[236:239], v137 offset:23136
	s_waitcnt lgkmcnt(5)
	v_mfma_f32_32x32x16_bf16 v[82:97], v[200:203], v[224:227], v[82:97]
	ds_read_b128 v[240:243], v137 offset:27744
	s_waitcnt lgkmcnt(5)
	v_mfma_f32_32x32x16_bf16 v[66:81], v[200:203], v[228:231], v[66:81]
	ds_read_b128 v[244:247], v137 offset:32352
	s_waitcnt lgkmcnt(5)
	v_mfma_f32_32x32x16_bf16 v[50:65], v[208:211], v[212:215], v[50:65]
	v_mfma_f32_32x32x16_bf16 v[34:49], v[208:211], v[216:219], v[34:49]
	v_mfma_f32_32x32x16_bf16 v[18:33], v[208:211], v[224:227], v[18:33]
	v_mfma_f32_32x32x16_bf16 v[2:17], v[208:211], v[228:231], v[2:17]
	ds_read_b128 v[208:211], v133 offset:4704
	s_waitcnt lgkmcnt(4)
	v_mfma_f32_32x32x16_bf16 v[114:129], v[204:207], v[232:235], v[114:129]
	s_waitcnt lgkmcnt(3)
	v_mfma_f32_32x32x16_bf16 v[98:113], v[204:207], v[236:239], v[98:113]
	s_waitcnt lgkmcnt(2)
	v_mfma_f32_32x32x16_bf16 v[82:97], v[204:207], v[240:243], v[82:97]
	s_waitcnt lgkmcnt(1)
	v_mfma_f32_32x32x16_bf16 v[66:81], v[204:207], v[244:247], v[66:81]
	s_waitcnt lgkmcnt(0)
	v_mfma_f32_32x32x16_bf16 v[50:65], v[208:211], v[232:235], v[50:65]
	v_mfma_f32_32x32x16_bf16 v[34:49], v[208:211], v[236:239], v[34:49]
	v_mfma_f32_32x32x16_bf16 v[18:33], v[208:211], v[240:243], v[18:33]
	v_mfma_f32_32x32x16_bf16 v[2:17], v[208:211], v[244:247], v[2:17]
	s_setprio 0
	s_add_i32 s15, s15, -1
	v_lshl_add_u64 v[148:149], v[148:149], 0, s[4:5]
	s_cmp_lg_u32 s15, 0
	v_lshl_add_u64 v[150:151], v[150:151], 0, s[10:11]
	s_barrier
	s_waitcnt vmcnt(11)
	ds_write_b128 v132, v[152:155]
	v_lshl_add_u64 v[152:153], v[150:151], 0, v[130:131]
	v_add_co_u32_e32 v152, vcc, s37, v152
	s_nop 1
	v_addc_co_u32_e32 v153, vcc, 0, v153, vcc
	global_load_dwordx4 v[152:155], v[152:153], off offset:384
	s_waitcnt vmcnt(11)
	ds_write_b128 v132, v[156:159] offset:4608
	v_lshl_add_u64 v[156:157], v[150:151], 0, v[130:131]
	v_add_co_u32_e32 v156, vcc, s38, v156
	s_nop 1
	v_addc_co_u32_e32 v157, vcc, 0, v157, vcc
	global_load_dwordx4 v[156:159], v[156:157], off offset:384
	s_waitcnt vmcnt(11)
	ds_write_b128 v132, v[160:163] offset:9216
	v_lshl_add_u64 v[160:161], v[150:151], 0, v[130:131]
	v_add_co_u32_e32 v160, vcc, s39, v160
	s_nop 1
	v_addc_co_u32_e32 v161, vcc, 0, v161, vcc
	global_load_dwordx4 v[160:163], v[160:161], off offset:384
	s_waitcnt vmcnt(11)
	ds_write_b128 v132, v[164:167] offset:13824
	s_waitcnt vmcnt(10)
	ds_write_b128 v132, v[168:171] offset:18432
	s_waitcnt vmcnt(9)
	ds_write_b128 v132, v[172:175] offset:23040
	s_waitcnt vmcnt(8)
	ds_write_b128 v132, v[176:179] offset:27648
	s_waitcnt vmcnt(7)
	ds_write_b128 v132, v[180:183] offset:32256
	s_waitcnt vmcnt(6)
	ds_write_b128 v132, v[184:187] offset:36864
	s_waitcnt vmcnt(5)
	ds_write_b128 v132, v[188:191] offset:41472
	s_waitcnt vmcnt(4)
	ds_write_b128 v132, v[192:195] offset:46080
	s_waitcnt vmcnt(3)
	ds_write_b128 v132, v[196:199] offset:50688
	s_waitcnt lgkmcnt(0)
	s_barrier
	s_cbranch_scc1 .LBB0_2143
;     ...
;   for (int kt = 0; kt < nk; ++kt) {
;     const int kn = (kt + 1 < nk) ? kt + 1 : kt;
;     GW_LOAD2(kn * 64, kn * bkstep)
;     __builtin_amdgcn_sched_barrier(0);
;     __builtin_amdgcn_s_setprio(1);
; #pragma unroll
;     for (int st = 0; st < 4; ++st) {
;       bf16x8 a0 = *(const bf16x8*)(Ab + st * 32);
;       bf16x8 a1 = *(const bf16x8*)(Ab + 32 * LSTR + st * 32);
;       bf16x8 b0 = *(const bf16x8*)(Bb + st * 32);
;       bf16x8 b1 = *(const bf16x8*)(Bb + 32 * LSTR + st * 32);
;       bf16x8 b2 = *(const bf16x8*)(Bb + 64 * LSTR + st * 32);
;       bf16x8 b3 = *(const bf16x8*)(Bb + 96 * LSTR + st * 32);
;       acc[0][0] = mfma32(a0, b0, acc[0][0]);
;       acc[0][1] = mfma32(a0, b1, acc[0][1]);
;       acc[0][2] = mfma32(a0, b2, acc[0][2]);
;       acc[0][3] = mfma32(a0, b3, acc[0][3]);
;       acc[1][0] = mfma32(a1, b0, acc[1][0]);
;       acc[1][1] = mfma32(a1, b1, acc[1][1]);
;       acc[1][2] = mfma32(a1, b2, acc[1][2]);
;       acc[1][3] = mfma32(a1, b3, acc[1][3]);
;     }
;     __builtin_amdgcn_s_setprio(0);
;     __builtin_amdgcn_sched_barrier(0);
	s_setprio 1
	ds_read_b128 v[200:203], v133 offset:0
	ds_read_b128 v[212:215], v137 offset:18432
	ds_read_b128 v[216:219], v137 offset:23040
	ds_read_b128 v[224:227], v137 offset:27648
	ds_read_b128 v[228:231], v137 offset:32256
	ds_read_b128 v[208:211], v133 offset:4608
	s_waitcnt lgkmcnt(4)
	v_mfma_f32_32x32x16_bf16 v[114:129], v[200:203], v[212:215], v[114:129]
	ds_read_b128 v[204:207], v133 offset:32
	ds_read_b128 v[232:235], v137 offset:18464
	s_waitcnt lgkmcnt(5)
	v_mfma_f32_32x32x16_bf16 v[98:113], v[200:203], v[216:219], v[98:113]
	v_lshl_add_u64 v[164:165], v[150:151], 0, v[130:131]
	v_add_co_u32_e32 v164, vcc, s40, v164
	s_nop 1
	v_addc_co_u32_e32 v165, vcc, 0, v165, vcc
	global_load_dwordx4 v[164:167], v[164:165], off offset:384
	ds_read_b128 v[236:239], v137 offset:23072
	s_waitcnt lgkmcnt(5)
	v_mfma_f32_32x32x16_bf16 v[82:97], v[200:203], v[224:227], v[82:97]
	ds_read_b128 v[240:243], v137 offset:27680
	s_waitcnt lgkmcnt(5)
	v_mfma_f32_32x32x16_bf16 v[66:81], v[200:203], v[228:231], v[66:81]
	v_lshl_add_u64 v[168:169], v[148:149], 0, v[130:131]
	v_add_co_u32_e32 v168, vcc, s41, v168
	s_nop 1
	v_addc_co_u32_e32 v169, vcc, 0, v169, vcc
	global_load_dwordx4 v[168:171], v[168:169], off offset:-4096
	ds_read_b128 v[244:247], v137 offset:32288
	s_waitcnt lgkmcnt(5)
	v_mfma_f32_32x32x16_bf16 v[50:65], v[208:211], v[212:215], v[50:65]
	v_mfma_f32_32x32x16_bf16 v[34:49], v[208:211], v[216:219], v[34:49]
	v_lshl_add_u64 v[172:173], v[148:149], 0, v[130:131]
	v_add_co_u32_e32 v172, vcc, s41, v172
	s_nop 1
	v_addc_co_u32_e32 v173, vcc, 0, v173, vcc
	global_load_dwordx4 v[172:175], v[172:173], off
	v_mfma_f32_32x32x16_bf16 v[18:33], v[208:211], v[224:227], v[18:33]
	v_mfma_f32_32x32x16_bf16 v[2:17], v[208:211], v[228:231], v[2:17]
	v_lshl_add_u64 v[176:177], v[148:149], 0, v[130:131]
	v_add_co_u32_e32 v176, vcc, s42, v176
	s_nop 1
	v_addc_co_u32_e32 v177, vcc, 0, v177, vcc
	global_load_dwordx4 v[176:179], v[176:177], off offset:-4096
	ds_read_b128 v[208:211], v133 offset:4640
	s_waitcnt lgkmcnt(4)
	v_mfma_f32_32x32x16_bf16 v[114:129], v[204:207], v[232:235], v[114:129]
	ds_read_b128 v[200:203], v133 offset:64
	ds_read_b128 v[212:215], v137 offset:18496
	s_waitcnt lgkmcnt(5)
	v_mfma_f32_32x32x16_bf16 v[98:113], v[204:207], v[236:239], v[98:113]
	v_lshl_add_u64 v[180:181], v[148:149], 0, v[130:131]
	v_add_co_u32_e32 v180, vcc, s42, v180
	s_nop 1
	v_addc_co_u32_e32 v181, vcc, 0, v181, vcc
	global_load_dwordx4 v[180:183], v[180:181], off
	ds_read_b128 v[216:219], v137 offset:23104
	s_waitcnt lgkmcnt(5)
	v_mfma_f32_32x32x16_bf16 v[82:97], v[204:207], v[240:243], v[82:97]
	ds_read_b128 v[224:227], v137 offset:27712
	s_waitcnt lgkmcnt(5)
	v_mfma_f32_32x32x16_bf16 v[66:81], v[204:207], v[244:247], v[66:81]
	v_lshl_add_u64 v[184:185], v[148:149], 0, v[130:131]
	v_add_co_u32_e32 v184, vcc, s43, v184
	s_nop 1
	v_addc_co_u32_e32 v185, vcc, 0, v185, vcc
	global_load_dwordx4 v[184:187], v[184:185], off offset:-4096
	ds_read_b128 v[228:231], v137 offset:32320
	s_waitcnt lgkmcnt(5)
	v_mfma_f32_32x32x16_bf16 v[50:65], v[208:211], v[232:235], v[50:65]
	v_mfma_f32_32x32x16_bf16 v[34:49], v[208:211], v[236:239], v[34:49]
	v_lshl_add_u64 v[188:189], v[148:149], 0, v[130:131]
	v_add_co_u32_e32 v188, vcc, s43, v188
	s_nop 1
	v_addc_co_u32_e32 v189, vcc, 0, v189, vcc
	global_load_dwordx4 v[188:191], v[188:189], off
	v_mfma_f32_32x32x16_bf16 v[18:33], v[208:211], v[240:243], v[18:33]
	v_mfma_f32_32x32x16_bf16 v[2:17], v[208:211], v[244:247], v[2:17]
	v_lshl_add_u64 v[192:193], v[148:149], 0, v[130:131]
	v_add_co_u32_e32 v192, vcc, s44, v192
	s_nop 1
	v_addc_co_u32_e32 v193, vcc, 0, v193, vcc
	global_load_dwordx4 v[192:195], v[192:193], off offset:-4096
	ds_read_b128 v[208:211], v133 offset:4672
	s_waitcnt lgkmcnt(4)
	v_mfma_f32_32x32x16_bf16 v[114:129], v[200:203], v[212:215], v[114:129]
	ds_read_b128 v[204:207], v133 offset:96
	ds_read_b128 v[232:235], v137 offset:18528
	s_waitcnt lgkmcnt(5)
	v_mfma_f32_32x32x16_bf16 v[98:113], v[200:203], v[216:219], v[98:113]
	v_lshl_add_u64 v[196:197], v[148:149], 0, v[130:131]
	v_add_co_u32_e32 v196, vcc, s44, v196
	s_nop 1
	v_addc_co_u32_e32 v197, vcc, 0, v197, vcc
	global_load_dwordx4 v[196:199], v[196:197], off
	ds_read_b128 v[236:239], v137 offset:23136
	s_waitcnt lgkmcnt(5)
	v_mfma_f32_32x32x16_bf16 v[82:97], v[200:203], v[224:227], v[82:97]
	ds_read_b128 v[240:243], v137 offset:27744
	s_waitcnt lgkmcnt(5)
	v_mfma_f32_32x32x16_bf16 v[66:81], v[200:203], v[228:231], v[66:81]
	ds_read_b128 v[244:247], v137 offset:32352
	s_waitcnt lgkmcnt(5)
	v_mfma_f32_32x32x16_bf16 v[50:65], v[208:211], v[212:215], v[50:65]
	v_mfma_f32_32x32x16_bf16 v[34:49], v[208:211], v[216:219], v[34:49]
	v_mfma_f32_32x32x16_bf16 v[18:33], v[208:211], v[224:227], v[18:33]
	v_mfma_f32_32x32x16_bf16 v[2:17], v[208:211], v[228:231], v[2:17]
	ds_read_b128 v[208:211], v133 offset:4704
	s_waitcnt lgkmcnt(4)
	v_mfma_f32_32x32x16_bf16 v[114:129], v[204:207], v[232:235], v[114:129]
	s_waitcnt lgkmcnt(3)
	v_mfma_f32_32x32x16_bf16 v[98:113], v[204:207], v[236:239], v[98:113]
	s_waitcnt lgkmcnt(2)
	v_mfma_f32_32x32x16_bf16 v[82:97], v[204:207], v[240:243], v[82:97]
	s_waitcnt lgkmcnt(1)
	v_mfma_f32_32x32x16_bf16 v[66:81], v[204:207], v[244:247], v[66:81]
	s_waitcnt lgkmcnt(0)
	v_mfma_f32_32x32x16_bf16 v[50:65], v[208:211], v[232:235], v[50:65]
	v_mfma_f32_32x32x16_bf16 v[34:49], v[208:211], v[236:239], v[34:49]
	v_mfma_f32_32x32x16_bf16 v[18:33], v[208:211], v[240:243], v[18:33]
	v_mfma_f32_32x32x16_bf16 v[2:17], v[208:211], v[244:247], v[2:17]
	s_setprio 0
	v_lshl_add_u64 v[148:149], v[148:149], 0, s[4:5]
	v_lshl_add_u64 v[150:151], v[150:151], 0, s[10:11]
	s_barrier
;     ...
;   for (int kt = 0; kt < nk; ++kt) {
;     const int kn = (kt + 1 < nk) ? kt + 1 : kt;
;     GW_LOAD2(kn * 64, kn * bkstep)
;     __builtin_amdgcn_sched_barrier(0);
;     __builtin_amdgcn_s_setprio(1);
; #pragma unroll
;     for (int st = 0; st < 4; ++st) {
;       bf16x8 a0 = *(const bf16x8*)(Ab + st * 32);
;       bf16x8 a1 = *(const bf16x8*)(Ab + 32 * LSTR + st * 32);
;       bf16x8 b0 = *(const bf16x8*)(Bb + st * 32);
;       bf16x8 b1 = *(const bf16x8*)(Bb + 32 * LSTR + st * 32);
;       bf16x8 b2 = *(const bf16x8*)(Bb + 64 * LSTR + st * 32);
;       bf16x8 b3 = *(const bf16x8*)(Bb + 96 * LSTR + st * 32);
;       acc[0][0] = mfma32(a0, b0, acc[0][0]);
;       acc[0][1] = mfma32(a0, b1, acc[0][1]);
;       acc[0][2] = mfma32(a0, b2, acc[0][2]);
;       acc[0][3] = mfma32(a0, b3, acc[0][3]);
;       acc[1][0] = mfma32(a1, b0, acc[1][0]);
;       acc[1][1] = mfma32(a1, b1, acc[1][1]);
;       acc[1][2] = mfma32(a1, b2, acc[1][2]);
;       acc[1][3] = mfma32(a1, b3, acc[1][3]);
;     }
;     __builtin_amdgcn_s_setprio(0);
;     __builtin_amdgcn_sched_barrier(0);
;     __syncthreads();
;     GW_STORE()
;     __syncthreads();
	s_waitcnt vmcnt(11)
	ds_write_b128 v132, v[152:155]
	s_waitcnt vmcnt(10)
	ds_write_b128 v132, v[156:159] offset:4608
	s_waitcnt vmcnt(9)
	ds_write_b128 v132, v[160:163] offset:9216
	s_waitcnt vmcnt(8)
	ds_write_b128 v132, v[164:167] offset:13824
	s_waitcnt vmcnt(7)
	ds_write_b128 v132, v[168:171] offset:18432
	s_waitcnt vmcnt(6)
	ds_write_b128 v132, v[172:175] offset:23040
	s_waitcnt vmcnt(5)
	ds_write_b128 v132, v[176:179] offset:27648
	s_waitcnt vmcnt(4)
	ds_write_b128 v132, v[180:183] offset:32256
	s_waitcnt vmcnt(3)
	ds_write_b128 v132, v[184:187] offset:36864
	s_waitcnt vmcnt(2)
	ds_write_b128 v132, v[188:191] offset:41472
	s_waitcnt vmcnt(1)
	ds_write_b128 v132, v[192:195] offset:46080
	s_waitcnt vmcnt(0)
	ds_write_b128 v132, v[196:199] offset:50688
	s_waitcnt lgkmcnt(0)
	s_barrier
	v_add_co_u32_e32 v156, vcc, 0x3e0000, v138
	s_nop 0
	s_nop 0
	s_nop 0
	v_addc_co_u32_e32 v157, vcc, 0, v139, vcc
	v_add_co_u32_e32 v160, vcc, 0x3e1000, v138
	s_mov_b32 s18, 0
	s_nop 0
	v_addc_co_u32_e32 v161, vcc, 0, v139, vcc
	v_add_co_u32_e32 v164, vcc, 0x3e2000, v138
	s_nop 0
	v_addc_co_u32_e32 v165, vcc, 0, v139, vcc
	v_add_co_u32_e32 v168, vcc, 0x3e3000, v138
	s_nop 1
	v_addc_co_u32_e32 v169, vcc, 0, v139, vcc
	v_add_co_u32_e32 v172, vcc, 0x3e4000, v138
	s_nop 0
	v_addc_co_u32_e32 v173, vcc, 0, v139, vcc
	v_add_co_u32_e32 v176, vcc, 0x3e5000, v138
	s_nop 1
	v_addc_co_u32_e32 v177, vcc, 0, v139, vcc
	v_add_co_u32_e32 v180, vcc, 0x3e6000, v138
	s_nop 0
	v_addc_co_u32_e32 v181, vcc, 0, v139, vcc
	v_add_co_u32_e32 v138, vcc, 0x3e7000, v138
	s_nop 1
	v_addc_co_u32_e32 v139, vcc, 0, v139, vcc
	s_nop 0
	s_setprio 1
	ds_read_b128 v[188:191], v133 offset:0
	ds_read_b128 v[200:203], v137 offset:18432
	ds_read_b128 v[204:207], v137 offset:23040
	ds_read_b128 v[208:211], v137 offset:27648
	ds_read_b128 v[212:215], v137 offset:32256
	ds_read_b128 v[196:199], v133 offset:4608
	s_waitcnt lgkmcnt(4)
	v_mfma_f32_32x32x16_bf16 v[114:129], v[188:191], v[200:203], v[114:129]
	ds_read_b128 v[192:195], v133 offset:32
	ds_read_b128 v[216:219], v137 offset:18464
	s_waitcnt lgkmcnt(5)
	v_mfma_f32_32x32x16_bf16 v[98:113], v[188:191], v[204:207], v[98:113]
	ds_read_b128 v[224:227], v137 offset:23072
	s_waitcnt lgkmcnt(5)
	v_mfma_f32_32x32x16_bf16 v[82:97], v[188:191], v[208:211], v[82:97]
	ds_read_b128 v[228:231], v137 offset:27680
	s_waitcnt lgkmcnt(5)
	v_mfma_f32_32x32x16_bf16 v[66:81], v[188:191], v[212:215], v[66:81]
	ds_read_b128 v[232:235], v137 offset:32288
	s_waitcnt lgkmcnt(5)
	v_mfma_f32_32x32x16_bf16 v[50:65], v[196:199], v[200:203], v[50:65]
	v_mfma_f32_32x32x16_bf16 v[34:49], v[196:199], v[204:207], v[34:49]
	v_mfma_f32_32x32x16_bf16 v[18:33], v[196:199], v[208:211], v[18:33]
	v_mfma_f32_32x32x16_bf16 v[2:17], v[196:199], v[212:215], v[2:17]
	ds_read_b128 v[196:199], v133 offset:4640
	s_waitcnt lgkmcnt(4)
	v_mfma_f32_32x32x16_bf16 v[114:129], v[192:195], v[216:219], v[114:129]
	ds_read_b128 v[188:191], v133 offset:64
	ds_read_b128 v[200:203], v137 offset:18496
	s_waitcnt lgkmcnt(5)
	v_mfma_f32_32x32x16_bf16 v[98:113], v[192:195], v[224:227], v[98:113]
	ds_read_b128 v[204:207], v137 offset:23104
	s_waitcnt lgkmcnt(5)
	v_mfma_f32_32x32x16_bf16 v[82:97], v[192:195], v[228:231], v[82:97]
	ds_read_b128 v[208:211], v137 offset:27712
	s_waitcnt lgkmcnt(5)
	v_mfma_f32_32x32x16_bf16 v[66:81], v[192:195], v[232:235], v[66:81]
	ds_read_b128 v[212:215], v137 offset:32320
	s_waitcnt lgkmcnt(5)
	v_mfma_f32_32x32x16_bf16 v[50:65], v[196:199], v[216:219], v[50:65]
	v_mfma_f32_32x32x16_bf16 v[34:49], v[196:199], v[224:227], v[34:49]
	v_mfma_f32_32x32x16_bf16 v[18:33], v[196:199], v[228:231], v[18:33]
	v_mfma_f32_32x32x16_bf16 v[2:17], v[196:199], v[232:235], v[2:17]
	ds_read_b128 v[196:199], v133 offset:4672
	s_waitcnt lgkmcnt(4)
	v_mfma_f32_32x32x16_bf16 v[114:129], v[188:191], v[200:203], v[114:129]
	ds_read_b128 v[192:195], v133 offset:96
	ds_read_b128 v[216:219], v137 offset:18528
	s_waitcnt lgkmcnt(5)
	v_mfma_f32_32x32x16_bf16 v[98:113], v[188:191], v[204:207], v[98:113]
	ds_read_b128 v[224:227], v137 offset:23136
	s_waitcnt lgkmcnt(5)
	v_mfma_f32_32x32x16_bf16 v[82:97], v[188:191], v[208:211], v[82:97]
	ds_read_b128 v[228:231], v137 offset:27744
	s_waitcnt lgkmcnt(5)
	v_mfma_f32_32x32x16_bf16 v[66:81], v[188:191], v[212:215], v[66:81]
	ds_read_b128 v[232:235], v137 offset:32352
	s_waitcnt lgkmcnt(5)
	v_mfma_f32_32x32x16_bf16 v[50:65], v[196:199], v[200:203], v[50:65]
	v_mfma_f32_32x32x16_bf16 v[34:49], v[196:199], v[204:207], v[34:49]
	v_mfma_f32_32x32x16_bf16 v[18:33], v[196:199], v[208:211], v[18:33]
	v_mfma_f32_32x32x16_bf16 v[2:17], v[196:199], v[212:215], v[2:17]
	ds_read_b128 v[196:199], v133 offset:4704
	s_waitcnt lgkmcnt(4)
	v_mfma_f32_32x32x16_bf16 v[114:129], v[192:195], v[216:219], v[114:129]
	s_waitcnt lgkmcnt(3)
	v_mfma_f32_32x32x16_bf16 v[98:113], v[192:195], v[224:227], v[98:113]
	s_waitcnt lgkmcnt(2)
	v_mfma_f32_32x32x16_bf16 v[82:97], v[192:195], v[228:231], v[82:97]
	s_waitcnt lgkmcnt(1)
	v_mfma_f32_32x32x16_bf16 v[66:81], v[192:195], v[232:235], v[66:81]
	s_waitcnt lgkmcnt(0)
	v_mfma_f32_32x32x16_bf16 v[50:65], v[196:199], v[216:219], v[50:65]
	v_mfma_f32_32x32x16_bf16 v[34:49], v[196:199], v[224:227], v[34:49]
	v_mfma_f32_32x32x16_bf16 v[18:33], v[196:199], v[228:231], v[18:33]
	v_mfma_f32_32x32x16_bf16 v[2:17], v[196:199], v[232:235], v[2:17]
	s_setprio 0
	s_lshl_b32 s19, s14, 8
	s_mov_b64 s[14:15], -1
	s_barrier
	s_waitcnt lgkmcnt(0)
	s_branch .LBB0_2146
